# adds: gMLP prompt item (VALU-bound erf-gelu): |v|*c+1 via two v_fma with |.| modifier (169 sites), final select as fma(-|v|, qe, max(v,0)) (51 sites); bit-identical results
# speedup vs baseline: 1.0057x; 1.0054x over previous
.LBB0_443:
	s_waitcnt vmcnt(0)
	v_mov_b32_e32 v55, v0
	s_mov_b64 s[12:13], s[74:75]
	v_readfirstlane_b32 s0, v55
	s_ashr_i32 s10, s0, 6
	s_add_u32 s4, s12, 0x696e000
	v_bfe_u32 v3, v55, 4, 2
	s_addc_u32 s5, s13, 0
	s_lshl_b32 s11, s10, 4
	s_ashr_i32 s71, s70, 31
	v_or_b32_e32 v16, s11, v3
	s_lshl_b64 s[6:7], s[70:71], 7
	v_ashrrev_i32_e32 v17, 31, v16
	v_lshl_add_u64 v[4:5], s[6:7], 0, v[16:17]
	v_and_b32_e32 v54, 15, v55
	v_lshlrev_b64 v[4:5], 11, v[4:5]
	v_lshl_add_u64 v[4:5], s[4:5], 0, v[4:5]
	v_lshlrev_b32_e32 v6, 4, v54
	s_waitcnt lgkmcnt(0)
	v_mov_b32_e32 v7, v2
	v_lshl_add_u64 v[20:21], v[4:5], 0, v[6:7]
	s_barrier
	global_load_dwordx4 v[8:11], v[20:21], off
	global_load_dwordx4 v[4:7], v[20:21], off offset:256
	v_mov_b64_e32 v[18:19], s[44:45]
	v_mov_b32_e32 v13, v2
	s_waitcnt vmcnt(1)
	v_lshlrev_b32_e32 v24, 16, v10
	v_and_b32_e32 v25, 0xffff0000, v10
	v_and_b32_e32 v15, 0xffff0000, v8
	v_and_b32_e32 v23, 0xffff0000, v9
	v_lshlrev_b32_e32 v22, 16, v9
	v_lshlrev_b32_e32 v14, 16, v8
	v_lshlrev_b32_e32 v8, 16, v11
	v_and_b32_e32 v9, 0xffff0000, v11
	v_fma_f32 v10, |v24|, s40, 1.0
	v_fma_f32 v11, |v25|, s40, 1.0
	v_fma_f32 v28, |v14|, s40, 1.0
	v_fma_f32 v29, |v15|, s40, 1.0
	v_rcp_f32_e32 v10, v10
	v_rcp_f32_e32 v11, v11
	v_fma_f32 v32, |v22|, s40, 1.0
	v_fma_f32 v33, |v23|, s40, 1.0
	v_rcp_f32_e32 v28, v28
	v_rcp_f32_e32 v29, v29
	v_rcp_f32_e32 v32, v32
	v_rcp_f32_e32 v33, v33
	v_pk_mul_f32 v[26:27], v[24:25], v[24:25]
	v_pk_mul_f32 v[30:31], v[14:15], v[14:15]
	v_pk_mul_f32 v[26:27], v[26:27], s[64:65] op_sel_hi:[1,0]
	v_pk_fma_f32 v[36:37], v[10:11], s[42:43], v[18:19] op_sel_hi:[1,0,0]
	v_pk_mul_f32 v[34:35], v[22:23], v[22:23]
	v_pk_mul_f32 v[30:31], v[30:31], s[64:65] op_sel_hi:[1,0]
	v_exp_f32_e32 v26, v26
	v_exp_f32_e32 v27, v27
	v_pk_fma_f32 v[38:39], v[28:29], s[42:43], v[18:19] op_sel_hi:[1,0,0]
	v_pk_fma_f32 v[36:37], v[10:11], v[36:37], s[48:49] op_sel_hi:[1,1,0]
	v_pk_mul_f32 v[34:35], v[34:35], s[64:65] op_sel_hi:[1,0]
	v_exp_f32_e32 v30, v30
	v_exp_f32_e32 v31, v31
	v_pk_fma_f32 v[40:41], v[32:33], s[42:43], v[18:19] op_sel_hi:[1,0,0]
	v_pk_fma_f32 v[38:39], v[28:29], v[38:39], s[48:49] op_sel_hi:[1,1,0]
	v_pk_fma_f32 v[36:37], v[10:11], v[36:37], s[50:51] op_sel_hi:[1,1,0]
	v_exp_f32_e32 v34, v34
	v_exp_f32_e32 v35, v35
	v_pk_fma_f32 v[40:41], v[32:33], v[40:41], s[48:49] op_sel_hi:[1,1,0]
	v_pk_fma_f32 v[38:39], v[28:29], v[38:39], s[50:51] op_sel_hi:[1,1,0]
	v_pk_fma_f32 v[36:37], v[10:11], v[36:37], s[56:57] op_sel_hi:[1,1,0]
	v_pk_fma_f32 v[40:41], v[32:33], v[40:41], s[50:51] op_sel_hi:[1,1,0]
	v_pk_fma_f32 v[38:39], v[28:29], v[38:39], s[56:57] op_sel_hi:[1,1,0]
	v_pk_mul_f32 v[10:11], v[10:11], v[36:37]
	v_pk_fma_f32 v[40:41], v[32:33], v[40:41], s[56:57] op_sel_hi:[1,1,0]
	v_pk_mul_f32 v[28:29], v[28:29], v[38:39]
	v_pk_mul_f32 v[10:11], v[26:27], v[10:11]
	v_pk_mul_f32 v[32:33], v[32:33], v[40:41]
	v_pk_mul_f32 v[26:27], v[30:31], v[28:29]
	v_max_f32_e32 v80, 0, v24
	v_pk_mul_f32 v[28:29], v[34:35], v[32:33]
	v_pk_mul_f32 v[32:33], v[26:27], v[14:15]
	v_fma_f32 v37, -|v24|, v10, v80
	v_max_f32_e32 v81, 0, v25
	v_pk_mul_f32 v[34:35], v[22:23], v[28:29]
	v_pk_fma_f32 v[28:29], v[22:23], v[28:29], v[22:23] neg_lo:[1,0,0] neg_hi:[1,0,0]
	v_fma_f32 v11, -|v25|, v11, v81
	v_cmp_gt_f32_e32 vcc, 0, v22
	v_pk_fma_f32 v[26:27], v[26:27], v[14:15], v[14:15] neg_lo:[1,0,0] neg_hi:[1,0,0]
	v_mul_f32_e32 v36, v37, v37
	v_cndmask_b32_e32 v25, v28, v34, vcc
	v_cmp_gt_f32_e32 vcc, 0, v14
	v_mov_b32_e32 v14, v25
	v_mul_f32_e32 v10, v11, v11
	v_cndmask_b32_e32 v24, v26, v32, vcc
	v_cmp_gt_f32_e32 vcc, 0, v15
	v_mul_f32_e32 v26, v24, v24
	v_pk_add_f32 v[10:11], v[36:37], v[10:11]
	v_cndmask_b32_e32 v15, v27, v33, vcc
	v_cmp_gt_f32_e32 vcc, 0, v23
	v_mov_b32_e32 v27, v25
	v_mul_f32_e32 v22, v15, v15
	v_cndmask_b32_e32 v23, v29, v35, vcc
	v_mul_f32_e32 v12, v23, v23
	v_pk_add_f32 v[22:23], v[26:27], v[22:23]
	v_pk_mul_f32 v[26:27], v[24:25], v[14:15] op_sel:[1,0] op_sel_hi:[0,1]
	v_pk_add_f32 v[14:15], v[24:25], v[14:15] op_sel:[1,0] op_sel_hi:[0,1]
	v_mov_b32_e32 v27, v15
	v_fma_f32 v14, |v8|, s40, 1.0
	v_fma_f32 v15, |v9|, s40, 1.0
	v_pk_add_f32 v[12:13], v[26:27], v[12:13]
	v_rcp_f32_e32 v14, v14
	v_rcp_f32_e32 v15, v15
	v_pk_add_f32 v[12:13], v[22:23], v[12:13]
	v_cmp_gt_f32_e32 vcc, 0, v8
	v_pk_add_f32 v[22:23], v[10:11], v[12:13]
	v_pk_mul_f32 v[12:13], v[8:9], v[8:9]
	v_pk_fma_f32 v[10:11], v[14:15], s[42:43], v[18:19] op_sel_hi:[1,0,0]
	v_pk_mul_f32 v[12:13], v[12:13], s[64:65] op_sel_hi:[1,0]
	v_pk_fma_f32 v[10:11], v[14:15], v[10:11], s[48:49] op_sel_hi:[1,1,0]
	v_exp_f32_e32 v12, v12
	v_exp_f32_e32 v13, v13
	v_pk_fma_f32 v[10:11], v[14:15], v[10:11], s[50:51] op_sel_hi:[1,1,0]
	s_waitcnt vmcnt(0)
	v_lshlrev_b32_e32 v36, 16, v6
	v_pk_fma_f32 v[10:11], v[14:15], v[10:11], s[56:57] op_sel_hi:[1,1,0]
	v_and_b32_e32 v37, 0xffff0000, v6
	v_pk_mul_f32 v[10:11], v[14:15], v[10:11]
	v_pk_mul_f32 v[10:11], v[12:13], v[10:11]
	v_pk_mul_f32 v[12:13], v[8:9], v[10:11]
	v_pk_fma_f32 v[10:11], v[8:9], v[10:11], v[8:9] neg_lo:[1,0,0] neg_hi:[1,0,0]
	v_fma_f32 v32, |v36|, s40, 1.0
	v_fma_f32 v33, |v37|, s40, 1.0
	v_cndmask_b32_e32 v15, v10, v12, vcc
	v_cmp_gt_f32_e32 vcc, 0, v9
	v_lshlrev_b32_e32 v12, 16, v4
	v_and_b32_e32 v10, 0x7fffffff, v12
	v_cndmask_b32_e32 v9, v11, v13, vcc
	v_and_b32_e32 v13, 0xffff0000, v4
	v_and_b32_e32 v11, 0x7fffffff, v13
	v_pk_fma_f32 v[10:11], v[10:11], s[40:41], 1.0 op_sel_hi:[1,0,0]
	v_mul_f32_e32 v14, v15, v15
	v_rcp_f32_e32 v10, v10
	v_rcp_f32_e32 v11, v11
	v_mul_f32_e32 v8, v9, v9
	v_pk_add_f32 v[24:25], v[14:15], v[8:9]
	v_pk_mul_f32 v[14:15], v[12:13], v[12:13]
	v_pk_fma_f32 v[8:9], v[10:11], s[42:43], v[18:19] op_sel_hi:[1,0,0]
	v_pk_mul_f32 v[14:15], v[14:15], s[64:65] op_sel_hi:[1,0]
	v_pk_fma_f32 v[8:9], v[10:11], v[8:9], s[48:49] op_sel_hi:[1,1,0]
	v_exp_f32_e32 v14, v14
	v_exp_f32_e32 v15, v15
	v_pk_fma_f32 v[8:9], v[10:11], v[8:9], s[50:51] op_sel_hi:[1,1,0]
	v_lshlrev_b32_e32 v4, 16, v5
	v_pk_fma_f32 v[8:9], v[10:11], v[8:9], s[56:57] op_sel_hi:[1,1,0]
	v_and_b32_e32 v5, 0xffff0000, v5
	v_pk_mul_f32 v[8:9], v[10:11], v[8:9]
	v_pk_mul_f32 v[14:15], v[14:15], v[8:9]
	global_load_dwordx4 v[8:11], v[20:21], off offset:512
	v_fma_f32 v30, |v4|, s40, 1.0
	v_fma_f32 v31, |v5|, s40, 1.0
	v_pk_mul_f32 v[28:29], v[12:13], v[14:15]
	v_rcp_f32_e32 v30, v30
	v_rcp_f32_e32 v31, v31
	v_pk_fma_f32 v[14:15], v[12:13], v[14:15], v[12:13] neg_lo:[1,0,0] neg_hi:[1,0,0]
	v_cmp_gt_f32_e32 vcc, 0, v12
	v_rcp_f32_e32 v34, v32
	v_rcp_f32_e32 v35, v33
	v_cndmask_b32_e32 v27, v14, v28, vcc
	v_cmp_gt_f32_e32 vcc, 0, v13
	v_pk_fma_f32 v[12:13], v[30:31], s[42:43], v[18:19] op_sel_hi:[1,0,0]
	v_mul_f32_e32 v26, v27, v27
	v_cndmask_b32_e32 v29, v15, v29, vcc
	v_pk_mul_f32 v[14:15], v[4:5], v[4:5]
	v_pk_fma_f32 v[12:13], v[30:31], v[12:13], s[48:49] op_sel_hi:[1,1,0]
	v_pk_mul_f32 v[14:15], v[14:15], s[64:65] op_sel_hi:[1,0]
	v_pk_fma_f32 v[12:13], v[30:31], v[12:13], s[50:51] op_sel_hi:[1,1,0]
	v_exp_f32_e32 v14, v14
	v_exp_f32_e32 v15, v15
	v_pk_fma_f32 v[12:13], v[30:31], v[12:13], s[56:57] op_sel_hi:[1,1,0]
	v_cmp_gt_f32_e32 vcc, 0, v4
	v_pk_mul_f32 v[12:13], v[30:31], v[12:13]
	v_mul_f32_e32 v28, v29, v29
	v_pk_mul_f32 v[12:13], v[14:15], v[12:13]
	v_pk_add_f32 v[22:23], v[24:25], v[22:23]
	v_pk_mul_f32 v[14:15], v[4:5], v[12:13]
	v_pk_fma_f32 v[12:13], v[4:5], v[12:13], v[4:5] neg_lo:[1,0,0] neg_hi:[1,0,0]
	v_pk_add_f32 v[24:25], v[26:27], v[28:29]
	v_cndmask_b32_e32 v31, v12, v14, vcc
	v_cmp_gt_f32_e32 vcc, 0, v5
	v_pk_fma_f32 v[4:5], v[34:35], s[42:43], v[18:19] op_sel_hi:[1,0,0]
	v_lshlrev_b32_e32 v14, 16, v7
	v_cndmask_b32_e32 v33, v13, v15, vcc
	v_pk_mul_f32 v[12:13], v[36:37], v[36:37]
	v_pk_fma_f32 v[4:5], v[34:35], v[4:5], s[48:49] op_sel_hi:[1,1,0]
	v_pk_mul_f32 v[12:13], v[12:13], s[64:65] op_sel_hi:[1,0]
	v_pk_fma_f32 v[4:5], v[34:35], v[4:5], s[50:51] op_sel_hi:[1,1,0]
	v_exp_f32_e32 v12, v12
	v_exp_f32_e32 v13, v13
	v_and_b32_e32 v15, 0xffff0000, v7
	v_pk_fma_f32 v[4:5], v[34:35], v[4:5], s[56:57] op_sel_hi:[1,1,0]
	v_pk_mul_f32 v[4:5], v[34:35], v[4:5]
	v_fma_f32 v6, |v14|, s40, 1.0
	v_fma_f32 v7, |v15|, s40, 1.0
	v_pk_mul_f32 v[4:5], v[12:13], v[4:5]
	v_rcp_f32_e32 v6, v6
	v_rcp_f32_e32 v7, v7
	v_max_f32_e32 v82, 0, v36
	v_mul_f32_e32 v30, v31, v31
	v_mul_f32_e32 v32, v33, v33
	v_fma_f32 v35, -|v36|, v4, v82
	v_max_f32_e32 v83, 0, v37
	v_mul_f32_e32 v34, v35, v35
	v_pk_add_f32 v[22:23], v[24:25], v[22:23]
	v_fma_f32 v37, -|v37|, v5, v83
	v_pk_mul_f32 v[12:13], v[14:15], v[14:15]
	v_pk_fma_f32 v[4:5], v[6:7], s[42:43], v[18:19] op_sel_hi:[1,0,0]
	v_pk_mul_f32 v[12:13], v[12:13], s[64:65] op_sel_hi:[1,0]
	v_pk_fma_f32 v[4:5], v[6:7], v[4:5], s[48:49] op_sel_hi:[1,1,0]
	v_exp_f32_e32 v12, v12
	v_exp_f32_e32 v13, v13
	v_pk_fma_f32 v[4:5], v[6:7], v[4:5], s[50:51] op_sel_hi:[1,1,0]
	v_cmp_gt_f32_e32 vcc, 0, v14
	v_pk_fma_f32 v[4:5], v[6:7], v[4:5], s[56:57] op_sel_hi:[1,1,0]
	v_mul_f32_e32 v36, v37, v37
	v_pk_mul_f32 v[4:5], v[6:7], v[4:5]
	v_pk_add_f32 v[24:25], v[30:31], v[32:33]
	v_pk_mul_f32 v[4:5], v[12:13], v[4:5]
	v_pk_add_f32 v[22:23], v[24:25], v[22:23]
	v_pk_mul_f32 v[12:13], v[14:15], v[4:5]
	v_pk_fma_f32 v[40:41], v[14:15], v[4:5], v[14:15] neg_lo:[1,0,0] neg_hi:[1,0,0]
	global_load_dwordx4 v[4:7], v[20:21], off offset:768
	v_cndmask_b32_e32 v39, v40, v12, vcc
	v_cmp_gt_f32_e32 vcc, 0, v15
	v_mul_f32_e32 v38, v39, v39
	s_waitcnt vmcnt(1)
	v_lshlrev_b32_e32 v44, 16, v8
	v_and_b32_e32 v45, 0xffff0000, v8
	v_fma_f32 v42, |v44|, s40, 1.0
	v_fma_f32 v43, |v45|, s40, 1.0
	v_pk_mul_f32 v[14:15], v[44:45], v[44:45]
	v_rcp_f32_e32 v42, v42
	v_rcp_f32_e32 v43, v43
	v_cndmask_b32_e32 v41, v41, v13, vcc
	v_pk_mul_f32 v[14:15], v[14:15], s[64:65] op_sel_hi:[1,0]
	v_lshlrev_b32_e32 v46, 16, v9
	v_pk_fma_f32 v[12:13], v[42:43], s[42:43], v[18:19] op_sel_hi:[1,0,0]
	v_exp_f32_e32 v14, v14
	v_pk_fma_f32 v[12:13], v[42:43], v[12:13], s[48:49] op_sel_hi:[1,1,0]
	v_exp_f32_e32 v15, v15
	v_and_b32_e32 v47, 0xffff0000, v9
	v_pk_fma_f32 v[12:13], v[42:43], v[12:13], s[50:51] op_sel_hi:[1,1,0]
	v_pk_fma_f32 v[12:13], v[42:43], v[12:13], s[56:57] op_sel_hi:[1,1,0]
	v_fma_f32 v8, |v46|, s40, 1.0
	v_fma_f32 v9, |v47|, s40, 1.0
	v_pk_mul_f32 v[12:13], v[42:43], v[12:13]
	v_rcp_f32_e32 v48, v8
	v_rcp_f32_e32 v49, v9
	v_pk_mul_f32 v[12:13], v[14:15], v[12:13]
	v_cmp_gt_f32_e32 vcc, 0, v44
	v_pk_mul_f32 v[14:15], v[44:45], v[12:13]
	v_pk_fma_f32 v[12:13], v[44:45], v[12:13], v[44:45] neg_lo:[1,0,0] neg_hi:[1,0,0]
	v_lshlrev_b32_e32 v50, 16, v10
	v_cndmask_b32_e32 v43, v12, v14, vcc
	v_cmp_gt_f32_e32 vcc, 0, v45
	v_and_b32_e32 v51, 0xffff0000, v10
	v_lshlrev_b32_e32 v10, 16, v11
	v_cndmask_b32_e32 v9, v13, v15, vcc
	v_pk_fma_f32 v[12:13], v[48:49], s[42:43], v[18:19] op_sel_hi:[1,0,0]
	v_pk_mul_f32 v[14:15], v[46:47], v[46:47]
	v_pk_fma_f32 v[12:13], v[48:49], v[12:13], s[48:49] op_sel_hi:[1,1,0]
	v_pk_mul_f32 v[14:15], v[14:15], s[64:65] op_sel_hi:[1,0]
	v_pk_fma_f32 v[12:13], v[48:49], v[12:13], s[50:51] op_sel_hi:[1,1,0]
	v_exp_f32_e32 v14, v14
	v_exp_f32_e32 v15, v15
	v_pk_fma_f32 v[12:13], v[48:49], v[12:13], s[56:57] op_sel_hi:[1,1,0]
	v_cmp_gt_f32_e32 vcc, 0, v46
	v_pk_mul_f32 v[12:13], v[48:49], v[12:13]
	v_fma_f32 v48, |v50|, s40, 1.0
	v_fma_f32 v49, |v51|, s40, 1.0
	v_pk_mul_f32 v[12:13], v[14:15], v[12:13]
	v_rcp_f32_e32 v48, v48
	v_rcp_f32_e32 v49, v49
	v_pk_mul_f32 v[14:15], v[46:47], v[12:13]
	v_pk_fma_f32 v[12:13], v[46:47], v[12:13], v[46:47] neg_lo:[1,0,0] neg_hi:[1,0,0]
	v_and_b32_e32 v11, 0xffff0000, v11
	v_cndmask_b32_e32 v45, v12, v14, vcc
	v_cmp_gt_f32_e32 vcc, 0, v47
	v_cndmask_b32_e32 v47, v13, v15, vcc
	v_pk_mul_f32 v[14:15], v[50:51], v[50:51]
	v_pk_fma_f32 v[12:13], v[48:49], s[42:43], v[18:19] op_sel_hi:[1,0,0]
	v_pk_mul_f32 v[14:15], v[14:15], s[64:65] op_sel_hi:[1,0]
	v_pk_fma_f32 v[12:13], v[48:49], v[12:13], s[48:49] op_sel_hi:[1,1,0]
	v_exp_f32_e32 v14, v14
	v_exp_f32_e32 v15, v15
	v_pk_fma_f32 v[12:13], v[48:49], v[12:13], s[50:51] op_sel_hi:[1,1,0]
	v_fma_f32 v52, |v10|, s40, 1.0
	v_fma_f32 v53, |v11|, s40, 1.0
	v_pk_fma_f32 v[12:13], v[48:49], v[12:13], s[56:57] op_sel_hi:[1,1,0]
	v_rcp_f32_e32 v52, v52
	v_pk_mul_f32 v[12:13], v[48:49], v[12:13]
	v_rcp_f32_e32 v53, v53
	v_pk_mul_f32 v[12:13], v[14:15], v[12:13]
	v_cmp_gt_f32_e32 vcc, 0, v50
	v_pk_mul_f32 v[14:15], v[50:51], v[12:13]
	v_pk_fma_f32 v[12:13], v[50:51], v[12:13], v[50:51] neg_lo:[1,0,0] neg_hi:[1,0,0]
	v_mul_f32_e32 v40, v41, v41
	v_cndmask_b32_e32 v49, v12, v14, vcc
	v_cmp_gt_f32_e32 vcc, 0, v51
	s_waitcnt vmcnt(0)
	v_lshlrev_b32_e32 v56, 16, v4
	v_and_b32_e32 v57, 0xffff0000, v4
	v_cndmask_b32_e32 v51, v13, v15, vcc
	v_pk_mul_f32 v[14:15], v[10:11], v[10:11]
	v_pk_fma_f32 v[12:13], v[52:53], s[42:43], v[18:19] op_sel_hi:[1,0,0]
	v_pk_mul_f32 v[14:15], v[14:15], s[64:65] op_sel_hi:[1,0]
	v_pk_fma_f32 v[12:13], v[52:53], v[12:13], s[48:49] op_sel_hi:[1,1,0]
	v_exp_f32_e32 v14, v14
	v_exp_f32_e32 v15, v15
	v_pk_fma_f32 v[12:13], v[52:53], v[12:13], s[50:51] op_sel_hi:[1,1,0]
	v_pk_fma_f32 v[12:13], v[52:53], v[12:13], s[56:57] op_sel_hi:[1,1,0]
	v_pk_mul_f32 v[12:13], v[52:53], v[12:13]
	v_fma_f32 v58, |v56|, s40, 1.0
	v_fma_f32 v59, |v57|, s40, 1.0
	v_pk_mul_f32 v[12:13], v[14:15], v[12:13]
	v_rcp_f32_e32 v58, v58
	v_rcp_f32_e32 v59, v59
	v_max_f32_e32 v84, 0, v10
	v_lshlrev_b32_e32 v4, 16, v5
	v_and_b32_e32 v5, 0xffff0000, v5
	v_fma_f32 v53, -|v10|, v12, v84
	v_max_f32_e32 v85, 0, v11
	v_fma_f32 v11, -|v11|, v13, v85
	v_pk_mul_f32 v[14:15], v[56:57], v[56:57]
	v_pk_fma_f32 v[12:13], v[58:59], s[42:43], v[18:19] op_sel_hi:[1,0,0]
	v_pk_mul_f32 v[14:15], v[14:15], s[64:65] op_sel_hi:[1,0]
	v_pk_fma_f32 v[12:13], v[58:59], v[12:13], s[48:49] op_sel_hi:[1,1,0]
	v_exp_f32_e32 v14, v14
	v_exp_f32_e32 v15, v15
	v_pk_fma_f32 v[12:13], v[58:59], v[12:13], s[50:51] op_sel_hi:[1,1,0]
	v_fma_f32 v60, |v4|, s40, 1.0
	v_fma_f32 v61, |v5|, s40, 1.0
	v_pk_fma_f32 v[12:13], v[58:59], v[12:13], s[56:57] op_sel_hi:[1,1,0]
	v_rcp_f32_e32 v60, v60
	v_pk_mul_f32 v[12:13], v[58:59], v[12:13]
	v_rcp_f32_e32 v61, v61
	v_pk_mul_f32 v[12:13], v[14:15], v[12:13]
	v_cmp_gt_f32_e32 vcc, 0, v56
	v_pk_mul_f32 v[14:15], v[56:57], v[12:13]
	v_pk_fma_f32 v[12:13], v[56:57], v[12:13], v[56:57] neg_lo:[1,0,0] neg_hi:[1,0,0]
	v_pk_add_f32 v[24:25], v[34:35], v[36:37]
	v_cndmask_b32_e32 v59, v12, v14, vcc
	v_cmp_gt_f32_e32 vcc, 0, v57
	v_mul_f32_e32 v42, v43, v43
	v_mul_f32_e32 v8, v9, v9
	v_cndmask_b32_e32 v57, v13, v15, vcc
	v_pk_fma_f32 v[12:13], v[60:61], s[42:43], v[18:19] op_sel_hi:[1,0,0]
	v_pk_mul_f32 v[14:15], v[4:5], v[4:5]
	v_pk_fma_f32 v[12:13], v[60:61], v[12:13], s[48:49] op_sel_hi:[1,1,0]
	v_pk_mul_f32 v[14:15], v[14:15], s[64:65] op_sel_hi:[1,0]
	v_pk_fma_f32 v[12:13], v[60:61], v[12:13], s[50:51] op_sel_hi:[1,1,0]
	v_exp_f32_e32 v62, v14
	v_exp_f32_e32 v63, v15
	v_pk_fma_f32 v[64:65], v[60:61], v[12:13], s[56:57] op_sel_hi:[1,1,0]
	global_load_dwordx4 v[12:15], v[20:21], off offset:1024
	v_pk_add_f32 v[22:23], v[24:25], v[22:23]
	v_pk_add_f32 v[24:25], v[38:39], v[40:41]
	v_mul_f32_e32 v44, v45, v45
	v_mul_f32_e32 v46, v47, v47
	v_pk_add_f32 v[22:23], v[24:25], v[22:23]
	v_pk_add_f32 v[8:9], v[42:43], v[8:9]
	v_mul_f32_e32 v48, v49, v49
	v_mul_f32_e32 v50, v51, v51
	v_pk_mul_f32 v[60:61], v[60:61], v[64:65]
	v_pk_add_f32 v[8:9], v[8:9], v[22:23]
	v_pk_add_f32 v[22:23], v[44:45], v[46:47]
	v_pk_mul_f32 v[60:61], v[62:63], v[60:61]
	v_pk_add_f32 v[8:9], v[22:23], v[8:9]
	v_pk_add_f32 v[22:23], v[48:49], v[50:51]
	v_lshlrev_b32_e32 v24, 16, v6
	v_and_b32_e32 v25, 0xffff0000, v6
	v_max_f32_e32 v86, 0, v4
	v_pk_add_f32 v[8:9], v[22:23], v[8:9]
	v_mul_f32_e32 v52, v53, v53
	v_mul_f32_e32 v10, v11, v11
	v_fma_f32 v65, -|v4|, v60, v86
	v_max_f32_e32 v90, 0, v5
	v_fma_f32 v22, |v24|, s40, 1.0
	v_fma_f32 v23, |v25|, s40, 1.0
	v_mul_f32_e32 v58, v59, v59
	v_mul_f32_e32 v56, v57, v57
	v_fma_f32 v5, -|v5|, v61, v90
	v_pk_add_f32 v[10:11], v[52:53], v[10:11]
	v_rcp_f32_e32 v26, v22
	v_rcp_f32_e32 v27, v23
	v_mul_f32_e32 v64, v65, v65
	v_mul_f32_e32 v4, v5, v5
	v_pk_add_f32 v[8:9], v[10:11], v[8:9]
	v_pk_add_f32 v[10:11], v[58:59], v[56:57]
	v_pk_add_f32 v[4:5], v[64:65], v[4:5]
	v_pk_add_f32 v[8:9], v[10:11], v[8:9]
	v_cmp_gt_f32_e32 vcc, 0, v24
	v_pk_add_f32 v[22:23], v[4:5], v[8:9]
	v_pk_mul_f32 v[8:9], v[24:25], v[24:25]
	v_pk_fma_f32 v[4:5], v[26:27], s[42:43], v[18:19] op_sel_hi:[1,0,0]
	v_pk_mul_f32 v[8:9], v[8:9], s[64:65] op_sel_hi:[1,0]
	v_pk_fma_f32 v[4:5], v[26:27], v[4:5], s[48:49] op_sel_hi:[1,1,0]
	v_exp_f32_e32 v8, v8
	v_exp_f32_e32 v9, v9
	v_pk_fma_f32 v[4:5], v[26:27], v[4:5], s[50:51] op_sel_hi:[1,1,0]
	v_lshlrev_b32_e32 v6, 16, v7
	v_pk_fma_f32 v[4:5], v[26:27], v[4:5], s[56:57] op_sel_hi:[1,1,0]
	v_and_b32_e32 v7, 0xffff0000, v7
	v_pk_mul_f32 v[4:5], v[26:27], v[4:5]
	s_nop 0
	v_pk_mul_f32 v[4:5], v[8:9], v[4:5]
	s_nop 0
	v_pk_mul_f32 v[8:9], v[24:25], v[4:5]
	v_pk_fma_f32 v[4:5], v[24:25], v[4:5], v[24:25] neg_lo:[1,0,0] neg_hi:[1,0,0]
	s_nop 0
	v_cndmask_b32_e32 v11, v4, v8, vcc
	v_cmp_gt_f32_e32 vcc, 0, v25
	v_and_b32_e32 v8, 0x7fffffff, v6
	v_mul_f32_e32 v10, v11, v11
	v_cndmask_b32_e32 v5, v5, v9, vcc
	v_and_b32_e32 v9, 0x7fffffff, v7
	v_pk_fma_f32 v[8:9], v[8:9], s[40:41], 1.0 op_sel_hi:[1,0,0]
	v_mul_f32_e32 v4, v5, v5
	v_rcp_f32_e32 v8, v8
	v_rcp_f32_e32 v9, v9
	v_pk_add_f32 v[24:25], v[10:11], v[4:5]
	v_pk_mul_f32 v[10:11], v[6:7], v[6:7]
	v_cmp_gt_f32_e32 vcc, 0, v6
	v_pk_fma_f32 v[4:5], v[8:9], s[42:43], v[18:19] op_sel_hi:[1,0,0]
	v_pk_mul_f32 v[10:11], v[10:11], s[64:65] op_sel_hi:[1,0]
	v_pk_fma_f32 v[4:5], v[8:9], v[4:5], s[48:49] op_sel_hi:[1,1,0]
	v_exp_f32_e32 v10, v10
	v_exp_f32_e32 v11, v11
	v_pk_fma_f32 v[4:5], v[8:9], v[4:5], s[50:51] op_sel_hi:[1,1,0]
	v_pk_add_f32 v[22:23], v[24:25], v[22:23]
	v_pk_fma_f32 v[4:5], v[8:9], v[4:5], s[56:57] op_sel_hi:[1,1,0]
	s_nop 0
	v_pk_mul_f32 v[4:5], v[8:9], v[4:5]
	s_nop 0
	v_pk_mul_f32 v[4:5], v[10:11], v[4:5]
	global_load_dwordx4 v[8:11], v[20:21], off offset:1280
	s_waitcnt vmcnt(1)
	v_lshlrev_b32_e32 v32, 16, v12
	v_and_b32_e32 v33, 0xffff0000, v12
	v_fma_f32 v30, |v32|, s40, 1.0
	v_fma_f32 v31, |v33|, s40, 1.0
	v_pk_mul_f32 v[28:29], v[6:7], v[4:5]
	v_rcp_f32_e32 v30, v30
	v_rcp_f32_e32 v31, v31
	v_pk_fma_f32 v[4:5], v[6:7], v[4:5], v[6:7] neg_lo:[1,0,0] neg_hi:[1,0,0]
	v_lshlrev_b32_e32 v34, 16, v13
	v_cndmask_b32_e32 v27, v4, v28, vcc
	v_cmp_gt_f32_e32 vcc, 0, v7
	v_pk_mul_f32 v[6:7], v[32:33], v[32:33]
	v_and_b32_e32 v35, 0xffff0000, v13
	v_cndmask_b32_e32 v29, v5, v29, vcc
	v_pk_fma_f32 v[4:5], v[30:31], s[42:43], v[18:19] op_sel_hi:[1,0,0]
	v_pk_mul_f32 v[6:7], v[6:7], s[64:65] op_sel_hi:[1,0]
	v_pk_fma_f32 v[4:5], v[30:31], v[4:5], s[48:49] op_sel_hi:[1,1,0]
	v_exp_f32_e32 v6, v6
	v_exp_f32_e32 v7, v7
	v_pk_fma_f32 v[4:5], v[30:31], v[4:5], s[50:51] op_sel_hi:[1,1,0]
	v_pk_fma_f32 v[4:5], v[30:31], v[4:5], s[56:57] op_sel_hi:[1,1,0]
	v_fma_f32 v12, |v34|, s40, 1.0
	v_fma_f32 v13, |v35|, s40, 1.0
	v_pk_mul_f32 v[4:5], v[30:31], v[4:5]
	v_rcp_f32_e32 v36, v12
	v_rcp_f32_e32 v37, v13
	v_pk_mul_f32 v[4:5], v[6:7], v[4:5]
	v_cmp_gt_f32_e32 vcc, 0, v32
	v_pk_mul_f32 v[6:7], v[32:33], v[4:5]
	v_pk_fma_f32 v[4:5], v[32:33], v[4:5], v[32:33] neg_lo:[1,0,0] neg_hi:[1,0,0]
	v_lshlrev_b32_e32 v38, 16, v14
	v_cndmask_b32_e32 v31, v4, v6, vcc
	v_cmp_gt_f32_e32 vcc, 0, v33
	v_and_b32_e32 v39, 0xffff0000, v14
	v_lshlrev_b32_e32 v40, 16, v15
	v_cndmask_b32_e32 v13, v5, v7, vcc
	v_pk_fma_f32 v[4:5], v[36:37], s[42:43], v[18:19] op_sel_hi:[1,0,0]
	v_pk_mul_f32 v[6:7], v[34:35], v[34:35]
	v_pk_fma_f32 v[4:5], v[36:37], v[4:5], s[48:49] op_sel_hi:[1,1,0]
	v_pk_mul_f32 v[6:7], v[6:7], s[64:65] op_sel_hi:[1,0]
	v_pk_fma_f32 v[4:5], v[36:37], v[4:5], s[50:51] op_sel_hi:[1,1,0]
	v_exp_f32_e32 v6, v6
	v_exp_f32_e32 v7, v7
	v_pk_fma_f32 v[4:5], v[36:37], v[4:5], s[56:57] op_sel_hi:[1,1,0]
	v_cmp_gt_f32_e32 vcc, 0, v34
	v_pk_mul_f32 v[4:5], v[36:37], v[4:5]
	v_fma_f32 v36, |v38|, s40, 1.0
	v_fma_f32 v37, |v39|, s40, 1.0
	v_pk_mul_f32 v[4:5], v[6:7], v[4:5]
	v_rcp_f32_e32 v36, v36
	v_rcp_f32_e32 v37, v37
	v_pk_mul_f32 v[6:7], v[34:35], v[4:5]
	v_pk_fma_f32 v[4:5], v[34:35], v[4:5], v[34:35] neg_lo:[1,0,0] neg_hi:[1,0,0]
	v_and_b32_e32 v41, 0xffff0000, v15
	v_cndmask_b32_e32 v33, v4, v6, vcc
	v_cmp_gt_f32_e32 vcc, 0, v35
	v_cndmask_b32_e32 v35, v5, v7, vcc
	v_pk_mul_f32 v[6:7], v[38:39], v[38:39]
	v_pk_fma_f32 v[4:5], v[36:37], s[42:43], v[18:19] op_sel_hi:[1,0,0]
	v_pk_mul_f32 v[6:7], v[6:7], s[64:65] op_sel_hi:[1,0]
	v_pk_fma_f32 v[4:5], v[36:37], v[4:5], s[48:49] op_sel_hi:[1,1,0]
	v_exp_f32_e32 v6, v6
	v_exp_f32_e32 v7, v7
	v_pk_fma_f32 v[4:5], v[36:37], v[4:5], s[50:51] op_sel_hi:[1,1,0]
	v_fma_f32 v14, |v40|, s40, 1.0
	v_fma_f32 v15, |v41|, s40, 1.0
	v_pk_fma_f32 v[4:5], v[36:37], v[4:5], s[56:57] op_sel_hi:[1,1,0]
	v_rcp_f32_e32 v42, v14
	v_pk_mul_f32 v[4:5], v[36:37], v[4:5]
	v_rcp_f32_e32 v43, v15
	v_pk_mul_f32 v[4:5], v[6:7], v[4:5]
	v_cmp_gt_f32_e32 vcc, 0, v38
	v_pk_mul_f32 v[6:7], v[38:39], v[4:5]
	v_pk_fma_f32 v[4:5], v[38:39], v[4:5], v[38:39] neg_lo:[1,0,0] neg_hi:[1,0,0]
	v_mul_f32_e32 v26, v27, v27
	v_cndmask_b32_e32 v37, v4, v6, vcc
	v_cmp_gt_f32_e32 vcc, 0, v39
	s_waitcnt vmcnt(0)
	v_lshlrev_b32_e32 v44, 16, v8
	v_and_b32_e32 v45, 0xffff0000, v8
	v_cndmask_b32_e32 v15, v5, v7, vcc
	v_pk_fma_f32 v[4:5], v[42:43], s[42:43], v[18:19] op_sel_hi:[1,0,0]
	v_pk_mul_f32 v[6:7], v[40:41], v[40:41]
	v_pk_fma_f32 v[4:5], v[42:43], v[4:5], s[48:49] op_sel_hi:[1,1,0]
	v_pk_mul_f32 v[6:7], v[6:7], s[64:65] op_sel_hi:[1,0]
	v_pk_fma_f32 v[4:5], v[42:43], v[4:5], s[50:51] op_sel_hi:[1,1,0]
	v_exp_f32_e32 v6, v6
	v_exp_f32_e32 v7, v7
	v_pk_fma_f32 v[4:5], v[42:43], v[4:5], s[56:57] op_sel_hi:[1,1,0]
	v_cmp_gt_f32_e32 vcc, 0, v40
	v_pk_mul_f32 v[4:5], v[42:43], v[4:5]
	v_fma_f32 v42, |v44|, s40, 1.0
	v_fma_f32 v43, |v45|, s40, 1.0
	v_pk_mul_f32 v[4:5], v[6:7], v[4:5]
	v_rcp_f32_e32 v42, v42
	v_rcp_f32_e32 v43, v43
	v_pk_mul_f32 v[6:7], v[40:41], v[4:5]
	v_pk_fma_f32 v[4:5], v[40:41], v[4:5], v[40:41] neg_lo:[1,0,0] neg_hi:[1,0,0]
	v_lshlrev_b32_e32 v50, 16, v9
	v_cndmask_b32_e32 v39, v4, v6, vcc
	v_cmp_gt_f32_e32 vcc, 0, v41
	v_and_b32_e32 v51, 0xffff0000, v9
	v_cndmask_b32_e32 v41, v5, v7, vcc
	v_pk_mul_f32 v[6:7], v[44:45], v[44:45]
	v_pk_fma_f32 v[4:5], v[42:43], s[42:43], v[18:19] op_sel_hi:[1,0,0]
	v_pk_mul_f32 v[6:7], v[6:7], s[64:65] op_sel_hi:[1,0]
	v_pk_fma_f32 v[4:5], v[42:43], v[4:5], s[48:49] op_sel_hi:[1,1,0]
	v_exp_f32_e32 v6, v6
	v_exp_f32_e32 v7, v7
	v_pk_fma_f32 v[4:5], v[42:43], v[4:5], s[50:51] op_sel_hi:[1,1,0]
	v_pk_fma_f32 v[4:5], v[42:43], v[4:5], s[56:57] op_sel_hi:[1,1,0]
	v_fma_f32 v8, |v50|, s40, 1.0
	v_fma_f32 v9, |v51|, s40, 1.0
	v_pk_mul_f32 v[4:5], v[42:43], v[4:5]
	v_rcp_f32_e32 v52, v8
	v_pk_mul_f32 v[42:43], v[6:7], v[4:5]
	global_load_dwordx4 v[4:7], v[20:21], off offset:1536
	v_rcp_f32_e32 v53, v9
	v_pk_mul_f32 v[46:47], v[44:45], v[42:43]
	v_pk_fma_f32 v[48:49], v[44:45], v[42:43], v[44:45] neg_lo:[1,0,0] neg_hi:[1,0,0]
	v_cmp_gt_f32_e32 vcc, 0, v44
	v_lshlrev_b32_e32 v58, 16, v11
	v_and_b32_e32 v59, 0xffff0000, v11
	v_cndmask_b32_e32 v43, v48, v46, vcc
	v_cmp_gt_f32_e32 vcc, 0, v45
	v_pk_fma_f32 v[44:45], v[52:53], s[42:43], v[18:19] op_sel_hi:[1,0,0]
	v_and_b32_e32 v11, 0x7fffffff, v59
	v_pk_fma_f32 v[44:45], v[52:53], v[44:45], s[48:49] op_sel_hi:[1,1,0]
	v_cndmask_b32_e32 v9, v49, v47, vcc
	v_pk_mul_f32 v[46:47], v[50:51], v[50:51]
	v_pk_fma_f32 v[44:45], v[52:53], v[44:45], s[50:51] op_sel_hi:[1,1,0]
	v_pk_mul_f32 v[46:47], v[46:47], s[64:65] op_sel_hi:[1,0]
	v_pk_fma_f32 v[44:45], v[52:53], v[44:45], s[56:57] op_sel_hi:[1,1,0]
	v_exp_f32_e32 v46, v46
	v_exp_f32_e32 v47, v47
	v_pk_mul_f32 v[44:45], v[52:53], v[44:45]
	v_lshlrev_b32_e32 v52, 16, v10
	v_and_b32_e32 v53, 0xffff0000, v10
	v_fma_f32 v56, |v52|, s40, 1.0
	v_fma_f32 v57, |v53|, s40, 1.0
	v_pk_mul_f32 v[44:45], v[46:47], v[44:45]
	v_rcp_f32_e32 v56, v56
	v_rcp_f32_e32 v57, v57
	v_pk_mul_f32 v[46:47], v[50:51], v[44:45]
	v_pk_fma_f32 v[48:49], v[50:51], v[44:45], v[50:51] neg_lo:[1,0,0] neg_hi:[1,0,0]
	v_cmp_gt_f32_e32 vcc, 0, v50
	v_and_b32_e32 v10, 0x7fffffff, v58
	v_pk_fma_f32 v[10:11], v[10:11], s[40:41], 1.0 op_sel_hi:[1,0,0]
	v_cndmask_b32_e32 v45, v48, v46, vcc
	v_cmp_gt_f32_e32 vcc, 0, v51
	v_pk_mul_f32 v[50:51], v[52:53], v[52:53]
	v_rcp_f32_e32 v60, v10
	v_cndmask_b32_e32 v47, v49, v47, vcc
	v_pk_fma_f32 v[48:49], v[56:57], s[42:43], v[18:19] op_sel_hi:[1,0,0]
	v_pk_mul_f32 v[50:51], v[50:51], s[64:65] op_sel_hi:[1,0]
	v_pk_fma_f32 v[48:49], v[56:57], v[48:49], s[48:49] op_sel_hi:[1,1,0]
	v_exp_f32_e32 v50, v50
	v_exp_f32_e32 v51, v51
	v_pk_fma_f32 v[48:49], v[56:57], v[48:49], s[50:51] op_sel_hi:[1,1,0]
	v_rcp_f32_e32 v61, v11
	v_pk_fma_f32 v[48:49], v[56:57], v[48:49], s[56:57] op_sel_hi:[1,1,0]
	v_cmp_gt_f32_e32 vcc, 0, v52
	v_pk_mul_f32 v[48:49], v[56:57], v[48:49]
	v_mul_f32_e32 v28, v29, v29
	v_pk_mul_f32 v[48:49], v[50:51], v[48:49]
	v_mul_f32_e32 v30, v31, v31
	v_pk_mul_f32 v[50:51], v[52:53], v[48:49]
	v_pk_fma_f32 v[56:57], v[52:53], v[48:49], v[52:53] neg_lo:[1,0,0] neg_hi:[1,0,0]
	v_mul_f32_e32 v12, v13, v13
	v_cndmask_b32_e32 v49, v56, v50, vcc
	v_cmp_gt_f32_e32 vcc, 0, v53
	v_pk_mul_f32 v[52:53], v[58:59], v[58:59]
	v_pk_add_f32 v[24:25], v[26:27], v[28:29]
	v_cndmask_b32_e32 v11, v57, v51, vcc
	v_pk_fma_f32 v[50:51], v[60:61], s[42:43], v[18:19] op_sel_hi:[1,0,0]
	v_pk_mul_f32 v[52:53], v[52:53], s[64:65] op_sel_hi:[1,0]
	v_pk_fma_f32 v[50:51], v[60:61], v[50:51], s[48:49] op_sel_hi:[1,1,0]
	v_exp_f32_e32 v52, v52
	v_exp_f32_e32 v53, v53
	v_pk_fma_f32 v[50:51], v[60:61], v[50:51], s[50:51] op_sel_hi:[1,1,0]
	v_cmp_gt_f32_e32 vcc, 0, v58
	v_pk_fma_f32 v[50:51], v[60:61], v[50:51], s[56:57] op_sel_hi:[1,1,0]
	v_mul_f32_e32 v32, v33, v33
	v_pk_mul_f32 v[50:51], v[60:61], v[50:51]
	v_mul_f32_e32 v34, v35, v35
	v_pk_mul_f32 v[50:51], v[52:53], v[50:51]
	v_pk_add_f32 v[22:23], v[24:25], v[22:23]
	v_pk_mul_f32 v[56:57], v[58:59], v[50:51]
	v_pk_fma_f32 v[60:61], v[58:59], v[50:51], v[58:59] neg_lo:[1,0,0] neg_hi:[1,0,0]
	global_load_dwordx4 v[50:53], v[20:21], off offset:1792
	v_cndmask_b32_e32 v63, v60, v56, vcc
	v_cmp_gt_f32_e32 vcc, 0, v59
	v_pk_add_f32 v[12:13], v[30:31], v[12:13]
	v_mul_f32_e32 v36, v37, v37
	v_cndmask_b32_e32 v57, v61, v57, vcc
	s_waitcnt vmcnt(1)
	v_lshlrev_b32_e32 v20, 16, v4
	v_and_b32_e32 v21, 0xffff0000, v4
	v_fma_f32 v64, |v20|, s40, 1.0
	v_fma_f32 v65, |v21|, s40, 1.0
	v_pk_mul_f32 v[60:61], v[20:21], v[20:21]
	v_rcp_f32_e32 v64, v64
	v_rcp_f32_e32 v65, v65
	v_mul_f32_e32 v14, v15, v15
	v_pk_mul_f32 v[60:61], v[60:61], s[64:65] op_sel_hi:[1,0]
	v_pk_add_f32 v[12:13], v[12:13], v[22:23]
	v_pk_fma_f32 v[58:59], v[64:65], s[42:43], v[18:19] op_sel_hi:[1,0,0]
	v_pk_add_f32 v[22:23], v[32:33], v[34:35]
	v_mul_f32_e32 v38, v39, v39
	v_mul_f32_e32 v40, v41, v41
	v_pk_fma_f32 v[58:59], v[64:65], v[58:59], s[48:49] op_sel_hi:[1,1,0]
	v_exp_f32_e32 v60, v60
	v_exp_f32_e32 v61, v61
	v_pk_add_f32 v[12:13], v[22:23], v[12:13]
	v_pk_add_f32 v[14:15], v[36:37], v[14:15]
	v_mul_f32_e32 v42, v43, v43
	v_mul_f32_e32 v8, v9, v9
	v_pk_fma_f32 v[58:59], v[64:65], v[58:59], s[50:51] op_sel_hi:[1,1,0]
	v_pk_add_f32 v[12:13], v[14:15], v[12:13]
	v_pk_add_f32 v[14:15], v[38:39], v[40:41]
	v_mul_f32_e32 v44, v45, v45
	v_mul_f32_e32 v46, v47, v47
	v_pk_fma_f32 v[58:59], v[64:65], v[58:59], s[56:57] op_sel_hi:[1,1,0]
	v_pk_add_f32 v[12:13], v[14:15], v[12:13]
	v_pk_add_f32 v[8:9], v[42:43], v[8:9]
	v_pk_mul_f32 v[58:59], v[64:65], v[58:59]
	v_pk_add_f32 v[8:9], v[8:9], v[12:13]
	v_pk_add_f32 v[12:13], v[44:45], v[46:47]
	v_lshlrev_b32_e32 v4, 16, v5
	v_and_b32_e32 v5, 0xffff0000, v5
	v_pk_mul_f32 v[58:59], v[60:61], v[58:59]
	v_pk_add_f32 v[8:9], v[12:13], v[8:9]
	v_max_f32_e32 v91, 0, v20
	v_fma_f32 v12, |v4|, s40, 1.0
	v_fma_f32 v13, |v5|, s40, 1.0
	v_mul_f32_e32 v48, v49, v49
	v_mul_f32_e32 v10, v11, v11
	v_fma_f32 v65, -|v20|, v58, v91
	v_max_f32_e32 v92, 0, v21
	v_rcp_f32_e32 v12, v12
	v_rcp_f32_e32 v13, v13
	v_mul_f32_e32 v62, v63, v63
	v_mul_f32_e32 v56, v57, v57
	v_fma_f32 v21, -|v21|, v59, v92
	v_pk_add_f32 v[10:11], v[48:49], v[10:11]
	v_mul_f32_e32 v64, v65, v65
	v_mul_f32_e32 v20, v21, v21
	v_pk_add_f32 v[8:9], v[10:11], v[8:9]
	v_pk_add_f32 v[10:11], v[62:63], v[56:57]
	v_pk_mul_f32 v[14:15], v[4:5], v[4:5]
	v_pk_add_f32 v[8:9], v[10:11], v[8:9]
	v_pk_add_f32 v[10:11], v[64:65], v[20:21]
	v_pk_mul_f32 v[14:15], v[14:15], s[64:65] op_sel_hi:[1,0]
	v_pk_add_f32 v[8:9], v[10:11], v[8:9]
	v_pk_fma_f32 v[10:11], v[12:13], s[42:43], v[18:19] op_sel_hi:[1,0,0]
	v_exp_f32_e32 v14, v14
	v_pk_fma_f32 v[10:11], v[12:13], v[10:11], s[48:49] op_sel_hi:[1,1,0]
	v_exp_f32_e32 v15, v15
	v_pk_fma_f32 v[10:11], v[12:13], v[10:11], s[50:51] op_sel_hi:[1,1,0]
	v_cmp_gt_f32_e32 vcc, 0, v4
	v_pk_fma_f32 v[10:11], v[12:13], v[10:11], s[56:57] op_sel_hi:[1,1,0]
	s_waitcnt vmcnt(0)
	v_lshlrev_b32_e32 v24, 16, v50
	v_pk_mul_f32 v[10:11], v[12:13], v[10:11]
	v_and_b32_e32 v25, 0xffff0000, v50
	v_pk_mul_f32 v[10:11], v[14:15], v[10:11]
	v_and_b32_e32 v27, 0x7fffffff, v25
	v_pk_mul_f32 v[12:13], v[4:5], v[10:11]
	v_pk_fma_f32 v[10:11], v[4:5], v[10:11], v[4:5] neg_lo:[1,0,0] neg_hi:[1,0,0]
	v_and_b32_e32 v26, 0x7fffffff, v24
	v_cndmask_b32_e32 v15, v10, v12, vcc
	v_cmp_gt_f32_e32 vcc, 0, v5
	v_lshlrev_b32_e32 v10, 16, v6
	v_and_b32_e32 v12, 0x7fffffff, v10
	v_cndmask_b32_e32 v5, v11, v13, vcc
	v_and_b32_e32 v11, 0xffff0000, v6
	v_and_b32_e32 v13, 0x7fffffff, v11
	v_pk_fma_f32 v[12:13], v[12:13], s[40:41], 1.0 op_sel_hi:[1,0,0]
	v_mul_f32_e32 v14, v15, v15
	v_rcp_f32_e32 v12, v12
	v_rcp_f32_e32 v13, v13
	v_mul_f32_e32 v4, v5, v5
	v_pk_mul_f32 v[20:21], v[10:11], v[10:11]
	v_pk_add_f32 v[4:5], v[14:15], v[4:5]
	v_pk_fma_f32 v[14:15], v[12:13], s[42:43], v[18:19] op_sel_hi:[1,0,0]
	v_pk_mul_f32 v[20:21], v[20:21], s[64:65] op_sel_hi:[1,0]
	v_pk_fma_f32 v[14:15], v[12:13], v[14:15], s[48:49] op_sel_hi:[1,1,0]
	v_exp_f32_e32 v20, v20
	v_exp_f32_e32 v21, v21
	v_pk_fma_f32 v[14:15], v[12:13], v[14:15], s[50:51] op_sel_hi:[1,1,0]
	v_lshlrev_b32_e32 v6, 16, v7
	v_and_b32_e32 v7, 0xffff0000, v7
	v_pk_fma_f32 v[14:15], v[12:13], v[14:15], s[56:57] op_sel_hi:[1,1,0]
	v_pk_mul_f32 v[12:13], v[12:13], v[14:15]
	v_fma_f32 v22, |v6|, s40, 1.0
	v_fma_f32 v23, |v7|, s40, 1.0
	v_pk_mul_f32 v[12:13], v[20:21], v[12:13]
	v_rcp_f32_e32 v22, v22
	v_rcp_f32_e32 v23, v23
	v_max_f32_e32 v93, 0, v10
	v_pk_fma_f32 v[26:27], v[26:27], s[40:41], 1.0 op_sel_hi:[1,0,0]
	v_lshlrev_b32_e32 v28, 16, v51
	v_fma_f32 v21, -|v10|, v12, v93
	v_max_f32_e32 v94, 0, v11
	v_rcp_f32_e32 v26, v26
	v_rcp_f32_e32 v27, v27
	v_fma_f32 v11, -|v11|, v13, v94
	v_pk_mul_f32 v[14:15], v[6:7], v[6:7]
	v_pk_fma_f32 v[12:13], v[22:23], s[42:43], v[18:19] op_sel_hi:[1,0,0]
	v_pk_mul_f32 v[14:15], v[14:15], s[64:65] op_sel_hi:[1,0]
	v_pk_fma_f32 v[12:13], v[22:23], v[12:13], s[48:49] op_sel_hi:[1,1,0]
	v_exp_f32_e32 v14, v14
	v_exp_f32_e32 v15, v15
	v_pk_fma_f32 v[12:13], v[22:23], v[12:13], s[50:51] op_sel_hi:[1,1,0]
	v_cmp_gt_f32_e32 vcc, 0, v6
	v_pk_fma_f32 v[12:13], v[22:23], v[12:13], s[56:57] op_sel_hi:[1,1,0]
	v_and_b32_e32 v29, 0xffff0000, v51
	v_pk_mul_f32 v[12:13], v[22:23], v[12:13]
	v_pk_mul_f32 v[12:13], v[14:15], v[12:13]
	v_pk_mul_f32 v[14:15], v[6:7], v[12:13]
	v_pk_fma_f32 v[12:13], v[6:7], v[12:13], v[6:7] neg_lo:[1,0,0] neg_hi:[1,0,0]
	v_fma_f32 v30, |v28|, s40, 1.0
	v_fma_f32 v31, |v29|, s40, 1.0
	v_cndmask_b32_e32 v23, v12, v14, vcc
	v_cmp_gt_f32_e32 vcc, 0, v7
	v_rcp_f32_e32 v30, v30
	v_rcp_f32_e32 v31, v31
	v_cndmask_b32_e32 v7, v13, v15, vcc
	v_pk_mul_f32 v[14:15], v[24:25], v[24:25]
	v_pk_fma_f32 v[12:13], v[26:27], s[42:43], v[18:19] op_sel_hi:[1,0,0]
	v_pk_mul_f32 v[14:15], v[14:15], s[64:65] op_sel_hi:[1,0]
	v_pk_fma_f32 v[12:13], v[26:27], v[12:13], s[48:49] op_sel_hi:[1,1,0]
	v_exp_f32_e32 v14, v14
	v_exp_f32_e32 v15, v15
	v_pk_fma_f32 v[12:13], v[26:27], v[12:13], s[50:51] op_sel_hi:[1,1,0]
	v_cmp_gt_f32_e32 vcc, 0, v24
	v_pk_fma_f32 v[12:13], v[26:27], v[12:13], s[56:57] op_sel_hi:[1,1,0]
	v_lshlrev_b32_e32 v32, 16, v52
	v_pk_mul_f32 v[12:13], v[26:27], v[12:13]
	v_and_b32_e32 v33, 0xffff0000, v52
	v_pk_mul_f32 v[12:13], v[14:15], v[12:13]
	v_pk_mul_f32 v[14:15], v[24:25], v[12:13]
	v_pk_fma_f32 v[12:13], v[24:25], v[12:13], v[24:25] neg_lo:[1,0,0] neg_hi:[1,0,0]
	v_cndmask_b32_e32 v27, v12, v14, vcc
	v_cmp_gt_f32_e32 vcc, 0, v25
	v_pk_mul_f32 v[24:25], v[28:29], v[28:29]
	v_fma_f32 v34, |v32|, s40, 1.0
	v_fma_f32 v35, |v33|, s40, 1.0
	v_cndmask_b32_e32 v13, v13, v15, vcc
	v_pk_fma_f32 v[14:15], v[30:31], s[42:43], v[18:19] op_sel_hi:[1,0,0]
	v_pk_mul_f32 v[24:25], v[24:25], s[64:65] op_sel_hi:[1,0]
	v_pk_fma_f32 v[14:15], v[30:31], v[14:15], s[48:49] op_sel_hi:[1,1,0]
	v_exp_f32_e32 v24, v24
	v_exp_f32_e32 v25, v25
	v_pk_fma_f32 v[14:15], v[30:31], v[14:15], s[50:51] op_sel_hi:[1,1,0]
	v_rcp_f32_e32 v34, v34
	v_pk_fma_f32 v[14:15], v[30:31], v[14:15], s[56:57] op_sel_hi:[1,1,0]
	v_rcp_f32_e32 v35, v35
	v_pk_mul_f32 v[14:15], v[30:31], v[14:15]
	v_cmp_gt_f32_e32 vcc, 0, v28
	v_pk_mul_f32 v[14:15], v[24:25], v[14:15]
	v_lshlrev_b32_e32 v36, 16, v53
	v_pk_mul_f32 v[24:25], v[28:29], v[14:15]
	v_pk_fma_f32 v[14:15], v[28:29], v[14:15], v[28:29] neg_lo:[1,0,0] neg_hi:[1,0,0]
	v_and_b32_e32 v37, 0xffff0000, v53
	v_cndmask_b32_e32 v31, v14, v24, vcc
	v_cmp_gt_f32_e32 vcc, 0, v29
	v_pk_mul_f32 v[28:29], v[32:33], v[32:33]
	v_cndmask_b32_e32 v15, v15, v25, vcc
	v_pk_fma_f32 v[24:25], v[34:35], s[42:43], v[18:19] op_sel_hi:[1,0,0]
	v_pk_mul_f32 v[28:29], v[28:29], s[64:65] op_sel_hi:[1,0]
	v_pk_fma_f32 v[24:25], v[34:35], v[24:25], s[48:49] op_sel_hi:[1,1,0]
	v_exp_f32_e32 v28, v28
	v_exp_f32_e32 v29, v29
	v_pk_fma_f32 v[24:25], v[34:35], v[24:25], s[50:51] op_sel_hi:[1,1,0]
	v_pk_fma_f32 v[24:25], v[34:35], v[24:25], s[56:57] op_sel_hi:[1,1,0]
	v_fma_f32 v38, |v36|, s40, 1.0
	v_fma_f32 v39, |v37|, s40, 1.0
	v_pk_mul_f32 v[24:25], v[34:35], v[24:25]
	v_rcp_f32_e32 v38, v38
	v_pk_mul_f32 v[24:25], v[28:29], v[24:25]
	v_rcp_f32_e32 v39, v39
	v_max_f32_e32 v95, 0, v32
	v_pk_fma_f32 v[18:19], v[38:39], s[42:43], v[18:19] op_sel_hi:[1,0,0]
	v_mul_f32_e32 v20, v21, v21
	v_fma_f32 v35, -|v32|, v24, v95
	v_max_f32_e32 v96, 0, v33
	v_pk_fma_f32 v[18:19], v[38:39], v[18:19], s[48:49] op_sel_hi:[1,1,0]
	v_mul_f32_e32 v10, v11, v11
	v_fma_f32 v25, -|v33|, v25, v96
	v_pk_mul_f32 v[28:29], v[36:37], v[36:37]
	v_pk_fma_f32 v[18:19], v[38:39], v[18:19], s[50:51] op_sel_hi:[1,1,0]
	v_pk_mul_f32 v[28:29], v[28:29], s[64:65] op_sel_hi:[1,0]
	v_pk_fma_f32 v[18:19], v[38:39], v[18:19], s[56:57] op_sel_hi:[1,1,0]
	v_exp_f32_e32 v28, v28
	v_exp_f32_e32 v29, v29
	v_pk_mul_f32 v[18:19], v[38:39], v[18:19]
	v_mul_f32_e32 v22, v23, v23
	v_mul_f32_e32 v6, v7, v7
	v_pk_mul_f32 v[18:19], v[28:29], v[18:19]
	v_pk_add_f32 v[4:5], v[4:5], v[8:9]
	v_pk_add_f32 v[8:9], v[20:21], v[10:11]
	v_mul_f32_e32 v26, v27, v27
	v_mul_f32_e32 v12, v13, v13
	v_max_f32_e32 v97, 0, v36
	v_pk_add_f32 v[4:5], v[8:9], v[4:5]
	v_pk_add_f32 v[6:7], v[22:23], v[6:7]
	v_mul_f32_e32 v30, v31, v31
	v_mul_f32_e32 v14, v15, v15
	v_fma_f32 v33, -|v36|, v18, v97
	v_max_f32_e32 v98, 0, v37
	v_pk_add_f32 v[4:5], v[6:7], v[4:5]
	v_pk_add_f32 v[6:7], v[26:27], v[12:13]
	v_mul_f32_e32 v34, v35, v35
	v_mul_f32_e32 v24, v25, v25
	v_fma_f32 v19, -|v37|, v19, v98
	v_pk_add_f32 v[4:5], v[6:7], v[4:5]
	v_pk_add_f32 v[6:7], v[30:31], v[14:15]
	v_mul_f32_e32 v32, v33, v33
	v_mul_f32_e32 v18, v19, v19
	v_cmp_lt_i32_e32 vcc, v167, v161
	v_pk_add_f32 v[4:5], v[6:7], v[4:5]
	v_pk_add_f32 v[6:7], v[34:35], v[24:25]
	v_cndmask_b32_e32 v17, v160, v167, vcc
	v_pk_add_f32 v[4:5], v[6:7], v[4:5]
	v_pk_add_f32 v[6:7], v[32:33], v[18:19]
	v_lshlrev_b32_e32 v56, 2, v17
	v_pk_add_f32 v[4:5], v[6:7], v[4:5]
	ds_bpermute_b32 v7, v56, v5
	ds_bpermute_b32 v6, v56, v4
	v_cmp_lt_i32_e32 vcc, v166, v161
	s_waitcnt lgkmcnt(0)
	v_pk_add_f32 v[4:5], v[4:5], v[6:7]
	v_cndmask_b32_e32 v8, v160, v166, vcc
	v_lshlrev_b32_e32 v57, 2, v8
	ds_bpermute_b32 v7, v57, v5
	ds_bpermute_b32 v6, v57, v4
	v_cmp_lt_i32_e32 vcc, v165, v161
	s_waitcnt lgkmcnt(0)
	v_pk_add_f32 v[4:5], v[4:5], v[6:7]
	v_cndmask_b32_e32 v8, v160, v165, vcc
	v_lshlrev_b32_e32 v58, 2, v8
	ds_bpermute_b32 v7, v58, v5
	ds_bpermute_b32 v6, v58, v4
	v_cmp_lt_i32_e32 vcc, v164, v161
	s_waitcnt lgkmcnt(0)
	v_pk_add_f32 v[4:5], v[4:5], v[6:7]
	v_cndmask_b32_e32 v6, v160, v164, vcc
	v_lshlrev_b32_e32 v59, 2, v6
	ds_bpermute_b32 v7, v59, v5
	ds_bpermute_b32 v6, v59, v4
	v_cmp_eq_u32_e32 vcc, 0, v54
	s_and_saveexec_b64 s[8:9], vcc
	s_cbranch_execz .LBB0_445
	s_waitcnt lgkmcnt(0)
	v_pk_add_f32 v[4:5], v[4:5], v[6:7]
	s_nop 0
	v_pk_mul_f32 v[4:5], v[4:5], s[66:67] op_sel_hi:[1,0]
	s_nop 0
	v_fma_f32 v4, -v5, v5, v4
	v_max_f32_e32 v4, 0, v4
	v_add_f32_e32 v4, 0x358637bd, v4
	v_mul_f32_e32 v6, 0x4b800000, v4
	v_cmp_gt_f32_e64 s[0:1], s36, v4
	s_nop 1
	v_cndmask_b32_e64 v4, v4, v6, s[0:1]
	v_rsq_f32_e32 v4, v4
	v_lshl_add_u32 v6, v16, 2, 0
	v_add_u32_e32 v7, 0x11000, v6
	ds_write_b32 v7, v5
	v_mul_f32_e32 v5, 0x45800000, v4
	v_cndmask_b32_e64 v4, v4, v5, s[0:1]
	v_add_u32_e32 v5, 0x11200, v6
	ds_write_b32 v5, v4
.LBB0_445:
	s_or_b64 exec, exec, s[8:9]
	v_or_b32_e32 v20, 4, v16
	v_ashrrev_i32_e32 v21, 31, v20
	v_lshl_add_u64 v[4:5], s[6:7], 0, v[20:21]
	s_waitcnt lgkmcnt(0)
	v_lshlrev_b32_e32 v6, 3, v54
	v_lshlrev_b64 v[4:5], 11, v[4:5]
	v_lshl_add_u64 v[4:5], s[4:5], 0, v[4:5]
	v_lshlrev_b32_e32 v18, 1, v6
	v_mov_b32_e32 v19, v2
	v_lshl_add_u64 v[24:25], v[4:5], 0, v[18:19]
	global_load_dwordx4 v[8:11], v[24:25], off
	global_load_dwordx4 v[4:7], v[24:25], off offset:256
	v_mov_b64_e32 v[22:23], s[44:45]
	v_mov_b32_e32 v13, v2
	s_waitcnt vmcnt(1)
	v_lshlrev_b32_e32 v28, 16, v10
	v_and_b32_e32 v29, 0xffff0000, v10
	v_and_b32_e32 v15, 0xffff0000, v8
	v_and_b32_e32 v27, 0xffff0000, v9
	v_lshlrev_b32_e32 v26, 16, v9
	v_lshlrev_b32_e32 v14, 16, v8
	v_lshlrev_b32_e32 v8, 16, v11
	v_and_b32_e32 v9, 0xffff0000, v11
	v_fma_f32 v10, |v28|, s40, 1.0
	v_fma_f32 v11, |v29|, s40, 1.0
	v_fma_f32 v32, |v14|, s40, 1.0
	v_fma_f32 v33, |v15|, s40, 1.0
	v_rcp_f32_e32 v10, v10
	v_rcp_f32_e32 v11, v11
	v_fma_f32 v36, |v26|, s40, 1.0
	v_fma_f32 v37, |v27|, s40, 1.0
	v_rcp_f32_e32 v32, v32
	v_rcp_f32_e32 v33, v33
	v_rcp_f32_e32 v36, v36
	v_rcp_f32_e32 v37, v37
	v_pk_mul_f32 v[30:31], v[28:29], v[28:29]
	v_pk_mul_f32 v[34:35], v[14:15], v[14:15]
	v_pk_mul_f32 v[30:31], v[30:31], s[64:65] op_sel_hi:[1,0]
	v_pk_fma_f32 v[44:45], v[10:11], s[42:43], v[22:23] op_sel_hi:[1,0,0]
	v_pk_mul_f32 v[38:39], v[26:27], v[26:27]
	v_pk_mul_f32 v[34:35], v[34:35], s[64:65] op_sel_hi:[1,0]
	v_exp_f32_e32 v30, v30
	v_exp_f32_e32 v31, v31
	v_pk_fma_f32 v[46:47], v[32:33], s[42:43], v[22:23] op_sel_hi:[1,0,0]
	v_pk_fma_f32 v[44:45], v[10:11], v[44:45], s[48:49] op_sel_hi:[1,1,0]
	v_pk_mul_f32 v[38:39], v[38:39], s[64:65] op_sel_hi:[1,0]
	v_exp_f32_e32 v34, v34
	v_exp_f32_e32 v35, v35
	v_pk_fma_f32 v[48:49], v[36:37], s[42:43], v[22:23] op_sel_hi:[1,0,0]
	v_pk_fma_f32 v[46:47], v[32:33], v[46:47], s[48:49] op_sel_hi:[1,1,0]
	v_pk_fma_f32 v[44:45], v[10:11], v[44:45], s[50:51] op_sel_hi:[1,1,0]
	v_exp_f32_e32 v38, v38
	v_exp_f32_e32 v39, v39
	v_pk_fma_f32 v[48:49], v[36:37], v[48:49], s[48:49] op_sel_hi:[1,1,0]
	v_pk_fma_f32 v[46:47], v[32:33], v[46:47], s[50:51] op_sel_hi:[1,1,0]
	v_pk_fma_f32 v[44:45], v[10:11], v[44:45], s[56:57] op_sel_hi:[1,1,0]
	v_pk_fma_f32 v[48:49], v[36:37], v[48:49], s[50:51] op_sel_hi:[1,1,0]
	v_pk_fma_f32 v[46:47], v[32:33], v[46:47], s[56:57] op_sel_hi:[1,1,0]
	v_pk_mul_f32 v[10:11], v[10:11], v[44:45]
	v_pk_fma_f32 v[48:49], v[36:37], v[48:49], s[56:57] op_sel_hi:[1,1,0]
	v_pk_mul_f32 v[32:33], v[32:33], v[46:47]
	v_pk_mul_f32 v[10:11], v[30:31], v[10:11]
	v_pk_mul_f32 v[36:37], v[36:37], v[48:49]
	v_pk_mul_f32 v[30:31], v[34:35], v[32:33]
	v_max_f32_e32 v99, 0, v28
	v_pk_mul_f32 v[32:33], v[38:39], v[36:37]
	v_pk_mul_f32 v[36:37], v[30:31], v[14:15]
	v_fma_f32 v45, -|v28|, v10, v99
	v_max_f32_e32 v100, 0, v29
	v_pk_mul_f32 v[38:39], v[26:27], v[32:33]
	v_pk_fma_f32 v[32:33], v[26:27], v[32:33], v[26:27] neg_lo:[1,0,0] neg_hi:[1,0,0]
	v_fma_f32 v11, -|v29|, v11, v100
	v_cmp_gt_f32_e64 s[0:1], 0, v26
	v_pk_fma_f32 v[30:31], v[30:31], v[14:15], v[14:15] neg_lo:[1,0,0] neg_hi:[1,0,0]
	v_cndmask_b32_e64 v29, v32, v38, s[0:1]
	v_cmp_gt_f32_e64 s[0:1], 0, v14
	v_fma_f32 v40, |v8|, s40, 1.0
	v_fma_f32 v41, |v9|, s40, 1.0
	v_cndmask_b32_e64 v28, v30, v36, s[0:1]
	v_cmp_gt_f32_e64 s[0:1], 0, v15
	v_mul_f32_e32 v30, v28, v28
	v_mov_b32_e32 v14, v29
	v_cndmask_b32_e64 v15, v31, v37, s[0:1]
	v_cmp_gt_f32_e64 s[0:1], 0, v27
	v_mov_b32_e32 v31, v29
	v_mul_f32_e32 v26, v15, v15
	v_cndmask_b32_e64 v27, v33, v39, s[0:1]
	v_rcp_f32_e32 v40, v40
	v_rcp_f32_e32 v41, v41
	v_mul_f32_e32 v12, v27, v27
	v_pk_add_f32 v[26:27], v[30:31], v[26:27]
	v_pk_mul_f32 v[30:31], v[28:29], v[14:15] op_sel:[1,0] op_sel_hi:[0,1]
	v_pk_add_f32 v[14:15], v[28:29], v[14:15] op_sel:[1,0] op_sel_hi:[0,1]
	v_mov_b32_e32 v31, v15
	v_mul_f32_e32 v44, v45, v45
	v_mul_f32_e32 v10, v11, v11
	v_pk_add_f32 v[12:13], v[30:31], v[12:13]
	v_pk_mul_f32 v[42:43], v[8:9], v[8:9]
	v_pk_add_f32 v[10:11], v[44:45], v[10:11]
	v_pk_add_f32 v[12:13], v[26:27], v[12:13]
	v_pk_fma_f32 v[50:51], v[40:41], s[42:43], v[22:23] op_sel_hi:[1,0,0]
	v_pk_add_f32 v[26:27], v[10:11], v[12:13]
	v_pk_mul_f32 v[10:11], v[42:43], s[64:65] op_sel_hi:[1,0]
	v_pk_fma_f32 v[50:51], v[40:41], v[50:51], s[48:49] op_sel_hi:[1,1,0]
	v_exp_f32_e32 v10, v10
	v_exp_f32_e32 v11, v11
	v_pk_fma_f32 v[12:13], v[40:41], v[50:51], s[50:51] op_sel_hi:[1,1,0]
	v_cmp_gt_f32_e64 s[0:1], 0, v8
	v_pk_fma_f32 v[12:13], v[40:41], v[12:13], s[56:57] op_sel_hi:[1,1,0]
	s_nop 0
	v_pk_mul_f32 v[12:13], v[40:41], v[12:13]
	s_waitcnt vmcnt(0)
	v_lshlrev_b32_e32 v40, 16, v6
	v_pk_mul_f32 v[10:11], v[10:11], v[12:13]
	v_and_b32_e32 v41, 0xffff0000, v6
	v_pk_mul_f32 v[12:13], v[8:9], v[10:11]
	v_pk_fma_f32 v[10:11], v[8:9], v[10:11], v[8:9] neg_lo:[1,0,0] neg_hi:[1,0,0]
	v_and_b32_e32 v37, 0x7fffffff, v41
	v_cndmask_b32_e64 v15, v10, v12, s[0:1]
	v_cmp_gt_f32_e64 s[0:1], 0, v9
	v_lshlrev_b32_e32 v12, 16, v4
	v_and_b32_e32 v10, 0x7fffffff, v12
	v_cndmask_b32_e64 v9, v11, v13, s[0:1]
	v_and_b32_e32 v13, 0xffff0000, v4
	v_and_b32_e32 v11, 0x7fffffff, v13
	v_pk_fma_f32 v[10:11], v[10:11], s[40:41], 1.0 op_sel_hi:[1,0,0]
	v_mul_f32_e32 v14, v15, v15
	v_rcp_f32_e32 v10, v10
	v_rcp_f32_e32 v11, v11
	v_mul_f32_e32 v8, v9, v9
	v_pk_add_f32 v[28:29], v[14:15], v[8:9]
	v_pk_mul_f32 v[14:15], v[12:13], v[12:13]
	v_pk_fma_f32 v[8:9], v[10:11], s[42:43], v[22:23] op_sel_hi:[1,0,0]
	v_pk_mul_f32 v[14:15], v[14:15], s[64:65] op_sel_hi:[1,0]
	v_pk_fma_f32 v[8:9], v[10:11], v[8:9], s[48:49] op_sel_hi:[1,1,0]
	v_exp_f32_e32 v14, v14
	v_exp_f32_e32 v15, v15
	v_pk_fma_f32 v[8:9], v[10:11], v[8:9], s[50:51] op_sel_hi:[1,1,0]
	v_lshlrev_b32_e32 v4, 16, v5
	v_pk_fma_f32 v[8:9], v[10:11], v[8:9], s[56:57] op_sel_hi:[1,1,0]
	v_and_b32_e32 v5, 0xffff0000, v5
	v_pk_mul_f32 v[8:9], v[10:11], v[8:9]
	v_pk_mul_f32 v[14:15], v[14:15], v[8:9]
	global_load_dwordx4 v[8:11], v[24:25], off offset:512
	v_fma_f32 v34, |v4|, s40, 1.0
	v_fma_f32 v35, |v5|, s40, 1.0
	v_pk_mul_f32 v[32:33], v[12:13], v[14:15]
	v_rcp_f32_e32 v34, v34
	v_rcp_f32_e32 v35, v35
	v_pk_fma_f32 v[14:15], v[12:13], v[14:15], v[12:13] neg_lo:[1,0,0] neg_hi:[1,0,0]
	v_cmp_gt_f32_e64 s[0:1], 0, v12
	v_and_b32_e32 v36, 0x7fffffff, v40
	v_pk_fma_f32 v[36:37], v[36:37], s[40:41], 1.0 op_sel_hi:[1,0,0]
	v_cndmask_b32_e64 v31, v14, v32, s[0:1]
	v_cmp_gt_f32_e64 s[0:1], 0, v13
	v_pk_fma_f32 v[12:13], v[34:35], s[42:43], v[22:23] op_sel_hi:[1,0,0]
	v_rcp_f32_e32 v38, v36
	v_cndmask_b32_e64 v33, v15, v33, s[0:1]
	v_pk_mul_f32 v[14:15], v[4:5], v[4:5]
	v_pk_fma_f32 v[12:13], v[34:35], v[12:13], s[48:49] op_sel_hi:[1,1,0]
	v_pk_mul_f32 v[14:15], v[14:15], s[64:65] op_sel_hi:[1,0]
	v_pk_fma_f32 v[12:13], v[34:35], v[12:13], s[50:51] op_sel_hi:[1,1,0]
	v_exp_f32_e32 v14, v14
	v_exp_f32_e32 v15, v15
	v_pk_fma_f32 v[12:13], v[34:35], v[12:13], s[56:57] op_sel_hi:[1,1,0]
	v_rcp_f32_e32 v39, v37
	v_pk_mul_f32 v[12:13], v[34:35], v[12:13]
	v_cmp_gt_f32_e64 s[0:1], 0, v4
	v_pk_mul_f32 v[12:13], v[14:15], v[12:13]
	v_mul_f32_e32 v30, v31, v31
	v_pk_mul_f32 v[14:15], v[4:5], v[12:13]
	v_pk_fma_f32 v[12:13], v[4:5], v[12:13], v[4:5] neg_lo:[1,0,0] neg_hi:[1,0,0]
	v_mul_f32_e32 v32, v33, v33
	v_cndmask_b32_e64 v35, v12, v14, s[0:1]
	v_cmp_gt_f32_e64 s[0:1], 0, v5
	v_pk_fma_f32 v[4:5], v[38:39], s[42:43], v[22:23] op_sel_hi:[1,0,0]
	v_lshlrev_b32_e32 v14, 16, v7
	v_cndmask_b32_e64 v37, v13, v15, s[0:1]
	v_pk_mul_f32 v[12:13], v[40:41], v[40:41]
	v_pk_fma_f32 v[4:5], v[38:39], v[4:5], s[48:49] op_sel_hi:[1,1,0]
	v_pk_mul_f32 v[12:13], v[12:13], s[64:65] op_sel_hi:[1,0]
	v_pk_fma_f32 v[4:5], v[38:39], v[4:5], s[50:51] op_sel_hi:[1,1,0]
	v_exp_f32_e32 v12, v12
	v_exp_f32_e32 v13, v13
	v_and_b32_e32 v15, 0xffff0000, v7
	v_pk_fma_f32 v[4:5], v[38:39], v[4:5], s[56:57] op_sel_hi:[1,1,0]
	v_pk_mul_f32 v[4:5], v[38:39], v[4:5]
	v_fma_f32 v6, |v14|, s40, 1.0
	v_fma_f32 v7, |v15|, s40, 1.0
	v_pk_mul_f32 v[4:5], v[12:13], v[4:5]
	v_rcp_f32_e32 v6, v6
	v_rcp_f32_e32 v7, v7
	v_max_f32_e32 v104, 0, v40
	v_mul_f32_e32 v34, v35, v35
	v_mul_f32_e32 v36, v37, v37
	v_fma_f32 v39, -|v40|, v4, v104
	v_max_f32_e32 v105, 0, v41
	v_pk_add_f32 v[26:27], v[28:29], v[26:27]
	v_pk_add_f32 v[28:29], v[30:31], v[32:33]
	v_fma_f32 v41, -|v41|, v5, v105
	v_pk_mul_f32 v[12:13], v[14:15], v[14:15]
	v_pk_fma_f32 v[4:5], v[6:7], s[42:43], v[22:23] op_sel_hi:[1,0,0]
	v_pk_mul_f32 v[12:13], v[12:13], s[64:65] op_sel_hi:[1,0]
	v_pk_fma_f32 v[4:5], v[6:7], v[4:5], s[48:49] op_sel_hi:[1,1,0]
	v_exp_f32_e32 v12, v12
	v_exp_f32_e32 v13, v13
	v_pk_fma_f32 v[4:5], v[6:7], v[4:5], s[50:51] op_sel_hi:[1,1,0]
	v_cmp_gt_f32_e64 s[0:1], 0, v14
	v_pk_fma_f32 v[4:5], v[6:7], v[4:5], s[56:57] op_sel_hi:[1,1,0]
	v_mul_f32_e32 v38, v39, v39
	v_pk_mul_f32 v[4:5], v[6:7], v[4:5]
	v_mul_f32_e32 v40, v41, v41
	v_pk_mul_f32 v[4:5], v[12:13], v[4:5]
	v_pk_add_f32 v[26:27], v[28:29], v[26:27]
	v_pk_mul_f32 v[12:13], v[14:15], v[4:5]
	v_pk_fma_f32 v[44:45], v[14:15], v[4:5], v[14:15] neg_lo:[1,0,0] neg_hi:[1,0,0]
	global_load_dwordx4 v[4:7], v[24:25], off offset:768
	v_cndmask_b32_e64 v43, v44, v12, s[0:1]
	v_cmp_gt_f32_e64 s[0:1], 0, v15
	v_pk_add_f32 v[28:29], v[34:35], v[36:37]
	s_waitcnt vmcnt(1)
	v_lshlrev_b32_e32 v48, 16, v8
	v_and_b32_e32 v49, 0xffff0000, v8
	v_fma_f32 v46, |v48|, s40, 1.0
	v_fma_f32 v47, |v49|, s40, 1.0
	v_pk_mul_f32 v[14:15], v[48:49], v[48:49]
	v_rcp_f32_e32 v46, v46
	v_rcp_f32_e32 v47, v47
	v_cndmask_b32_e64 v45, v45, v13, s[0:1]
	v_pk_mul_f32 v[14:15], v[14:15], s[64:65] op_sel_hi:[1,0]
	v_lshlrev_b32_e32 v50, 16, v9
	v_pk_fma_f32 v[12:13], v[46:47], s[42:43], v[22:23] op_sel_hi:[1,0,0]
	v_exp_f32_e32 v14, v14
	v_pk_fma_f32 v[12:13], v[46:47], v[12:13], s[48:49] op_sel_hi:[1,1,0]
	v_exp_f32_e32 v15, v15
	v_and_b32_e32 v51, 0xffff0000, v9
	v_pk_fma_f32 v[12:13], v[46:47], v[12:13], s[50:51] op_sel_hi:[1,1,0]
	v_pk_fma_f32 v[12:13], v[46:47], v[12:13], s[56:57] op_sel_hi:[1,1,0]
	v_fma_f32 v8, |v50|, s40, 1.0
	v_fma_f32 v9, |v51|, s40, 1.0
	v_pk_mul_f32 v[12:13], v[46:47], v[12:13]
	v_rcp_f32_e32 v52, v8
	v_rcp_f32_e32 v53, v9
	v_pk_mul_f32 v[12:13], v[14:15], v[12:13]
	v_cmp_gt_f32_e64 s[0:1], 0, v48
	v_pk_mul_f32 v[14:15], v[48:49], v[12:13]
	v_pk_fma_f32 v[12:13], v[48:49], v[12:13], v[48:49] neg_lo:[1,0,0] neg_hi:[1,0,0]
	v_lshlrev_b32_e32 v60, 16, v10
	v_cndmask_b32_e64 v47, v12, v14, s[0:1]
	v_cmp_gt_f32_e64 s[0:1], 0, v49
	v_and_b32_e32 v61, 0xffff0000, v10
	v_lshlrev_b32_e32 v10, 16, v11
	v_cndmask_b32_e64 v9, v13, v15, s[0:1]
	v_pk_fma_f32 v[12:13], v[52:53], s[42:43], v[22:23] op_sel_hi:[1,0,0]
	v_pk_mul_f32 v[14:15], v[50:51], v[50:51]
	v_pk_fma_f32 v[12:13], v[52:53], v[12:13], s[48:49] op_sel_hi:[1,1,0]
	v_pk_mul_f32 v[14:15], v[14:15], s[64:65] op_sel_hi:[1,0]
	v_pk_fma_f32 v[12:13], v[52:53], v[12:13], s[50:51] op_sel_hi:[1,1,0]
	v_exp_f32_e32 v14, v14
	v_exp_f32_e32 v15, v15
	v_pk_fma_f32 v[12:13], v[52:53], v[12:13], s[56:57] op_sel_hi:[1,1,0]
	v_cmp_gt_f32_e64 s[0:1], 0, v50
	v_pk_mul_f32 v[12:13], v[52:53], v[12:13]
	v_fma_f32 v52, |v60|, s40, 1.0
	v_fma_f32 v53, |v61|, s40, 1.0
	v_pk_mul_f32 v[12:13], v[14:15], v[12:13]
	v_rcp_f32_e32 v52, v52
	v_rcp_f32_e32 v53, v53
	v_pk_mul_f32 v[14:15], v[50:51], v[12:13]
	v_pk_fma_f32 v[12:13], v[50:51], v[12:13], v[50:51] neg_lo:[1,0,0] neg_hi:[1,0,0]
	v_and_b32_e32 v11, 0xffff0000, v11
	v_cndmask_b32_e64 v49, v12, v14, s[0:1]
	v_cmp_gt_f32_e64 s[0:1], 0, v51
	v_cndmask_b32_e64 v51, v13, v15, s[0:1]
	v_pk_mul_f32 v[14:15], v[60:61], v[60:61]
	v_pk_fma_f32 v[12:13], v[52:53], s[42:43], v[22:23] op_sel_hi:[1,0,0]
	v_pk_mul_f32 v[14:15], v[14:15], s[64:65] op_sel_hi:[1,0]
	v_pk_fma_f32 v[12:13], v[52:53], v[12:13], s[48:49] op_sel_hi:[1,1,0]
	v_exp_f32_e32 v14, v14
	v_exp_f32_e32 v15, v15
	v_pk_fma_f32 v[12:13], v[52:53], v[12:13], s[50:51] op_sel_hi:[1,1,0]
	v_fma_f32 v62, |v10|, s40, 1.0
	v_fma_f32 v63, |v11|, s40, 1.0
	v_pk_fma_f32 v[12:13], v[52:53], v[12:13], s[56:57] op_sel_hi:[1,1,0]
	v_rcp_f32_e32 v62, v62
	v_pk_mul_f32 v[12:13], v[52:53], v[12:13]
	v_rcp_f32_e32 v63, v63
	v_pk_mul_f32 v[12:13], v[14:15], v[12:13]
	v_cmp_gt_f32_e64 s[0:1], 0, v60
	v_pk_mul_f32 v[14:15], v[60:61], v[12:13]
	v_pk_fma_f32 v[12:13], v[60:61], v[12:13], v[60:61] neg_lo:[1,0,0] neg_hi:[1,0,0]
	v_mul_f32_e32 v42, v43, v43
	v_cndmask_b32_e64 v53, v12, v14, s[0:1]
	v_cmp_gt_f32_e64 s[0:1], 0, v61
	s_waitcnt vmcnt(0)
	v_lshlrev_b32_e32 v64, 16, v4
	v_and_b32_e32 v65, 0xffff0000, v4
	v_cndmask_b32_e64 v61, v13, v15, s[0:1]
	v_pk_mul_f32 v[14:15], v[10:11], v[10:11]
	v_pk_fma_f32 v[12:13], v[62:63], s[42:43], v[22:23] op_sel_hi:[1,0,0]
	v_pk_mul_f32 v[14:15], v[14:15], s[64:65] op_sel_hi:[1,0]
	v_pk_fma_f32 v[12:13], v[62:63], v[12:13], s[48:49] op_sel_hi:[1,1,0]
	v_exp_f32_e32 v14, v14
	v_exp_f32_e32 v15, v15
	v_pk_fma_f32 v[12:13], v[62:63], v[12:13], s[50:51] op_sel_hi:[1,1,0]
	v_pk_fma_f32 v[12:13], v[62:63], v[12:13], s[56:57] op_sel_hi:[1,1,0]
	v_pk_mul_f32 v[12:13], v[62:63], v[12:13]
	v_fma_f32 v66, |v64|, s40, 1.0
	v_fma_f32 v67, |v65|, s40, 1.0
	v_pk_mul_f32 v[12:13], v[14:15], v[12:13]
	v_rcp_f32_e32 v66, v66
	v_rcp_f32_e32 v67, v67
	v_max_f32_e32 v106, 0, v10
	v_lshlrev_b32_e32 v4, 16, v5
	v_and_b32_e32 v5, 0xffff0000, v5
	v_fma_f32 v63, -|v10|, v12, v106
	v_max_f32_e32 v107, 0, v11
	v_fma_f32 v11, -|v11|, v13, v107
	v_pk_mul_f32 v[14:15], v[64:65], v[64:65]
	v_pk_fma_f32 v[12:13], v[66:67], s[42:43], v[22:23] op_sel_hi:[1,0,0]
	v_pk_mul_f32 v[14:15], v[14:15], s[64:65] op_sel_hi:[1,0]
	v_pk_fma_f32 v[12:13], v[66:67], v[12:13], s[48:49] op_sel_hi:[1,1,0]
	v_exp_f32_e32 v14, v14
	v_exp_f32_e32 v15, v15
	v_pk_fma_f32 v[12:13], v[66:67], v[12:13], s[50:51] op_sel_hi:[1,1,0]
	v_fma_f32 v68, |v4|, s40, 1.0
	v_fma_f32 v69, |v5|, s40, 1.0
	v_pk_fma_f32 v[12:13], v[66:67], v[12:13], s[56:57] op_sel_hi:[1,1,0]
	v_rcp_f32_e32 v68, v68
	v_pk_mul_f32 v[12:13], v[66:67], v[12:13]
	v_rcp_f32_e32 v69, v69
	v_pk_mul_f32 v[12:13], v[14:15], v[12:13]
	v_cmp_gt_f32_e64 s[0:1], 0, v64
	v_pk_mul_f32 v[14:15], v[64:65], v[12:13]
	v_pk_fma_f32 v[12:13], v[64:65], v[12:13], v[64:65] neg_lo:[1,0,0] neg_hi:[1,0,0]
	v_mul_f32_e32 v44, v45, v45
	v_cndmask_b32_e64 v67, v12, v14, s[0:1]
	v_cmp_gt_f32_e64 s[0:1], 0, v65
	v_pk_add_f32 v[26:27], v[28:29], v[26:27]
	v_pk_add_f32 v[28:29], v[38:39], v[40:41]
	v_cndmask_b32_e64 v65, v13, v15, s[0:1]
	v_pk_fma_f32 v[12:13], v[68:69], s[42:43], v[22:23] op_sel_hi:[1,0,0]
	v_pk_mul_f32 v[14:15], v[4:5], v[4:5]
	v_pk_fma_f32 v[12:13], v[68:69], v[12:13], s[48:49] op_sel_hi:[1,1,0]
	v_pk_mul_f32 v[14:15], v[14:15], s[64:65] op_sel_hi:[1,0]
	v_pk_fma_f32 v[12:13], v[68:69], v[12:13], s[50:51] op_sel_hi:[1,1,0]
	v_exp_f32_e32 v70, v14
	v_exp_f32_e32 v71, v15
	v_pk_fma_f32 v[72:73], v[68:69], v[12:13], s[56:57] op_sel_hi:[1,1,0]
	global_load_dwordx4 v[12:15], v[24:25], off offset:1024
	v_mul_f32_e32 v46, v47, v47
	v_mul_f32_e32 v8, v9, v9
	v_pk_add_f32 v[26:27], v[28:29], v[26:27]
	v_pk_add_f32 v[28:29], v[42:43], v[44:45]
	v_mul_f32_e32 v48, v49, v49
	v_mul_f32_e32 v50, v51, v51
	v_pk_add_f32 v[26:27], v[28:29], v[26:27]
	v_pk_add_f32 v[8:9], v[46:47], v[8:9]
	v_mul_f32_e32 v52, v53, v53
	v_mul_f32_e32 v60, v61, v61
	v_pk_mul_f32 v[68:69], v[68:69], v[72:73]
	v_pk_add_f32 v[8:9], v[8:9], v[26:27]
	v_pk_add_f32 v[26:27], v[48:49], v[50:51]
	v_pk_mul_f32 v[68:69], v[70:71], v[68:69]
	v_pk_add_f32 v[8:9], v[26:27], v[8:9]
	v_pk_add_f32 v[26:27], v[52:53], v[60:61]
	v_lshlrev_b32_e32 v28, 16, v6
	v_and_b32_e32 v29, 0xffff0000, v6
	v_max_f32_e32 v108, 0, v4
	v_pk_add_f32 v[8:9], v[26:27], v[8:9]
	v_mul_f32_e32 v62, v63, v63
	v_mul_f32_e32 v10, v11, v11
	v_fma_f32 v73, -|v4|, v68, v108
	v_max_f32_e32 v109, 0, v5
	v_fma_f32 v26, |v28|, s40, 1.0
	v_fma_f32 v27, |v29|, s40, 1.0
	v_mul_f32_e32 v66, v67, v67
	v_mul_f32_e32 v64, v65, v65
	v_fma_f32 v5, -|v5|, v69, v109
	v_pk_add_f32 v[10:11], v[62:63], v[10:11]
	v_rcp_f32_e32 v30, v26
	v_rcp_f32_e32 v31, v27
	v_mul_f32_e32 v72, v73, v73
	v_mul_f32_e32 v4, v5, v5
	v_pk_add_f32 v[8:9], v[10:11], v[8:9]
	v_pk_add_f32 v[10:11], v[66:67], v[64:65]
	v_pk_add_f32 v[4:5], v[72:73], v[4:5]
	v_pk_add_f32 v[8:9], v[10:11], v[8:9]
	v_cmp_gt_f32_e64 s[0:1], 0, v28
	v_pk_add_f32 v[26:27], v[4:5], v[8:9]
	v_pk_mul_f32 v[8:9], v[28:29], v[28:29]
	v_pk_fma_f32 v[4:5], v[30:31], s[42:43], v[22:23] op_sel_hi:[1,0,0]
	v_pk_mul_f32 v[8:9], v[8:9], s[64:65] op_sel_hi:[1,0]
	v_pk_fma_f32 v[4:5], v[30:31], v[4:5], s[48:49] op_sel_hi:[1,1,0]
	v_exp_f32_e32 v8, v8
	v_exp_f32_e32 v9, v9
	v_pk_fma_f32 v[4:5], v[30:31], v[4:5], s[50:51] op_sel_hi:[1,1,0]
	v_lshlrev_b32_e32 v6, 16, v7
	v_pk_fma_f32 v[4:5], v[30:31], v[4:5], s[56:57] op_sel_hi:[1,1,0]
	v_and_b32_e32 v7, 0xffff0000, v7
	v_pk_mul_f32 v[4:5], v[30:31], v[4:5]
	s_nop 0
	v_pk_mul_f32 v[4:5], v[8:9], v[4:5]
	s_nop 0
	v_pk_mul_f32 v[8:9], v[28:29], v[4:5]
	v_pk_fma_f32 v[4:5], v[28:29], v[4:5], v[28:29] neg_lo:[1,0,0] neg_hi:[1,0,0]
	s_nop 0
	v_cndmask_b32_e64 v11, v4, v8, s[0:1]
	v_cmp_gt_f32_e64 s[0:1], 0, v29
	v_and_b32_e32 v8, 0x7fffffff, v6
	v_mul_f32_e32 v10, v11, v11
	v_cndmask_b32_e64 v5, v5, v9, s[0:1]
	v_and_b32_e32 v9, 0x7fffffff, v7
	v_pk_fma_f32 v[8:9], v[8:9], s[40:41], 1.0 op_sel_hi:[1,0,0]
	v_mul_f32_e32 v4, v5, v5
	v_rcp_f32_e32 v8, v8
	v_rcp_f32_e32 v9, v9
	v_pk_add_f32 v[28:29], v[10:11], v[4:5]
	v_pk_mul_f32 v[10:11], v[6:7], v[6:7]
	v_cmp_gt_f32_e64 s[0:1], 0, v6
	v_pk_fma_f32 v[4:5], v[8:9], s[42:43], v[22:23] op_sel_hi:[1,0,0]
	v_pk_mul_f32 v[10:11], v[10:11], s[64:65] op_sel_hi:[1,0]
	v_pk_fma_f32 v[4:5], v[8:9], v[4:5], s[48:49] op_sel_hi:[1,1,0]
	v_exp_f32_e32 v10, v10
	v_exp_f32_e32 v11, v11
	v_pk_fma_f32 v[4:5], v[8:9], v[4:5], s[50:51] op_sel_hi:[1,1,0]
	v_pk_add_f32 v[26:27], v[28:29], v[26:27]
	v_pk_fma_f32 v[4:5], v[8:9], v[4:5], s[56:57] op_sel_hi:[1,1,0]
	s_nop 0
	v_pk_mul_f32 v[4:5], v[8:9], v[4:5]
	s_nop 0
	v_pk_mul_f32 v[4:5], v[10:11], v[4:5]
	global_load_dwordx4 v[8:11], v[24:25], off offset:1280
	s_waitcnt vmcnt(1)
	v_lshlrev_b32_e32 v36, 16, v12
	v_and_b32_e32 v37, 0xffff0000, v12
	v_fma_f32 v34, |v36|, s40, 1.0
	v_fma_f32 v35, |v37|, s40, 1.0
	v_pk_mul_f32 v[32:33], v[6:7], v[4:5]
	v_rcp_f32_e32 v34, v34
	v_rcp_f32_e32 v35, v35
	v_pk_fma_f32 v[4:5], v[6:7], v[4:5], v[6:7] neg_lo:[1,0,0] neg_hi:[1,0,0]
	v_lshlrev_b32_e32 v38, 16, v13
	v_cndmask_b32_e64 v31, v4, v32, s[0:1]
	v_cmp_gt_f32_e64 s[0:1], 0, v7
	v_pk_mul_f32 v[6:7], v[36:37], v[36:37]
	v_and_b32_e32 v39, 0xffff0000, v13
	v_cndmask_b32_e64 v33, v5, v33, s[0:1]
	v_pk_fma_f32 v[4:5], v[34:35], s[42:43], v[22:23] op_sel_hi:[1,0,0]
	v_pk_mul_f32 v[6:7], v[6:7], s[64:65] op_sel_hi:[1,0]
	v_pk_fma_f32 v[4:5], v[34:35], v[4:5], s[48:49] op_sel_hi:[1,1,0]
	v_exp_f32_e32 v6, v6
	v_exp_f32_e32 v7, v7
	v_pk_fma_f32 v[4:5], v[34:35], v[4:5], s[50:51] op_sel_hi:[1,1,0]
	v_pk_fma_f32 v[4:5], v[34:35], v[4:5], s[56:57] op_sel_hi:[1,1,0]
	v_fma_f32 v12, |v38|, s40, 1.0
	v_fma_f32 v13, |v39|, s40, 1.0
	v_pk_mul_f32 v[4:5], v[34:35], v[4:5]
	v_rcp_f32_e32 v40, v12
	v_rcp_f32_e32 v41, v13
	v_pk_mul_f32 v[4:5], v[6:7], v[4:5]
	v_cmp_gt_f32_e64 s[0:1], 0, v36
	v_pk_mul_f32 v[6:7], v[36:37], v[4:5]
	v_pk_fma_f32 v[4:5], v[36:37], v[4:5], v[36:37] neg_lo:[1,0,0] neg_hi:[1,0,0]
	v_lshlrev_b32_e32 v42, 16, v14
	v_cndmask_b32_e64 v35, v4, v6, s[0:1]
	v_cmp_gt_f32_e64 s[0:1], 0, v37
	v_and_b32_e32 v43, 0xffff0000, v14
	v_lshlrev_b32_e32 v44, 16, v15
	v_cndmask_b32_e64 v13, v5, v7, s[0:1]
	v_pk_fma_f32 v[4:5], v[40:41], s[42:43], v[22:23] op_sel_hi:[1,0,0]
	v_pk_mul_f32 v[6:7], v[38:39], v[38:39]
	v_pk_fma_f32 v[4:5], v[40:41], v[4:5], s[48:49] op_sel_hi:[1,1,0]
	v_pk_mul_f32 v[6:7], v[6:7], s[64:65] op_sel_hi:[1,0]
	v_pk_fma_f32 v[4:5], v[40:41], v[4:5], s[50:51] op_sel_hi:[1,1,0]
	v_exp_f32_e32 v6, v6
	v_exp_f32_e32 v7, v7
	v_pk_fma_f32 v[4:5], v[40:41], v[4:5], s[56:57] op_sel_hi:[1,1,0]
	v_cmp_gt_f32_e64 s[0:1], 0, v38
	v_pk_mul_f32 v[4:5], v[40:41], v[4:5]
	v_fma_f32 v40, |v42|, s40, 1.0
	v_fma_f32 v41, |v43|, s40, 1.0
	v_pk_mul_f32 v[4:5], v[6:7], v[4:5]
	v_rcp_f32_e32 v40, v40
	v_rcp_f32_e32 v41, v41
	v_pk_mul_f32 v[6:7], v[38:39], v[4:5]
	v_pk_fma_f32 v[4:5], v[38:39], v[4:5], v[38:39] neg_lo:[1,0,0] neg_hi:[1,0,0]
	v_and_b32_e32 v45, 0xffff0000, v15
	v_cndmask_b32_e64 v37, v4, v6, s[0:1]
	v_cmp_gt_f32_e64 s[0:1], 0, v39
	v_cndmask_b32_e64 v39, v5, v7, s[0:1]
	v_pk_mul_f32 v[6:7], v[42:43], v[42:43]
	v_pk_fma_f32 v[4:5], v[40:41], s[42:43], v[22:23] op_sel_hi:[1,0,0]
	v_pk_mul_f32 v[6:7], v[6:7], s[64:65] op_sel_hi:[1,0]
	v_pk_fma_f32 v[4:5], v[40:41], v[4:5], s[48:49] op_sel_hi:[1,1,0]
	v_exp_f32_e32 v6, v6
	v_exp_f32_e32 v7, v7
	v_pk_fma_f32 v[4:5], v[40:41], v[4:5], s[50:51] op_sel_hi:[1,1,0]
	v_fma_f32 v14, |v44|, s40, 1.0
	v_fma_f32 v15, |v45|, s40, 1.0
	v_pk_fma_f32 v[4:5], v[40:41], v[4:5], s[56:57] op_sel_hi:[1,1,0]
	v_rcp_f32_e32 v46, v14
	v_pk_mul_f32 v[4:5], v[40:41], v[4:5]
	v_rcp_f32_e32 v47, v15
	v_pk_mul_f32 v[4:5], v[6:7], v[4:5]
	v_cmp_gt_f32_e64 s[0:1], 0, v42
	v_pk_mul_f32 v[6:7], v[42:43], v[4:5]
	v_pk_fma_f32 v[4:5], v[42:43], v[4:5], v[42:43] neg_lo:[1,0,0] neg_hi:[1,0,0]
	v_mul_f32_e32 v30, v31, v31
	v_cndmask_b32_e64 v41, v4, v6, s[0:1]
	v_cmp_gt_f32_e64 s[0:1], 0, v43
	s_waitcnt vmcnt(0)
	v_lshlrev_b32_e32 v48, 16, v8
	v_and_b32_e32 v49, 0xffff0000, v8
	v_cndmask_b32_e64 v15, v5, v7, s[0:1]
	v_pk_fma_f32 v[4:5], v[46:47], s[42:43], v[22:23] op_sel_hi:[1,0,0]
	v_pk_mul_f32 v[6:7], v[44:45], v[44:45]
	v_pk_fma_f32 v[4:5], v[46:47], v[4:5], s[48:49] op_sel_hi:[1,1,0]
	v_pk_mul_f32 v[6:7], v[6:7], s[64:65] op_sel_hi:[1,0]
	v_pk_fma_f32 v[4:5], v[46:47], v[4:5], s[50:51] op_sel_hi:[1,1,0]
	v_exp_f32_e32 v6, v6
	v_exp_f32_e32 v7, v7
	v_pk_fma_f32 v[4:5], v[46:47], v[4:5], s[56:57] op_sel_hi:[1,1,0]
	v_cmp_gt_f32_e64 s[0:1], 0, v44
	v_pk_mul_f32 v[4:5], v[46:47], v[4:5]
	v_fma_f32 v46, |v48|, s40, 1.0
	v_fma_f32 v47, |v49|, s40, 1.0
	v_pk_mul_f32 v[4:5], v[6:7], v[4:5]
	v_rcp_f32_e32 v46, v46
	v_rcp_f32_e32 v47, v47
	v_pk_mul_f32 v[6:7], v[44:45], v[4:5]
	v_pk_fma_f32 v[4:5], v[44:45], v[4:5], v[44:45] neg_lo:[1,0,0] neg_hi:[1,0,0]
	v_lshlrev_b32_e32 v60, 16, v9
	v_cndmask_b32_e64 v43, v4, v6, s[0:1]
	v_cmp_gt_f32_e64 s[0:1], 0, v45
	v_and_b32_e32 v61, 0xffff0000, v9
	v_cndmask_b32_e64 v45, v5, v7, s[0:1]
	v_pk_mul_f32 v[6:7], v[48:49], v[48:49]
	v_pk_fma_f32 v[4:5], v[46:47], s[42:43], v[22:23] op_sel_hi:[1,0,0]
	v_pk_mul_f32 v[6:7], v[6:7], s[64:65] op_sel_hi:[1,0]
	v_pk_fma_f32 v[4:5], v[46:47], v[4:5], s[48:49] op_sel_hi:[1,1,0]
	v_exp_f32_e32 v6, v6
	v_exp_f32_e32 v7, v7
	v_pk_fma_f32 v[4:5], v[46:47], v[4:5], s[50:51] op_sel_hi:[1,1,0]
	v_pk_fma_f32 v[4:5], v[46:47], v[4:5], s[56:57] op_sel_hi:[1,1,0]
	v_fma_f32 v8, |v60|, s40, 1.0
	v_fma_f32 v9, |v61|, s40, 1.0
	v_pk_mul_f32 v[4:5], v[46:47], v[4:5]
	v_rcp_f32_e32 v62, v8
	v_pk_mul_f32 v[46:47], v[6:7], v[4:5]
	global_load_dwordx4 v[4:7], v[24:25], off offset:1536
	v_rcp_f32_e32 v63, v9
	v_pk_mul_f32 v[50:51], v[48:49], v[46:47]
	v_pk_fma_f32 v[52:53], v[48:49], v[46:47], v[48:49] neg_lo:[1,0,0] neg_hi:[1,0,0]
	v_cmp_gt_f32_e64 s[0:1], 0, v48
	v_lshlrev_b32_e32 v66, 16, v11
	v_and_b32_e32 v67, 0xffff0000, v11
	v_cndmask_b32_e64 v47, v52, v50, s[0:1]
	v_cmp_gt_f32_e64 s[0:1], 0, v49
	v_pk_fma_f32 v[48:49], v[62:63], s[42:43], v[22:23] op_sel_hi:[1,0,0]
	v_and_b32_e32 v11, 0x7fffffff, v67
	v_pk_fma_f32 v[48:49], v[62:63], v[48:49], s[48:49] op_sel_hi:[1,1,0]
	v_cndmask_b32_e64 v9, v53, v51, s[0:1]
	v_pk_mul_f32 v[50:51], v[60:61], v[60:61]
	v_pk_fma_f32 v[48:49], v[62:63], v[48:49], s[50:51] op_sel_hi:[1,1,0]
	v_pk_mul_f32 v[50:51], v[50:51], s[64:65] op_sel_hi:[1,0]
	v_pk_fma_f32 v[48:49], v[62:63], v[48:49], s[56:57] op_sel_hi:[1,1,0]
	v_exp_f32_e32 v50, v50
	v_exp_f32_e32 v51, v51
	v_pk_mul_f32 v[48:49], v[62:63], v[48:49]
	v_lshlrev_b32_e32 v62, 16, v10
	v_and_b32_e32 v63, 0xffff0000, v10
	v_fma_f32 v64, |v62|, s40, 1.0
	v_fma_f32 v65, |v63|, s40, 1.0
	v_pk_mul_f32 v[48:49], v[50:51], v[48:49]
	v_rcp_f32_e32 v64, v64
	v_rcp_f32_e32 v65, v65
	v_pk_mul_f32 v[50:51], v[60:61], v[48:49]
	v_pk_fma_f32 v[52:53], v[60:61], v[48:49], v[60:61] neg_lo:[1,0,0] neg_hi:[1,0,0]
	v_cmp_gt_f32_e64 s[0:1], 0, v60
	v_and_b32_e32 v10, 0x7fffffff, v66
	v_pk_fma_f32 v[10:11], v[10:11], s[40:41], 1.0 op_sel_hi:[1,0,0]
	v_cndmask_b32_e64 v49, v52, v50, s[0:1]
	v_cmp_gt_f32_e64 s[0:1], 0, v61
	v_pk_mul_f32 v[60:61], v[62:63], v[62:63]
	v_rcp_f32_e32 v68, v10
	v_cndmask_b32_e64 v51, v53, v51, s[0:1]
	v_pk_fma_f32 v[52:53], v[64:65], s[42:43], v[22:23] op_sel_hi:[1,0,0]
	v_pk_mul_f32 v[60:61], v[60:61], s[64:65] op_sel_hi:[1,0]
	v_pk_fma_f32 v[52:53], v[64:65], v[52:53], s[48:49] op_sel_hi:[1,1,0]
	v_exp_f32_e32 v60, v60
	v_exp_f32_e32 v61, v61
	v_pk_fma_f32 v[52:53], v[64:65], v[52:53], s[50:51] op_sel_hi:[1,1,0]
	v_rcp_f32_e32 v69, v11
	v_pk_fma_f32 v[52:53], v[64:65], v[52:53], s[56:57] op_sel_hi:[1,1,0]
	v_cmp_gt_f32_e64 s[0:1], 0, v62
	v_pk_mul_f32 v[52:53], v[64:65], v[52:53]
	v_mul_f32_e32 v32, v33, v33
	v_pk_mul_f32 v[52:53], v[60:61], v[52:53]
	v_mul_f32_e32 v34, v35, v35
	v_pk_mul_f32 v[60:61], v[62:63], v[52:53]
	v_pk_fma_f32 v[64:65], v[62:63], v[52:53], v[62:63] neg_lo:[1,0,0] neg_hi:[1,0,0]
	v_mul_f32_e32 v12, v13, v13
	v_cndmask_b32_e64 v53, v64, v60, s[0:1]
	v_cmp_gt_f32_e64 s[0:1], 0, v63
	v_pk_mul_f32 v[62:63], v[66:67], v[66:67]
	v_pk_add_f32 v[28:29], v[30:31], v[32:33]
	v_cndmask_b32_e64 v11, v65, v61, s[0:1]
	v_pk_fma_f32 v[60:61], v[68:69], s[42:43], v[22:23] op_sel_hi:[1,0,0]
	v_pk_mul_f32 v[62:63], v[62:63], s[64:65] op_sel_hi:[1,0]
	v_pk_fma_f32 v[60:61], v[68:69], v[60:61], s[48:49] op_sel_hi:[1,1,0]
	v_exp_f32_e32 v62, v62
	v_exp_f32_e32 v63, v63
	v_pk_fma_f32 v[60:61], v[68:69], v[60:61], s[50:51] op_sel_hi:[1,1,0]
	v_cmp_gt_f32_e64 s[0:1], 0, v66
	v_pk_fma_f32 v[60:61], v[68:69], v[60:61], s[56:57] op_sel_hi:[1,1,0]
	v_mul_f32_e32 v36, v37, v37
	v_pk_mul_f32 v[60:61], v[68:69], v[60:61]
	v_mul_f32_e32 v38, v39, v39
	v_pk_mul_f32 v[60:61], v[62:63], v[60:61]
	v_pk_add_f32 v[26:27], v[28:29], v[26:27]
	v_pk_mul_f32 v[64:65], v[66:67], v[60:61]
	v_pk_fma_f32 v[68:69], v[66:67], v[60:61], v[66:67] neg_lo:[1,0,0] neg_hi:[1,0,0]
	global_load_dwordx4 v[60:63], v[24:25], off offset:1792
	v_cndmask_b32_e64 v71, v68, v64, s[0:1]
	v_cmp_gt_f32_e64 s[0:1], 0, v67
	v_pk_add_f32 v[12:13], v[34:35], v[12:13]
	v_mul_f32_e32 v40, v41, v41
	v_cndmask_b32_e64 v65, v69, v65, s[0:1]
	s_waitcnt vmcnt(1)
	v_lshlrev_b32_e32 v24, 16, v4
	v_and_b32_e32 v25, 0xffff0000, v4
	v_fma_f32 v72, |v24|, s40, 1.0
	v_fma_f32 v73, |v25|, s40, 1.0
	v_pk_mul_f32 v[68:69], v[24:25], v[24:25]
	v_rcp_f32_e32 v72, v72
	v_rcp_f32_e32 v73, v73
	v_mul_f32_e32 v14, v15, v15
	v_pk_mul_f32 v[68:69], v[68:69], s[64:65] op_sel_hi:[1,0]
	v_pk_add_f32 v[12:13], v[12:13], v[26:27]
	v_pk_fma_f32 v[66:67], v[72:73], s[42:43], v[22:23] op_sel_hi:[1,0,0]
	v_pk_add_f32 v[26:27], v[36:37], v[38:39]
	v_mul_f32_e32 v42, v43, v43
	v_mul_f32_e32 v44, v45, v45
	v_pk_fma_f32 v[66:67], v[72:73], v[66:67], s[48:49] op_sel_hi:[1,1,0]
	v_exp_f32_e32 v68, v68
	v_exp_f32_e32 v69, v69
	v_pk_add_f32 v[12:13], v[26:27], v[12:13]
	v_pk_add_f32 v[14:15], v[40:41], v[14:15]
	v_mul_f32_e32 v46, v47, v47
	v_mul_f32_e32 v8, v9, v9
	v_pk_fma_f32 v[66:67], v[72:73], v[66:67], s[50:51] op_sel_hi:[1,1,0]
	v_pk_add_f32 v[12:13], v[14:15], v[12:13]
	v_pk_add_f32 v[14:15], v[42:43], v[44:45]
	v_mul_f32_e32 v48, v49, v49
	v_mul_f32_e32 v50, v51, v51
	v_pk_fma_f32 v[66:67], v[72:73], v[66:67], s[56:57] op_sel_hi:[1,1,0]
	v_pk_add_f32 v[12:13], v[14:15], v[12:13]
	v_pk_add_f32 v[8:9], v[46:47], v[8:9]
	v_pk_mul_f32 v[66:67], v[72:73], v[66:67]
	v_pk_add_f32 v[8:9], v[8:9], v[12:13]
	v_pk_add_f32 v[12:13], v[48:49], v[50:51]
	v_lshlrev_b32_e32 v4, 16, v5
	v_and_b32_e32 v5, 0xffff0000, v5
	v_pk_mul_f32 v[66:67], v[68:69], v[66:67]
	v_pk_add_f32 v[8:9], v[12:13], v[8:9]
	v_max_f32_e32 v110, 0, v24
	v_fma_f32 v12, |v4|, s40, 1.0
	v_fma_f32 v13, |v5|, s40, 1.0
	v_mul_f32_e32 v52, v53, v53
	v_mul_f32_e32 v10, v11, v11
	v_fma_f32 v73, -|v24|, v66, v110
	v_max_f32_e32 v111, 0, v25
	v_rcp_f32_e32 v12, v12
	v_rcp_f32_e32 v13, v13
	v_mul_f32_e32 v70, v71, v71
	v_mul_f32_e32 v64, v65, v65
	v_fma_f32 v25, -|v25|, v67, v111
	v_pk_add_f32 v[10:11], v[52:53], v[10:11]
	v_mul_f32_e32 v72, v73, v73
	v_mul_f32_e32 v24, v25, v25
	v_pk_add_f32 v[8:9], v[10:11], v[8:9]
	v_pk_add_f32 v[10:11], v[70:71], v[64:65]
	v_pk_mul_f32 v[14:15], v[4:5], v[4:5]
	v_pk_add_f32 v[8:9], v[10:11], v[8:9]
	v_pk_add_f32 v[10:11], v[72:73], v[24:25]
	v_pk_mul_f32 v[14:15], v[14:15], s[64:65] op_sel_hi:[1,0]
	v_pk_add_f32 v[8:9], v[10:11], v[8:9]
	v_pk_fma_f32 v[10:11], v[12:13], s[42:43], v[22:23] op_sel_hi:[1,0,0]
	v_exp_f32_e32 v14, v14
	v_pk_fma_f32 v[10:11], v[12:13], v[10:11], s[48:49] op_sel_hi:[1,1,0]
	v_exp_f32_e32 v15, v15
	v_pk_fma_f32 v[10:11], v[12:13], v[10:11], s[50:51] op_sel_hi:[1,1,0]
	v_cmp_gt_f32_e64 s[0:1], 0, v4
	v_pk_fma_f32 v[10:11], v[12:13], v[10:11], s[56:57] op_sel_hi:[1,1,0]
	s_waitcnt vmcnt(0)
	v_lshlrev_b32_e32 v28, 16, v60
	v_pk_mul_f32 v[10:11], v[12:13], v[10:11]
	v_and_b32_e32 v29, 0xffff0000, v60
	v_pk_mul_f32 v[10:11], v[14:15], v[10:11]
	v_and_b32_e32 v31, 0x7fffffff, v29
	v_pk_mul_f32 v[12:13], v[4:5], v[10:11]
	v_pk_fma_f32 v[10:11], v[4:5], v[10:11], v[4:5] neg_lo:[1,0,0] neg_hi:[1,0,0]
	v_and_b32_e32 v30, 0x7fffffff, v28
	v_cndmask_b32_e64 v15, v10, v12, s[0:1]
	v_cmp_gt_f32_e64 s[0:1], 0, v5
	v_lshlrev_b32_e32 v10, 16, v6
	v_and_b32_e32 v12, 0x7fffffff, v10
	v_cndmask_b32_e64 v5, v11, v13, s[0:1]
	v_and_b32_e32 v11, 0xffff0000, v6
	v_and_b32_e32 v13, 0x7fffffff, v11
	v_pk_fma_f32 v[12:13], v[12:13], s[40:41], 1.0 op_sel_hi:[1,0,0]
	v_mul_f32_e32 v14, v15, v15
	v_rcp_f32_e32 v12, v12
	v_rcp_f32_e32 v13, v13
	v_mul_f32_e32 v4, v5, v5
	v_pk_mul_f32 v[24:25], v[10:11], v[10:11]
	v_pk_add_f32 v[4:5], v[14:15], v[4:5]
	v_pk_fma_f32 v[14:15], v[12:13], s[42:43], v[22:23] op_sel_hi:[1,0,0]
	v_pk_mul_f32 v[24:25], v[24:25], s[64:65] op_sel_hi:[1,0]
	v_pk_fma_f32 v[14:15], v[12:13], v[14:15], s[48:49] op_sel_hi:[1,1,0]
	v_exp_f32_e32 v24, v24
	v_exp_f32_e32 v25, v25
	v_pk_fma_f32 v[14:15], v[12:13], v[14:15], s[50:51] op_sel_hi:[1,1,0]
	v_lshlrev_b32_e32 v6, 16, v7
	v_and_b32_e32 v7, 0xffff0000, v7
	v_pk_fma_f32 v[14:15], v[12:13], v[14:15], s[56:57] op_sel_hi:[1,1,0]
	v_pk_mul_f32 v[12:13], v[12:13], v[14:15]
	v_fma_f32 v26, |v6|, s40, 1.0
	v_fma_f32 v27, |v7|, s40, 1.0
	v_pk_mul_f32 v[12:13], v[24:25], v[12:13]
	v_rcp_f32_e32 v26, v26
	v_rcp_f32_e32 v27, v27
	v_max_f32_e32 v112, 0, v10
	v_pk_fma_f32 v[30:31], v[30:31], s[40:41], 1.0 op_sel_hi:[1,0,0]
	v_lshlrev_b32_e32 v32, 16, v61
	v_fma_f32 v25, -|v10|, v12, v112
	v_max_f32_e32 v113, 0, v11
	v_rcp_f32_e32 v30, v30
	v_rcp_f32_e32 v31, v31
	v_fma_f32 v11, -|v11|, v13, v113
	v_pk_mul_f32 v[14:15], v[6:7], v[6:7]
	v_pk_fma_f32 v[12:13], v[26:27], s[42:43], v[22:23] op_sel_hi:[1,0,0]
	v_pk_mul_f32 v[14:15], v[14:15], s[64:65] op_sel_hi:[1,0]
	v_pk_fma_f32 v[12:13], v[26:27], v[12:13], s[48:49] op_sel_hi:[1,1,0]
	v_exp_f32_e32 v14, v14
	v_exp_f32_e32 v15, v15
	v_pk_fma_f32 v[12:13], v[26:27], v[12:13], s[50:51] op_sel_hi:[1,1,0]
	v_cmp_gt_f32_e64 s[0:1], 0, v6
	v_pk_fma_f32 v[12:13], v[26:27], v[12:13], s[56:57] op_sel_hi:[1,1,0]
	v_and_b32_e32 v33, 0xffff0000, v61
	v_pk_mul_f32 v[12:13], v[26:27], v[12:13]
	v_pk_mul_f32 v[12:13], v[14:15], v[12:13]
	v_pk_mul_f32 v[14:15], v[6:7], v[12:13]
	v_pk_fma_f32 v[12:13], v[6:7], v[12:13], v[6:7] neg_lo:[1,0,0] neg_hi:[1,0,0]
	v_fma_f32 v34, |v32|, s40, 1.0
	v_fma_f32 v35, |v33|, s40, 1.0
	v_cndmask_b32_e64 v27, v12, v14, s[0:1]
	v_cmp_gt_f32_e64 s[0:1], 0, v7
	v_rcp_f32_e32 v34, v34
	v_rcp_f32_e32 v35, v35
	v_cndmask_b32_e64 v7, v13, v15, s[0:1]
	v_pk_mul_f32 v[14:15], v[28:29], v[28:29]
	v_pk_fma_f32 v[12:13], v[30:31], s[42:43], v[22:23] op_sel_hi:[1,0,0]
	v_pk_mul_f32 v[14:15], v[14:15], s[64:65] op_sel_hi:[1,0]
	v_pk_fma_f32 v[12:13], v[30:31], v[12:13], s[48:49] op_sel_hi:[1,1,0]
	v_exp_f32_e32 v14, v14
	v_exp_f32_e32 v15, v15
	v_pk_fma_f32 v[12:13], v[30:31], v[12:13], s[50:51] op_sel_hi:[1,1,0]
	v_cmp_gt_f32_e64 s[0:1], 0, v28
	v_pk_fma_f32 v[12:13], v[30:31], v[12:13], s[56:57] op_sel_hi:[1,1,0]
	v_lshlrev_b32_e32 v36, 16, v62
	v_pk_mul_f32 v[12:13], v[30:31], v[12:13]
	v_and_b32_e32 v37, 0xffff0000, v62
	v_pk_mul_f32 v[12:13], v[14:15], v[12:13]
	v_pk_mul_f32 v[14:15], v[28:29], v[12:13]
	v_pk_fma_f32 v[12:13], v[28:29], v[12:13], v[28:29] neg_lo:[1,0,0] neg_hi:[1,0,0]
	v_cndmask_b32_e64 v31, v12, v14, s[0:1]
	v_cmp_gt_f32_e64 s[0:1], 0, v29
	v_pk_mul_f32 v[28:29], v[32:33], v[32:33]
	v_fma_f32 v38, |v36|, s40, 1.0
	v_fma_f32 v39, |v37|, s40, 1.0
	v_cndmask_b32_e64 v13, v13, v15, s[0:1]
	v_pk_fma_f32 v[14:15], v[34:35], s[42:43], v[22:23] op_sel_hi:[1,0,0]
	v_pk_mul_f32 v[28:29], v[28:29], s[64:65] op_sel_hi:[1,0]
	v_pk_fma_f32 v[14:15], v[34:35], v[14:15], s[48:49] op_sel_hi:[1,1,0]
	v_exp_f32_e32 v28, v28
	v_exp_f32_e32 v29, v29
	v_pk_fma_f32 v[14:15], v[34:35], v[14:15], s[50:51] op_sel_hi:[1,1,0]
	v_rcp_f32_e32 v38, v38
	v_pk_fma_f32 v[14:15], v[34:35], v[14:15], s[56:57] op_sel_hi:[1,1,0]
	v_rcp_f32_e32 v39, v39
	v_pk_mul_f32 v[14:15], v[34:35], v[14:15]
	v_cmp_gt_f32_e64 s[0:1], 0, v32
	v_pk_mul_f32 v[14:15], v[28:29], v[14:15]
	v_lshlrev_b32_e32 v40, 16, v63
	v_pk_mul_f32 v[28:29], v[32:33], v[14:15]
	v_pk_fma_f32 v[14:15], v[32:33], v[14:15], v[32:33] neg_lo:[1,0,0] neg_hi:[1,0,0]
	v_and_b32_e32 v41, 0xffff0000, v63
	v_cndmask_b32_e64 v35, v14, v28, s[0:1]
	v_cmp_gt_f32_e64 s[0:1], 0, v33
	v_pk_mul_f32 v[32:33], v[36:37], v[36:37]
	v_cndmask_b32_e64 v15, v15, v29, s[0:1]
	v_pk_fma_f32 v[28:29], v[38:39], s[42:43], v[22:23] op_sel_hi:[1,0,0]
	v_pk_mul_f32 v[32:33], v[32:33], s[64:65] op_sel_hi:[1,0]
	v_pk_fma_f32 v[28:29], v[38:39], v[28:29], s[48:49] op_sel_hi:[1,1,0]
	v_exp_f32_e32 v32, v32
	v_exp_f32_e32 v33, v33
	v_pk_fma_f32 v[28:29], v[38:39], v[28:29], s[50:51] op_sel_hi:[1,1,0]
	v_pk_fma_f32 v[28:29], v[38:39], v[28:29], s[56:57] op_sel_hi:[1,1,0]
	v_fma_f32 v42, |v40|, s40, 1.0
	v_fma_f32 v43, |v41|, s40, 1.0
	v_pk_mul_f32 v[28:29], v[38:39], v[28:29]
	v_rcp_f32_e32 v42, v42
	v_pk_mul_f32 v[28:29], v[32:33], v[28:29]
	v_rcp_f32_e32 v43, v43
	v_max_f32_e32 v114, 0, v36
	v_pk_fma_f32 v[22:23], v[42:43], s[42:43], v[22:23] op_sel_hi:[1,0,0]
	v_mul_f32_e32 v24, v25, v25
	v_fma_f32 v39, -|v36|, v28, v114
	v_max_f32_e32 v115, 0, v37
	v_pk_fma_f32 v[22:23], v[42:43], v[22:23], s[48:49] op_sel_hi:[1,1,0]
	v_mul_f32_e32 v10, v11, v11
	v_fma_f32 v29, -|v37|, v29, v115
	v_pk_mul_f32 v[32:33], v[40:41], v[40:41]
	v_pk_fma_f32 v[22:23], v[42:43], v[22:23], s[50:51] op_sel_hi:[1,1,0]
	v_pk_mul_f32 v[32:33], v[32:33], s[64:65] op_sel_hi:[1,0]
	v_pk_fma_f32 v[22:23], v[42:43], v[22:23], s[56:57] op_sel_hi:[1,1,0]
	v_exp_f32_e32 v32, v32
	v_exp_f32_e32 v33, v33
	v_pk_mul_f32 v[22:23], v[42:43], v[22:23]
	v_mul_f32_e32 v26, v27, v27
	v_mul_f32_e32 v6, v7, v7
	v_pk_mul_f32 v[22:23], v[32:33], v[22:23]
	v_pk_add_f32 v[4:5], v[4:5], v[8:9]
	v_pk_add_f32 v[8:9], v[24:25], v[10:11]
	v_mul_f32_e32 v30, v31, v31
	v_mul_f32_e32 v12, v13, v13
	v_max_f32_e32 v116, 0, v40
	v_pk_add_f32 v[4:5], v[8:9], v[4:5]
	v_pk_add_f32 v[6:7], v[26:27], v[6:7]
	v_mul_f32_e32 v34, v35, v35
	v_mul_f32_e32 v14, v15, v15
	v_fma_f32 v37, -|v40|, v22, v116
	v_max_f32_e32 v117, 0, v41
	v_pk_add_f32 v[4:5], v[6:7], v[4:5]
	v_pk_add_f32 v[6:7], v[30:31], v[12:13]
	v_mul_f32_e32 v38, v39, v39
	v_mul_f32_e32 v28, v29, v29
	v_fma_f32 v23, -|v41|, v23, v117
	v_pk_add_f32 v[4:5], v[6:7], v[4:5]
	v_pk_add_f32 v[6:7], v[34:35], v[14:15]
	v_mul_f32_e32 v36, v37, v37
	v_mul_f32_e32 v22, v23, v23
	v_pk_add_f32 v[4:5], v[6:7], v[4:5]
	v_pk_add_f32 v[6:7], v[38:39], v[28:29]
	s_nop 0
	v_pk_add_f32 v[4:5], v[6:7], v[4:5]
	v_pk_add_f32 v[6:7], v[36:37], v[22:23]
	s_nop 0
	v_pk_add_f32 v[4:5], v[6:7], v[4:5]
	ds_bpermute_b32 v7, v56, v5
	ds_bpermute_b32 v6, v56, v4
	s_waitcnt lgkmcnt(0)
	v_pk_add_f32 v[4:5], v[4:5], v[6:7]
	ds_bpermute_b32 v7, v57, v5
	ds_bpermute_b32 v6, v57, v4
	s_waitcnt lgkmcnt(0)
	v_pk_add_f32 v[4:5], v[4:5], v[6:7]
	ds_bpermute_b32 v7, v58, v5
	ds_bpermute_b32 v6, v58, v4
	s_waitcnt lgkmcnt(0)
	v_pk_add_f32 v[4:5], v[4:5], v[6:7]
	ds_bpermute_b32 v7, v59, v5
	ds_bpermute_b32 v6, v59, v4
	s_and_saveexec_b64 s[8:9], vcc
	s_cbranch_execz .LBB0_447
	s_waitcnt lgkmcnt(0)
	v_pk_add_f32 v[4:5], v[4:5], v[6:7]
	s_nop 0
	v_pk_mul_f32 v[4:5], v[4:5], s[66:67] op_sel_hi:[1,0]
	s_nop 0
	v_fma_f32 v4, -v5, v5, v4
	v_max_f32_e32 v4, 0, v4
	v_add_f32_e32 v4, 0x358637bd, v4
	v_mul_f32_e32 v6, 0x4b800000, v4
	v_cmp_gt_f32_e64 s[0:1], s36, v4
	s_nop 1
	v_cndmask_b32_e64 v4, v4, v6, s[0:1]
	v_rsq_f32_e32 v4, v4
	v_lshl_add_u32 v6, v20, 2, 0
	v_add_u32_e32 v7, 0x11000, v6
	ds_write_b32 v7, v5
	v_mul_f32_e32 v5, 0x45800000, v4
	v_cndmask_b32_e64 v4, v4, v5, s[0:1]
	v_add_u32_e32 v5, 0x11200, v6
	ds_write_b32 v5, v4
.LBB0_447:
	s_or_b64 exec, exec, s[8:9]
	v_or_b32_e32 v20, 8, v16
	v_ashrrev_i32_e32 v21, 31, v20
	v_lshl_add_u64 v[4:5], s[6:7], 0, v[20:21]
	v_lshlrev_b64 v[4:5], 11, v[4:5]
	v_lshl_add_u64 v[4:5], s[4:5], 0, v[4:5]
	v_lshl_add_u64 v[24:25], v[4:5], 0, v[18:19]
	global_load_dwordx4 v[8:11], v[24:25], off
	s_waitcnt lgkmcnt(0)
	global_load_dwordx4 v[4:7], v[24:25], off offset:256
	v_mov_b64_e32 v[22:23], s[44:45]
	v_mov_b32_e32 v13, v2
	s_waitcnt vmcnt(1)
	v_lshlrev_b32_e32 v28, 16, v10
	v_and_b32_e32 v29, 0xffff0000, v10
	v_and_b32_e32 v15, 0xffff0000, v8
	v_and_b32_e32 v27, 0xffff0000, v9
	v_lshlrev_b32_e32 v26, 16, v9
	v_lshlrev_b32_e32 v14, 16, v8
	v_lshlrev_b32_e32 v8, 16, v11
	v_and_b32_e32 v9, 0xffff0000, v11
	v_fma_f32 v10, |v28|, s40, 1.0
	v_fma_f32 v11, |v29|, s40, 1.0
	v_fma_f32 v32, |v14|, s40, 1.0
	v_fma_f32 v33, |v15|, s40, 1.0
	v_rcp_f32_e32 v10, v10
	v_rcp_f32_e32 v11, v11
	v_fma_f32 v36, |v26|, s40, 1.0
	v_fma_f32 v37, |v27|, s40, 1.0
	v_rcp_f32_e32 v32, v32
	v_rcp_f32_e32 v33, v33
	v_rcp_f32_e32 v36, v36
	v_rcp_f32_e32 v37, v37
	v_pk_mul_f32 v[30:31], v[28:29], v[28:29]
	v_pk_mul_f32 v[34:35], v[14:15], v[14:15]
	v_pk_mul_f32 v[30:31], v[30:31], s[64:65] op_sel_hi:[1,0]
	v_pk_fma_f32 v[44:45], v[10:11], s[42:43], v[22:23] op_sel_hi:[1,0,0]
	v_pk_mul_f32 v[38:39], v[26:27], v[26:27]
	v_pk_mul_f32 v[34:35], v[34:35], s[64:65] op_sel_hi:[1,0]
	v_exp_f32_e32 v30, v30
	v_exp_f32_e32 v31, v31
	v_pk_fma_f32 v[46:47], v[32:33], s[42:43], v[22:23] op_sel_hi:[1,0,0]
	v_pk_fma_f32 v[44:45], v[10:11], v[44:45], s[48:49] op_sel_hi:[1,1,0]
	v_pk_mul_f32 v[38:39], v[38:39], s[64:65] op_sel_hi:[1,0]
	v_exp_f32_e32 v34, v34
	v_exp_f32_e32 v35, v35
	v_pk_fma_f32 v[48:49], v[36:37], s[42:43], v[22:23] op_sel_hi:[1,0,0]
	v_pk_fma_f32 v[46:47], v[32:33], v[46:47], s[48:49] op_sel_hi:[1,1,0]
	v_pk_fma_f32 v[44:45], v[10:11], v[44:45], s[50:51] op_sel_hi:[1,1,0]
	v_exp_f32_e32 v38, v38
	v_exp_f32_e32 v39, v39
	v_pk_fma_f32 v[48:49], v[36:37], v[48:49], s[48:49] op_sel_hi:[1,1,0]
	v_pk_fma_f32 v[46:47], v[32:33], v[46:47], s[50:51] op_sel_hi:[1,1,0]
	v_pk_fma_f32 v[44:45], v[10:11], v[44:45], s[56:57] op_sel_hi:[1,1,0]
	v_pk_fma_f32 v[48:49], v[36:37], v[48:49], s[50:51] op_sel_hi:[1,1,0]
	v_pk_fma_f32 v[46:47], v[32:33], v[46:47], s[56:57] op_sel_hi:[1,1,0]
	v_pk_mul_f32 v[10:11], v[10:11], v[44:45]
	v_pk_fma_f32 v[48:49], v[36:37], v[48:49], s[56:57] op_sel_hi:[1,1,0]
	v_pk_mul_f32 v[32:33], v[32:33], v[46:47]
	v_pk_mul_f32 v[10:11], v[30:31], v[10:11]
	v_pk_mul_f32 v[36:37], v[36:37], v[48:49]
	v_pk_mul_f32 v[30:31], v[34:35], v[32:33]
	v_max_f32_e32 v80, 0, v28
	v_pk_mul_f32 v[32:33], v[38:39], v[36:37]
	v_fma_f32 v45, -|v28|, v10, v80
	v_max_f32_e32 v81, 0, v29
	v_fma_f32 v11, -|v29|, v11, v81
	v_max_f32_e32 v82, 0, v26
	v_pk_mul_f32 v[36:37], v[30:31], v[14:15]
	v_pk_fma_f32 v[30:31], v[30:31], v[14:15], v[14:15] neg_lo:[1,0,0] neg_hi:[1,0,0]
	v_fma_f32 v29, -|v26|, v32, v82
	v_cmp_gt_f32_e64 s[0:1], 0, v14
	v_fma_f32 v40, |v8|, s40, 1.0
	v_fma_f32 v41, |v9|, s40, 1.0
	v_mov_b32_e32 v14, v29
	v_cndmask_b32_e64 v28, v30, v36, s[0:1]
	v_cmp_gt_f32_e64 s[0:1], 0, v15
	v_rcp_f32_e32 v40, v40
	v_rcp_f32_e32 v41, v41
	v_cndmask_b32_e64 v15, v31, v37, s[0:1]
	v_max_f32_e32 v83, 0, v27
	v_mul_f32_e32 v30, v28, v28
	v_mov_b32_e32 v31, v29
	v_fma_f32 v27, -|v27|, v33, v83
	v_mul_f32_e32 v26, v15, v15
	v_mul_f32_e32 v12, v27, v27
	v_pk_add_f32 v[26:27], v[30:31], v[26:27]
	v_pk_mul_f32 v[30:31], v[28:29], v[14:15] op_sel:[1,0] op_sel_hi:[0,1]
	v_pk_add_f32 v[14:15], v[28:29], v[14:15] op_sel:[1,0] op_sel_hi:[0,1]
	v_pk_mul_f32 v[42:43], v[8:9], v[8:9]
	v_mov_b32_e32 v31, v15
	v_pk_mul_f32 v[42:43], v[42:43], s[64:65] op_sel_hi:[1,0]
	v_pk_fma_f32 v[50:51], v[40:41], s[42:43], v[22:23] op_sel_hi:[1,0,0]
	v_mul_f32_e32 v44, v45, v45
	v_mul_f32_e32 v10, v11, v11
	v_pk_add_f32 v[12:13], v[30:31], v[12:13]
	v_exp_f32_e32 v42, v42
	v_exp_f32_e32 v43, v43
	v_pk_fma_f32 v[50:51], v[40:41], v[50:51], s[48:49] op_sel_hi:[1,1,0]
	v_pk_add_f32 v[10:11], v[44:45], v[10:11]
	v_pk_add_f32 v[12:13], v[26:27], v[12:13]
	v_cmp_gt_f32_e64 s[0:1], 0, v8
	v_pk_add_f32 v[26:27], v[10:11], v[12:13]
	v_pk_fma_f32 v[10:11], v[40:41], v[50:51], s[50:51] op_sel_hi:[1,1,0]
	s_nop 0
	v_pk_fma_f32 v[10:11], v[40:41], v[10:11], s[56:57] op_sel_hi:[1,1,0]
	s_nop 0
	v_pk_mul_f32 v[10:11], v[40:41], v[10:11]
	s_waitcnt vmcnt(0)
	v_lshlrev_b32_e32 v40, 16, v6
	v_pk_mul_f32 v[10:11], v[42:43], v[10:11]
	v_and_b32_e32 v41, 0xffff0000, v6
	v_pk_mul_f32 v[12:13], v[8:9], v[10:11]
	v_pk_fma_f32 v[10:11], v[8:9], v[10:11], v[8:9] neg_lo:[1,0,0] neg_hi:[1,0,0]
	v_and_b32_e32 v37, 0x7fffffff, v41
	v_cndmask_b32_e64 v15, v10, v12, s[0:1]
	v_cmp_gt_f32_e64 s[0:1], 0, v9
	v_lshlrev_b32_e32 v12, 16, v4
	v_and_b32_e32 v10, 0x7fffffff, v12
	v_cndmask_b32_e64 v9, v11, v13, s[0:1]
	v_and_b32_e32 v13, 0xffff0000, v4
	v_and_b32_e32 v11, 0x7fffffff, v13
	v_pk_fma_f32 v[10:11], v[10:11], s[40:41], 1.0 op_sel_hi:[1,0,0]
	v_mul_f32_e32 v14, v15, v15
	v_rcp_f32_e32 v10, v10
	v_rcp_f32_e32 v11, v11
	v_mul_f32_e32 v8, v9, v9
	v_pk_add_f32 v[28:29], v[14:15], v[8:9]
	v_pk_mul_f32 v[14:15], v[12:13], v[12:13]
	v_pk_fma_f32 v[8:9], v[10:11], s[42:43], v[22:23] op_sel_hi:[1,0,0]
	v_pk_mul_f32 v[14:15], v[14:15], s[64:65] op_sel_hi:[1,0]
	v_pk_fma_f32 v[8:9], v[10:11], v[8:9], s[48:49] op_sel_hi:[1,1,0]
	v_exp_f32_e32 v14, v14
	v_exp_f32_e32 v15, v15
	v_pk_fma_f32 v[8:9], v[10:11], v[8:9], s[50:51] op_sel_hi:[1,1,0]
	v_lshlrev_b32_e32 v4, 16, v5
	v_pk_fma_f32 v[8:9], v[10:11], v[8:9], s[56:57] op_sel_hi:[1,1,0]
	v_and_b32_e32 v5, 0xffff0000, v5
	v_pk_mul_f32 v[8:9], v[10:11], v[8:9]
	v_pk_mul_f32 v[14:15], v[14:15], v[8:9]
	global_load_dwordx4 v[8:11], v[24:25], off offset:512
	v_fma_f32 v34, |v4|, s40, 1.0
	v_fma_f32 v35, |v5|, s40, 1.0
	v_pk_mul_f32 v[32:33], v[12:13], v[14:15]
	v_rcp_f32_e32 v34, v34
	v_rcp_f32_e32 v35, v35
	v_pk_fma_f32 v[14:15], v[12:13], v[14:15], v[12:13] neg_lo:[1,0,0] neg_hi:[1,0,0]
	v_cmp_gt_f32_e64 s[0:1], 0, v12
	v_and_b32_e32 v36, 0x7fffffff, v40
	v_pk_fma_f32 v[36:37], v[36:37], s[40:41], 1.0 op_sel_hi:[1,0,0]
	v_cndmask_b32_e64 v31, v14, v32, s[0:1]
	v_cmp_gt_f32_e64 s[0:1], 0, v13
	v_pk_fma_f32 v[12:13], v[34:35], s[42:43], v[22:23] op_sel_hi:[1,0,0]
	v_rcp_f32_e32 v38, v36
	v_cndmask_b32_e64 v33, v15, v33, s[0:1]
	v_pk_mul_f32 v[14:15], v[4:5], v[4:5]
	v_pk_fma_f32 v[12:13], v[34:35], v[12:13], s[48:49] op_sel_hi:[1,1,0]
	v_pk_mul_f32 v[14:15], v[14:15], s[64:65] op_sel_hi:[1,0]
	v_pk_fma_f32 v[12:13], v[34:35], v[12:13], s[50:51] op_sel_hi:[1,1,0]
	v_exp_f32_e32 v14, v14
	v_exp_f32_e32 v15, v15
	v_pk_fma_f32 v[12:13], v[34:35], v[12:13], s[56:57] op_sel_hi:[1,1,0]
	v_rcp_f32_e32 v39, v37
	v_pk_mul_f32 v[12:13], v[34:35], v[12:13]
	v_cmp_gt_f32_e64 s[0:1], 0, v4
	v_pk_mul_f32 v[12:13], v[14:15], v[12:13]
	v_mul_f32_e32 v30, v31, v31
	v_pk_mul_f32 v[14:15], v[4:5], v[12:13]
	v_pk_fma_f32 v[12:13], v[4:5], v[12:13], v[4:5] neg_lo:[1,0,0] neg_hi:[1,0,0]
	v_mul_f32_e32 v32, v33, v33
	v_cndmask_b32_e64 v35, v12, v14, s[0:1]
	v_cmp_gt_f32_e64 s[0:1], 0, v5
	v_pk_fma_f32 v[4:5], v[38:39], s[42:43], v[22:23] op_sel_hi:[1,0,0]
	v_lshlrev_b32_e32 v14, 16, v7
	v_cndmask_b32_e64 v37, v13, v15, s[0:1]
	v_pk_mul_f32 v[12:13], v[40:41], v[40:41]
	v_pk_fma_f32 v[4:5], v[38:39], v[4:5], s[48:49] op_sel_hi:[1,1,0]
	v_pk_mul_f32 v[12:13], v[12:13], s[64:65] op_sel_hi:[1,0]
	v_pk_fma_f32 v[4:5], v[38:39], v[4:5], s[50:51] op_sel_hi:[1,1,0]
	v_exp_f32_e32 v12, v12
	v_exp_f32_e32 v13, v13
	v_and_b32_e32 v15, 0xffff0000, v7
	v_pk_fma_f32 v[4:5], v[38:39], v[4:5], s[56:57] op_sel_hi:[1,1,0]
	v_pk_mul_f32 v[4:5], v[38:39], v[4:5]
	v_fma_f32 v6, |v14|, s40, 1.0
	v_fma_f32 v7, |v15|, s40, 1.0
	v_pk_mul_f32 v[4:5], v[12:13], v[4:5]
	v_rcp_f32_e32 v6, v6
	v_rcp_f32_e32 v7, v7
	v_max_f32_e32 v84, 0, v40
	v_mul_f32_e32 v34, v35, v35
	v_mul_f32_e32 v36, v37, v37
	v_fma_f32 v39, -|v40|, v4, v84
	v_max_f32_e32 v85, 0, v41
	v_pk_add_f32 v[26:27], v[28:29], v[26:27]
	v_pk_add_f32 v[28:29], v[30:31], v[32:33]
	v_fma_f32 v41, -|v41|, v5, v85
	v_pk_mul_f32 v[12:13], v[14:15], v[14:15]
	v_pk_fma_f32 v[4:5], v[6:7], s[42:43], v[22:23] op_sel_hi:[1,0,0]
	v_pk_mul_f32 v[12:13], v[12:13], s[64:65] op_sel_hi:[1,0]
	v_pk_fma_f32 v[4:5], v[6:7], v[4:5], s[48:49] op_sel_hi:[1,1,0]
	v_exp_f32_e32 v12, v12
	v_exp_f32_e32 v13, v13
	v_pk_fma_f32 v[4:5], v[6:7], v[4:5], s[50:51] op_sel_hi:[1,1,0]
	v_cmp_gt_f32_e64 s[0:1], 0, v14
	v_pk_fma_f32 v[4:5], v[6:7], v[4:5], s[56:57] op_sel_hi:[1,1,0]
	v_mul_f32_e32 v38, v39, v39
	v_pk_mul_f32 v[4:5], v[6:7], v[4:5]
	v_mul_f32_e32 v40, v41, v41
	v_pk_mul_f32 v[4:5], v[12:13], v[4:5]
	v_pk_add_f32 v[26:27], v[28:29], v[26:27]
	v_pk_mul_f32 v[12:13], v[14:15], v[4:5]
	v_pk_fma_f32 v[44:45], v[14:15], v[4:5], v[14:15] neg_lo:[1,0,0] neg_hi:[1,0,0]
	global_load_dwordx4 v[4:7], v[24:25], off offset:768
	v_cndmask_b32_e64 v43, v44, v12, s[0:1]
	v_cmp_gt_f32_e64 s[0:1], 0, v15
	v_pk_add_f32 v[28:29], v[34:35], v[36:37]
	s_waitcnt vmcnt(1)
	v_lshlrev_b32_e32 v48, 16, v8
	v_and_b32_e32 v49, 0xffff0000, v8
	v_fma_f32 v46, |v48|, s40, 1.0
	v_fma_f32 v47, |v49|, s40, 1.0
	v_pk_mul_f32 v[14:15], v[48:49], v[48:49]
	v_rcp_f32_e32 v46, v46
	v_rcp_f32_e32 v47, v47
	v_cndmask_b32_e64 v45, v45, v13, s[0:1]
	v_pk_mul_f32 v[14:15], v[14:15], s[64:65] op_sel_hi:[1,0]
	v_lshlrev_b32_e32 v50, 16, v9
	v_pk_fma_f32 v[12:13], v[46:47], s[42:43], v[22:23] op_sel_hi:[1,0,0]
	v_exp_f32_e32 v14, v14
	v_pk_fma_f32 v[12:13], v[46:47], v[12:13], s[48:49] op_sel_hi:[1,1,0]
	v_exp_f32_e32 v15, v15
	v_and_b32_e32 v51, 0xffff0000, v9
	v_pk_fma_f32 v[12:13], v[46:47], v[12:13], s[50:51] op_sel_hi:[1,1,0]
	v_pk_fma_f32 v[12:13], v[46:47], v[12:13], s[56:57] op_sel_hi:[1,1,0]
	v_fma_f32 v8, |v50|, s40, 1.0
	v_fma_f32 v9, |v51|, s40, 1.0
	v_pk_mul_f32 v[12:13], v[46:47], v[12:13]
	v_rcp_f32_e32 v52, v8
	v_rcp_f32_e32 v53, v9
	v_pk_mul_f32 v[12:13], v[14:15], v[12:13]
	v_cmp_gt_f32_e64 s[0:1], 0, v48
	v_pk_mul_f32 v[14:15], v[48:49], v[12:13]
	v_pk_fma_f32 v[12:13], v[48:49], v[12:13], v[48:49] neg_lo:[1,0,0] neg_hi:[1,0,0]
	v_lshlrev_b32_e32 v60, 16, v10
	v_cndmask_b32_e64 v47, v12, v14, s[0:1]
	v_cmp_gt_f32_e64 s[0:1], 0, v49
	v_and_b32_e32 v61, 0xffff0000, v10
	v_lshlrev_b32_e32 v10, 16, v11
	v_cndmask_b32_e64 v9, v13, v15, s[0:1]
	v_pk_fma_f32 v[12:13], v[52:53], s[42:43], v[22:23] op_sel_hi:[1,0,0]
	v_pk_mul_f32 v[14:15], v[50:51], v[50:51]
	v_pk_fma_f32 v[12:13], v[52:53], v[12:13], s[48:49] op_sel_hi:[1,1,0]
	v_pk_mul_f32 v[14:15], v[14:15], s[64:65] op_sel_hi:[1,0]
	v_pk_fma_f32 v[12:13], v[52:53], v[12:13], s[50:51] op_sel_hi:[1,1,0]
	v_exp_f32_e32 v14, v14
	v_exp_f32_e32 v15, v15
	v_pk_fma_f32 v[12:13], v[52:53], v[12:13], s[56:57] op_sel_hi:[1,1,0]
	v_cmp_gt_f32_e64 s[0:1], 0, v50
	v_pk_mul_f32 v[12:13], v[52:53], v[12:13]
	v_fma_f32 v52, |v60|, s40, 1.0
	v_fma_f32 v53, |v61|, s40, 1.0
	v_pk_mul_f32 v[12:13], v[14:15], v[12:13]
	v_rcp_f32_e32 v52, v52
	v_rcp_f32_e32 v53, v53
	v_pk_mul_f32 v[14:15], v[50:51], v[12:13]
	v_pk_fma_f32 v[12:13], v[50:51], v[12:13], v[50:51] neg_lo:[1,0,0] neg_hi:[1,0,0]
	v_and_b32_e32 v11, 0xffff0000, v11
	v_cndmask_b32_e64 v49, v12, v14, s[0:1]
	v_cmp_gt_f32_e64 s[0:1], 0, v51
	v_cndmask_b32_e64 v51, v13, v15, s[0:1]
	v_pk_mul_f32 v[14:15], v[60:61], v[60:61]
	v_pk_fma_f32 v[12:13], v[52:53], s[42:43], v[22:23] op_sel_hi:[1,0,0]
	v_pk_mul_f32 v[14:15], v[14:15], s[64:65] op_sel_hi:[1,0]
	v_pk_fma_f32 v[12:13], v[52:53], v[12:13], s[48:49] op_sel_hi:[1,1,0]
	v_exp_f32_e32 v14, v14
	v_exp_f32_e32 v15, v15
	v_pk_fma_f32 v[12:13], v[52:53], v[12:13], s[50:51] op_sel_hi:[1,1,0]
	v_fma_f32 v62, |v10|, s40, 1.0
	v_fma_f32 v63, |v11|, s40, 1.0
	v_pk_fma_f32 v[12:13], v[52:53], v[12:13], s[56:57] op_sel_hi:[1,1,0]
	v_rcp_f32_e32 v62, v62
	v_pk_mul_f32 v[12:13], v[52:53], v[12:13]
	v_rcp_f32_e32 v63, v63
	v_pk_mul_f32 v[12:13], v[14:15], v[12:13]
	v_cmp_gt_f32_e64 s[0:1], 0, v60
	v_pk_mul_f32 v[14:15], v[60:61], v[12:13]
	v_pk_fma_f32 v[12:13], v[60:61], v[12:13], v[60:61] neg_lo:[1,0,0] neg_hi:[1,0,0]
	v_mul_f32_e32 v42, v43, v43
	v_cndmask_b32_e64 v53, v12, v14, s[0:1]
	v_cmp_gt_f32_e64 s[0:1], 0, v61
	s_waitcnt vmcnt(0)
	v_lshlrev_b32_e32 v64, 16, v4
	v_and_b32_e32 v65, 0xffff0000, v4
	v_cndmask_b32_e64 v61, v13, v15, s[0:1]
	v_pk_mul_f32 v[14:15], v[10:11], v[10:11]
	v_pk_fma_f32 v[12:13], v[62:63], s[42:43], v[22:23] op_sel_hi:[1,0,0]
	v_pk_mul_f32 v[14:15], v[14:15], s[64:65] op_sel_hi:[1,0]
	v_pk_fma_f32 v[12:13], v[62:63], v[12:13], s[48:49] op_sel_hi:[1,1,0]
	v_exp_f32_e32 v14, v14
	v_exp_f32_e32 v15, v15
	v_pk_fma_f32 v[12:13], v[62:63], v[12:13], s[50:51] op_sel_hi:[1,1,0]
	v_pk_fma_f32 v[12:13], v[62:63], v[12:13], s[56:57] op_sel_hi:[1,1,0]
	v_pk_mul_f32 v[12:13], v[62:63], v[12:13]
	v_fma_f32 v66, |v64|, s40, 1.0
	v_fma_f32 v67, |v65|, s40, 1.0
	v_pk_mul_f32 v[12:13], v[14:15], v[12:13]
	v_rcp_f32_e32 v66, v66
	v_rcp_f32_e32 v67, v67
	v_max_f32_e32 v86, 0, v10
	v_lshlrev_b32_e32 v4, 16, v5
	v_and_b32_e32 v5, 0xffff0000, v5
	v_fma_f32 v63, -|v10|, v12, v86
	v_max_f32_e32 v90, 0, v11
	v_fma_f32 v11, -|v11|, v13, v90
	v_pk_mul_f32 v[14:15], v[64:65], v[64:65]
	v_pk_fma_f32 v[12:13], v[66:67], s[42:43], v[22:23] op_sel_hi:[1,0,0]
	v_pk_mul_f32 v[14:15], v[14:15], s[64:65] op_sel_hi:[1,0]
	v_pk_fma_f32 v[12:13], v[66:67], v[12:13], s[48:49] op_sel_hi:[1,1,0]
	v_exp_f32_e32 v14, v14
	v_exp_f32_e32 v15, v15
	v_pk_fma_f32 v[12:13], v[66:67], v[12:13], s[50:51] op_sel_hi:[1,1,0]
	v_fma_f32 v68, |v4|, s40, 1.0
	v_fma_f32 v69, |v5|, s40, 1.0
	v_pk_fma_f32 v[12:13], v[66:67], v[12:13], s[56:57] op_sel_hi:[1,1,0]
	v_rcp_f32_e32 v68, v68
	v_pk_mul_f32 v[12:13], v[66:67], v[12:13]
	v_rcp_f32_e32 v69, v69
	v_pk_mul_f32 v[12:13], v[14:15], v[12:13]
	v_cmp_gt_f32_e64 s[0:1], 0, v64
	v_pk_mul_f32 v[14:15], v[64:65], v[12:13]
	v_pk_fma_f32 v[12:13], v[64:65], v[12:13], v[64:65] neg_lo:[1,0,0] neg_hi:[1,0,0]
	v_mul_f32_e32 v44, v45, v45
	v_cndmask_b32_e64 v67, v12, v14, s[0:1]
	v_cmp_gt_f32_e64 s[0:1], 0, v65
	v_pk_add_f32 v[26:27], v[28:29], v[26:27]
	v_pk_add_f32 v[28:29], v[38:39], v[40:41]
	v_cndmask_b32_e64 v65, v13, v15, s[0:1]
	v_pk_fma_f32 v[12:13], v[68:69], s[42:43], v[22:23] op_sel_hi:[1,0,0]
	v_pk_mul_f32 v[14:15], v[4:5], v[4:5]
	v_pk_fma_f32 v[12:13], v[68:69], v[12:13], s[48:49] op_sel_hi:[1,1,0]
	v_pk_mul_f32 v[14:15], v[14:15], s[64:65] op_sel_hi:[1,0]
	v_pk_fma_f32 v[12:13], v[68:69], v[12:13], s[50:51] op_sel_hi:[1,1,0]
	v_exp_f32_e32 v70, v14
	v_exp_f32_e32 v71, v15
	v_pk_fma_f32 v[72:73], v[68:69], v[12:13], s[56:57] op_sel_hi:[1,1,0]
	global_load_dwordx4 v[12:15], v[24:25], off offset:1024
	v_mul_f32_e32 v46, v47, v47
	v_mul_f32_e32 v8, v9, v9
	v_pk_add_f32 v[26:27], v[28:29], v[26:27]
	v_pk_add_f32 v[28:29], v[42:43], v[44:45]
	v_mul_f32_e32 v48, v49, v49
	v_mul_f32_e32 v50, v51, v51
	v_pk_add_f32 v[26:27], v[28:29], v[26:27]
	v_pk_add_f32 v[8:9], v[46:47], v[8:9]
	v_mul_f32_e32 v52, v53, v53
	v_mul_f32_e32 v60, v61, v61
	v_pk_mul_f32 v[68:69], v[68:69], v[72:73]
	v_pk_add_f32 v[8:9], v[8:9], v[26:27]
	v_pk_add_f32 v[26:27], v[48:49], v[50:51]
	v_pk_mul_f32 v[68:69], v[70:71], v[68:69]
	v_pk_add_f32 v[8:9], v[26:27], v[8:9]
	v_pk_add_f32 v[26:27], v[52:53], v[60:61]
	v_lshlrev_b32_e32 v28, 16, v6
	v_and_b32_e32 v29, 0xffff0000, v6
	v_max_f32_e32 v91, 0, v4
	v_pk_add_f32 v[8:9], v[26:27], v[8:9]
	v_mul_f32_e32 v62, v63, v63
	v_mul_f32_e32 v10, v11, v11
	v_fma_f32 v73, -|v4|, v68, v91
	v_max_f32_e32 v92, 0, v5
	v_fma_f32 v26, |v28|, s40, 1.0
	v_fma_f32 v27, |v29|, s40, 1.0
	v_mul_f32_e32 v66, v67, v67
	v_mul_f32_e32 v64, v65, v65
	v_fma_f32 v5, -|v5|, v69, v92
	v_pk_add_f32 v[10:11], v[62:63], v[10:11]
	v_rcp_f32_e32 v30, v26
	v_rcp_f32_e32 v31, v27
	v_mul_f32_e32 v72, v73, v73
	v_mul_f32_e32 v4, v5, v5
	v_pk_add_f32 v[8:9], v[10:11], v[8:9]
	v_pk_add_f32 v[10:11], v[66:67], v[64:65]
	v_pk_add_f32 v[4:5], v[72:73], v[4:5]
	v_pk_add_f32 v[8:9], v[10:11], v[8:9]
	v_cmp_gt_f32_e64 s[0:1], 0, v28
	v_pk_add_f32 v[26:27], v[4:5], v[8:9]
	v_pk_mul_f32 v[8:9], v[28:29], v[28:29]
	v_pk_fma_f32 v[4:5], v[30:31], s[42:43], v[22:23] op_sel_hi:[1,0,0]
	v_pk_mul_f32 v[8:9], v[8:9], s[64:65] op_sel_hi:[1,0]
	v_pk_fma_f32 v[4:5], v[30:31], v[4:5], s[48:49] op_sel_hi:[1,1,0]
	v_exp_f32_e32 v8, v8
	v_exp_f32_e32 v9, v9
	v_pk_fma_f32 v[4:5], v[30:31], v[4:5], s[50:51] op_sel_hi:[1,1,0]
	v_lshlrev_b32_e32 v6, 16, v7
	v_pk_fma_f32 v[4:5], v[30:31], v[4:5], s[56:57] op_sel_hi:[1,1,0]
	v_and_b32_e32 v7, 0xffff0000, v7
	v_pk_mul_f32 v[4:5], v[30:31], v[4:5]
	s_nop 0
	v_pk_mul_f32 v[4:5], v[8:9], v[4:5]
	s_nop 0
	v_pk_mul_f32 v[8:9], v[28:29], v[4:5]
	v_pk_fma_f32 v[4:5], v[28:29], v[4:5], v[28:29] neg_lo:[1,0,0] neg_hi:[1,0,0]
	s_nop 0
	v_cndmask_b32_e64 v11, v4, v8, s[0:1]
	v_cmp_gt_f32_e64 s[0:1], 0, v29
	v_and_b32_e32 v8, 0x7fffffff, v6
	v_mul_f32_e32 v10, v11, v11
	v_cndmask_b32_e64 v5, v5, v9, s[0:1]
	v_and_b32_e32 v9, 0x7fffffff, v7
	v_pk_fma_f32 v[8:9], v[8:9], s[40:41], 1.0 op_sel_hi:[1,0,0]
	v_mul_f32_e32 v4, v5, v5
	v_rcp_f32_e32 v8, v8
	v_rcp_f32_e32 v9, v9
	v_pk_add_f32 v[28:29], v[10:11], v[4:5]
	v_pk_mul_f32 v[10:11], v[6:7], v[6:7]
	v_cmp_gt_f32_e64 s[0:1], 0, v6
	v_pk_fma_f32 v[4:5], v[8:9], s[42:43], v[22:23] op_sel_hi:[1,0,0]
	v_pk_mul_f32 v[10:11], v[10:11], s[64:65] op_sel_hi:[1,0]
	v_pk_fma_f32 v[4:5], v[8:9], v[4:5], s[48:49] op_sel_hi:[1,1,0]
	v_exp_f32_e32 v10, v10
	v_exp_f32_e32 v11, v11
	v_pk_fma_f32 v[4:5], v[8:9], v[4:5], s[50:51] op_sel_hi:[1,1,0]
	v_pk_add_f32 v[26:27], v[28:29], v[26:27]
	v_pk_fma_f32 v[4:5], v[8:9], v[4:5], s[56:57] op_sel_hi:[1,1,0]
	s_nop 0
	v_pk_mul_f32 v[4:5], v[8:9], v[4:5]
	s_nop 0
	v_pk_mul_f32 v[4:5], v[10:11], v[4:5]
	global_load_dwordx4 v[8:11], v[24:25], off offset:1280
	s_waitcnt vmcnt(1)
	v_lshlrev_b32_e32 v36, 16, v12
	v_and_b32_e32 v37, 0xffff0000, v12
	v_fma_f32 v34, |v36|, s40, 1.0
	v_fma_f32 v35, |v37|, s40, 1.0
	v_pk_mul_f32 v[32:33], v[6:7], v[4:5]
	v_rcp_f32_e32 v34, v34
	v_rcp_f32_e32 v35, v35
	v_pk_fma_f32 v[4:5], v[6:7], v[4:5], v[6:7] neg_lo:[1,0,0] neg_hi:[1,0,0]
	v_lshlrev_b32_e32 v38, 16, v13
	v_cndmask_b32_e64 v31, v4, v32, s[0:1]
	v_cmp_gt_f32_e64 s[0:1], 0, v7
	v_pk_mul_f32 v[6:7], v[36:37], v[36:37]
	v_and_b32_e32 v39, 0xffff0000, v13
	v_cndmask_b32_e64 v33, v5, v33, s[0:1]
	v_pk_fma_f32 v[4:5], v[34:35], s[42:43], v[22:23] op_sel_hi:[1,0,0]
	v_pk_mul_f32 v[6:7], v[6:7], s[64:65] op_sel_hi:[1,0]
	v_pk_fma_f32 v[4:5], v[34:35], v[4:5], s[48:49] op_sel_hi:[1,1,0]
	v_exp_f32_e32 v6, v6
	v_exp_f32_e32 v7, v7
	v_pk_fma_f32 v[4:5], v[34:35], v[4:5], s[50:51] op_sel_hi:[1,1,0]
	v_pk_fma_f32 v[4:5], v[34:35], v[4:5], s[56:57] op_sel_hi:[1,1,0]
	v_fma_f32 v12, |v38|, s40, 1.0
	v_fma_f32 v13, |v39|, s40, 1.0
	v_pk_mul_f32 v[4:5], v[34:35], v[4:5]
	v_rcp_f32_e32 v40, v12
	v_rcp_f32_e32 v41, v13
	v_pk_mul_f32 v[4:5], v[6:7], v[4:5]
	v_cmp_gt_f32_e64 s[0:1], 0, v36
	v_pk_mul_f32 v[6:7], v[36:37], v[4:5]
	v_pk_fma_f32 v[4:5], v[36:37], v[4:5], v[36:37] neg_lo:[1,0,0] neg_hi:[1,0,0]
	v_lshlrev_b32_e32 v42, 16, v14
	v_cndmask_b32_e64 v35, v4, v6, s[0:1]
	v_cmp_gt_f32_e64 s[0:1], 0, v37
	v_and_b32_e32 v43, 0xffff0000, v14
	v_lshlrev_b32_e32 v44, 16, v15
	v_cndmask_b32_e64 v13, v5, v7, s[0:1]
	v_pk_fma_f32 v[4:5], v[40:41], s[42:43], v[22:23] op_sel_hi:[1,0,0]
	v_pk_mul_f32 v[6:7], v[38:39], v[38:39]
	v_pk_fma_f32 v[4:5], v[40:41], v[4:5], s[48:49] op_sel_hi:[1,1,0]
	v_pk_mul_f32 v[6:7], v[6:7], s[64:65] op_sel_hi:[1,0]
	v_pk_fma_f32 v[4:5], v[40:41], v[4:5], s[50:51] op_sel_hi:[1,1,0]
	v_exp_f32_e32 v6, v6
	v_exp_f32_e32 v7, v7
	v_pk_fma_f32 v[4:5], v[40:41], v[4:5], s[56:57] op_sel_hi:[1,1,0]
	v_cmp_gt_f32_e64 s[0:1], 0, v38
	v_pk_mul_f32 v[4:5], v[40:41], v[4:5]
	v_fma_f32 v40, |v42|, s40, 1.0
	v_fma_f32 v41, |v43|, s40, 1.0
	v_pk_mul_f32 v[4:5], v[6:7], v[4:5]
	v_rcp_f32_e32 v40, v40
	v_rcp_f32_e32 v41, v41
	v_pk_mul_f32 v[6:7], v[38:39], v[4:5]
	v_pk_fma_f32 v[4:5], v[38:39], v[4:5], v[38:39] neg_lo:[1,0,0] neg_hi:[1,0,0]
	v_and_b32_e32 v45, 0xffff0000, v15
	v_cndmask_b32_e64 v37, v4, v6, s[0:1]
	v_cmp_gt_f32_e64 s[0:1], 0, v39
	v_cndmask_b32_e64 v39, v5, v7, s[0:1]
	v_pk_mul_f32 v[6:7], v[42:43], v[42:43]
	v_pk_fma_f32 v[4:5], v[40:41], s[42:43], v[22:23] op_sel_hi:[1,0,0]
	v_pk_mul_f32 v[6:7], v[6:7], s[64:65] op_sel_hi:[1,0]
	v_pk_fma_f32 v[4:5], v[40:41], v[4:5], s[48:49] op_sel_hi:[1,1,0]
	v_exp_f32_e32 v6, v6
	v_exp_f32_e32 v7, v7
	v_pk_fma_f32 v[4:5], v[40:41], v[4:5], s[50:51] op_sel_hi:[1,1,0]
	v_fma_f32 v14, |v44|, s40, 1.0
	v_fma_f32 v15, |v45|, s40, 1.0
	v_pk_fma_f32 v[4:5], v[40:41], v[4:5], s[56:57] op_sel_hi:[1,1,0]
	v_rcp_f32_e32 v46, v14
	v_pk_mul_f32 v[4:5], v[40:41], v[4:5]
	v_rcp_f32_e32 v47, v15
	v_pk_mul_f32 v[4:5], v[6:7], v[4:5]
	v_cmp_gt_f32_e64 s[0:1], 0, v42
	v_pk_mul_f32 v[6:7], v[42:43], v[4:5]
	v_pk_fma_f32 v[4:5], v[42:43], v[4:5], v[42:43] neg_lo:[1,0,0] neg_hi:[1,0,0]
	v_mul_f32_e32 v30, v31, v31
	v_cndmask_b32_e64 v41, v4, v6, s[0:1]
	v_cmp_gt_f32_e64 s[0:1], 0, v43
	s_waitcnt vmcnt(0)
	v_lshlrev_b32_e32 v48, 16, v8
	v_and_b32_e32 v49, 0xffff0000, v8
	v_cndmask_b32_e64 v15, v5, v7, s[0:1]
	v_pk_fma_f32 v[4:5], v[46:47], s[42:43], v[22:23] op_sel_hi:[1,0,0]
	v_pk_mul_f32 v[6:7], v[44:45], v[44:45]
	v_pk_fma_f32 v[4:5], v[46:47], v[4:5], s[48:49] op_sel_hi:[1,1,0]
	v_pk_mul_f32 v[6:7], v[6:7], s[64:65] op_sel_hi:[1,0]
	v_pk_fma_f32 v[4:5], v[46:47], v[4:5], s[50:51] op_sel_hi:[1,1,0]
	v_exp_f32_e32 v6, v6
	v_exp_f32_e32 v7, v7
	v_pk_fma_f32 v[4:5], v[46:47], v[4:5], s[56:57] op_sel_hi:[1,1,0]
	v_cmp_gt_f32_e64 s[0:1], 0, v44
	v_pk_mul_f32 v[4:5], v[46:47], v[4:5]
	v_fma_f32 v46, |v48|, s40, 1.0
	v_fma_f32 v47, |v49|, s40, 1.0
	v_pk_mul_f32 v[4:5], v[6:7], v[4:5]
	v_rcp_f32_e32 v46, v46
	v_rcp_f32_e32 v47, v47
	v_pk_mul_f32 v[6:7], v[44:45], v[4:5]
	v_pk_fma_f32 v[4:5], v[44:45], v[4:5], v[44:45] neg_lo:[1,0,0] neg_hi:[1,0,0]
	v_lshlrev_b32_e32 v60, 16, v9
	v_cndmask_b32_e64 v43, v4, v6, s[0:1]
	v_cmp_gt_f32_e64 s[0:1], 0, v45
	v_and_b32_e32 v61, 0xffff0000, v9
	v_cndmask_b32_e64 v45, v5, v7, s[0:1]
	v_pk_mul_f32 v[6:7], v[48:49], v[48:49]
	v_pk_fma_f32 v[4:5], v[46:47], s[42:43], v[22:23] op_sel_hi:[1,0,0]
	v_pk_mul_f32 v[6:7], v[6:7], s[64:65] op_sel_hi:[1,0]
	v_pk_fma_f32 v[4:5], v[46:47], v[4:5], s[48:49] op_sel_hi:[1,1,0]
	v_exp_f32_e32 v6, v6
	v_exp_f32_e32 v7, v7
	v_pk_fma_f32 v[4:5], v[46:47], v[4:5], s[50:51] op_sel_hi:[1,1,0]
	v_pk_fma_f32 v[4:5], v[46:47], v[4:5], s[56:57] op_sel_hi:[1,1,0]
	v_fma_f32 v8, |v60|, s40, 1.0
	v_fma_f32 v9, |v61|, s40, 1.0
	v_pk_mul_f32 v[4:5], v[46:47], v[4:5]
	v_rcp_f32_e32 v62, v8
	v_pk_mul_f32 v[46:47], v[6:7], v[4:5]
	global_load_dwordx4 v[4:7], v[24:25], off offset:1536
	v_rcp_f32_e32 v63, v9
	v_pk_mul_f32 v[50:51], v[48:49], v[46:47]
	v_pk_fma_f32 v[52:53], v[48:49], v[46:47], v[48:49] neg_lo:[1,0,0] neg_hi:[1,0,0]
	v_cmp_gt_f32_e64 s[0:1], 0, v48
	v_lshlrev_b32_e32 v66, 16, v11
	v_and_b32_e32 v67, 0xffff0000, v11
	v_cndmask_b32_e64 v47, v52, v50, s[0:1]
	v_cmp_gt_f32_e64 s[0:1], 0, v49
	v_pk_fma_f32 v[48:49], v[62:63], s[42:43], v[22:23] op_sel_hi:[1,0,0]
	v_and_b32_e32 v11, 0x7fffffff, v67
	v_pk_fma_f32 v[48:49], v[62:63], v[48:49], s[48:49] op_sel_hi:[1,1,0]
	v_cndmask_b32_e64 v9, v53, v51, s[0:1]
	v_pk_mul_f32 v[50:51], v[60:61], v[60:61]
	v_pk_fma_f32 v[48:49], v[62:63], v[48:49], s[50:51] op_sel_hi:[1,1,0]
	v_pk_mul_f32 v[50:51], v[50:51], s[64:65] op_sel_hi:[1,0]
	v_pk_fma_f32 v[48:49], v[62:63], v[48:49], s[56:57] op_sel_hi:[1,1,0]
	v_exp_f32_e32 v50, v50
	v_exp_f32_e32 v51, v51
	v_pk_mul_f32 v[48:49], v[62:63], v[48:49]
	v_lshlrev_b32_e32 v62, 16, v10
	v_and_b32_e32 v63, 0xffff0000, v10
	v_fma_f32 v64, |v62|, s40, 1.0
	v_fma_f32 v65, |v63|, s40, 1.0
	v_pk_mul_f32 v[48:49], v[50:51], v[48:49]
	v_rcp_f32_e32 v64, v64
	v_rcp_f32_e32 v65, v65
	v_pk_mul_f32 v[50:51], v[60:61], v[48:49]
	v_pk_fma_f32 v[52:53], v[60:61], v[48:49], v[60:61] neg_lo:[1,0,0] neg_hi:[1,0,0]
	v_cmp_gt_f32_e64 s[0:1], 0, v60
	v_and_b32_e32 v10, 0x7fffffff, v66
	v_pk_fma_f32 v[10:11], v[10:11], s[40:41], 1.0 op_sel_hi:[1,0,0]
	v_cndmask_b32_e64 v49, v52, v50, s[0:1]
	v_cmp_gt_f32_e64 s[0:1], 0, v61
	v_pk_mul_f32 v[60:61], v[62:63], v[62:63]
	v_rcp_f32_e32 v68, v10
	v_cndmask_b32_e64 v51, v53, v51, s[0:1]
	v_pk_fma_f32 v[52:53], v[64:65], s[42:43], v[22:23] op_sel_hi:[1,0,0]
	v_pk_mul_f32 v[60:61], v[60:61], s[64:65] op_sel_hi:[1,0]
	v_pk_fma_f32 v[52:53], v[64:65], v[52:53], s[48:49] op_sel_hi:[1,1,0]
	v_exp_f32_e32 v60, v60
	v_exp_f32_e32 v61, v61
	v_pk_fma_f32 v[52:53], v[64:65], v[52:53], s[50:51] op_sel_hi:[1,1,0]
	v_rcp_f32_e32 v69, v11
	v_pk_fma_f32 v[52:53], v[64:65], v[52:53], s[56:57] op_sel_hi:[1,1,0]
	v_cmp_gt_f32_e64 s[0:1], 0, v62
	v_pk_mul_f32 v[52:53], v[64:65], v[52:53]
	v_mul_f32_e32 v32, v33, v33
	v_pk_mul_f32 v[52:53], v[60:61], v[52:53]
	v_mul_f32_e32 v34, v35, v35
	v_pk_mul_f32 v[60:61], v[62:63], v[52:53]
	v_pk_fma_f32 v[64:65], v[62:63], v[52:53], v[62:63] neg_lo:[1,0,0] neg_hi:[1,0,0]
	v_mul_f32_e32 v12, v13, v13
	v_cndmask_b32_e64 v53, v64, v60, s[0:1]
	v_cmp_gt_f32_e64 s[0:1], 0, v63
	v_pk_mul_f32 v[62:63], v[66:67], v[66:67]
	v_pk_add_f32 v[28:29], v[30:31], v[32:33]
	v_cndmask_b32_e64 v11, v65, v61, s[0:1]
	v_pk_fma_f32 v[60:61], v[68:69], s[42:43], v[22:23] op_sel_hi:[1,0,0]
	v_pk_mul_f32 v[62:63], v[62:63], s[64:65] op_sel_hi:[1,0]
	v_pk_fma_f32 v[60:61], v[68:69], v[60:61], s[48:49] op_sel_hi:[1,1,0]
	v_exp_f32_e32 v62, v62
	v_exp_f32_e32 v63, v63
	v_pk_fma_f32 v[60:61], v[68:69], v[60:61], s[50:51] op_sel_hi:[1,1,0]
	v_cmp_gt_f32_e64 s[0:1], 0, v66
	v_pk_fma_f32 v[60:61], v[68:69], v[60:61], s[56:57] op_sel_hi:[1,1,0]
	v_mul_f32_e32 v36, v37, v37
	v_pk_mul_f32 v[60:61], v[68:69], v[60:61]
	v_mul_f32_e32 v38, v39, v39
	v_pk_mul_f32 v[60:61], v[62:63], v[60:61]
	v_pk_add_f32 v[26:27], v[28:29], v[26:27]
	v_pk_mul_f32 v[64:65], v[66:67], v[60:61]
	v_pk_fma_f32 v[68:69], v[66:67], v[60:61], v[66:67] neg_lo:[1,0,0] neg_hi:[1,0,0]
	global_load_dwordx4 v[60:63], v[24:25], off offset:1792
	v_cndmask_b32_e64 v71, v68, v64, s[0:1]
	v_cmp_gt_f32_e64 s[0:1], 0, v67
	v_pk_add_f32 v[12:13], v[34:35], v[12:13]
	v_mul_f32_e32 v40, v41, v41
	v_cndmask_b32_e64 v65, v69, v65, s[0:1]
	s_waitcnt vmcnt(1)
	v_lshlrev_b32_e32 v24, 16, v4
	v_and_b32_e32 v25, 0xffff0000, v4
	v_fma_f32 v72, |v24|, s40, 1.0
	v_fma_f32 v73, |v25|, s40, 1.0
	v_pk_mul_f32 v[68:69], v[24:25], v[24:25]
	v_rcp_f32_e32 v72, v72
	v_rcp_f32_e32 v73, v73
	v_mul_f32_e32 v14, v15, v15
	v_pk_mul_f32 v[68:69], v[68:69], s[64:65] op_sel_hi:[1,0]
	v_pk_add_f32 v[12:13], v[12:13], v[26:27]
	v_pk_fma_f32 v[66:67], v[72:73], s[42:43], v[22:23] op_sel_hi:[1,0,0]
	v_pk_add_f32 v[26:27], v[36:37], v[38:39]
	v_mul_f32_e32 v42, v43, v43
	v_mul_f32_e32 v44, v45, v45
	v_pk_fma_f32 v[66:67], v[72:73], v[66:67], s[48:49] op_sel_hi:[1,1,0]
	v_exp_f32_e32 v68, v68
	v_exp_f32_e32 v69, v69
	v_pk_add_f32 v[12:13], v[26:27], v[12:13]
	v_pk_add_f32 v[14:15], v[40:41], v[14:15]
	v_mul_f32_e32 v46, v47, v47
	v_mul_f32_e32 v8, v9, v9
	v_pk_fma_f32 v[66:67], v[72:73], v[66:67], s[50:51] op_sel_hi:[1,1,0]
	v_pk_add_f32 v[12:13], v[14:15], v[12:13]
	v_pk_add_f32 v[14:15], v[42:43], v[44:45]
	v_mul_f32_e32 v48, v49, v49
	v_mul_f32_e32 v50, v51, v51
	v_pk_fma_f32 v[66:67], v[72:73], v[66:67], s[56:57] op_sel_hi:[1,1,0]
	v_pk_add_f32 v[12:13], v[14:15], v[12:13]
	v_pk_add_f32 v[8:9], v[46:47], v[8:9]
	v_pk_mul_f32 v[66:67], v[72:73], v[66:67]
	v_pk_add_f32 v[8:9], v[8:9], v[12:13]
	v_pk_add_f32 v[12:13], v[48:49], v[50:51]
	v_lshlrev_b32_e32 v4, 16, v5
	v_and_b32_e32 v5, 0xffff0000, v5
	v_pk_mul_f32 v[66:67], v[68:69], v[66:67]
	v_pk_add_f32 v[8:9], v[12:13], v[8:9]
	v_max_f32_e32 v93, 0, v24
	v_fma_f32 v12, |v4|, s40, 1.0
	v_fma_f32 v13, |v5|, s40, 1.0
	v_mul_f32_e32 v52, v53, v53
	v_mul_f32_e32 v10, v11, v11
	v_fma_f32 v73, -|v24|, v66, v93
	v_max_f32_e32 v94, 0, v25
	v_rcp_f32_e32 v12, v12
	v_rcp_f32_e32 v13, v13
	v_mul_f32_e32 v70, v71, v71
	v_mul_f32_e32 v64, v65, v65
	v_fma_f32 v25, -|v25|, v67, v94
	v_pk_add_f32 v[10:11], v[52:53], v[10:11]
	v_mul_f32_e32 v72, v73, v73
	v_mul_f32_e32 v24, v25, v25
	v_pk_add_f32 v[8:9], v[10:11], v[8:9]
	v_pk_add_f32 v[10:11], v[70:71], v[64:65]
	v_pk_mul_f32 v[14:15], v[4:5], v[4:5]
	v_pk_add_f32 v[8:9], v[10:11], v[8:9]
	v_pk_add_f32 v[10:11], v[72:73], v[24:25]
	v_pk_mul_f32 v[14:15], v[14:15], s[64:65] op_sel_hi:[1,0]
	v_pk_add_f32 v[8:9], v[10:11], v[8:9]
	v_pk_fma_f32 v[10:11], v[12:13], s[42:43], v[22:23] op_sel_hi:[1,0,0]
	v_exp_f32_e32 v14, v14
	v_pk_fma_f32 v[10:11], v[12:13], v[10:11], s[48:49] op_sel_hi:[1,1,0]
	v_exp_f32_e32 v15, v15
	v_pk_fma_f32 v[10:11], v[12:13], v[10:11], s[50:51] op_sel_hi:[1,1,0]
	v_cmp_gt_f32_e64 s[0:1], 0, v4
	v_pk_fma_f32 v[10:11], v[12:13], v[10:11], s[56:57] op_sel_hi:[1,1,0]
	s_waitcnt vmcnt(0)
	v_lshlrev_b32_e32 v28, 16, v60
	v_pk_mul_f32 v[10:11], v[12:13], v[10:11]
	v_and_b32_e32 v29, 0xffff0000, v60
	v_pk_mul_f32 v[10:11], v[14:15], v[10:11]
	v_and_b32_e32 v31, 0x7fffffff, v29
	v_pk_mul_f32 v[12:13], v[4:5], v[10:11]
	v_pk_fma_f32 v[10:11], v[4:5], v[10:11], v[4:5] neg_lo:[1,0,0] neg_hi:[1,0,0]
	v_and_b32_e32 v30, 0x7fffffff, v28
	v_cndmask_b32_e64 v15, v10, v12, s[0:1]
	v_cmp_gt_f32_e64 s[0:1], 0, v5
	v_lshlrev_b32_e32 v10, 16, v6
	v_and_b32_e32 v12, 0x7fffffff, v10
	v_cndmask_b32_e64 v5, v11, v13, s[0:1]
	v_and_b32_e32 v11, 0xffff0000, v6
	v_and_b32_e32 v13, 0x7fffffff, v11
	v_pk_fma_f32 v[12:13], v[12:13], s[40:41], 1.0 op_sel_hi:[1,0,0]
	v_mul_f32_e32 v14, v15, v15
	v_rcp_f32_e32 v12, v12
	v_rcp_f32_e32 v13, v13
	v_mul_f32_e32 v4, v5, v5
	v_pk_mul_f32 v[24:25], v[10:11], v[10:11]
	v_pk_add_f32 v[4:5], v[14:15], v[4:5]
	v_pk_fma_f32 v[14:15], v[12:13], s[42:43], v[22:23] op_sel_hi:[1,0,0]
	v_pk_mul_f32 v[24:25], v[24:25], s[64:65] op_sel_hi:[1,0]
	v_pk_fma_f32 v[14:15], v[12:13], v[14:15], s[48:49] op_sel_hi:[1,1,0]
	v_exp_f32_e32 v24, v24
	v_exp_f32_e32 v25, v25
	v_pk_fma_f32 v[14:15], v[12:13], v[14:15], s[50:51] op_sel_hi:[1,1,0]
	v_lshlrev_b32_e32 v6, 16, v7
	v_and_b32_e32 v7, 0xffff0000, v7
	v_pk_fma_f32 v[14:15], v[12:13], v[14:15], s[56:57] op_sel_hi:[1,1,0]
	v_pk_mul_f32 v[12:13], v[12:13], v[14:15]
	v_fma_f32 v26, |v6|, s40, 1.0
	v_fma_f32 v27, |v7|, s40, 1.0
	v_pk_mul_f32 v[12:13], v[24:25], v[12:13]
	v_rcp_f32_e32 v26, v26
	v_rcp_f32_e32 v27, v27
	v_max_f32_e32 v95, 0, v10
	v_pk_fma_f32 v[30:31], v[30:31], s[40:41], 1.0 op_sel_hi:[1,0,0]
	v_lshlrev_b32_e32 v32, 16, v61
	v_fma_f32 v25, -|v10|, v12, v95
	v_max_f32_e32 v96, 0, v11
	v_rcp_f32_e32 v30, v30
	v_rcp_f32_e32 v31, v31
	v_fma_f32 v11, -|v11|, v13, v96
	v_pk_mul_f32 v[14:15], v[6:7], v[6:7]
	v_pk_fma_f32 v[12:13], v[26:27], s[42:43], v[22:23] op_sel_hi:[1,0,0]
	v_pk_mul_f32 v[14:15], v[14:15], s[64:65] op_sel_hi:[1,0]
	v_pk_fma_f32 v[12:13], v[26:27], v[12:13], s[48:49] op_sel_hi:[1,1,0]
	v_exp_f32_e32 v14, v14
	v_exp_f32_e32 v15, v15
	v_pk_fma_f32 v[12:13], v[26:27], v[12:13], s[50:51] op_sel_hi:[1,1,0]
	v_cmp_gt_f32_e64 s[0:1], 0, v6
	v_pk_fma_f32 v[12:13], v[26:27], v[12:13], s[56:57] op_sel_hi:[1,1,0]
	v_and_b32_e32 v33, 0xffff0000, v61
	v_pk_mul_f32 v[12:13], v[26:27], v[12:13]
	v_pk_mul_f32 v[12:13], v[14:15], v[12:13]
	v_pk_mul_f32 v[14:15], v[6:7], v[12:13]
	v_pk_fma_f32 v[12:13], v[6:7], v[12:13], v[6:7] neg_lo:[1,0,0] neg_hi:[1,0,0]
	v_fma_f32 v34, |v32|, s40, 1.0
	v_fma_f32 v35, |v33|, s40, 1.0
	v_cndmask_b32_e64 v27, v12, v14, s[0:1]
	v_cmp_gt_f32_e64 s[0:1], 0, v7
	v_rcp_f32_e32 v34, v34
	v_rcp_f32_e32 v35, v35
	v_cndmask_b32_e64 v7, v13, v15, s[0:1]
	v_pk_mul_f32 v[14:15], v[28:29], v[28:29]
	v_pk_fma_f32 v[12:13], v[30:31], s[42:43], v[22:23] op_sel_hi:[1,0,0]
	v_pk_mul_f32 v[14:15], v[14:15], s[64:65] op_sel_hi:[1,0]
	v_pk_fma_f32 v[12:13], v[30:31], v[12:13], s[48:49] op_sel_hi:[1,1,0]
	v_exp_f32_e32 v14, v14
	v_exp_f32_e32 v15, v15
	v_pk_fma_f32 v[12:13], v[30:31], v[12:13], s[50:51] op_sel_hi:[1,1,0]
	v_cmp_gt_f32_e64 s[0:1], 0, v28
	v_pk_fma_f32 v[12:13], v[30:31], v[12:13], s[56:57] op_sel_hi:[1,1,0]
	v_lshlrev_b32_e32 v36, 16, v62
	v_pk_mul_f32 v[12:13], v[30:31], v[12:13]
	v_and_b32_e32 v37, 0xffff0000, v62
	v_pk_mul_f32 v[12:13], v[14:15], v[12:13]
	v_pk_mul_f32 v[14:15], v[28:29], v[12:13]
	v_pk_fma_f32 v[12:13], v[28:29], v[12:13], v[28:29] neg_lo:[1,0,0] neg_hi:[1,0,0]
	v_cndmask_b32_e64 v31, v12, v14, s[0:1]
	v_cmp_gt_f32_e64 s[0:1], 0, v29
	v_pk_mul_f32 v[28:29], v[32:33], v[32:33]
	v_fma_f32 v38, |v36|, s40, 1.0
	v_fma_f32 v39, |v37|, s40, 1.0
	v_cndmask_b32_e64 v13, v13, v15, s[0:1]
	v_pk_fma_f32 v[14:15], v[34:35], s[42:43], v[22:23] op_sel_hi:[1,0,0]
	v_pk_mul_f32 v[28:29], v[28:29], s[64:65] op_sel_hi:[1,0]
	v_pk_fma_f32 v[14:15], v[34:35], v[14:15], s[48:49] op_sel_hi:[1,1,0]
	v_exp_f32_e32 v28, v28
	v_exp_f32_e32 v29, v29
	v_pk_fma_f32 v[14:15], v[34:35], v[14:15], s[50:51] op_sel_hi:[1,1,0]
	v_rcp_f32_e32 v38, v38
	v_pk_fma_f32 v[14:15], v[34:35], v[14:15], s[56:57] op_sel_hi:[1,1,0]
	v_rcp_f32_e32 v39, v39
	v_pk_mul_f32 v[14:15], v[34:35], v[14:15]
	v_cmp_gt_f32_e64 s[0:1], 0, v32
	v_pk_mul_f32 v[14:15], v[28:29], v[14:15]
	v_lshlrev_b32_e32 v40, 16, v63
	v_pk_mul_f32 v[28:29], v[32:33], v[14:15]
	v_pk_fma_f32 v[14:15], v[32:33], v[14:15], v[32:33] neg_lo:[1,0,0] neg_hi:[1,0,0]
	v_and_b32_e32 v41, 0xffff0000, v63
	v_cndmask_b32_e64 v35, v14, v28, s[0:1]
	v_cmp_gt_f32_e64 s[0:1], 0, v33
	v_pk_mul_f32 v[32:33], v[36:37], v[36:37]
	v_cndmask_b32_e64 v15, v15, v29, s[0:1]
	v_pk_fma_f32 v[28:29], v[38:39], s[42:43], v[22:23] op_sel_hi:[1,0,0]
	v_pk_mul_f32 v[32:33], v[32:33], s[64:65] op_sel_hi:[1,0]
	v_pk_fma_f32 v[28:29], v[38:39], v[28:29], s[48:49] op_sel_hi:[1,1,0]
	v_exp_f32_e32 v32, v32
	v_exp_f32_e32 v33, v33
	v_pk_fma_f32 v[28:29], v[38:39], v[28:29], s[50:51] op_sel_hi:[1,1,0]
	v_pk_fma_f32 v[28:29], v[38:39], v[28:29], s[56:57] op_sel_hi:[1,1,0]
	v_fma_f32 v42, |v40|, s40, 1.0
	v_fma_f32 v43, |v41|, s40, 1.0
	v_pk_mul_f32 v[28:29], v[38:39], v[28:29]
	v_rcp_f32_e32 v42, v42
	v_pk_mul_f32 v[28:29], v[32:33], v[28:29]
	v_rcp_f32_e32 v43, v43
	v_max_f32_e32 v97, 0, v36
	v_pk_fma_f32 v[22:23], v[42:43], s[42:43], v[22:23] op_sel_hi:[1,0,0]
	v_mul_f32_e32 v24, v25, v25
	v_fma_f32 v39, -|v36|, v28, v97
	v_max_f32_e32 v98, 0, v37
	v_pk_fma_f32 v[22:23], v[42:43], v[22:23], s[48:49] op_sel_hi:[1,1,0]
	v_mul_f32_e32 v10, v11, v11
	v_fma_f32 v29, -|v37|, v29, v98
	v_pk_mul_f32 v[32:33], v[40:41], v[40:41]
	v_pk_fma_f32 v[22:23], v[42:43], v[22:23], s[50:51] op_sel_hi:[1,1,0]
	v_pk_mul_f32 v[32:33], v[32:33], s[64:65] op_sel_hi:[1,0]
	v_pk_fma_f32 v[22:23], v[42:43], v[22:23], s[56:57] op_sel_hi:[1,1,0]
	v_exp_f32_e32 v32, v32
	v_exp_f32_e32 v33, v33
	v_pk_mul_f32 v[22:23], v[42:43], v[22:23]
	v_mul_f32_e32 v26, v27, v27
	v_mul_f32_e32 v6, v7, v7
	v_pk_mul_f32 v[22:23], v[32:33], v[22:23]
	v_pk_add_f32 v[4:5], v[4:5], v[8:9]
	v_pk_add_f32 v[8:9], v[24:25], v[10:11]
	v_mul_f32_e32 v30, v31, v31
	v_mul_f32_e32 v12, v13, v13
	v_max_f32_e32 v99, 0, v40
	v_pk_add_f32 v[4:5], v[8:9], v[4:5]
	v_pk_add_f32 v[6:7], v[26:27], v[6:7]
	v_mul_f32_e32 v34, v35, v35
	v_mul_f32_e32 v14, v15, v15
	v_fma_f32 v37, -|v40|, v22, v99
	v_max_f32_e32 v100, 0, v41
	v_pk_add_f32 v[4:5], v[6:7], v[4:5]
	v_pk_add_f32 v[6:7], v[30:31], v[12:13]
	v_mul_f32_e32 v38, v39, v39
	v_mul_f32_e32 v28, v29, v29
	v_fma_f32 v23, -|v41|, v23, v100
	v_pk_add_f32 v[4:5], v[6:7], v[4:5]
	v_pk_add_f32 v[6:7], v[34:35], v[14:15]
	v_mul_f32_e32 v36, v37, v37
	v_mul_f32_e32 v22, v23, v23
	v_pk_add_f32 v[4:5], v[6:7], v[4:5]
	v_pk_add_f32 v[6:7], v[38:39], v[28:29]
	s_nop 0
	v_pk_add_f32 v[4:5], v[6:7], v[4:5]
	v_pk_add_f32 v[6:7], v[36:37], v[22:23]
	s_nop 0
	v_pk_add_f32 v[4:5], v[6:7], v[4:5]
	ds_bpermute_b32 v7, v56, v5
	ds_bpermute_b32 v6, v56, v4
	s_waitcnt lgkmcnt(0)
	v_pk_add_f32 v[4:5], v[4:5], v[6:7]
	ds_bpermute_b32 v7, v57, v5
	ds_bpermute_b32 v6, v57, v4
	s_waitcnt lgkmcnt(0)
	v_pk_add_f32 v[4:5], v[4:5], v[6:7]
	ds_bpermute_b32 v7, v58, v5
	ds_bpermute_b32 v6, v58, v4
	s_waitcnt lgkmcnt(0)
	v_pk_add_f32 v[4:5], v[4:5], v[6:7]
	ds_bpermute_b32 v7, v59, v5
	ds_bpermute_b32 v6, v59, v4
	s_and_saveexec_b64 s[8:9], vcc
	s_cbranch_execz .LBB0_449
	s_waitcnt lgkmcnt(0)
	v_pk_add_f32 v[4:5], v[4:5], v[6:7]
	s_nop 0
	v_pk_mul_f32 v[4:5], v[4:5], s[66:67] op_sel_hi:[1,0]
	s_nop 0
	v_fma_f32 v4, -v5, v5, v4
	v_max_f32_e32 v4, 0, v4
	v_add_f32_e32 v4, 0x358637bd, v4
	v_mul_f32_e32 v6, 0x4b800000, v4
	v_cmp_gt_f32_e64 s[0:1], s36, v4
	s_nop 1
	v_cndmask_b32_e64 v4, v4, v6, s[0:1]
	v_rsq_f32_e32 v4, v4
	v_lshl_add_u32 v6, v20, 2, 0
	v_add_u32_e32 v7, 0x11000, v6
	ds_write_b32 v7, v5
	v_mul_f32_e32 v5, 0x45800000, v4
	v_cndmask_b32_e64 v4, v4, v5, s[0:1]
	v_add_u32_e32 v5, 0x11200, v6
	ds_write_b32 v5, v4
.LBB0_449:
	s_or_b64 exec, exec, s[8:9]
	v_or_b32_e32 v16, 12, v16
	v_ashrrev_i32_e32 v17, 31, v16
	v_lshl_add_u64 v[4:5], s[6:7], 0, v[16:17]
	v_lshlrev_b64 v[4:5], 11, v[4:5]
	v_lshl_add_u64 v[4:5], s[4:5], 0, v[4:5]
	v_mov_b32_e32 v19, v2
	v_lshl_add_u64 v[20:21], v[4:5], 0, v[18:19]
	global_load_dwordx4 v[8:11], v[20:21], off
	s_waitcnt lgkmcnt(0)
	global_load_dwordx4 v[4:7], v[20:21], off offset:256
	v_mov_b64_e32 v[18:19], s[44:45]
	v_mov_b32_e32 v13, v2
	s_waitcnt vmcnt(1)
	v_lshlrev_b32_e32 v24, 16, v10
	v_and_b32_e32 v25, 0xffff0000, v10
	v_and_b32_e32 v15, 0xffff0000, v8
	v_and_b32_e32 v23, 0xffff0000, v9
	v_lshlrev_b32_e32 v22, 16, v9
	v_lshlrev_b32_e32 v14, 16, v8
	v_lshlrev_b32_e32 v8, 16, v11
	v_and_b32_e32 v9, 0xffff0000, v11
	v_fma_f32 v10, |v24|, s40, 1.0
	v_fma_f32 v11, |v25|, s40, 1.0
	v_fma_f32 v28, |v14|, s40, 1.0
	v_fma_f32 v29, |v15|, s40, 1.0
	v_rcp_f32_e32 v10, v10
	v_rcp_f32_e32 v11, v11
	v_fma_f32 v32, |v22|, s40, 1.0
	v_fma_f32 v33, |v23|, s40, 1.0
	v_rcp_f32_e32 v28, v28
	v_rcp_f32_e32 v29, v29
	v_rcp_f32_e32 v32, v32
	v_rcp_f32_e32 v33, v33
	v_pk_mul_f32 v[26:27], v[24:25], v[24:25]
	v_pk_mul_f32 v[30:31], v[14:15], v[14:15]
	v_pk_mul_f32 v[26:27], v[26:27], s[64:65] op_sel_hi:[1,0]
	v_pk_fma_f32 v[40:41], v[10:11], s[42:43], v[18:19] op_sel_hi:[1,0,0]
	v_pk_mul_f32 v[34:35], v[22:23], v[22:23]
	v_pk_mul_f32 v[30:31], v[30:31], s[64:65] op_sel_hi:[1,0]
	v_exp_f32_e32 v26, v26
	v_exp_f32_e32 v27, v27
	v_pk_fma_f32 v[42:43], v[28:29], s[42:43], v[18:19] op_sel_hi:[1,0,0]
	v_pk_fma_f32 v[40:41], v[10:11], v[40:41], s[48:49] op_sel_hi:[1,1,0]
	v_pk_mul_f32 v[34:35], v[34:35], s[64:65] op_sel_hi:[1,0]
	v_exp_f32_e32 v30, v30
	v_exp_f32_e32 v31, v31
	v_pk_fma_f32 v[44:45], v[32:33], s[42:43], v[18:19] op_sel_hi:[1,0,0]
	v_pk_fma_f32 v[42:43], v[28:29], v[42:43], s[48:49] op_sel_hi:[1,1,0]
	v_pk_fma_f32 v[40:41], v[10:11], v[40:41], s[50:51] op_sel_hi:[1,1,0]
	v_exp_f32_e32 v34, v34
	v_exp_f32_e32 v35, v35
	v_pk_fma_f32 v[44:45], v[32:33], v[44:45], s[48:49] op_sel_hi:[1,1,0]
	v_pk_fma_f32 v[42:43], v[28:29], v[42:43], s[50:51] op_sel_hi:[1,1,0]
	v_pk_fma_f32 v[40:41], v[10:11], v[40:41], s[56:57] op_sel_hi:[1,1,0]
	v_pk_fma_f32 v[44:45], v[32:33], v[44:45], s[50:51] op_sel_hi:[1,1,0]
	v_pk_fma_f32 v[42:43], v[28:29], v[42:43], s[56:57] op_sel_hi:[1,1,0]
	v_pk_mul_f32 v[10:11], v[10:11], v[40:41]
	v_pk_fma_f32 v[44:45], v[32:33], v[44:45], s[56:57] op_sel_hi:[1,1,0]
	v_pk_mul_f32 v[28:29], v[28:29], v[42:43]
	v_pk_mul_f32 v[10:11], v[26:27], v[10:11]
	v_pk_mul_f32 v[32:33], v[32:33], v[44:45]
	v_pk_mul_f32 v[26:27], v[30:31], v[28:29]
	v_max_f32_e32 v104, 0, v24
	v_pk_mul_f32 v[28:29], v[34:35], v[32:33]
	v_fma_f32 v41, -|v24|, v10, v104
	v_max_f32_e32 v105, 0, v25
	v_fma_f32 v11, -|v25|, v11, v105
	v_max_f32_e32 v106, 0, v22
	v_pk_mul_f32 v[32:33], v[26:27], v[14:15]
	v_pk_fma_f32 v[26:27], v[26:27], v[14:15], v[14:15] neg_lo:[1,0,0] neg_hi:[1,0,0]
	v_fma_f32 v25, -|v22|, v28, v106
	v_cmp_gt_f32_e64 s[0:1], 0, v14
	v_fma_f32 v36, |v8|, s40, 1.0
	v_fma_f32 v37, |v9|, s40, 1.0
	v_mov_b32_e32 v14, v25
	v_cndmask_b32_e64 v24, v26, v32, s[0:1]
	v_cmp_gt_f32_e64 s[0:1], 0, v15
	v_rcp_f32_e32 v36, v36
	v_rcp_f32_e32 v37, v37
	v_cndmask_b32_e64 v15, v27, v33, s[0:1]
	v_max_f32_e32 v107, 0, v23
	v_mul_f32_e32 v26, v24, v24
	v_mov_b32_e32 v27, v25
	v_fma_f32 v23, -|v23|, v29, v107
	v_mul_f32_e32 v22, v15, v15
	v_mul_f32_e32 v12, v23, v23
	v_pk_add_f32 v[22:23], v[26:27], v[22:23]
	v_pk_mul_f32 v[26:27], v[24:25], v[14:15] op_sel:[1,0] op_sel_hi:[0,1]
	v_pk_add_f32 v[14:15], v[24:25], v[14:15] op_sel:[1,0] op_sel_hi:[0,1]
	v_pk_mul_f32 v[38:39], v[8:9], v[8:9]
	v_mov_b32_e32 v27, v15
	v_pk_mul_f32 v[38:39], v[38:39], s[64:65] op_sel_hi:[1,0]
	v_pk_fma_f32 v[46:47], v[36:37], s[42:43], v[18:19] op_sel_hi:[1,0,0]
	v_mul_f32_e32 v40, v41, v41
	v_mul_f32_e32 v10, v11, v11
	v_pk_add_f32 v[12:13], v[26:27], v[12:13]
	v_exp_f32_e32 v38, v38
	v_pk_fma_f32 v[46:47], v[36:37], v[46:47], s[48:49] op_sel_hi:[1,1,0]
	v_pk_add_f32 v[10:11], v[40:41], v[10:11]
	v_pk_add_f32 v[12:13], v[22:23], v[12:13]
	v_exp_f32_e32 v39, v39
	v_pk_add_f32 v[22:23], v[10:11], v[12:13]
	v_pk_fma_f32 v[10:11], v[36:37], v[46:47], s[50:51] op_sel_hi:[1,1,0]
	v_cmp_gt_f32_e64 s[0:1], 0, v8
	v_pk_fma_f32 v[10:11], v[36:37], v[10:11], s[56:57] op_sel_hi:[1,1,0]
	s_nop 0
	v_pk_mul_f32 v[10:11], v[36:37], v[10:11]
	s_waitcnt vmcnt(0)
	v_lshlrev_b32_e32 v36, 16, v6
	v_pk_mul_f32 v[10:11], v[38:39], v[10:11]
	v_and_b32_e32 v37, 0xffff0000, v6
	v_pk_mul_f32 v[12:13], v[8:9], v[10:11]
	v_pk_fma_f32 v[10:11], v[8:9], v[10:11], v[8:9] neg_lo:[1,0,0] neg_hi:[1,0,0]
	v_and_b32_e32 v33, 0x7fffffff, v37
	v_cndmask_b32_e64 v15, v10, v12, s[0:1]
	v_cmp_gt_f32_e64 s[0:1], 0, v9
	v_lshlrev_b32_e32 v12, 16, v4
	v_and_b32_e32 v10, 0x7fffffff, v12
	v_cndmask_b32_e64 v9, v11, v13, s[0:1]
	v_and_b32_e32 v13, 0xffff0000, v4
	v_and_b32_e32 v11, 0x7fffffff, v13
	v_pk_fma_f32 v[10:11], v[10:11], s[40:41], 1.0 op_sel_hi:[1,0,0]
	v_mul_f32_e32 v14, v15, v15
	v_rcp_f32_e32 v10, v10
	v_rcp_f32_e32 v11, v11
	v_mul_f32_e32 v8, v9, v9
	v_pk_add_f32 v[24:25], v[14:15], v[8:9]
	v_pk_mul_f32 v[14:15], v[12:13], v[12:13]
	v_pk_fma_f32 v[8:9], v[10:11], s[42:43], v[18:19] op_sel_hi:[1,0,0]
	v_pk_mul_f32 v[14:15], v[14:15], s[64:65] op_sel_hi:[1,0]
	v_pk_fma_f32 v[8:9], v[10:11], v[8:9], s[48:49] op_sel_hi:[1,1,0]
	v_exp_f32_e32 v14, v14
	v_exp_f32_e32 v15, v15
	v_pk_fma_f32 v[8:9], v[10:11], v[8:9], s[50:51] op_sel_hi:[1,1,0]
	v_lshlrev_b32_e32 v4, 16, v5
	v_pk_fma_f32 v[8:9], v[10:11], v[8:9], s[56:57] op_sel_hi:[1,1,0]
	v_and_b32_e32 v5, 0xffff0000, v5
	v_pk_mul_f32 v[8:9], v[10:11], v[8:9]
	v_pk_mul_f32 v[14:15], v[14:15], v[8:9]
	global_load_dwordx4 v[8:11], v[20:21], off offset:512
	v_fma_f32 v30, |v4|, s40, 1.0
	v_fma_f32 v31, |v5|, s40, 1.0
	v_pk_mul_f32 v[28:29], v[12:13], v[14:15]
	v_rcp_f32_e32 v30, v30
	v_rcp_f32_e32 v31, v31
	v_pk_fma_f32 v[14:15], v[12:13], v[14:15], v[12:13] neg_lo:[1,0,0] neg_hi:[1,0,0]
	v_cmp_gt_f32_e64 s[0:1], 0, v12
	v_and_b32_e32 v32, 0x7fffffff, v36
	v_pk_fma_f32 v[32:33], v[32:33], s[40:41], 1.0 op_sel_hi:[1,0,0]
	v_cndmask_b32_e64 v27, v14, v28, s[0:1]
	v_cmp_gt_f32_e64 s[0:1], 0, v13
	v_pk_fma_f32 v[12:13], v[30:31], s[42:43], v[18:19] op_sel_hi:[1,0,0]
	v_rcp_f32_e32 v34, v32
	v_cndmask_b32_e64 v29, v15, v29, s[0:1]
	v_pk_mul_f32 v[14:15], v[4:5], v[4:5]
	v_pk_fma_f32 v[12:13], v[30:31], v[12:13], s[48:49] op_sel_hi:[1,1,0]
	v_pk_mul_f32 v[14:15], v[14:15], s[64:65] op_sel_hi:[1,0]
	v_pk_fma_f32 v[12:13], v[30:31], v[12:13], s[50:51] op_sel_hi:[1,1,0]
	v_exp_f32_e32 v14, v14
	v_exp_f32_e32 v15, v15
	v_pk_fma_f32 v[12:13], v[30:31], v[12:13], s[56:57] op_sel_hi:[1,1,0]
	v_rcp_f32_e32 v35, v33
	v_pk_mul_f32 v[12:13], v[30:31], v[12:13]
	v_cmp_gt_f32_e64 s[0:1], 0, v4
	v_pk_mul_f32 v[12:13], v[14:15], v[12:13]
	v_mul_f32_e32 v26, v27, v27
	v_pk_mul_f32 v[14:15], v[4:5], v[12:13]
	v_pk_fma_f32 v[12:13], v[4:5], v[12:13], v[4:5] neg_lo:[1,0,0] neg_hi:[1,0,0]
	v_mul_f32_e32 v28, v29, v29
	v_cndmask_b32_e64 v31, v12, v14, s[0:1]
	v_cmp_gt_f32_e64 s[0:1], 0, v5
	v_pk_fma_f32 v[4:5], v[34:35], s[42:43], v[18:19] op_sel_hi:[1,0,0]
	v_lshlrev_b32_e32 v14, 16, v7
	v_cndmask_b32_e64 v33, v13, v15, s[0:1]
	v_pk_mul_f32 v[12:13], v[36:37], v[36:37]
	v_pk_fma_f32 v[4:5], v[34:35], v[4:5], s[48:49] op_sel_hi:[1,1,0]
	v_pk_mul_f32 v[12:13], v[12:13], s[64:65] op_sel_hi:[1,0]
	v_pk_fma_f32 v[4:5], v[34:35], v[4:5], s[50:51] op_sel_hi:[1,1,0]
	v_exp_f32_e32 v12, v12
	v_exp_f32_e32 v13, v13
	v_and_b32_e32 v15, 0xffff0000, v7
	v_pk_fma_f32 v[4:5], v[34:35], v[4:5], s[56:57] op_sel_hi:[1,1,0]
	v_pk_mul_f32 v[4:5], v[34:35], v[4:5]
	v_fma_f32 v6, |v14|, s40, 1.0
	v_fma_f32 v7, |v15|, s40, 1.0
	v_pk_mul_f32 v[4:5], v[12:13], v[4:5]
	v_rcp_f32_e32 v6, v6
	v_rcp_f32_e32 v7, v7
	v_max_f32_e32 v108, 0, v36
	v_mul_f32_e32 v30, v31, v31
	v_mul_f32_e32 v32, v33, v33
	v_fma_f32 v35, -|v36|, v4, v108
	v_max_f32_e32 v109, 0, v37
	v_pk_add_f32 v[22:23], v[24:25], v[22:23]
	v_pk_add_f32 v[24:25], v[26:27], v[28:29]
	v_fma_f32 v37, -|v37|, v5, v109
	v_pk_mul_f32 v[12:13], v[14:15], v[14:15]
	v_pk_fma_f32 v[4:5], v[6:7], s[42:43], v[18:19] op_sel_hi:[1,0,0]
	v_pk_mul_f32 v[12:13], v[12:13], s[64:65] op_sel_hi:[1,0]
	v_pk_fma_f32 v[4:5], v[6:7], v[4:5], s[48:49] op_sel_hi:[1,1,0]
	v_exp_f32_e32 v12, v12
	v_exp_f32_e32 v13, v13
	v_pk_fma_f32 v[4:5], v[6:7], v[4:5], s[50:51] op_sel_hi:[1,1,0]
	v_cmp_gt_f32_e64 s[0:1], 0, v14
	v_pk_fma_f32 v[4:5], v[6:7], v[4:5], s[56:57] op_sel_hi:[1,1,0]
	v_mul_f32_e32 v34, v35, v35
	v_pk_mul_f32 v[4:5], v[6:7], v[4:5]
	v_mul_f32_e32 v36, v37, v37
	v_pk_mul_f32 v[4:5], v[12:13], v[4:5]
	v_pk_add_f32 v[22:23], v[24:25], v[22:23]
	v_pk_mul_f32 v[12:13], v[14:15], v[4:5]
	v_pk_fma_f32 v[40:41], v[14:15], v[4:5], v[14:15] neg_lo:[1,0,0] neg_hi:[1,0,0]
	global_load_dwordx4 v[4:7], v[20:21], off offset:768
	v_cndmask_b32_e64 v39, v40, v12, s[0:1]
	v_cmp_gt_f32_e64 s[0:1], 0, v15
	v_pk_add_f32 v[24:25], v[30:31], v[32:33]
	s_waitcnt vmcnt(1)
	v_lshlrev_b32_e32 v44, 16, v8
	v_and_b32_e32 v45, 0xffff0000, v8
	v_fma_f32 v42, |v44|, s40, 1.0
	v_fma_f32 v43, |v45|, s40, 1.0
	v_pk_mul_f32 v[14:15], v[44:45], v[44:45]
	v_rcp_f32_e32 v42, v42
	v_rcp_f32_e32 v43, v43
	v_cndmask_b32_e64 v41, v41, v13, s[0:1]
	v_pk_mul_f32 v[14:15], v[14:15], s[64:65] op_sel_hi:[1,0]
	v_lshlrev_b32_e32 v46, 16, v9
	v_pk_fma_f32 v[12:13], v[42:43], s[42:43], v[18:19] op_sel_hi:[1,0,0]
	v_exp_f32_e32 v14, v14
	v_pk_fma_f32 v[12:13], v[42:43], v[12:13], s[48:49] op_sel_hi:[1,1,0]
	v_exp_f32_e32 v15, v15
	v_and_b32_e32 v47, 0xffff0000, v9
	v_pk_fma_f32 v[12:13], v[42:43], v[12:13], s[50:51] op_sel_hi:[1,1,0]
	v_pk_fma_f32 v[12:13], v[42:43], v[12:13], s[56:57] op_sel_hi:[1,1,0]
	v_fma_f32 v8, |v46|, s40, 1.0
	v_fma_f32 v9, |v47|, s40, 1.0
	v_pk_mul_f32 v[12:13], v[42:43], v[12:13]
	v_rcp_f32_e32 v48, v8
	v_rcp_f32_e32 v49, v9
	v_pk_mul_f32 v[12:13], v[14:15], v[12:13]
	v_cmp_gt_f32_e64 s[0:1], 0, v44
	v_pk_mul_f32 v[14:15], v[44:45], v[12:13]
	v_pk_fma_f32 v[12:13], v[44:45], v[12:13], v[44:45] neg_lo:[1,0,0] neg_hi:[1,0,0]
	v_lshlrev_b32_e32 v50, 16, v10
	v_cndmask_b32_e64 v43, v12, v14, s[0:1]
	v_cmp_gt_f32_e64 s[0:1], 0, v45
	v_and_b32_e32 v51, 0xffff0000, v10
	v_lshlrev_b32_e32 v10, 16, v11
	v_cndmask_b32_e64 v9, v13, v15, s[0:1]
	v_pk_fma_f32 v[12:13], v[48:49], s[42:43], v[18:19] op_sel_hi:[1,0,0]
	v_pk_mul_f32 v[14:15], v[46:47], v[46:47]
	v_pk_fma_f32 v[12:13], v[48:49], v[12:13], s[48:49] op_sel_hi:[1,1,0]
	v_pk_mul_f32 v[14:15], v[14:15], s[64:65] op_sel_hi:[1,0]
	v_pk_fma_f32 v[12:13], v[48:49], v[12:13], s[50:51] op_sel_hi:[1,1,0]
	v_exp_f32_e32 v14, v14
	v_exp_f32_e32 v15, v15
	v_pk_fma_f32 v[12:13], v[48:49], v[12:13], s[56:57] op_sel_hi:[1,1,0]
	v_cmp_gt_f32_e64 s[0:1], 0, v46
	v_pk_mul_f32 v[12:13], v[48:49], v[12:13]
	v_fma_f32 v48, |v50|, s40, 1.0
	v_fma_f32 v49, |v51|, s40, 1.0
	v_pk_mul_f32 v[12:13], v[14:15], v[12:13]
	v_rcp_f32_e32 v48, v48
	v_rcp_f32_e32 v49, v49
	v_pk_mul_f32 v[14:15], v[46:47], v[12:13]
	v_pk_fma_f32 v[12:13], v[46:47], v[12:13], v[46:47] neg_lo:[1,0,0] neg_hi:[1,0,0]
	v_and_b32_e32 v11, 0xffff0000, v11
	v_cndmask_b32_e64 v45, v12, v14, s[0:1]
	v_cmp_gt_f32_e64 s[0:1], 0, v47
	v_cndmask_b32_e64 v47, v13, v15, s[0:1]
	v_pk_mul_f32 v[14:15], v[50:51], v[50:51]
	v_pk_fma_f32 v[12:13], v[48:49], s[42:43], v[18:19] op_sel_hi:[1,0,0]
	v_pk_mul_f32 v[14:15], v[14:15], s[64:65] op_sel_hi:[1,0]
	v_pk_fma_f32 v[12:13], v[48:49], v[12:13], s[48:49] op_sel_hi:[1,1,0]
	v_exp_f32_e32 v14, v14
	v_exp_f32_e32 v15, v15
	v_pk_fma_f32 v[12:13], v[48:49], v[12:13], s[50:51] op_sel_hi:[1,1,0]
	v_fma_f32 v52, |v10|, s40, 1.0
	v_fma_f32 v53, |v11|, s40, 1.0
	v_pk_fma_f32 v[12:13], v[48:49], v[12:13], s[56:57] op_sel_hi:[1,1,0]
	v_rcp_f32_e32 v52, v52
	v_pk_mul_f32 v[12:13], v[48:49], v[12:13]
	v_rcp_f32_e32 v53, v53
	v_pk_mul_f32 v[12:13], v[14:15], v[12:13]
	v_cmp_gt_f32_e64 s[0:1], 0, v50
	v_pk_mul_f32 v[14:15], v[50:51], v[12:13]
	v_pk_fma_f32 v[12:13], v[50:51], v[12:13], v[50:51] neg_lo:[1,0,0] neg_hi:[1,0,0]
	v_mul_f32_e32 v38, v39, v39
	v_cndmask_b32_e64 v49, v12, v14, s[0:1]
	v_cmp_gt_f32_e64 s[0:1], 0, v51
	s_waitcnt vmcnt(0)
	v_lshlrev_b32_e32 v60, 16, v4
	v_and_b32_e32 v61, 0xffff0000, v4
	v_cndmask_b32_e64 v51, v13, v15, s[0:1]
	v_pk_mul_f32 v[14:15], v[10:11], v[10:11]
	v_pk_fma_f32 v[12:13], v[52:53], s[42:43], v[18:19] op_sel_hi:[1,0,0]
	v_pk_mul_f32 v[14:15], v[14:15], s[64:65] op_sel_hi:[1,0]
	v_pk_fma_f32 v[12:13], v[52:53], v[12:13], s[48:49] op_sel_hi:[1,1,0]
	v_exp_f32_e32 v14, v14
	v_exp_f32_e32 v15, v15
	v_pk_fma_f32 v[12:13], v[52:53], v[12:13], s[50:51] op_sel_hi:[1,1,0]
	v_pk_fma_f32 v[12:13], v[52:53], v[12:13], s[56:57] op_sel_hi:[1,1,0]
	v_pk_mul_f32 v[12:13], v[52:53], v[12:13]
	v_fma_f32 v62, |v60|, s40, 1.0
	v_fma_f32 v63, |v61|, s40, 1.0
	v_pk_mul_f32 v[12:13], v[14:15], v[12:13]
	v_rcp_f32_e32 v62, v62
	v_rcp_f32_e32 v63, v63
	v_max_f32_e32 v110, 0, v10
	v_lshlrev_b32_e32 v4, 16, v5
	v_and_b32_e32 v5, 0xffff0000, v5
	v_fma_f32 v53, -|v10|, v12, v110
	v_max_f32_e32 v111, 0, v11
	v_fma_f32 v11, -|v11|, v13, v111
	v_pk_mul_f32 v[14:15], v[60:61], v[60:61]
	v_pk_fma_f32 v[12:13], v[62:63], s[42:43], v[18:19] op_sel_hi:[1,0,0]
	v_pk_mul_f32 v[14:15], v[14:15], s[64:65] op_sel_hi:[1,0]
	v_pk_fma_f32 v[12:13], v[62:63], v[12:13], s[48:49] op_sel_hi:[1,1,0]
	v_exp_f32_e32 v14, v14
	v_exp_f32_e32 v15, v15
	v_pk_fma_f32 v[12:13], v[62:63], v[12:13], s[50:51] op_sel_hi:[1,1,0]
	v_fma_f32 v64, |v4|, s40, 1.0
	v_fma_f32 v65, |v5|, s40, 1.0
	v_pk_fma_f32 v[12:13], v[62:63], v[12:13], s[56:57] op_sel_hi:[1,1,0]
	v_rcp_f32_e32 v64, v64
	v_pk_mul_f32 v[12:13], v[62:63], v[12:13]
	v_rcp_f32_e32 v65, v65
	v_pk_mul_f32 v[12:13], v[14:15], v[12:13]
	v_cmp_gt_f32_e64 s[0:1], 0, v60
	v_pk_mul_f32 v[14:15], v[60:61], v[12:13]
	v_pk_fma_f32 v[12:13], v[60:61], v[12:13], v[60:61] neg_lo:[1,0,0] neg_hi:[1,0,0]
	v_mul_f32_e32 v40, v41, v41
	v_cndmask_b32_e64 v63, v12, v14, s[0:1]
	v_cmp_gt_f32_e64 s[0:1], 0, v61
	v_pk_add_f32 v[22:23], v[24:25], v[22:23]
	v_pk_add_f32 v[24:25], v[34:35], v[36:37]
	v_cndmask_b32_e64 v61, v13, v15, s[0:1]
	v_pk_fma_f32 v[12:13], v[64:65], s[42:43], v[18:19] op_sel_hi:[1,0,0]
	v_pk_mul_f32 v[14:15], v[4:5], v[4:5]
	v_pk_fma_f32 v[12:13], v[64:65], v[12:13], s[48:49] op_sel_hi:[1,1,0]
	v_pk_mul_f32 v[14:15], v[14:15], s[64:65] op_sel_hi:[1,0]
	v_pk_fma_f32 v[12:13], v[64:65], v[12:13], s[50:51] op_sel_hi:[1,1,0]
	v_exp_f32_e32 v66, v14
	v_exp_f32_e32 v67, v15
	v_pk_fma_f32 v[68:69], v[64:65], v[12:13], s[56:57] op_sel_hi:[1,1,0]
	global_load_dwordx4 v[12:15], v[20:21], off offset:1024
	v_mul_f32_e32 v42, v43, v43
	v_mul_f32_e32 v8, v9, v9
	v_pk_add_f32 v[22:23], v[24:25], v[22:23]
	v_pk_add_f32 v[24:25], v[38:39], v[40:41]
	v_mul_f32_e32 v44, v45, v45
	v_mul_f32_e32 v46, v47, v47
	v_pk_add_f32 v[22:23], v[24:25], v[22:23]
	v_pk_add_f32 v[8:9], v[42:43], v[8:9]
	v_mul_f32_e32 v48, v49, v49
	v_mul_f32_e32 v50, v51, v51
	v_pk_mul_f32 v[64:65], v[64:65], v[68:69]
	v_pk_add_f32 v[8:9], v[8:9], v[22:23]
	v_pk_add_f32 v[22:23], v[44:45], v[46:47]
	v_pk_mul_f32 v[64:65], v[66:67], v[64:65]
	v_pk_add_f32 v[8:9], v[22:23], v[8:9]
	v_pk_add_f32 v[22:23], v[48:49], v[50:51]
	v_lshlrev_b32_e32 v24, 16, v6
	v_and_b32_e32 v25, 0xffff0000, v6
	v_max_f32_e32 v112, 0, v4
	v_pk_add_f32 v[8:9], v[22:23], v[8:9]
	v_mul_f32_e32 v52, v53, v53
	v_mul_f32_e32 v10, v11, v11
	v_fma_f32 v69, -|v4|, v64, v112
	v_max_f32_e32 v113, 0, v5
	v_fma_f32 v22, |v24|, s40, 1.0
	v_fma_f32 v23, |v25|, s40, 1.0
	v_mul_f32_e32 v62, v63, v63
	v_mul_f32_e32 v60, v61, v61
	v_fma_f32 v5, -|v5|, v65, v113
	v_pk_add_f32 v[10:11], v[52:53], v[10:11]
	v_rcp_f32_e32 v26, v22
	v_rcp_f32_e32 v27, v23
	v_mul_f32_e32 v68, v69, v69
	v_mul_f32_e32 v4, v5, v5
	v_pk_add_f32 v[8:9], v[10:11], v[8:9]
	v_pk_add_f32 v[10:11], v[62:63], v[60:61]
	v_pk_add_f32 v[4:5], v[68:69], v[4:5]
	v_pk_add_f32 v[8:9], v[10:11], v[8:9]
	v_cmp_gt_f32_e64 s[0:1], 0, v24
	v_pk_add_f32 v[22:23], v[4:5], v[8:9]
	v_pk_mul_f32 v[8:9], v[24:25], v[24:25]
	v_pk_fma_f32 v[4:5], v[26:27], s[42:43], v[18:19] op_sel_hi:[1,0,0]
	v_pk_mul_f32 v[8:9], v[8:9], s[64:65] op_sel_hi:[1,0]
	v_pk_fma_f32 v[4:5], v[26:27], v[4:5], s[48:49] op_sel_hi:[1,1,0]
	v_exp_f32_e32 v8, v8
	v_exp_f32_e32 v9, v9
	v_pk_fma_f32 v[4:5], v[26:27], v[4:5], s[50:51] op_sel_hi:[1,1,0]
	v_lshlrev_b32_e32 v6, 16, v7
	v_pk_fma_f32 v[4:5], v[26:27], v[4:5], s[56:57] op_sel_hi:[1,1,0]
	v_and_b32_e32 v7, 0xffff0000, v7
	v_pk_mul_f32 v[4:5], v[26:27], v[4:5]
	s_nop 0
	v_pk_mul_f32 v[4:5], v[8:9], v[4:5]
	s_nop 0
	v_pk_mul_f32 v[8:9], v[24:25], v[4:5]
	v_pk_fma_f32 v[4:5], v[24:25], v[4:5], v[24:25] neg_lo:[1,0,0] neg_hi:[1,0,0]
	s_nop 0
	v_cndmask_b32_e64 v11, v4, v8, s[0:1]
	v_cmp_gt_f32_e64 s[0:1], 0, v25
	v_and_b32_e32 v8, 0x7fffffff, v6
	v_mul_f32_e32 v10, v11, v11
	v_cndmask_b32_e64 v5, v5, v9, s[0:1]
	v_and_b32_e32 v9, 0x7fffffff, v7
	v_pk_fma_f32 v[8:9], v[8:9], s[40:41], 1.0 op_sel_hi:[1,0,0]
	v_mul_f32_e32 v4, v5, v5
	v_rcp_f32_e32 v8, v8
	v_rcp_f32_e32 v9, v9
	v_pk_add_f32 v[24:25], v[10:11], v[4:5]
	v_pk_mul_f32 v[10:11], v[6:7], v[6:7]
	v_cmp_gt_f32_e64 s[0:1], 0, v6
	v_pk_fma_f32 v[4:5], v[8:9], s[42:43], v[18:19] op_sel_hi:[1,0,0]
	v_pk_mul_f32 v[10:11], v[10:11], s[64:65] op_sel_hi:[1,0]
	v_pk_fma_f32 v[4:5], v[8:9], v[4:5], s[48:49] op_sel_hi:[1,1,0]
	v_exp_f32_e32 v10, v10
	v_exp_f32_e32 v11, v11
	v_pk_fma_f32 v[4:5], v[8:9], v[4:5], s[50:51] op_sel_hi:[1,1,0]
	v_pk_add_f32 v[22:23], v[24:25], v[22:23]
	v_pk_fma_f32 v[4:5], v[8:9], v[4:5], s[56:57] op_sel_hi:[1,1,0]
	s_nop 0
	v_pk_mul_f32 v[4:5], v[8:9], v[4:5]
	s_nop 0
	v_pk_mul_f32 v[4:5], v[10:11], v[4:5]
	global_load_dwordx4 v[8:11], v[20:21], off offset:1280
	s_waitcnt vmcnt(1)
	v_lshlrev_b32_e32 v32, 16, v12
	v_and_b32_e32 v33, 0xffff0000, v12
	v_fma_f32 v30, |v32|, s40, 1.0
	v_fma_f32 v31, |v33|, s40, 1.0
	v_pk_mul_f32 v[28:29], v[6:7], v[4:5]
	v_rcp_f32_e32 v30, v30
	v_rcp_f32_e32 v31, v31
	v_pk_fma_f32 v[4:5], v[6:7], v[4:5], v[6:7] neg_lo:[1,0,0] neg_hi:[1,0,0]
	v_lshlrev_b32_e32 v34, 16, v13
	v_cndmask_b32_e64 v27, v4, v28, s[0:1]
	v_cmp_gt_f32_e64 s[0:1], 0, v7
	v_pk_mul_f32 v[6:7], v[32:33], v[32:33]
	v_and_b32_e32 v35, 0xffff0000, v13
	v_cndmask_b32_e64 v29, v5, v29, s[0:1]
	v_pk_fma_f32 v[4:5], v[30:31], s[42:43], v[18:19] op_sel_hi:[1,0,0]
	v_pk_mul_f32 v[6:7], v[6:7], s[64:65] op_sel_hi:[1,0]
	v_pk_fma_f32 v[4:5], v[30:31], v[4:5], s[48:49] op_sel_hi:[1,1,0]
	v_exp_f32_e32 v6, v6
	v_exp_f32_e32 v7, v7
	v_pk_fma_f32 v[4:5], v[30:31], v[4:5], s[50:51] op_sel_hi:[1,1,0]
	v_pk_fma_f32 v[4:5], v[30:31], v[4:5], s[56:57] op_sel_hi:[1,1,0]
	v_fma_f32 v12, |v34|, s40, 1.0
	v_fma_f32 v13, |v35|, s40, 1.0
	v_pk_mul_f32 v[4:5], v[30:31], v[4:5]
	v_rcp_f32_e32 v36, v12
	v_rcp_f32_e32 v37, v13
	v_pk_mul_f32 v[4:5], v[6:7], v[4:5]
	v_cmp_gt_f32_e64 s[0:1], 0, v32
	v_pk_mul_f32 v[6:7], v[32:33], v[4:5]
	v_pk_fma_f32 v[4:5], v[32:33], v[4:5], v[32:33] neg_lo:[1,0,0] neg_hi:[1,0,0]
	v_lshlrev_b32_e32 v38, 16, v14
	v_cndmask_b32_e64 v31, v4, v6, s[0:1]
	v_cmp_gt_f32_e64 s[0:1], 0, v33
	v_and_b32_e32 v39, 0xffff0000, v14
	v_lshlrev_b32_e32 v40, 16, v15
	v_cndmask_b32_e64 v13, v5, v7, s[0:1]
	v_pk_fma_f32 v[4:5], v[36:37], s[42:43], v[18:19] op_sel_hi:[1,0,0]
	v_pk_mul_f32 v[6:7], v[34:35], v[34:35]
	v_pk_fma_f32 v[4:5], v[36:37], v[4:5], s[48:49] op_sel_hi:[1,1,0]
	v_pk_mul_f32 v[6:7], v[6:7], s[64:65] op_sel_hi:[1,0]
	v_pk_fma_f32 v[4:5], v[36:37], v[4:5], s[50:51] op_sel_hi:[1,1,0]
	v_exp_f32_e32 v6, v6
	v_exp_f32_e32 v7, v7
	v_pk_fma_f32 v[4:5], v[36:37], v[4:5], s[56:57] op_sel_hi:[1,1,0]
	v_cmp_gt_f32_e64 s[0:1], 0, v34
	v_pk_mul_f32 v[4:5], v[36:37], v[4:5]
	v_fma_f32 v36, |v38|, s40, 1.0
	v_fma_f32 v37, |v39|, s40, 1.0
	v_pk_mul_f32 v[4:5], v[6:7], v[4:5]
	v_rcp_f32_e32 v36, v36
	v_rcp_f32_e32 v37, v37
	v_pk_mul_f32 v[6:7], v[34:35], v[4:5]
	v_pk_fma_f32 v[4:5], v[34:35], v[4:5], v[34:35] neg_lo:[1,0,0] neg_hi:[1,0,0]
	v_and_b32_e32 v41, 0xffff0000, v15
	v_cndmask_b32_e64 v33, v4, v6, s[0:1]
	v_cmp_gt_f32_e64 s[0:1], 0, v35
	v_cndmask_b32_e64 v35, v5, v7, s[0:1]
	v_pk_mul_f32 v[6:7], v[38:39], v[38:39]
	v_pk_fma_f32 v[4:5], v[36:37], s[42:43], v[18:19] op_sel_hi:[1,0,0]
	v_pk_mul_f32 v[6:7], v[6:7], s[64:65] op_sel_hi:[1,0]
	v_pk_fma_f32 v[4:5], v[36:37], v[4:5], s[48:49] op_sel_hi:[1,1,0]
	v_exp_f32_e32 v6, v6
	v_exp_f32_e32 v7, v7
	v_pk_fma_f32 v[4:5], v[36:37], v[4:5], s[50:51] op_sel_hi:[1,1,0]
	v_fma_f32 v14, |v40|, s40, 1.0
	v_fma_f32 v15, |v41|, s40, 1.0
	v_pk_fma_f32 v[4:5], v[36:37], v[4:5], s[56:57] op_sel_hi:[1,1,0]
	v_rcp_f32_e32 v42, v14
	v_pk_mul_f32 v[4:5], v[36:37], v[4:5]
	v_rcp_f32_e32 v43, v15
	v_pk_mul_f32 v[4:5], v[6:7], v[4:5]
	v_cmp_gt_f32_e64 s[0:1], 0, v38
	v_pk_mul_f32 v[6:7], v[38:39], v[4:5]
	v_pk_fma_f32 v[4:5], v[38:39], v[4:5], v[38:39] neg_lo:[1,0,0] neg_hi:[1,0,0]
	v_mul_f32_e32 v26, v27, v27
	v_cndmask_b32_e64 v37, v4, v6, s[0:1]
	v_cmp_gt_f32_e64 s[0:1], 0, v39
	s_waitcnt vmcnt(0)
	v_lshlrev_b32_e32 v44, 16, v8
	v_and_b32_e32 v45, 0xffff0000, v8
	v_cndmask_b32_e64 v15, v5, v7, s[0:1]
	v_pk_fma_f32 v[4:5], v[42:43], s[42:43], v[18:19] op_sel_hi:[1,0,0]
	v_pk_mul_f32 v[6:7], v[40:41], v[40:41]
	v_pk_fma_f32 v[4:5], v[42:43], v[4:5], s[48:49] op_sel_hi:[1,1,0]
	v_pk_mul_f32 v[6:7], v[6:7], s[64:65] op_sel_hi:[1,0]
	v_pk_fma_f32 v[4:5], v[42:43], v[4:5], s[50:51] op_sel_hi:[1,1,0]
	v_exp_f32_e32 v6, v6
	v_exp_f32_e32 v7, v7
	v_pk_fma_f32 v[4:5], v[42:43], v[4:5], s[56:57] op_sel_hi:[1,1,0]
	v_cmp_gt_f32_e64 s[0:1], 0, v40
	v_pk_mul_f32 v[4:5], v[42:43], v[4:5]
	v_fma_f32 v42, |v44|, s40, 1.0
	v_fma_f32 v43, |v45|, s40, 1.0
	v_pk_mul_f32 v[4:5], v[6:7], v[4:5]
	v_rcp_f32_e32 v42, v42
	v_rcp_f32_e32 v43, v43
	v_pk_mul_f32 v[6:7], v[40:41], v[4:5]
	v_pk_fma_f32 v[4:5], v[40:41], v[4:5], v[40:41] neg_lo:[1,0,0] neg_hi:[1,0,0]
	v_lshlrev_b32_e32 v50, 16, v9
	v_cndmask_b32_e64 v39, v4, v6, s[0:1]
	v_cmp_gt_f32_e64 s[0:1], 0, v41
	v_and_b32_e32 v51, 0xffff0000, v9
	v_cndmask_b32_e64 v41, v5, v7, s[0:1]
	v_pk_mul_f32 v[6:7], v[44:45], v[44:45]
	v_pk_fma_f32 v[4:5], v[42:43], s[42:43], v[18:19] op_sel_hi:[1,0,0]
	v_pk_mul_f32 v[6:7], v[6:7], s[64:65] op_sel_hi:[1,0]
	v_pk_fma_f32 v[4:5], v[42:43], v[4:5], s[48:49] op_sel_hi:[1,1,0]
	v_exp_f32_e32 v6, v6
	v_exp_f32_e32 v7, v7
	v_pk_fma_f32 v[4:5], v[42:43], v[4:5], s[50:51] op_sel_hi:[1,1,0]
	v_pk_fma_f32 v[4:5], v[42:43], v[4:5], s[56:57] op_sel_hi:[1,1,0]
	v_fma_f32 v8, |v50|, s40, 1.0
	v_fma_f32 v9, |v51|, s40, 1.0
	v_pk_mul_f32 v[4:5], v[42:43], v[4:5]
	v_rcp_f32_e32 v52, v8
	v_pk_mul_f32 v[42:43], v[6:7], v[4:5]
	global_load_dwordx4 v[4:7], v[20:21], off offset:1536
	v_rcp_f32_e32 v53, v9
	v_pk_mul_f32 v[46:47], v[44:45], v[42:43]
	v_pk_fma_f32 v[48:49], v[44:45], v[42:43], v[44:45] neg_lo:[1,0,0] neg_hi:[1,0,0]
	v_cmp_gt_f32_e64 s[0:1], 0, v44
	v_lshlrev_b32_e32 v62, 16, v11
	v_and_b32_e32 v63, 0xffff0000, v11
	v_cndmask_b32_e64 v43, v48, v46, s[0:1]
	v_cmp_gt_f32_e64 s[0:1], 0, v45
	v_pk_fma_f32 v[44:45], v[52:53], s[42:43], v[18:19] op_sel_hi:[1,0,0]
	v_and_b32_e32 v11, 0x7fffffff, v63
	v_pk_fma_f32 v[44:45], v[52:53], v[44:45], s[48:49] op_sel_hi:[1,1,0]
	v_cndmask_b32_e64 v9, v49, v47, s[0:1]
	v_pk_mul_f32 v[46:47], v[50:51], v[50:51]
	v_pk_fma_f32 v[44:45], v[52:53], v[44:45], s[50:51] op_sel_hi:[1,1,0]
	v_pk_mul_f32 v[46:47], v[46:47], s[64:65] op_sel_hi:[1,0]
	v_pk_fma_f32 v[44:45], v[52:53], v[44:45], s[56:57] op_sel_hi:[1,1,0]
	v_exp_f32_e32 v46, v46
	v_exp_f32_e32 v47, v47
	v_pk_mul_f32 v[44:45], v[52:53], v[44:45]
	v_lshlrev_b32_e32 v52, 16, v10
	v_and_b32_e32 v53, 0xffff0000, v10
	v_fma_f32 v60, |v52|, s40, 1.0
	v_fma_f32 v61, |v53|, s40, 1.0
	v_pk_mul_f32 v[44:45], v[46:47], v[44:45]
	v_rcp_f32_e32 v60, v60
	v_rcp_f32_e32 v61, v61
	v_pk_mul_f32 v[46:47], v[50:51], v[44:45]
	v_pk_fma_f32 v[48:49], v[50:51], v[44:45], v[50:51] neg_lo:[1,0,0] neg_hi:[1,0,0]
	v_cmp_gt_f32_e64 s[0:1], 0, v50
	v_and_b32_e32 v10, 0x7fffffff, v62
	v_pk_fma_f32 v[10:11], v[10:11], s[40:41], 1.0 op_sel_hi:[1,0,0]
	v_cndmask_b32_e64 v45, v48, v46, s[0:1]
	v_cmp_gt_f32_e64 s[0:1], 0, v51
	v_pk_mul_f32 v[50:51], v[52:53], v[52:53]
	v_rcp_f32_e32 v64, v10
	v_cndmask_b32_e64 v47, v49, v47, s[0:1]
	v_pk_fma_f32 v[48:49], v[60:61], s[42:43], v[18:19] op_sel_hi:[1,0,0]
	v_pk_mul_f32 v[50:51], v[50:51], s[64:65] op_sel_hi:[1,0]
	v_pk_fma_f32 v[48:49], v[60:61], v[48:49], s[48:49] op_sel_hi:[1,1,0]
	v_exp_f32_e32 v50, v50
	v_exp_f32_e32 v51, v51
	v_pk_fma_f32 v[48:49], v[60:61], v[48:49], s[50:51] op_sel_hi:[1,1,0]
	v_rcp_f32_e32 v65, v11
	v_pk_fma_f32 v[48:49], v[60:61], v[48:49], s[56:57] op_sel_hi:[1,1,0]
	v_cmp_gt_f32_e64 s[0:1], 0, v52
	v_pk_mul_f32 v[48:49], v[60:61], v[48:49]
	v_mul_f32_e32 v28, v29, v29
	v_pk_mul_f32 v[48:49], v[50:51], v[48:49]
	v_mul_f32_e32 v30, v31, v31
	v_pk_mul_f32 v[50:51], v[52:53], v[48:49]
	v_pk_fma_f32 v[60:61], v[52:53], v[48:49], v[52:53] neg_lo:[1,0,0] neg_hi:[1,0,0]
	v_mul_f32_e32 v12, v13, v13
	v_cndmask_b32_e64 v49, v60, v50, s[0:1]
	v_cmp_gt_f32_e64 s[0:1], 0, v53
	v_pk_mul_f32 v[52:53], v[62:63], v[62:63]
	v_pk_add_f32 v[24:25], v[26:27], v[28:29]
	v_cndmask_b32_e64 v11, v61, v51, s[0:1]
	v_pk_fma_f32 v[50:51], v[64:65], s[42:43], v[18:19] op_sel_hi:[1,0,0]
	v_pk_mul_f32 v[52:53], v[52:53], s[64:65] op_sel_hi:[1,0]
	v_pk_fma_f32 v[50:51], v[64:65], v[50:51], s[48:49] op_sel_hi:[1,1,0]
	v_exp_f32_e32 v52, v52
	v_exp_f32_e32 v53, v53
	v_pk_fma_f32 v[50:51], v[64:65], v[50:51], s[50:51] op_sel_hi:[1,1,0]
	v_cmp_gt_f32_e64 s[0:1], 0, v62
	v_pk_fma_f32 v[50:51], v[64:65], v[50:51], s[56:57] op_sel_hi:[1,1,0]
	v_mul_f32_e32 v32, v33, v33
	v_pk_mul_f32 v[50:51], v[64:65], v[50:51]
	v_mul_f32_e32 v34, v35, v35
	v_pk_mul_f32 v[50:51], v[52:53], v[50:51]
	v_pk_add_f32 v[22:23], v[24:25], v[22:23]
	v_pk_mul_f32 v[60:61], v[62:63], v[50:51]
	v_pk_fma_f32 v[64:65], v[62:63], v[50:51], v[62:63] neg_lo:[1,0,0] neg_hi:[1,0,0]
	global_load_dwordx4 v[50:53], v[20:21], off offset:1792
	v_cndmask_b32_e64 v67, v64, v60, s[0:1]
	v_cmp_gt_f32_e64 s[0:1], 0, v63
	v_pk_add_f32 v[12:13], v[30:31], v[12:13]
	v_mul_f32_e32 v36, v37, v37
	v_cndmask_b32_e64 v61, v65, v61, s[0:1]
	s_waitcnt vmcnt(1)
	v_lshlrev_b32_e32 v20, 16, v4
	v_and_b32_e32 v21, 0xffff0000, v4
	v_fma_f32 v68, |v20|, s40, 1.0
	v_fma_f32 v69, |v21|, s40, 1.0
	v_pk_mul_f32 v[64:65], v[20:21], v[20:21]
	v_rcp_f32_e32 v68, v68
	v_rcp_f32_e32 v69, v69
	v_mul_f32_e32 v14, v15, v15
	v_pk_mul_f32 v[64:65], v[64:65], s[64:65] op_sel_hi:[1,0]
	v_pk_add_f32 v[12:13], v[12:13], v[22:23]
	v_pk_fma_f32 v[62:63], v[68:69], s[42:43], v[18:19] op_sel_hi:[1,0,0]
	v_pk_add_f32 v[22:23], v[32:33], v[34:35]
	v_mul_f32_e32 v38, v39, v39
	v_mul_f32_e32 v40, v41, v41
	v_pk_fma_f32 v[62:63], v[68:69], v[62:63], s[48:49] op_sel_hi:[1,1,0]
	v_exp_f32_e32 v64, v64
	v_exp_f32_e32 v65, v65
	v_pk_add_f32 v[12:13], v[22:23], v[12:13]
	v_pk_add_f32 v[14:15], v[36:37], v[14:15]
	v_mul_f32_e32 v42, v43, v43
	v_mul_f32_e32 v8, v9, v9
	v_pk_fma_f32 v[62:63], v[68:69], v[62:63], s[50:51] op_sel_hi:[1,1,0]
	v_pk_add_f32 v[12:13], v[14:15], v[12:13]
	v_pk_add_f32 v[14:15], v[38:39], v[40:41]
	v_mul_f32_e32 v44, v45, v45
	v_mul_f32_e32 v46, v47, v47
	v_pk_fma_f32 v[62:63], v[68:69], v[62:63], s[56:57] op_sel_hi:[1,1,0]
	v_pk_add_f32 v[12:13], v[14:15], v[12:13]
	v_pk_add_f32 v[8:9], v[42:43], v[8:9]
	v_pk_mul_f32 v[62:63], v[68:69], v[62:63]
	v_pk_add_f32 v[8:9], v[8:9], v[12:13]
	v_pk_add_f32 v[12:13], v[44:45], v[46:47]
	v_lshlrev_b32_e32 v4, 16, v5
	v_and_b32_e32 v5, 0xffff0000, v5
	v_pk_mul_f32 v[62:63], v[64:65], v[62:63]
	v_pk_add_f32 v[8:9], v[12:13], v[8:9]
	v_max_f32_e32 v114, 0, v20
	v_fma_f32 v12, |v4|, s40, 1.0
	v_fma_f32 v13, |v5|, s40, 1.0
	v_mul_f32_e32 v48, v49, v49
	v_mul_f32_e32 v10, v11, v11
	v_fma_f32 v69, -|v20|, v62, v114
	v_max_f32_e32 v115, 0, v21
	v_rcp_f32_e32 v12, v12
	v_rcp_f32_e32 v13, v13
	v_mul_f32_e32 v66, v67, v67
	v_mul_f32_e32 v60, v61, v61
	v_fma_f32 v21, -|v21|, v63, v115
	v_pk_add_f32 v[10:11], v[48:49], v[10:11]
	v_mul_f32_e32 v68, v69, v69
	v_mul_f32_e32 v20, v21, v21
	v_pk_add_f32 v[8:9], v[10:11], v[8:9]
	v_pk_add_f32 v[10:11], v[66:67], v[60:61]
	v_pk_mul_f32 v[14:15], v[4:5], v[4:5]
	v_pk_add_f32 v[8:9], v[10:11], v[8:9]
	v_pk_add_f32 v[10:11], v[68:69], v[20:21]
	v_pk_mul_f32 v[14:15], v[14:15], s[64:65] op_sel_hi:[1,0]
	v_pk_add_f32 v[8:9], v[10:11], v[8:9]
	v_pk_fma_f32 v[10:11], v[12:13], s[42:43], v[18:19] op_sel_hi:[1,0,0]
	v_exp_f32_e32 v14, v14
	v_pk_fma_f32 v[10:11], v[12:13], v[10:11], s[48:49] op_sel_hi:[1,1,0]
	v_exp_f32_e32 v15, v15
	v_pk_fma_f32 v[10:11], v[12:13], v[10:11], s[50:51] op_sel_hi:[1,1,0]
	v_cmp_gt_f32_e64 s[0:1], 0, v4
	v_pk_fma_f32 v[10:11], v[12:13], v[10:11], s[56:57] op_sel_hi:[1,1,0]
	s_waitcnt vmcnt(0)
	v_lshlrev_b32_e32 v24, 16, v50
	v_pk_mul_f32 v[10:11], v[12:13], v[10:11]
	v_and_b32_e32 v25, 0xffff0000, v50
	v_pk_mul_f32 v[10:11], v[14:15], v[10:11]
	v_and_b32_e32 v27, 0x7fffffff, v25
	v_pk_mul_f32 v[12:13], v[4:5], v[10:11]
	v_pk_fma_f32 v[10:11], v[4:5], v[10:11], v[4:5] neg_lo:[1,0,0] neg_hi:[1,0,0]
	v_and_b32_e32 v26, 0x7fffffff, v24
	v_cndmask_b32_e64 v15, v10, v12, s[0:1]
	v_cmp_gt_f32_e64 s[0:1], 0, v5
	v_lshlrev_b32_e32 v10, 16, v6
	v_and_b32_e32 v12, 0x7fffffff, v10
	v_cndmask_b32_e64 v5, v11, v13, s[0:1]
	v_and_b32_e32 v11, 0xffff0000, v6
	v_and_b32_e32 v13, 0x7fffffff, v11
	v_pk_fma_f32 v[12:13], v[12:13], s[40:41], 1.0 op_sel_hi:[1,0,0]
	v_mul_f32_e32 v14, v15, v15
	v_rcp_f32_e32 v12, v12
	v_rcp_f32_e32 v13, v13
	v_mul_f32_e32 v4, v5, v5
	v_pk_mul_f32 v[20:21], v[10:11], v[10:11]
	v_pk_add_f32 v[4:5], v[14:15], v[4:5]
	v_pk_fma_f32 v[14:15], v[12:13], s[42:43], v[18:19] op_sel_hi:[1,0,0]
	v_pk_mul_f32 v[20:21], v[20:21], s[64:65] op_sel_hi:[1,0]
	v_pk_fma_f32 v[14:15], v[12:13], v[14:15], s[48:49] op_sel_hi:[1,1,0]
	v_exp_f32_e32 v20, v20
	v_exp_f32_e32 v21, v21
	v_pk_fma_f32 v[14:15], v[12:13], v[14:15], s[50:51] op_sel_hi:[1,1,0]
	v_lshlrev_b32_e32 v6, 16, v7
	v_and_b32_e32 v7, 0xffff0000, v7
	v_pk_fma_f32 v[14:15], v[12:13], v[14:15], s[56:57] op_sel_hi:[1,1,0]
	v_pk_mul_f32 v[12:13], v[12:13], v[14:15]
	v_fma_f32 v22, |v6|, s40, 1.0
	v_fma_f32 v23, |v7|, s40, 1.0
	v_pk_mul_f32 v[12:13], v[20:21], v[12:13]
	v_rcp_f32_e32 v22, v22
	v_rcp_f32_e32 v23, v23
	v_max_f32_e32 v116, 0, v10
	v_pk_fma_f32 v[26:27], v[26:27], s[40:41], 1.0 op_sel_hi:[1,0,0]
	v_lshlrev_b32_e32 v28, 16, v51
	v_fma_f32 v21, -|v10|, v12, v116
	v_max_f32_e32 v117, 0, v11
	v_rcp_f32_e32 v26, v26
	v_rcp_f32_e32 v27, v27
	v_fma_f32 v11, -|v11|, v13, v117
	v_pk_mul_f32 v[14:15], v[6:7], v[6:7]
	v_pk_fma_f32 v[12:13], v[22:23], s[42:43], v[18:19] op_sel_hi:[1,0,0]
	v_pk_mul_f32 v[14:15], v[14:15], s[64:65] op_sel_hi:[1,0]
	v_pk_fma_f32 v[12:13], v[22:23], v[12:13], s[48:49] op_sel_hi:[1,1,0]
	v_exp_f32_e32 v14, v14
	v_exp_f32_e32 v15, v15
	v_pk_fma_f32 v[12:13], v[22:23], v[12:13], s[50:51] op_sel_hi:[1,1,0]
	v_cmp_gt_f32_e64 s[0:1], 0, v6
	v_pk_fma_f32 v[12:13], v[22:23], v[12:13], s[56:57] op_sel_hi:[1,1,0]
	v_and_b32_e32 v29, 0xffff0000, v51
	v_pk_mul_f32 v[12:13], v[22:23], v[12:13]
	v_pk_mul_f32 v[12:13], v[14:15], v[12:13]
	v_pk_mul_f32 v[14:15], v[6:7], v[12:13]
	v_pk_fma_f32 v[12:13], v[6:7], v[12:13], v[6:7] neg_lo:[1,0,0] neg_hi:[1,0,0]
	v_fma_f32 v30, |v28|, s40, 1.0
	v_fma_f32 v31, |v29|, s40, 1.0
	v_cndmask_b32_e64 v23, v12, v14, s[0:1]
	v_cmp_gt_f32_e64 s[0:1], 0, v7
	v_rcp_f32_e32 v30, v30
	v_rcp_f32_e32 v31, v31
	v_cndmask_b32_e64 v7, v13, v15, s[0:1]
	v_pk_mul_f32 v[14:15], v[24:25], v[24:25]
	v_pk_fma_f32 v[12:13], v[26:27], s[42:43], v[18:19] op_sel_hi:[1,0,0]
	v_pk_mul_f32 v[14:15], v[14:15], s[64:65] op_sel_hi:[1,0]
	v_pk_fma_f32 v[12:13], v[26:27], v[12:13], s[48:49] op_sel_hi:[1,1,0]
	v_exp_f32_e32 v14, v14
	v_exp_f32_e32 v15, v15
	v_pk_fma_f32 v[12:13], v[26:27], v[12:13], s[50:51] op_sel_hi:[1,1,0]
	v_cmp_gt_f32_e64 s[0:1], 0, v24
	v_pk_fma_f32 v[12:13], v[26:27], v[12:13], s[56:57] op_sel_hi:[1,1,0]
	v_lshlrev_b32_e32 v32, 16, v52
	v_pk_mul_f32 v[12:13], v[26:27], v[12:13]
	v_and_b32_e32 v33, 0xffff0000, v52
	v_pk_mul_f32 v[12:13], v[14:15], v[12:13]
	v_pk_mul_f32 v[14:15], v[24:25], v[12:13]
	v_pk_fma_f32 v[12:13], v[24:25], v[12:13], v[24:25] neg_lo:[1,0,0] neg_hi:[1,0,0]
	v_cndmask_b32_e64 v27, v12, v14, s[0:1]
	v_cmp_gt_f32_e64 s[0:1], 0, v25
	v_pk_mul_f32 v[24:25], v[28:29], v[28:29]
	v_fma_f32 v34, |v32|, s40, 1.0
	v_fma_f32 v35, |v33|, s40, 1.0
	v_cndmask_b32_e64 v13, v13, v15, s[0:1]
	v_pk_fma_f32 v[14:15], v[30:31], s[42:43], v[18:19] op_sel_hi:[1,0,0]
	v_pk_mul_f32 v[24:25], v[24:25], s[64:65] op_sel_hi:[1,0]
	v_pk_fma_f32 v[14:15], v[30:31], v[14:15], s[48:49] op_sel_hi:[1,1,0]
	v_exp_f32_e32 v24, v24
	v_exp_f32_e32 v25, v25
	v_pk_fma_f32 v[14:15], v[30:31], v[14:15], s[50:51] op_sel_hi:[1,1,0]
	v_rcp_f32_e32 v34, v34
	v_pk_fma_f32 v[14:15], v[30:31], v[14:15], s[56:57] op_sel_hi:[1,1,0]
	v_rcp_f32_e32 v35, v35
	v_pk_mul_f32 v[14:15], v[30:31], v[14:15]
	v_cmp_gt_f32_e64 s[0:1], 0, v28
	v_pk_mul_f32 v[14:15], v[24:25], v[14:15]
	v_lshlrev_b32_e32 v36, 16, v53
	v_pk_mul_f32 v[24:25], v[28:29], v[14:15]
	v_pk_fma_f32 v[14:15], v[28:29], v[14:15], v[28:29] neg_lo:[1,0,0] neg_hi:[1,0,0]
	v_and_b32_e32 v37, 0xffff0000, v53
	v_cndmask_b32_e64 v31, v14, v24, s[0:1]
	v_cmp_gt_f32_e64 s[0:1], 0, v29
	v_pk_mul_f32 v[28:29], v[32:33], v[32:33]
	v_cndmask_b32_e64 v15, v15, v25, s[0:1]
	v_pk_fma_f32 v[24:25], v[34:35], s[42:43], v[18:19] op_sel_hi:[1,0,0]
	v_pk_mul_f32 v[28:29], v[28:29], s[64:65] op_sel_hi:[1,0]
	v_pk_fma_f32 v[24:25], v[34:35], v[24:25], s[48:49] op_sel_hi:[1,1,0]
	v_exp_f32_e32 v28, v28
	v_exp_f32_e32 v29, v29
	v_pk_fma_f32 v[24:25], v[34:35], v[24:25], s[50:51] op_sel_hi:[1,1,0]
	v_pk_fma_f32 v[24:25], v[34:35], v[24:25], s[56:57] op_sel_hi:[1,1,0]
	v_fma_f32 v38, |v36|, s40, 1.0
	v_fma_f32 v39, |v37|, s40, 1.0
	v_pk_mul_f32 v[24:25], v[34:35], v[24:25]
	v_rcp_f32_e32 v38, v38
	v_pk_mul_f32 v[24:25], v[28:29], v[24:25]
	v_rcp_f32_e32 v39, v39
	v_max_f32_e32 v80, 0, v32
	v_pk_fma_f32 v[18:19], v[38:39], s[42:43], v[18:19] op_sel_hi:[1,0,0]
	v_mul_f32_e32 v20, v21, v21
	v_fma_f32 v35, -|v32|, v24, v80
	v_max_f32_e32 v81, 0, v33
	v_pk_fma_f32 v[18:19], v[38:39], v[18:19], s[48:49] op_sel_hi:[1,1,0]
	v_mul_f32_e32 v10, v11, v11
	v_fma_f32 v25, -|v33|, v25, v81
	v_pk_mul_f32 v[28:29], v[36:37], v[36:37]
	v_pk_fma_f32 v[18:19], v[38:39], v[18:19], s[50:51] op_sel_hi:[1,1,0]
	v_pk_mul_f32 v[28:29], v[28:29], s[64:65] op_sel_hi:[1,0]
	v_pk_fma_f32 v[18:19], v[38:39], v[18:19], s[56:57] op_sel_hi:[1,1,0]
	v_exp_f32_e32 v28, v28
	v_exp_f32_e32 v29, v29
	v_pk_mul_f32 v[18:19], v[38:39], v[18:19]
	v_mul_f32_e32 v22, v23, v23
	v_mul_f32_e32 v6, v7, v7
	v_pk_mul_f32 v[18:19], v[28:29], v[18:19]
	v_pk_add_f32 v[4:5], v[4:5], v[8:9]
	v_pk_add_f32 v[8:9], v[20:21], v[10:11]
	v_mul_f32_e32 v26, v27, v27
	v_mul_f32_e32 v12, v13, v13
	v_max_f32_e32 v82, 0, v36
	v_pk_add_f32 v[4:5], v[8:9], v[4:5]
	v_pk_add_f32 v[6:7], v[22:23], v[6:7]
	v_mul_f32_e32 v30, v31, v31
	v_mul_f32_e32 v14, v15, v15
	v_fma_f32 v33, -|v36|, v18, v82
	v_max_f32_e32 v83, 0, v37
	v_pk_add_f32 v[4:5], v[6:7], v[4:5]
	v_pk_add_f32 v[6:7], v[26:27], v[12:13]
	v_mul_f32_e32 v34, v35, v35
	v_mul_f32_e32 v24, v25, v25
	v_fma_f32 v19, -|v37|, v19, v83
	v_pk_add_f32 v[4:5], v[6:7], v[4:5]
	v_pk_add_f32 v[6:7], v[30:31], v[14:15]
	v_mul_f32_e32 v32, v33, v33
	v_mul_f32_e32 v18, v19, v19
	v_pk_add_f32 v[4:5], v[6:7], v[4:5]
	v_pk_add_f32 v[6:7], v[34:35], v[24:25]
	s_nop 0
	v_pk_add_f32 v[4:5], v[6:7], v[4:5]
	v_pk_add_f32 v[6:7], v[32:33], v[18:19]
	s_nop 0
	v_pk_add_f32 v[4:5], v[6:7], v[4:5]
	ds_bpermute_b32 v7, v56, v5
	ds_bpermute_b32 v6, v56, v4
	s_waitcnt lgkmcnt(0)
	v_pk_add_f32 v[4:5], v[4:5], v[6:7]
	ds_bpermute_b32 v7, v57, v5
	ds_bpermute_b32 v6, v57, v4
	s_waitcnt lgkmcnt(0)
	v_pk_add_f32 v[4:5], v[4:5], v[6:7]
	ds_bpermute_b32 v7, v58, v5
	ds_bpermute_b32 v6, v58, v4
	s_waitcnt lgkmcnt(0)
	v_pk_add_f32 v[4:5], v[4:5], v[6:7]
	ds_bpermute_b32 v7, v59, v5
	ds_bpermute_b32 v6, v59, v4
	s_and_saveexec_b64 s[0:1], vcc
	s_cbranch_execz .LBB0_451
	s_waitcnt lgkmcnt(0)
	v_pk_add_f32 v[4:5], v[4:5], v[6:7]
	s_nop 0
	v_pk_mul_f32 v[4:5], v[4:5], s[66:67] op_sel_hi:[1,0]
	s_nop 0
	v_fma_f32 v4, -v5, v5, v4
	v_max_f32_e32 v4, 0, v4
	v_add_f32_e32 v4, 0x358637bd, v4
	v_mul_f32_e32 v6, 0x4b800000, v4
	v_cmp_gt_f32_e32 vcc, s36, v4
	s_nop 1
	v_cndmask_b32_e32 v4, v4, v6, vcc
	v_rsq_f32_e32 v4, v4
	v_lshl_add_u32 v6, v16, 2, 0
	v_add_u32_e32 v7, 0x11000, v6
	ds_write_b32 v7, v5
	v_mul_f32_e32 v5, 0x45800000, v4
	v_cndmask_b32_e32 v4, v4, v5, vcc
	v_add_u32_e32 v5, 0x11200, v6
	ds_write_b32 v5, v4

.LBB0_452:
	s_waitcnt vmcnt(15)
	v_lshlrev_b32_e32 v8, 16, v36
	v_and_b32_e32 v9, 0xffff0000, v36
	v_fma_f32 v10, |v8|, s40, 1.0
	v_fma_f32 v11, |v9|, s40, 1.0
	v_mov_b64_e32 v[12:13], s[44:45]
	v_rcp_f32_e32 v10, v10
	v_rcp_f32_e32 v11, v11
	v_pk_mul_f32 v[16:17], v[8:9], v[8:9]
	v_cmp_gt_f32_e32 vcc, 0, v8
	v_pk_mul_f32 v[16:17], v[16:17], s[64:65] op_sel_hi:[1,0]
	v_pk_fma_f32 v[14:15], v[10:11], s[42:43], v[12:13] op_sel_hi:[1,0,0]
	v_exp_f32_e32 v16, v16
	v_pk_fma_f32 v[14:15], v[10:11], v[14:15], s[48:49] op_sel_hi:[1,1,0]
	v_exp_f32_e32 v17, v17
	v_pk_fma_f32 v[14:15], v[10:11], v[14:15], s[50:51] op_sel_hi:[1,1,0]
	v_add_f32_e32 v4, v72, v4
	v_pk_fma_f32 v[14:15], v[10:11], v[14:15], s[56:57] op_sel_hi:[1,1,0]
	s_mov_b32 s0, 0x1506e000
	v_pk_mul_f32 v[10:11], v[10:11], v[14:15]
	s_add_u32 s70, s70, 0x400
	v_pk_mul_f32 v[10:11], v[16:17], v[10:11]
	v_lshlrev_b32_e32 v16, 16, v37
	v_and_b32_e32 v17, 0xffff0000, v37
	v_fma_f32 v18, |v16|, s40, 1.0
	v_fma_f32 v19, |v17|, s40, 1.0
	v_pk_mul_f32 v[14:15], v[8:9], v[10:11]
	v_rcp_f32_e32 v18, v18
	v_rcp_f32_e32 v19, v19
	v_pk_fma_f32 v[10:11], v[8:9], v[10:11], v[8:9] neg_lo:[1,0,0] neg_hi:[1,0,0]
	s_addc_u32 s71, s71, 0
	v_cndmask_b32_e32 v3, v10, v14, vcc
	v_cmp_gt_f32_e32 vcc, 0, v9
	v_pk_fma_f32 v[8:9], v[18:19], s[42:43], v[12:13] op_sel_hi:[1,0,0]
	v_mul_f32_e32 v3, v3, v4
	v_cndmask_b32_e32 v14, v11, v15, vcc
	v_pk_mul_f32 v[10:11], v[16:17], v[16:17]
	v_pk_fma_f32 v[8:9], v[18:19], v[8:9], s[48:49] op_sel_hi:[1,1,0]
	v_pk_mul_f32 v[10:11], v[10:11], s[64:65] op_sel_hi:[1,0]
	v_pk_fma_f32 v[8:9], v[18:19], v[8:9], s[50:51] op_sel_hi:[1,1,0]
	v_exp_f32_e32 v10, v10
	v_exp_f32_e32 v11, v11
	v_pk_fma_f32 v[8:9], v[18:19], v[8:9], s[56:57] op_sel_hi:[1,1,0]
	v_cmp_gt_f32_e32 vcc, 0, v16
	v_pk_mul_f32 v[8:9], v[18:19], v[8:9]
	v_add_f32_e32 v4, v72, v5
	v_pk_mul_f32 v[8:9], v[10:11], v[8:9]
	v_mul_f32_e32 v4, v14, v4
	v_pk_mul_f32 v[10:11], v[16:17], v[8:9]
	v_pk_fma_f32 v[8:9], v[16:17], v[8:9], v[16:17] neg_lo:[1,0,0] neg_hi:[1,0,0]
	v_cvt_pk_bf16_f32 v4, v3, v4
	v_add_f32_e32 v3, v72, v6
	v_cndmask_b32_e32 v8, v8, v10, vcc
	v_cmp_gt_f32_e32 vcc, 0, v17
	v_add_f32_e32 v5, v72, v7
	v_lshl_add_u64 v[26:27], v[26:27], 0, s[68:69]
	v_cndmask_b32_e32 v9, v9, v11, vcc
	v_add_co_u32_e32 v6, vcc, s0, v34
	s_mov_b64 s[0:1], 0x8000
	v_mul_f32_e32 v5, v9, v5
	v_addc_co_u32_e32 v7, vcc, 0, v35, vcc
	v_lshl_add_u64 v[28:29], v[28:29], 0, s[0:1]
	v_lshl_add_u64 v[30:31], v[30:31], 0, s[68:69]
	s_cmpk_eq_i32 s70, 0x1000
	v_lshl_add_u64 v[32:33], v[32:33], 0, s[68:69]
	v_mul_f32_e32 v3, v8, v3
	v_cvt_pk_bf16_f32 v5, v3, v5
	global_store_dwordx2 v[6:7], v[4:5], off offset:480
	s_barrier
	s_cbranch_scc1 .LBB0_410
.LBB0_453:
	v_lshl_add_u64 v[4:5], s[12:13], 0, v[32:33]
	v_add_co_u32_e32 v18, vcc, 0x696e000, v4
	s_add_u32 s0, s16, s70
	s_nop 0
	v_addc_co_u32_e32 v19, vcc, 0, v5, vcc
	global_load_dwordx4 v[8:11], v[18:19], off
	global_load_dwordx4 v[4:7], v[18:19], off offset:2048
	s_addc_u32 s1, s38, s71
	s_add_u32 s4, s88, s70
	s_addc_u32 s5, s89, s71
	global_load_dwordx2 v[20:21], v2, s[0:1]
	global_load_dwordx2 v[22:23], v2, s[4:5]
	v_mov_b64_e32 v[16:17], s[44:45]
	ds_read_b64 v[14:15], v68
	ds_read_b64 v[12:13], v69
	s_waitcnt vmcnt(3)
	v_lshlrev_b32_e32 v24, 16, v8
	v_and_b32_e32 v25, 0xffff0000, v8
	s_waitcnt vmcnt(2)
	v_lshlrev_b32_e32 v34, 16, v4
	v_and_b32_e32 v35, 0xffff0000, v4
	v_fma_f32 v36, |v24|, s40, 1.0
	v_fma_f32 v37, |v25|, s40, 1.0
	v_fma_f32 v40, |v34|, s40, 1.0
	v_fma_f32 v41, |v35|, s40, 1.0
	v_rcp_f32_e32 v36, v36
	v_rcp_f32_e32 v37, v37
	v_rcp_f32_e32 v40, v40
	v_rcp_f32_e32 v41, v41
	v_pk_mul_f32 v[38:39], v[24:25], v[24:25]
	v_pk_mul_f32 v[42:43], v[34:35], v[34:35]
	v_pk_mul_f32 v[38:39], v[38:39], s[64:65] op_sel_hi:[1,0]
	v_pk_fma_f32 v[44:45], v[36:37], s[42:43], v[16:17] op_sel_hi:[1,0,0]
	v_pk_mul_f32 v[42:43], v[42:43], s[64:65] op_sel_hi:[1,0]
	v_exp_f32_e32 v38, v38
	v_exp_f32_e32 v39, v39
	v_pk_fma_f32 v[46:47], v[40:41], s[42:43], v[16:17] op_sel_hi:[1,0,0]
	v_pk_fma_f32 v[44:45], v[36:37], v[44:45], s[48:49] op_sel_hi:[1,1,0]
	v_exp_f32_e32 v42, v42
	v_exp_f32_e32 v43, v43
	v_pk_fma_f32 v[46:47], v[40:41], v[46:47], s[48:49] op_sel_hi:[1,1,0]
	v_pk_fma_f32 v[44:45], v[36:37], v[44:45], s[50:51] op_sel_hi:[1,1,0]
	v_pk_fma_f32 v[46:47], v[40:41], v[46:47], s[50:51] op_sel_hi:[1,1,0]
	v_pk_fma_f32 v[44:45], v[36:37], v[44:45], s[56:57] op_sel_hi:[1,1,0]
	v_pk_fma_f32 v[46:47], v[40:41], v[46:47], s[56:57] op_sel_hi:[1,1,0]
	v_pk_mul_f32 v[36:37], v[36:37], v[44:45]
	v_pk_mul_f32 v[40:41], v[40:41], v[46:47]
	v_pk_mul_f32 v[36:37], v[38:39], v[36:37]
	v_pk_mul_f32 v[38:39], v[42:43], v[40:41]
	v_max_f32_e32 v84, 0, v24
	v_fma_f32 v3, -|v24|, v36, v84
	v_max_f32_e32 v85, 0, v25
	s_waitcnt lgkmcnt(1)
	v_sub_f32_e32 v3, v3, v14
	s_waitcnt lgkmcnt(0)
	v_mul_f32_e32 v3, v12, v3
	v_fma_f32 v4, -|v25|, v37, v85
	v_max_f32_e32 v86, 0, v34
	v_sub_f32_e32 v4, v4, v14
	v_mul_f32_e32 v4, v12, v4
	v_fma_f32 v8, -|v34|, v38, v86
	v_max_f32_e32 v90, 0, v35
	v_sub_f32_e32 v8, v8, v15
	v_mul_f32_e32 v8, v13, v8
	v_fma_f32 v24, -|v35|, v39, v90
	v_sub_f32_e32 v24, v24, v15
	v_mul_f32_e32 v24, v13, v24
	s_waitcnt vmcnt(0)
	v_fma_f32 v3, v20, v3, v22
	v_fma_f32 v4, v21, v4, v23
	v_fma_f32 v8, v20, v8, v22
	v_fmac_f32_e32 v23, v21, v24
	v_cvt_pk_bf16_f32 v3, v3, v8
	ds_write_b32 v70, v3
	v_cvt_pk_bf16_f32 v3, v4, v23
	global_load_dwordx2 v[22:23], v2, s[0:1] offset:8
	global_load_dwordx2 v[20:21], v2, s[4:5] offset:8
	v_lshlrev_b32_e32 v8, 16, v9
	v_and_b32_e32 v9, 0xffff0000, v9
	v_lshlrev_b32_e32 v4, 16, v5
	v_and_b32_e32 v5, 0xffff0000, v5
	v_fma_f32 v24, |v8|, s40, 1.0
	v_fma_f32 v25, |v9|, s40, 1.0
	v_fma_f32 v36, |v4|, s40, 1.0
	v_fma_f32 v37, |v5|, s40, 1.0
	v_rcp_f32_e32 v24, v24
	v_rcp_f32_e32 v25, v25
	v_rcp_f32_e32 v36, v36
	v_rcp_f32_e32 v37, v37
	v_pk_mul_f32 v[34:35], v[8:9], v[8:9]
	v_pk_mul_f32 v[38:39], v[4:5], v[4:5]
	v_pk_mul_f32 v[34:35], v[34:35], s[64:65] op_sel_hi:[1,0]
	v_pk_fma_f32 v[40:41], v[24:25], s[42:43], v[16:17] op_sel_hi:[1,0,0]
	v_pk_mul_f32 v[38:39], v[38:39], s[64:65] op_sel_hi:[1,0]
	v_exp_f32_e32 v34, v34
	v_exp_f32_e32 v35, v35
	v_pk_fma_f32 v[42:43], v[36:37], s[42:43], v[16:17] op_sel_hi:[1,0,0]
	v_pk_fma_f32 v[40:41], v[24:25], v[40:41], s[48:49] op_sel_hi:[1,1,0]
	v_exp_f32_e32 v38, v38
	v_exp_f32_e32 v39, v39
	v_pk_fma_f32 v[42:43], v[36:37], v[42:43], s[48:49] op_sel_hi:[1,1,0]
	v_pk_fma_f32 v[40:41], v[24:25], v[40:41], s[50:51] op_sel_hi:[1,1,0]
	v_pk_fma_f32 v[42:43], v[36:37], v[42:43], s[50:51] op_sel_hi:[1,1,0]
	v_pk_fma_f32 v[40:41], v[24:25], v[40:41], s[56:57] op_sel_hi:[1,1,0]
	v_pk_fma_f32 v[42:43], v[36:37], v[42:43], s[56:57] op_sel_hi:[1,1,0]
	v_pk_mul_f32 v[24:25], v[24:25], v[40:41]
	v_pk_mul_f32 v[36:37], v[36:37], v[42:43]
	v_pk_mul_f32 v[24:25], v[34:35], v[24:25]
	v_pk_mul_f32 v[34:35], v[38:39], v[36:37]
	v_pk_mul_f32 v[36:37], v[8:9], v[24:25]
	v_pk_fma_f32 v[24:25], v[8:9], v[24:25], v[8:9] neg_lo:[1,0,0] neg_hi:[1,0,0]
	v_cmp_gt_f32_e32 vcc, 0, v8
	v_pk_mul_f32 v[38:39], v[4:5], v[34:35]
	v_pk_fma_f32 v[34:35], v[4:5], v[34:35], v[4:5] neg_lo:[1,0,0] neg_hi:[1,0,0]
	v_cndmask_b32_e32 v8, v24, v36, vcc
	v_cmp_gt_f32_e32 vcc, 0, v9
	v_sub_f32_e32 v8, v8, v14
	v_mul_f32_e32 v8, v12, v8
	v_cndmask_b32_e32 v9, v25, v37, vcc
	v_cmp_gt_f32_e32 vcc, 0, v4
	v_sub_f32_e32 v9, v9, v14
	v_mul_f32_e32 v9, v12, v9
	v_cndmask_b32_e32 v4, v34, v38, vcc
	v_cmp_gt_f32_e32 vcc, 0, v5
	v_sub_f32_e32 v4, v4, v15
	v_mul_f32_e32 v4, v13, v4
	v_cndmask_b32_e32 v5, v35, v39, vcc
	v_sub_f32_e32 v5, v5, v15
	ds_write_b32 v70, v3 offset:272
	v_mul_f32_e32 v5, v13, v5
	s_waitcnt vmcnt(0)
	v_fma_f32 v3, v22, v8, v20
	v_fma_f32 v8, v23, v9, v21
	v_fma_f32 v4, v22, v4, v20
	v_cvt_pk_bf16_f32 v3, v3, v4
	v_fmac_f32_e32 v21, v23, v5
	ds_write_b32 v70, v3 offset:544
	v_cvt_pk_bf16_f32 v3, v8, v21
	global_load_dwordx2 v[8:9], v2, s[0:1] offset:16
	global_load_dwordx2 v[4:5], v2, s[4:5] offset:16
	v_lshlrev_b32_e32 v20, 16, v10
	v_and_b32_e32 v21, 0xffff0000, v10
	v_lshlrev_b32_e32 v22, 16, v6
	v_and_b32_e32 v23, 0xffff0000, v6
	v_fma_f32 v24, |v20|, s40, 1.0
	v_fma_f32 v25, |v21|, s40, 1.0
	v_fma_f32 v36, |v22|, s40, 1.0
	v_fma_f32 v37, |v23|, s40, 1.0
	v_rcp_f32_e32 v24, v24
	v_rcp_f32_e32 v25, v25
	v_rcp_f32_e32 v36, v36
	v_rcp_f32_e32 v37, v37
	v_pk_mul_f32 v[34:35], v[20:21], v[20:21]
	v_pk_mul_f32 v[38:39], v[22:23], v[22:23]
	v_pk_mul_f32 v[34:35], v[34:35], s[64:65] op_sel_hi:[1,0]
	v_pk_fma_f32 v[40:41], v[24:25], s[42:43], v[16:17] op_sel_hi:[1,0,0]
	v_pk_mul_f32 v[38:39], v[38:39], s[64:65] op_sel_hi:[1,0]
	v_exp_f32_e32 v34, v34
	v_exp_f32_e32 v35, v35
	v_pk_fma_f32 v[42:43], v[36:37], s[42:43], v[16:17] op_sel_hi:[1,0,0]
	v_pk_fma_f32 v[40:41], v[24:25], v[40:41], s[48:49] op_sel_hi:[1,1,0]
	v_exp_f32_e32 v38, v38
	v_exp_f32_e32 v39, v39
	v_pk_fma_f32 v[42:43], v[36:37], v[42:43], s[48:49] op_sel_hi:[1,1,0]
	v_pk_fma_f32 v[40:41], v[24:25], v[40:41], s[50:51] op_sel_hi:[1,1,0]
	v_pk_fma_f32 v[42:43], v[36:37], v[42:43], s[50:51] op_sel_hi:[1,1,0]
	v_pk_fma_f32 v[40:41], v[24:25], v[40:41], s[56:57] op_sel_hi:[1,1,0]
	v_pk_fma_f32 v[42:43], v[36:37], v[42:43], s[56:57] op_sel_hi:[1,1,0]
	v_pk_mul_f32 v[24:25], v[24:25], v[40:41]
	v_pk_mul_f32 v[36:37], v[36:37], v[42:43]
	v_pk_mul_f32 v[24:25], v[34:35], v[24:25]
	v_pk_mul_f32 v[34:35], v[38:39], v[36:37]
	v_max_f32_e32 v91, 0, v20
	v_fma_f32 v6, -|v20|, v24, v91
	v_max_f32_e32 v92, 0, v21
	v_sub_f32_e32 v6, v6, v14
	v_mul_f32_e32 v6, v12, v6
	v_fma_f32 v10, -|v21|, v25, v92
	v_max_f32_e32 v93, 0, v22
	v_sub_f32_e32 v10, v10, v14
	v_mul_f32_e32 v10, v12, v10
	v_fma_f32 v20, -|v22|, v34, v93
	v_max_f32_e32 v94, 0, v23
	v_sub_f32_e32 v20, v20, v15
	v_mul_f32_e32 v20, v13, v20
	v_fma_f32 v21, -|v23|, v35, v94
	v_sub_f32_e32 v21, v21, v15
	v_mul_f32_e32 v21, v13, v21
	ds_write_b32 v70, v3 offset:816
	s_waitcnt vmcnt(0)
	v_fma_f32 v3, v8, v6, v4
	v_fma_f32 v6, v9, v10, v5
	v_fma_f32 v4, v8, v20, v4
	v_fmac_f32_e32 v5, v9, v21
	v_cvt_pk_bf16_f32 v3, v3, v4
	ds_write_b32 v70, v3 offset:1088
	v_cvt_pk_bf16_f32 v3, v6, v5
	global_load_dwordx2 v[8:9], v2, s[0:1] offset:24
	global_load_dwordx2 v[4:5], v2, s[4:5] offset:24
	v_lshlrev_b32_e32 v10, 16, v11
	v_and_b32_e32 v11, 0xffff0000, v11
	v_lshlrev_b32_e32 v6, 16, v7
	v_and_b32_e32 v7, 0xffff0000, v7
	v_fma_f32 v20, |v10|, s40, 1.0
	v_fma_f32 v21, |v11|, s40, 1.0
	v_fma_f32 v24, |v6|, s40, 1.0
	v_fma_f32 v25, |v7|, s40, 1.0
	v_rcp_f32_e32 v20, v20
	v_rcp_f32_e32 v21, v21
	v_rcp_f32_e32 v24, v24
	v_rcp_f32_e32 v25, v25
	v_pk_mul_f32 v[22:23], v[10:11], v[10:11]
	v_pk_mul_f32 v[34:35], v[6:7], v[6:7]
	v_pk_mul_f32 v[22:23], v[22:23], s[64:65] op_sel_hi:[1,0]
	v_pk_fma_f32 v[36:37], v[20:21], s[42:43], v[16:17] op_sel_hi:[1,0,0]
	v_pk_mul_f32 v[34:35], v[34:35], s[64:65] op_sel_hi:[1,0]
	v_exp_f32_e32 v22, v22
	v_exp_f32_e32 v23, v23
	v_pk_fma_f32 v[38:39], v[24:25], s[42:43], v[16:17] op_sel_hi:[1,0,0]
	v_pk_fma_f32 v[36:37], v[20:21], v[36:37], s[48:49] op_sel_hi:[1,1,0]
	v_exp_f32_e32 v34, v34
	v_exp_f32_e32 v35, v35
	v_pk_fma_f32 v[38:39], v[24:25], v[38:39], s[48:49] op_sel_hi:[1,1,0]
	v_pk_fma_f32 v[36:37], v[20:21], v[36:37], s[50:51] op_sel_hi:[1,1,0]
	v_pk_fma_f32 v[38:39], v[24:25], v[38:39], s[50:51] op_sel_hi:[1,1,0]
	v_pk_fma_f32 v[36:37], v[20:21], v[36:37], s[56:57] op_sel_hi:[1,1,0]
	v_pk_fma_f32 v[38:39], v[24:25], v[38:39], s[56:57] op_sel_hi:[1,1,0]
	v_pk_mul_f32 v[20:21], v[20:21], v[36:37]
	v_pk_mul_f32 v[24:25], v[24:25], v[38:39]
	v_pk_mul_f32 v[20:21], v[22:23], v[20:21]
	v_pk_mul_f32 v[22:23], v[34:35], v[24:25]
	v_pk_mul_f32 v[24:25], v[10:11], v[20:21]
	v_pk_fma_f32 v[20:21], v[10:11], v[20:21], v[10:11] neg_lo:[1,0,0] neg_hi:[1,0,0]
	v_cmp_gt_f32_e32 vcc, 0, v10
	v_pk_mul_f32 v[34:35], v[6:7], v[22:23]
	v_pk_fma_f32 v[22:23], v[6:7], v[22:23], v[6:7] neg_lo:[1,0,0] neg_hi:[1,0,0]
	v_cndmask_b32_e32 v10, v20, v24, vcc
	v_cmp_gt_f32_e32 vcc, 0, v11
	v_sub_f32_e32 v10, v10, v14
	v_mul_f32_e32 v10, v12, v10
	v_cndmask_b32_e32 v11, v21, v25, vcc
	v_cmp_gt_f32_e32 vcc, 0, v6
	v_sub_f32_e32 v11, v11, v14
	v_mul_f32_e32 v11, v12, v11
	v_cndmask_b32_e32 v6, v22, v34, vcc
	v_cmp_gt_f32_e32 vcc, 0, v7
	v_sub_f32_e32 v6, v6, v15
	v_mul_f32_e32 v6, v13, v6
	v_cndmask_b32_e32 v7, v23, v35, vcc
	v_sub_f32_e32 v7, v7, v15
	v_mul_f32_e32 v7, v13, v7
	ds_write_b32 v70, v3 offset:1360
	s_waitcnt vmcnt(0)
	v_fma_f32 v3, v8, v10, v4
	v_fma_f32 v10, v9, v11, v5
	v_fma_f32 v4, v8, v6, v4
	v_fmac_f32_e32 v5, v9, v7
	v_cvt_pk_bf16_f32 v3, v3, v4
	ds_write_b32 v70, v3 offset:1632
	v_cvt_pk_bf16_f32 v3, v10, v5
	global_load_dwordx4 v[8:11], v[18:19], off offset:16
	global_load_dwordx4 v[4:7], v[18:19], off offset:2064
	global_load_dwordx2 v[22:23], v2, s[0:1] offset:32
	global_load_dwordx2 v[20:21], v2, s[4:5] offset:32
	ds_write_b32 v70, v3 offset:1904
	s_waitcnt vmcnt(3)
	v_lshlrev_b32_e32 v24, 16, v8
	v_and_b32_e32 v25, 0xffff0000, v8
	s_waitcnt vmcnt(2)
	v_lshlrev_b32_e32 v34, 16, v4
	v_and_b32_e32 v35, 0xffff0000, v4
	v_fma_f32 v36, |v24|, s40, 1.0
	v_fma_f32 v37, |v25|, s40, 1.0
	v_fma_f32 v40, |v34|, s40, 1.0
	v_fma_f32 v41, |v35|, s40, 1.0
	v_rcp_f32_e32 v36, v36
	v_rcp_f32_e32 v37, v37
	v_rcp_f32_e32 v40, v40
	v_rcp_f32_e32 v41, v41
	v_pk_mul_f32 v[38:39], v[24:25], v[24:25]
	v_pk_mul_f32 v[42:43], v[34:35], v[34:35]
	v_pk_mul_f32 v[38:39], v[38:39], s[64:65] op_sel_hi:[1,0]
	v_pk_fma_f32 v[44:45], v[36:37], s[42:43], v[16:17] op_sel_hi:[1,0,0]
	v_pk_mul_f32 v[42:43], v[42:43], s[64:65] op_sel_hi:[1,0]
	v_exp_f32_e32 v38, v38
	v_exp_f32_e32 v39, v39
	v_pk_fma_f32 v[46:47], v[40:41], s[42:43], v[16:17] op_sel_hi:[1,0,0]
	v_pk_fma_f32 v[44:45], v[36:37], v[44:45], s[48:49] op_sel_hi:[1,1,0]
	v_exp_f32_e32 v42, v42
	v_exp_f32_e32 v43, v43
	v_pk_fma_f32 v[46:47], v[40:41], v[46:47], s[48:49] op_sel_hi:[1,1,0]
	v_pk_fma_f32 v[44:45], v[36:37], v[44:45], s[50:51] op_sel_hi:[1,1,0]
	v_pk_fma_f32 v[46:47], v[40:41], v[46:47], s[50:51] op_sel_hi:[1,1,0]
	v_pk_fma_f32 v[44:45], v[36:37], v[44:45], s[56:57] op_sel_hi:[1,1,0]
	v_pk_fma_f32 v[46:47], v[40:41], v[46:47], s[56:57] op_sel_hi:[1,1,0]
	v_pk_mul_f32 v[36:37], v[36:37], v[44:45]
	v_pk_mul_f32 v[40:41], v[40:41], v[46:47]
	v_pk_mul_f32 v[36:37], v[38:39], v[36:37]
	v_pk_mul_f32 v[38:39], v[42:43], v[40:41]
	v_max_f32_e32 v95, 0, v24
	v_fma_f32 v3, -|v24|, v36, v95
	v_max_f32_e32 v96, 0, v25
	v_sub_f32_e32 v3, v3, v14
	v_mul_f32_e32 v3, v12, v3
	v_fma_f32 v4, -|v25|, v37, v96
	v_max_f32_e32 v97, 0, v34
	v_sub_f32_e32 v4, v4, v14
	v_mul_f32_e32 v4, v12, v4
	v_fma_f32 v8, -|v34|, v38, v97
	v_max_f32_e32 v98, 0, v35
	v_sub_f32_e32 v8, v8, v15
	v_mul_f32_e32 v8, v13, v8
	v_fma_f32 v24, -|v35|, v39, v98
	v_sub_f32_e32 v24, v24, v15
	v_mul_f32_e32 v24, v13, v24
	s_waitcnt vmcnt(0)
	v_fma_f32 v3, v22, v3, v20
	v_fma_f32 v4, v23, v4, v21
	v_fma_f32 v8, v22, v8, v20
	v_fmac_f32_e32 v21, v23, v24
	v_cvt_pk_bf16_f32 v3, v3, v8
	ds_write_b32 v70, v3 offset:2176
	v_cvt_pk_bf16_f32 v3, v4, v21
	global_load_dwordx2 v[22:23], v2, s[0:1] offset:40
	global_load_dwordx2 v[20:21], v2, s[4:5] offset:40
	v_lshlrev_b32_e32 v8, 16, v9
	v_and_b32_e32 v9, 0xffff0000, v9
	v_lshlrev_b32_e32 v4, 16, v5
	v_and_b32_e32 v5, 0xffff0000, v5
	v_fma_f32 v24, |v8|, s40, 1.0
	v_fma_f32 v25, |v9|, s40, 1.0
	v_fma_f32 v36, |v4|, s40, 1.0
	v_fma_f32 v37, |v5|, s40, 1.0
	v_rcp_f32_e32 v24, v24
	v_rcp_f32_e32 v25, v25
	v_rcp_f32_e32 v36, v36
	v_rcp_f32_e32 v37, v37
	v_pk_mul_f32 v[34:35], v[8:9], v[8:9]
	v_pk_mul_f32 v[38:39], v[4:5], v[4:5]
	v_pk_mul_f32 v[34:35], v[34:35], s[64:65] op_sel_hi:[1,0]
	v_pk_fma_f32 v[40:41], v[24:25], s[42:43], v[16:17] op_sel_hi:[1,0,0]
	v_pk_mul_f32 v[38:39], v[38:39], s[64:65] op_sel_hi:[1,0]
	v_exp_f32_e32 v34, v34
	v_exp_f32_e32 v35, v35
	v_pk_fma_f32 v[42:43], v[36:37], s[42:43], v[16:17] op_sel_hi:[1,0,0]
	v_pk_fma_f32 v[40:41], v[24:25], v[40:41], s[48:49] op_sel_hi:[1,1,0]
	v_exp_f32_e32 v38, v38
	v_exp_f32_e32 v39, v39
	v_pk_fma_f32 v[42:43], v[36:37], v[42:43], s[48:49] op_sel_hi:[1,1,0]
	v_pk_fma_f32 v[40:41], v[24:25], v[40:41], s[50:51] op_sel_hi:[1,1,0]
	v_pk_fma_f32 v[42:43], v[36:37], v[42:43], s[50:51] op_sel_hi:[1,1,0]
	v_pk_fma_f32 v[40:41], v[24:25], v[40:41], s[56:57] op_sel_hi:[1,1,0]
	v_pk_fma_f32 v[42:43], v[36:37], v[42:43], s[56:57] op_sel_hi:[1,1,0]
	v_pk_mul_f32 v[24:25], v[24:25], v[40:41]
	v_pk_mul_f32 v[36:37], v[36:37], v[42:43]
	v_pk_mul_f32 v[24:25], v[34:35], v[24:25]
	v_pk_mul_f32 v[34:35], v[38:39], v[36:37]
	v_pk_mul_f32 v[36:37], v[8:9], v[24:25]
	v_pk_fma_f32 v[24:25], v[8:9], v[24:25], v[8:9] neg_lo:[1,0,0] neg_hi:[1,0,0]
	v_cmp_gt_f32_e32 vcc, 0, v8
	v_pk_mul_f32 v[38:39], v[4:5], v[34:35]
	v_pk_fma_f32 v[34:35], v[4:5], v[34:35], v[4:5] neg_lo:[1,0,0] neg_hi:[1,0,0]
	v_cndmask_b32_e32 v8, v24, v36, vcc
	v_cmp_gt_f32_e32 vcc, 0, v9
	v_sub_f32_e32 v8, v8, v14
	v_mul_f32_e32 v8, v12, v8
	v_cndmask_b32_e32 v9, v25, v37, vcc
	v_cmp_gt_f32_e32 vcc, 0, v4
	v_sub_f32_e32 v9, v9, v14
	v_mul_f32_e32 v9, v12, v9
	v_cndmask_b32_e32 v4, v34, v38, vcc
	v_cmp_gt_f32_e32 vcc, 0, v5
	v_sub_f32_e32 v4, v4, v15
	v_mul_f32_e32 v4, v13, v4
	v_cndmask_b32_e32 v5, v35, v39, vcc
	v_sub_f32_e32 v5, v5, v15
	ds_write_b32 v70, v3 offset:2448
	v_mul_f32_e32 v5, v13, v5
	s_waitcnt vmcnt(0)
	v_fma_f32 v3, v22, v8, v20
	v_fma_f32 v8, v23, v9, v21
	v_fma_f32 v4, v22, v4, v20
	v_cvt_pk_bf16_f32 v3, v3, v4
	v_fmac_f32_e32 v21, v23, v5
	ds_write_b32 v70, v3 offset:2720
	v_cvt_pk_bf16_f32 v3, v8, v21
	global_load_dwordx2 v[8:9], v2, s[0:1] offset:48
	global_load_dwordx2 v[4:5], v2, s[4:5] offset:48
	v_lshlrev_b32_e32 v20, 16, v10
	v_and_b32_e32 v21, 0xffff0000, v10
	v_lshlrev_b32_e32 v22, 16, v6
	v_and_b32_e32 v23, 0xffff0000, v6
	v_fma_f32 v24, |v20|, s40, 1.0
	v_fma_f32 v25, |v21|, s40, 1.0
	v_fma_f32 v36, |v22|, s40, 1.0
	v_fma_f32 v37, |v23|, s40, 1.0
	v_rcp_f32_e32 v24, v24
	v_rcp_f32_e32 v25, v25
	v_rcp_f32_e32 v36, v36
	v_rcp_f32_e32 v37, v37
	v_pk_mul_f32 v[34:35], v[20:21], v[20:21]
	v_pk_mul_f32 v[38:39], v[22:23], v[22:23]
	v_pk_mul_f32 v[34:35], v[34:35], s[64:65] op_sel_hi:[1,0]
	v_pk_fma_f32 v[40:41], v[24:25], s[42:43], v[16:17] op_sel_hi:[1,0,0]
	v_pk_mul_f32 v[38:39], v[38:39], s[64:65] op_sel_hi:[1,0]
	v_exp_f32_e32 v34, v34
	v_exp_f32_e32 v35, v35
	v_pk_fma_f32 v[42:43], v[36:37], s[42:43], v[16:17] op_sel_hi:[1,0,0]
	v_pk_fma_f32 v[40:41], v[24:25], v[40:41], s[48:49] op_sel_hi:[1,1,0]
	v_exp_f32_e32 v38, v38
	v_exp_f32_e32 v39, v39
	v_pk_fma_f32 v[42:43], v[36:37], v[42:43], s[48:49] op_sel_hi:[1,1,0]
	v_pk_fma_f32 v[40:41], v[24:25], v[40:41], s[50:51] op_sel_hi:[1,1,0]
	v_pk_fma_f32 v[42:43], v[36:37], v[42:43], s[50:51] op_sel_hi:[1,1,0]
	v_pk_fma_f32 v[40:41], v[24:25], v[40:41], s[56:57] op_sel_hi:[1,1,0]
	v_pk_fma_f32 v[42:43], v[36:37], v[42:43], s[56:57] op_sel_hi:[1,1,0]
	v_pk_mul_f32 v[24:25], v[24:25], v[40:41]
	v_pk_mul_f32 v[36:37], v[36:37], v[42:43]
	v_pk_mul_f32 v[24:25], v[34:35], v[24:25]
	v_pk_mul_f32 v[34:35], v[38:39], v[36:37]
	v_max_f32_e32 v99, 0, v20
	v_fma_f32 v6, -|v20|, v24, v99
	v_max_f32_e32 v100, 0, v21
	v_sub_f32_e32 v6, v6, v14
	v_mul_f32_e32 v6, v12, v6
	v_fma_f32 v10, -|v21|, v25, v100
	v_max_f32_e32 v104, 0, v22
	v_sub_f32_e32 v10, v10, v14
	v_mul_f32_e32 v10, v12, v10
	v_fma_f32 v20, -|v22|, v34, v104
	v_max_f32_e32 v105, 0, v23
	v_sub_f32_e32 v20, v20, v15
	v_mul_f32_e32 v20, v13, v20
	v_fma_f32 v21, -|v23|, v35, v105
	v_sub_f32_e32 v21, v21, v15
	v_mul_f32_e32 v21, v13, v21
	ds_write_b32 v70, v3 offset:2992
	s_waitcnt vmcnt(0)
	v_fma_f32 v3, v8, v6, v4
	v_fma_f32 v6, v9, v10, v5
	v_fma_f32 v4, v8, v20, v4
	v_fmac_f32_e32 v5, v9, v21
	v_cvt_pk_bf16_f32 v3, v3, v4
	ds_write_b32 v70, v3 offset:3264
	v_cvt_pk_bf16_f32 v3, v6, v5
	global_load_dwordx2 v[8:9], v2, s[0:1] offset:56
	global_load_dwordx2 v[4:5], v2, s[4:5] offset:56
	v_lshlrev_b32_e32 v10, 16, v11
	v_and_b32_e32 v11, 0xffff0000, v11
	v_lshlrev_b32_e32 v6, 16, v7
	v_and_b32_e32 v7, 0xffff0000, v7
	v_fma_f32 v20, |v10|, s40, 1.0
	v_fma_f32 v21, |v11|, s40, 1.0
	v_fma_f32 v24, |v6|, s40, 1.0
	v_fma_f32 v25, |v7|, s40, 1.0
	v_rcp_f32_e32 v20, v20
	v_rcp_f32_e32 v21, v21
	v_rcp_f32_e32 v24, v24
	v_rcp_f32_e32 v25, v25
	v_pk_mul_f32 v[22:23], v[10:11], v[10:11]
	v_pk_mul_f32 v[34:35], v[6:7], v[6:7]
	v_pk_mul_f32 v[22:23], v[22:23], s[64:65] op_sel_hi:[1,0]
	v_pk_fma_f32 v[36:37], v[20:21], s[42:43], v[16:17] op_sel_hi:[1,0,0]
	v_pk_mul_f32 v[34:35], v[34:35], s[64:65] op_sel_hi:[1,0]
	v_exp_f32_e32 v22, v22
	v_exp_f32_e32 v23, v23
	v_pk_fma_f32 v[38:39], v[24:25], s[42:43], v[16:17] op_sel_hi:[1,0,0]
	v_pk_fma_f32 v[36:37], v[20:21], v[36:37], s[48:49] op_sel_hi:[1,1,0]
	v_exp_f32_e32 v34, v34
	v_exp_f32_e32 v35, v35
	v_pk_fma_f32 v[38:39], v[24:25], v[38:39], s[48:49] op_sel_hi:[1,1,0]
	v_pk_fma_f32 v[36:37], v[20:21], v[36:37], s[50:51] op_sel_hi:[1,1,0]
	v_pk_fma_f32 v[38:39], v[24:25], v[38:39], s[50:51] op_sel_hi:[1,1,0]
	v_pk_fma_f32 v[36:37], v[20:21], v[36:37], s[56:57] op_sel_hi:[1,1,0]
	v_pk_fma_f32 v[38:39], v[24:25], v[38:39], s[56:57] op_sel_hi:[1,1,0]
	v_pk_mul_f32 v[20:21], v[20:21], v[36:37]
	v_pk_mul_f32 v[24:25], v[24:25], v[38:39]
	v_pk_mul_f32 v[20:21], v[22:23], v[20:21]
	v_pk_mul_f32 v[22:23], v[34:35], v[24:25]
	v_pk_mul_f32 v[24:25], v[10:11], v[20:21]
	v_pk_fma_f32 v[20:21], v[10:11], v[20:21], v[10:11] neg_lo:[1,0,0] neg_hi:[1,0,0]
	v_cmp_gt_f32_e32 vcc, 0, v10
	v_pk_mul_f32 v[34:35], v[6:7], v[22:23]
	v_pk_fma_f32 v[22:23], v[6:7], v[22:23], v[6:7] neg_lo:[1,0,0] neg_hi:[1,0,0]
	v_cndmask_b32_e32 v10, v20, v24, vcc
	v_cmp_gt_f32_e32 vcc, 0, v11
	v_sub_f32_e32 v10, v10, v14
	v_mul_f32_e32 v10, v12, v10
	v_cndmask_b32_e32 v11, v21, v25, vcc
	v_cmp_gt_f32_e32 vcc, 0, v6
	v_sub_f32_e32 v11, v11, v14
	v_mul_f32_e32 v11, v12, v11
	v_cndmask_b32_e32 v6, v22, v34, vcc
	v_cmp_gt_f32_e32 vcc, 0, v7
	v_sub_f32_e32 v6, v6, v15
	v_mul_f32_e32 v6, v13, v6
	v_cndmask_b32_e32 v7, v23, v35, vcc
	v_sub_f32_e32 v7, v7, v15
	v_mul_f32_e32 v7, v13, v7
	ds_write_b32 v70, v3 offset:3536
	s_waitcnt vmcnt(0)
	v_fma_f32 v3, v8, v10, v4
	v_fma_f32 v10, v9, v11, v5
	v_fma_f32 v4, v8, v6, v4
	v_fmac_f32_e32 v5, v9, v7
	v_cvt_pk_bf16_f32 v3, v3, v4
	ds_write_b32 v70, v3 offset:3808
	v_cvt_pk_bf16_f32 v3, v10, v5
	global_load_dwordx4 v[8:11], v[18:19], off offset:32
	global_load_dwordx4 v[4:7], v[18:19], off offset:2080
	global_load_dwordx2 v[22:23], v2, s[0:1] offset:64
	global_load_dwordx2 v[20:21], v2, s[4:5] offset:64
	ds_write_b32 v70, v3 offset:4080
	s_waitcnt vmcnt(3)
	v_lshlrev_b32_e32 v24, 16, v8
	v_and_b32_e32 v25, 0xffff0000, v8
	s_waitcnt vmcnt(2)
	v_lshlrev_b32_e32 v34, 16, v4
	v_and_b32_e32 v35, 0xffff0000, v4
	v_fma_f32 v36, |v24|, s40, 1.0
	v_fma_f32 v37, |v25|, s40, 1.0
	v_fma_f32 v40, |v34|, s40, 1.0
	v_fma_f32 v41, |v35|, s40, 1.0
	v_rcp_f32_e32 v36, v36
	v_rcp_f32_e32 v37, v37
	v_rcp_f32_e32 v40, v40
	v_rcp_f32_e32 v41, v41
	v_pk_mul_f32 v[38:39], v[24:25], v[24:25]
	v_pk_mul_f32 v[42:43], v[34:35], v[34:35]
	v_pk_mul_f32 v[38:39], v[38:39], s[64:65] op_sel_hi:[1,0]
	v_pk_fma_f32 v[44:45], v[36:37], s[42:43], v[16:17] op_sel_hi:[1,0,0]
	v_pk_mul_f32 v[42:43], v[42:43], s[64:65] op_sel_hi:[1,0]
	v_exp_f32_e32 v38, v38
	v_exp_f32_e32 v39, v39
	v_pk_fma_f32 v[46:47], v[40:41], s[42:43], v[16:17] op_sel_hi:[1,0,0]
	v_pk_fma_f32 v[44:45], v[36:37], v[44:45], s[48:49] op_sel_hi:[1,1,0]
	v_exp_f32_e32 v42, v42
	v_exp_f32_e32 v43, v43
	v_pk_fma_f32 v[46:47], v[40:41], v[46:47], s[48:49] op_sel_hi:[1,1,0]
	v_pk_fma_f32 v[44:45], v[36:37], v[44:45], s[50:51] op_sel_hi:[1,1,0]
	v_pk_fma_f32 v[46:47], v[40:41], v[46:47], s[50:51] op_sel_hi:[1,1,0]
	v_pk_fma_f32 v[44:45], v[36:37], v[44:45], s[56:57] op_sel_hi:[1,1,0]
	v_pk_fma_f32 v[46:47], v[40:41], v[46:47], s[56:57] op_sel_hi:[1,1,0]
	v_pk_mul_f32 v[36:37], v[36:37], v[44:45]
	v_pk_mul_f32 v[40:41], v[40:41], v[46:47]
	v_pk_mul_f32 v[36:37], v[38:39], v[36:37]
	v_pk_mul_f32 v[38:39], v[42:43], v[40:41]
	v_max_f32_e32 v106, 0, v24
	v_fma_f32 v3, -|v24|, v36, v106
	v_max_f32_e32 v107, 0, v25
	v_sub_f32_e32 v3, v3, v14
	v_mul_f32_e32 v3, v12, v3
	v_fma_f32 v4, -|v25|, v37, v107
	v_max_f32_e32 v108, 0, v34
	v_sub_f32_e32 v4, v4, v14
	v_mul_f32_e32 v4, v12, v4
	v_fma_f32 v8, -|v34|, v38, v108
	v_max_f32_e32 v109, 0, v35
	v_sub_f32_e32 v8, v8, v15
	v_mul_f32_e32 v8, v13, v8
	v_fma_f32 v24, -|v35|, v39, v109
	v_sub_f32_e32 v24, v24, v15
	v_mul_f32_e32 v24, v13, v24
	s_waitcnt vmcnt(0)
	v_fma_f32 v3, v22, v3, v20
	v_fma_f32 v4, v23, v4, v21
	v_fma_f32 v8, v22, v8, v20
	v_fmac_f32_e32 v21, v23, v24
	v_cvt_pk_bf16_f32 v3, v3, v8
	ds_write_b32 v70, v3 offset:4352
	v_cvt_pk_bf16_f32 v3, v4, v21
	global_load_dwordx2 v[22:23], v2, s[0:1] offset:72
	global_load_dwordx2 v[20:21], v2, s[4:5] offset:72
	v_lshlrev_b32_e32 v8, 16, v9
	v_and_b32_e32 v9, 0xffff0000, v9
	v_lshlrev_b32_e32 v4, 16, v5
	v_and_b32_e32 v5, 0xffff0000, v5
	v_fma_f32 v24, |v8|, s40, 1.0
	v_fma_f32 v25, |v9|, s40, 1.0
	v_fma_f32 v36, |v4|, s40, 1.0
	v_fma_f32 v37, |v5|, s40, 1.0
	v_rcp_f32_e32 v24, v24
	v_rcp_f32_e32 v25, v25
	v_rcp_f32_e32 v36, v36
	v_rcp_f32_e32 v37, v37
	v_pk_mul_f32 v[34:35], v[8:9], v[8:9]
	v_pk_mul_f32 v[38:39], v[4:5], v[4:5]
	v_pk_mul_f32 v[34:35], v[34:35], s[64:65] op_sel_hi:[1,0]
	v_pk_fma_f32 v[40:41], v[24:25], s[42:43], v[16:17] op_sel_hi:[1,0,0]
	v_pk_mul_f32 v[38:39], v[38:39], s[64:65] op_sel_hi:[1,0]
	v_exp_f32_e32 v34, v34
	v_exp_f32_e32 v35, v35
	v_pk_fma_f32 v[42:43], v[36:37], s[42:43], v[16:17] op_sel_hi:[1,0,0]
	v_pk_fma_f32 v[40:41], v[24:25], v[40:41], s[48:49] op_sel_hi:[1,1,0]
	v_exp_f32_e32 v38, v38
	v_exp_f32_e32 v39, v39
	v_pk_fma_f32 v[42:43], v[36:37], v[42:43], s[48:49] op_sel_hi:[1,1,0]
	v_pk_fma_f32 v[40:41], v[24:25], v[40:41], s[50:51] op_sel_hi:[1,1,0]
	v_pk_fma_f32 v[42:43], v[36:37], v[42:43], s[50:51] op_sel_hi:[1,1,0]
	v_pk_fma_f32 v[40:41], v[24:25], v[40:41], s[56:57] op_sel_hi:[1,1,0]
	v_pk_fma_f32 v[42:43], v[36:37], v[42:43], s[56:57] op_sel_hi:[1,1,0]
	v_pk_mul_f32 v[24:25], v[24:25], v[40:41]
	v_pk_mul_f32 v[36:37], v[36:37], v[42:43]
	v_pk_mul_f32 v[24:25], v[34:35], v[24:25]
	v_pk_mul_f32 v[34:35], v[38:39], v[36:37]
	v_pk_mul_f32 v[36:37], v[8:9], v[24:25]
	v_pk_fma_f32 v[24:25], v[8:9], v[24:25], v[8:9] neg_lo:[1,0,0] neg_hi:[1,0,0]
	v_cmp_gt_f32_e32 vcc, 0, v8
	v_pk_mul_f32 v[38:39], v[4:5], v[34:35]
	v_pk_fma_f32 v[34:35], v[4:5], v[34:35], v[4:5] neg_lo:[1,0,0] neg_hi:[1,0,0]
	v_cndmask_b32_e32 v8, v24, v36, vcc
	v_cmp_gt_f32_e32 vcc, 0, v9
	v_sub_f32_e32 v8, v8, v14
	v_mul_f32_e32 v8, v12, v8
	v_cndmask_b32_e32 v9, v25, v37, vcc
	v_cmp_gt_f32_e32 vcc, 0, v4
	v_sub_f32_e32 v9, v9, v14
	v_mul_f32_e32 v9, v12, v9
	v_cndmask_b32_e32 v4, v34, v38, vcc
	v_cmp_gt_f32_e32 vcc, 0, v5
	v_sub_f32_e32 v4, v4, v15
	v_mul_f32_e32 v4, v13, v4
	v_cndmask_b32_e32 v5, v35, v39, vcc
	v_sub_f32_e32 v5, v5, v15
	ds_write_b32 v70, v3 offset:4624
	v_mul_f32_e32 v5, v13, v5
	s_waitcnt vmcnt(0)
	v_fma_f32 v3, v22, v8, v20
	v_fma_f32 v8, v23, v9, v21
	v_fma_f32 v4, v22, v4, v20
	v_cvt_pk_bf16_f32 v3, v3, v4
	v_fmac_f32_e32 v21, v23, v5
	ds_write_b32 v70, v3 offset:4896
	v_cvt_pk_bf16_f32 v3, v8, v21
	global_load_dwordx2 v[8:9], v2, s[0:1] offset:80
	global_load_dwordx2 v[4:5], v2, s[4:5] offset:80
	v_lshlrev_b32_e32 v20, 16, v10
	v_and_b32_e32 v21, 0xffff0000, v10
	v_lshlrev_b32_e32 v22, 16, v6
	v_and_b32_e32 v23, 0xffff0000, v6
	v_fma_f32 v24, |v20|, s40, 1.0
	v_fma_f32 v25, |v21|, s40, 1.0
	v_fma_f32 v36, |v22|, s40, 1.0
	v_fma_f32 v37, |v23|, s40, 1.0
	v_rcp_f32_e32 v24, v24
	v_rcp_f32_e32 v25, v25
	v_rcp_f32_e32 v36, v36
	v_rcp_f32_e32 v37, v37
	v_pk_mul_f32 v[34:35], v[20:21], v[20:21]
	v_pk_mul_f32 v[38:39], v[22:23], v[22:23]
	v_pk_mul_f32 v[34:35], v[34:35], s[64:65] op_sel_hi:[1,0]
	v_pk_fma_f32 v[40:41], v[24:25], s[42:43], v[16:17] op_sel_hi:[1,0,0]
	v_pk_mul_f32 v[38:39], v[38:39], s[64:65] op_sel_hi:[1,0]
	v_exp_f32_e32 v34, v34
	v_exp_f32_e32 v35, v35
	v_pk_fma_f32 v[42:43], v[36:37], s[42:43], v[16:17] op_sel_hi:[1,0,0]
	v_pk_fma_f32 v[40:41], v[24:25], v[40:41], s[48:49] op_sel_hi:[1,1,0]
	v_exp_f32_e32 v38, v38
	v_exp_f32_e32 v39, v39
	v_pk_fma_f32 v[42:43], v[36:37], v[42:43], s[48:49] op_sel_hi:[1,1,0]
	v_pk_fma_f32 v[40:41], v[24:25], v[40:41], s[50:51] op_sel_hi:[1,1,0]
	v_pk_fma_f32 v[42:43], v[36:37], v[42:43], s[50:51] op_sel_hi:[1,1,0]
	v_pk_fma_f32 v[40:41], v[24:25], v[40:41], s[56:57] op_sel_hi:[1,1,0]
	v_pk_fma_f32 v[42:43], v[36:37], v[42:43], s[56:57] op_sel_hi:[1,1,0]
	v_pk_mul_f32 v[24:25], v[24:25], v[40:41]
	v_pk_mul_f32 v[36:37], v[36:37], v[42:43]
	v_pk_mul_f32 v[24:25], v[34:35], v[24:25]
	v_pk_mul_f32 v[34:35], v[38:39], v[36:37]
	v_max_f32_e32 v110, 0, v20
	v_fma_f32 v6, -|v20|, v24, v110
	v_max_f32_e32 v111, 0, v21
	v_sub_f32_e32 v6, v6, v14
	v_mul_f32_e32 v6, v12, v6
	v_fma_f32 v10, -|v21|, v25, v111
	v_max_f32_e32 v112, 0, v22
	v_sub_f32_e32 v10, v10, v14
	v_mul_f32_e32 v10, v12, v10
	v_fma_f32 v20, -|v22|, v34, v112
	v_max_f32_e32 v113, 0, v23
	v_sub_f32_e32 v20, v20, v15
	v_mul_f32_e32 v20, v13, v20
	v_fma_f32 v21, -|v23|, v35, v113
	v_sub_f32_e32 v21, v21, v15
	v_mul_f32_e32 v21, v13, v21
	ds_write_b32 v70, v3 offset:5168
	s_waitcnt vmcnt(0)
	v_fma_f32 v3, v8, v6, v4
	v_fma_f32 v6, v9, v10, v5
	v_fma_f32 v4, v8, v20, v4
	v_fmac_f32_e32 v5, v9, v21
	v_cvt_pk_bf16_f32 v3, v3, v4
	ds_write_b32 v70, v3 offset:5440
	v_cvt_pk_bf16_f32 v3, v6, v5
	global_load_dwordx2 v[8:9], v2, s[0:1] offset:88
	global_load_dwordx2 v[4:5], v2, s[4:5] offset:88
	v_lshlrev_b32_e32 v10, 16, v11
	v_and_b32_e32 v11, 0xffff0000, v11
	v_lshlrev_b32_e32 v6, 16, v7
	v_and_b32_e32 v7, 0xffff0000, v7
	v_fma_f32 v20, |v10|, s40, 1.0
	v_fma_f32 v21, |v11|, s40, 1.0
	v_fma_f32 v24, |v6|, s40, 1.0
	v_fma_f32 v25, |v7|, s40, 1.0
	v_rcp_f32_e32 v20, v20
	v_rcp_f32_e32 v21, v21
	v_rcp_f32_e32 v24, v24
	v_rcp_f32_e32 v25, v25
	v_pk_mul_f32 v[22:23], v[10:11], v[10:11]
	v_pk_mul_f32 v[34:35], v[6:7], v[6:7]
	v_pk_mul_f32 v[22:23], v[22:23], s[64:65] op_sel_hi:[1,0]
	v_pk_fma_f32 v[36:37], v[20:21], s[42:43], v[16:17] op_sel_hi:[1,0,0]
	v_pk_mul_f32 v[34:35], v[34:35], s[64:65] op_sel_hi:[1,0]
	v_exp_f32_e32 v22, v22
	v_exp_f32_e32 v23, v23
	v_pk_fma_f32 v[38:39], v[24:25], s[42:43], v[16:17] op_sel_hi:[1,0,0]
	v_pk_fma_f32 v[36:37], v[20:21], v[36:37], s[48:49] op_sel_hi:[1,1,0]
	v_exp_f32_e32 v34, v34
	v_exp_f32_e32 v35, v35
	v_pk_fma_f32 v[38:39], v[24:25], v[38:39], s[48:49] op_sel_hi:[1,1,0]
	v_pk_fma_f32 v[36:37], v[20:21], v[36:37], s[50:51] op_sel_hi:[1,1,0]
	v_pk_fma_f32 v[38:39], v[24:25], v[38:39], s[50:51] op_sel_hi:[1,1,0]
	v_pk_fma_f32 v[36:37], v[20:21], v[36:37], s[56:57] op_sel_hi:[1,1,0]
	v_pk_fma_f32 v[38:39], v[24:25], v[38:39], s[56:57] op_sel_hi:[1,1,0]
	v_pk_mul_f32 v[20:21], v[20:21], v[36:37]
	v_pk_mul_f32 v[24:25], v[24:25], v[38:39]
	v_pk_mul_f32 v[20:21], v[22:23], v[20:21]
	v_pk_mul_f32 v[22:23], v[34:35], v[24:25]
	v_pk_mul_f32 v[24:25], v[10:11], v[20:21]
	v_pk_fma_f32 v[20:21], v[10:11], v[20:21], v[10:11] neg_lo:[1,0,0] neg_hi:[1,0,0]
	v_cmp_gt_f32_e32 vcc, 0, v10
	v_pk_mul_f32 v[34:35], v[6:7], v[22:23]
	v_pk_fma_f32 v[22:23], v[6:7], v[22:23], v[6:7] neg_lo:[1,0,0] neg_hi:[1,0,0]
	v_cndmask_b32_e32 v10, v20, v24, vcc
	v_cmp_gt_f32_e32 vcc, 0, v11
	v_sub_f32_e32 v10, v10, v14
	v_mul_f32_e32 v10, v12, v10
	v_cndmask_b32_e32 v11, v21, v25, vcc
	v_cmp_gt_f32_e32 vcc, 0, v6
	v_sub_f32_e32 v11, v11, v14
	v_mul_f32_e32 v11, v12, v11
	v_cndmask_b32_e32 v6, v22, v34, vcc
	v_cmp_gt_f32_e32 vcc, 0, v7
	v_sub_f32_e32 v6, v6, v15
	v_mul_f32_e32 v6, v13, v6
	v_cndmask_b32_e32 v7, v23, v35, vcc
	v_sub_f32_e32 v7, v7, v15
	v_mul_f32_e32 v7, v13, v7
	ds_write_b32 v70, v3 offset:5712
	s_waitcnt vmcnt(0)
	v_fma_f32 v3, v8, v10, v4
	v_fma_f32 v10, v9, v11, v5
	v_fma_f32 v4, v8, v6, v4
	v_fmac_f32_e32 v5, v9, v7
	v_cvt_pk_bf16_f32 v3, v3, v4
	ds_write_b32 v70, v3 offset:5984
	v_cvt_pk_bf16_f32 v3, v10, v5
	global_load_dwordx4 v[8:11], v[18:19], off offset:48
	global_load_dwordx4 v[4:7], v[18:19], off offset:2096
	global_load_dwordx2 v[20:21], v2, s[0:1] offset:96
	s_nop 0
	global_load_dwordx2 v[18:19], v2, s[4:5] offset:96
	ds_write_b32 v70, v3 offset:6256
	s_waitcnt vmcnt(3)
	v_lshlrev_b32_e32 v22, 16, v8
	v_and_b32_e32 v23, 0xffff0000, v8
	s_waitcnt vmcnt(2)
	v_lshlrev_b32_e32 v24, 16, v4
	v_and_b32_e32 v25, 0xffff0000, v4
	v_fma_f32 v34, |v22|, s40, 1.0
	v_fma_f32 v35, |v23|, s40, 1.0
	v_fma_f32 v38, |v24|, s40, 1.0
	v_fma_f32 v39, |v25|, s40, 1.0
	v_rcp_f32_e32 v34, v34
	v_rcp_f32_e32 v35, v35
	v_rcp_f32_e32 v38, v38
	v_rcp_f32_e32 v39, v39
	v_pk_mul_f32 v[36:37], v[22:23], v[22:23]
	v_pk_mul_f32 v[40:41], v[24:25], v[24:25]
	v_pk_mul_f32 v[36:37], v[36:37], s[64:65] op_sel_hi:[1,0]
	v_pk_fma_f32 v[42:43], v[34:35], s[42:43], v[16:17] op_sel_hi:[1,0,0]
	v_pk_mul_f32 v[40:41], v[40:41], s[64:65] op_sel_hi:[1,0]
	v_exp_f32_e32 v36, v36
	v_exp_f32_e32 v37, v37
	v_pk_fma_f32 v[44:45], v[38:39], s[42:43], v[16:17] op_sel_hi:[1,0,0]
	v_pk_fma_f32 v[42:43], v[34:35], v[42:43], s[48:49] op_sel_hi:[1,1,0]
	v_exp_f32_e32 v40, v40
	v_exp_f32_e32 v41, v41
	v_pk_fma_f32 v[44:45], v[38:39], v[44:45], s[48:49] op_sel_hi:[1,1,0]
	v_pk_fma_f32 v[42:43], v[34:35], v[42:43], s[50:51] op_sel_hi:[1,1,0]
	v_pk_fma_f32 v[44:45], v[38:39], v[44:45], s[50:51] op_sel_hi:[1,1,0]
	v_pk_fma_f32 v[42:43], v[34:35], v[42:43], s[56:57] op_sel_hi:[1,1,0]
	v_pk_fma_f32 v[44:45], v[38:39], v[44:45], s[56:57] op_sel_hi:[1,1,0]
	v_pk_mul_f32 v[34:35], v[34:35], v[42:43]
	v_pk_mul_f32 v[38:39], v[38:39], v[44:45]
	v_pk_mul_f32 v[34:35], v[36:37], v[34:35]
	v_pk_mul_f32 v[36:37], v[40:41], v[38:39]
	v_max_f32_e32 v114, 0, v22
	v_fma_f32 v3, -|v22|, v34, v114
	v_max_f32_e32 v115, 0, v23
	v_sub_f32_e32 v3, v3, v14
	v_mul_f32_e32 v3, v12, v3
	v_fma_f32 v4, -|v23|, v35, v115
	v_max_f32_e32 v116, 0, v24
	v_sub_f32_e32 v4, v4, v14
	v_mul_f32_e32 v4, v12, v4
	v_fma_f32 v8, -|v24|, v36, v116
	v_max_f32_e32 v117, 0, v25
	v_sub_f32_e32 v8, v8, v15
	v_mul_f32_e32 v8, v13, v8
	v_fma_f32 v22, -|v25|, v37, v117
	v_sub_f32_e32 v22, v22, v15
	v_mul_f32_e32 v22, v13, v22
	s_waitcnt vmcnt(0)
	v_fma_f32 v3, v20, v3, v18
	v_fma_f32 v4, v21, v4, v19
	v_fma_f32 v8, v20, v8, v18
	v_fmac_f32_e32 v19, v21, v22
	v_cvt_pk_bf16_f32 v3, v3, v8
	ds_write_b32 v70, v3 offset:6528
	v_cvt_pk_bf16_f32 v3, v4, v19
	global_load_dwordx2 v[20:21], v2, s[0:1] offset:104
	global_load_dwordx2 v[18:19], v2, s[4:5] offset:104
	v_lshlrev_b32_e32 v8, 16, v9
	v_and_b32_e32 v9, 0xffff0000, v9
	v_lshlrev_b32_e32 v4, 16, v5
	v_and_b32_e32 v5, 0xffff0000, v5
	v_fma_f32 v22, |v8|, s40, 1.0
	v_fma_f32 v23, |v9|, s40, 1.0
	v_fma_f32 v34, |v4|, s40, 1.0
	v_fma_f32 v35, |v5|, s40, 1.0
	v_rcp_f32_e32 v22, v22
	v_rcp_f32_e32 v23, v23
	v_rcp_f32_e32 v34, v34
	v_rcp_f32_e32 v35, v35
	v_pk_mul_f32 v[24:25], v[8:9], v[8:9]
	v_pk_mul_f32 v[36:37], v[4:5], v[4:5]
	v_pk_mul_f32 v[24:25], v[24:25], s[64:65] op_sel_hi:[1,0]
	v_pk_fma_f32 v[38:39], v[22:23], s[42:43], v[16:17] op_sel_hi:[1,0,0]
	v_pk_mul_f32 v[36:37], v[36:37], s[64:65] op_sel_hi:[1,0]
	v_exp_f32_e32 v24, v24
	v_exp_f32_e32 v25, v25
	v_pk_fma_f32 v[40:41], v[34:35], s[42:43], v[16:17] op_sel_hi:[1,0,0]
	v_pk_fma_f32 v[38:39], v[22:23], v[38:39], s[48:49] op_sel_hi:[1,1,0]
	v_exp_f32_e32 v36, v36
	v_exp_f32_e32 v37, v37
	v_pk_fma_f32 v[40:41], v[34:35], v[40:41], s[48:49] op_sel_hi:[1,1,0]
	v_pk_fma_f32 v[38:39], v[22:23], v[38:39], s[50:51] op_sel_hi:[1,1,0]
	v_pk_fma_f32 v[40:41], v[34:35], v[40:41], s[50:51] op_sel_hi:[1,1,0]
	v_pk_fma_f32 v[38:39], v[22:23], v[38:39], s[56:57] op_sel_hi:[1,1,0]
	v_pk_fma_f32 v[40:41], v[34:35], v[40:41], s[56:57] op_sel_hi:[1,1,0]
	v_pk_mul_f32 v[22:23], v[22:23], v[38:39]
	v_pk_mul_f32 v[34:35], v[34:35], v[40:41]
	v_pk_mul_f32 v[22:23], v[24:25], v[22:23]
	v_pk_mul_f32 v[24:25], v[36:37], v[34:35]
	v_pk_mul_f32 v[34:35], v[8:9], v[22:23]
	v_pk_fma_f32 v[22:23], v[8:9], v[22:23], v[8:9] neg_lo:[1,0,0] neg_hi:[1,0,0]
	v_cmp_gt_f32_e32 vcc, 0, v8
	v_pk_mul_f32 v[36:37], v[4:5], v[24:25]
	v_pk_fma_f32 v[24:25], v[4:5], v[24:25], v[4:5] neg_lo:[1,0,0] neg_hi:[1,0,0]
	v_cndmask_b32_e32 v8, v22, v34, vcc
	v_cmp_gt_f32_e32 vcc, 0, v9
	v_sub_f32_e32 v8, v8, v14
	v_mul_f32_e32 v8, v12, v8
	v_cndmask_b32_e32 v9, v23, v35, vcc
	v_cmp_gt_f32_e32 vcc, 0, v4
	v_sub_f32_e32 v9, v9, v14
	v_mul_f32_e32 v9, v12, v9
	v_cndmask_b32_e32 v4, v24, v36, vcc
	v_cmp_gt_f32_e32 vcc, 0, v5
	v_sub_f32_e32 v4, v4, v15
	v_mul_f32_e32 v4, v13, v4
	v_cndmask_b32_e32 v5, v25, v37, vcc
	v_sub_f32_e32 v5, v5, v15
	ds_write_b32 v70, v3 offset:6800
	v_mul_f32_e32 v5, v13, v5
	s_waitcnt vmcnt(0)
	v_fma_f32 v3, v20, v8, v18
	v_fma_f32 v8, v21, v9, v19
	v_fma_f32 v4, v20, v4, v18
	v_cvt_pk_bf16_f32 v3, v3, v4
	v_fmac_f32_e32 v19, v21, v5
	ds_write_b32 v70, v3 offset:7072
	v_cvt_pk_bf16_f32 v3, v8, v19
	global_load_dwordx2 v[8:9], v2, s[0:1] offset:112
	global_load_dwordx2 v[4:5], v2, s[4:5] offset:112
	v_lshlrev_b32_e32 v18, 16, v10
	v_and_b32_e32 v19, 0xffff0000, v10
	v_lshlrev_b32_e32 v20, 16, v6
	v_and_b32_e32 v21, 0xffff0000, v6
	v_fma_f32 v22, |v18|, s40, 1.0
	v_fma_f32 v23, |v19|, s40, 1.0
	v_fma_f32 v34, |v20|, s40, 1.0
	v_fma_f32 v35, |v21|, s40, 1.0
	v_rcp_f32_e32 v22, v22
	v_rcp_f32_e32 v23, v23
	v_rcp_f32_e32 v34, v34
	v_rcp_f32_e32 v35, v35
	v_pk_mul_f32 v[24:25], v[18:19], v[18:19]
	v_pk_mul_f32 v[36:37], v[20:21], v[20:21]
	v_pk_mul_f32 v[24:25], v[24:25], s[64:65] op_sel_hi:[1,0]
	v_pk_fma_f32 v[38:39], v[22:23], s[42:43], v[16:17] op_sel_hi:[1,0,0]
	v_pk_mul_f32 v[36:37], v[36:37], s[64:65] op_sel_hi:[1,0]
	v_exp_f32_e32 v24, v24
	v_exp_f32_e32 v25, v25
	v_pk_fma_f32 v[40:41], v[34:35], s[42:43], v[16:17] op_sel_hi:[1,0,0]
	v_pk_fma_f32 v[38:39], v[22:23], v[38:39], s[48:49] op_sel_hi:[1,1,0]
	v_exp_f32_e32 v36, v36
	v_exp_f32_e32 v37, v37
	v_pk_fma_f32 v[40:41], v[34:35], v[40:41], s[48:49] op_sel_hi:[1,1,0]
	v_pk_fma_f32 v[38:39], v[22:23], v[38:39], s[50:51] op_sel_hi:[1,1,0]
	v_pk_fma_f32 v[40:41], v[34:35], v[40:41], s[50:51] op_sel_hi:[1,1,0]
	v_pk_fma_f32 v[38:39], v[22:23], v[38:39], s[56:57] op_sel_hi:[1,1,0]
	v_pk_fma_f32 v[40:41], v[34:35], v[40:41], s[56:57] op_sel_hi:[1,1,0]
	v_pk_mul_f32 v[22:23], v[22:23], v[38:39]
	v_pk_mul_f32 v[34:35], v[34:35], v[40:41]
	v_pk_mul_f32 v[22:23], v[24:25], v[22:23]
	v_pk_mul_f32 v[24:25], v[36:37], v[34:35]
	v_max_f32_e32 v80, 0, v18
	v_fma_f32 v6, -|v18|, v22, v80
	v_max_f32_e32 v81, 0, v19
	v_sub_f32_e32 v6, v6, v14
	v_mul_f32_e32 v6, v12, v6
	v_fma_f32 v10, -|v19|, v23, v81
	v_max_f32_e32 v82, 0, v20
	v_sub_f32_e32 v10, v10, v14
	v_mul_f32_e32 v10, v12, v10
	v_fma_f32 v18, -|v20|, v24, v82
	v_max_f32_e32 v83, 0, v21
	v_sub_f32_e32 v18, v18, v15
	v_mul_f32_e32 v18, v13, v18
	v_fma_f32 v19, -|v21|, v25, v83
	v_sub_f32_e32 v19, v19, v15
	v_mul_f32_e32 v19, v13, v19
	ds_write_b32 v70, v3 offset:7344
	s_andn2_b64 vcc, exec, s[80:81]
	s_waitcnt vmcnt(0)
	v_fma_f32 v3, v8, v6, v4
	v_fma_f32 v6, v9, v10, v5
	v_fma_f32 v4, v8, v18, v4
	v_fmac_f32_e32 v5, v9, v19
	v_cvt_pk_bf16_f32 v3, v3, v4
	ds_write_b32 v70, v3 offset:7616
	v_cvt_pk_bf16_f32 v3, v6, v5
	global_load_dwordx2 v[8:9], v2, s[0:1] offset:120
	global_load_dwordx2 v[4:5], v2, s[4:5] offset:120
	v_lshlrev_b32_e32 v10, 16, v11
	v_and_b32_e32 v11, 0xffff0000, v11
	v_cndmask_b32_e64 v6, 0, 1, s[80:81]
	v_cmp_ne_u32_e64 s[4:5], 1, v6
	v_lshlrev_b32_e32 v6, 16, v7
	v_and_b32_e32 v7, 0xffff0000, v7
	v_fma_f32 v18, |v10|, s40, 1.0
	v_fma_f32 v19, |v11|, s40, 1.0
	v_rcp_f32_e32 v18, v18
	v_rcp_f32_e32 v19, v19
	v_fma_f32 v22, |v6|, s40, 1.0
	v_fma_f32 v23, |v7|, s40, 1.0
	v_pk_mul_f32 v[20:21], v[10:11], v[10:11]
	v_rcp_f32_e32 v22, v22
	v_rcp_f32_e32 v23, v23
	v_pk_mul_f32 v[20:21], v[20:21], s[64:65] op_sel_hi:[1,0]
	v_pk_fma_f32 v[34:35], v[18:19], s[42:43], v[16:17] op_sel_hi:[1,0,0]
	v_pk_mul_f32 v[24:25], v[6:7], v[6:7]
	v_exp_f32_e32 v20, v20
	v_exp_f32_e32 v21, v21
	v_pk_fma_f32 v[34:35], v[18:19], v[34:35], s[48:49] op_sel_hi:[1,1,0]
	v_pk_mul_f32 v[24:25], v[24:25], s[64:65] op_sel_hi:[1,0]
	v_pk_fma_f32 v[16:17], v[22:23], s[42:43], v[16:17] op_sel_hi:[1,0,0]
	v_pk_fma_f32 v[34:35], v[18:19], v[34:35], s[50:51] op_sel_hi:[1,1,0]
	v_exp_f32_e32 v24, v24
	v_exp_f32_e32 v25, v25
	v_pk_fma_f32 v[16:17], v[22:23], v[16:17], s[48:49] op_sel_hi:[1,1,0]
	v_pk_fma_f32 v[34:35], v[18:19], v[34:35], s[56:57] op_sel_hi:[1,1,0]
	v_pk_fma_f32 v[16:17], v[22:23], v[16:17], s[50:51] op_sel_hi:[1,1,0]
	v_pk_mul_f32 v[18:19], v[18:19], v[34:35]
	v_pk_fma_f32 v[16:17], v[22:23], v[16:17], s[56:57] op_sel_hi:[1,1,0]
	v_pk_mul_f32 v[18:19], v[20:21], v[18:19]
	v_pk_mul_f32 v[16:17], v[22:23], v[16:17]
	v_max_f32_e32 v84, 0, v10
	v_pk_mul_f32 v[16:17], v[24:25], v[16:17]
	ds_write_b32 v70, v3 offset:7888
	v_fma_f32 v10, -|v10|, v18, v84
	v_max_f32_e32 v85, 0, v11
	v_pk_mul_f32 v[22:23], v[6:7], v[16:17]
	v_pk_fma_f32 v[16:17], v[6:7], v[16:17], v[6:7] neg_lo:[1,0,0] neg_hi:[1,0,0]
	v_fma_f32 v11, -|v11|, v19, v85
	v_cmp_gt_f32_e64 s[0:1], 0, v6
	v_sub_f32_e32 v10, v10, v14
	v_sub_f32_e32 v11, v11, v14
	v_cndmask_b32_e64 v6, v16, v22, s[0:1]
	v_cmp_gt_f32_e64 s[0:1], 0, v7
	v_sub_f32_e32 v6, v6, v15
	v_mul_f32_e32 v10, v12, v10
	v_cndmask_b32_e64 v7, v17, v23, s[0:1]
	v_sub_f32_e32 v7, v7, v15
	v_mul_f32_e32 v11, v12, v11
	v_mul_f32_e32 v6, v13, v6
	v_mul_f32_e32 v7, v13, v7
	s_waitcnt vmcnt(0)
	v_fma_f32 v3, v8, v10, v4
	v_fma_f32 v10, v9, v11, v5
	v_fma_f32 v4, v8, v6, v4
	v_fmac_f32_e32 v5, v9, v7
	v_cvt_pk_bf16_f32 v3, v3, v4
	ds_write_b32 v70, v3 offset:8160
	v_cvt_pk_bf16_f32 v3, v10, v5
	v_lshl_add_u64 v[4:5], s[12:13], 0, v[28:29]
	ds_write_b32 v70, v3 offset:8432
	s_cbranch_vccnz .LBB0_458
	v_add_co_u32_e32 v6, vcc, 0x2688000, v4
	s_nop 1
	v_addc_co_u32_e32 v7, vcc, 0, v5, vcc
	global_load_dwordx4 v[6:9], v[6:7], off
	v_cndmask_b32_e64 v3, 0, 1, s[82:83]
	v_cmp_ne_u32_e64 s[6:7], 1, v3
	s_andn2_b64 vcc, exec, s[82:83]
	s_cbranch_vccz .LBB0_459

.LBB0_470:
	s_waitcnt vmcnt(15)
	v_lshlrev_b32_e32 v4, 16, v66
	v_and_b32_e32 v5, 0xffff0000, v66
	v_fma_f32 v74, |v4|, s40, 1.0
	v_fma_f32 v75, |v5|, s40, 1.0
	v_mov_b64_e32 v[76:77], s[44:45]
	v_rcp_f32_e32 v74, v74
	v_rcp_f32_e32 v75, v75
	v_cmp_gt_f32_e32 vcc, 0, v4
	v_pk_fma_f32 v[78:79], v[74:75], s[42:43], v[76:77] op_sel_hi:[1,0,0]
	s_nop 0
	v_pk_fma_f32 v[78:79], v[74:75], v[78:79], s[48:49] op_sel_hi:[1,1,0]
	s_nop 0
	v_pk_fma_f32 v[78:79], v[74:75], v[78:79], s[50:51] op_sel_hi:[1,1,0]
	s_nop 0
	v_pk_fma_f32 v[78:79], v[74:75], v[78:79], s[56:57] op_sel_hi:[1,1,0]
	s_nop 0
	v_pk_mul_f32 v[74:75], v[74:75], v[78:79]
	v_pk_mul_f32 v[78:79], v[4:5], v[4:5]
	s_nop 0
	v_pk_mul_f32 v[78:79], v[78:79], s[64:65] op_sel_hi:[1,0]
	s_nop 0
	v_exp_f32_e32 v78, v78
	v_exp_f32_e32 v79, v79
	s_nop 0
	v_pk_mul_f32 v[74:75], v[78:79], v[74:75]
	s_nop 0
	v_pk_mul_f32 v[78:79], v[4:5], v[74:75]
	v_pk_fma_f32 v[74:75], v[4:5], v[74:75], v[4:5] neg_lo:[1,0,0] neg_hi:[1,0,0]
	v_lshlrev_b32_e32 v4, 16, v67
	v_cndmask_b32_e32 v3, v74, v78, vcc
	v_cmp_gt_f32_e32 vcc, 0, v5
	v_and_b32_e32 v5, 0xffff0000, v67
	v_fma_f32 v66, |v4|, s40, 1.0
	v_fma_f32 v67, |v5|, s40, 1.0
	v_cndmask_b32_e32 v73, v75, v79, vcc
	v_rcp_f32_e32 v66, v66
	v_rcp_f32_e32 v67, v67
	v_cmp_gt_f32_e32 vcc, 0, v4
	v_pk_fma_f32 v[74:75], v[66:67], s[42:43], v[76:77] op_sel_hi:[1,0,0]
	s_nop 0
	v_pk_fma_f32 v[74:75], v[66:67], v[74:75], s[48:49] op_sel_hi:[1,1,0]
	s_nop 0
	v_pk_fma_f32 v[74:75], v[66:67], v[74:75], s[50:51] op_sel_hi:[1,1,0]
	s_nop 0
	v_pk_fma_f32 v[74:75], v[66:67], v[74:75], s[56:57] op_sel_hi:[1,1,0]
	s_nop 0
	v_pk_mul_f32 v[66:67], v[66:67], v[74:75]
	v_pk_mul_f32 v[74:75], v[4:5], v[4:5]
	s_nop 0
	v_pk_mul_f32 v[74:75], v[74:75], s[64:65] op_sel_hi:[1,0]
	s_nop 0
	v_exp_f32_e32 v74, v74
	v_exp_f32_e32 v75, v75
	s_nop 0
	v_pk_mul_f32 v[66:67], v[74:75], v[66:67]
	s_nop 0
	v_pk_mul_f32 v[74:75], v[4:5], v[66:67]
	v_pk_fma_f32 v[66:67], v[4:5], v[66:67], v[4:5] neg_lo:[1,0,0] neg_hi:[1,0,0]
	v_add_f32_e32 v4, v72, v22
	v_cndmask_b32_e32 v66, v66, v74, vcc
	v_cmp_gt_f32_e32 vcc, 0, v5
	v_add_f32_e32 v22, v72, v25
	v_mul_f32_e32 v3, v3, v4
	v_cndmask_b32_e32 v5, v67, v75, vcc
	v_add_f32_e32 v4, v72, v23
	v_mul_f32_e32 v5, v5, v22
	v_add_co_u32_e32 v22, vcc, 0x1506e000, v34
	v_mul_f32_e32 v4, v73, v4
	s_nop 0
	v_addc_co_u32_e32 v23, vcc, 0, v35, vcc
	v_cvt_pk_bf16_f32 v4, v3, v4
	v_add_f32_e32 v3, v72, v24
	s_and_b64 vcc, exec, s[4:5]
	v_mul_f32_e32 v3, v66, v3
	v_cvt_pk_bf16_f32 v5, v3, v5
	global_store_dwordx2 v[22:23], v[4:5], off
	s_cbranch_vccnz .LBB0_472
	ds_read_b128 v[22:25], v71 offset:4352
	s_waitcnt lgkmcnt(0)
	v_mfma_f32_16x16x32_bf16 v[22:25], v[22:25], v[6:9], 0
	s_and_b64 vcc, exec, s[6:7]
	s_cbranch_vccz .LBB0_473
	s_branch .LBB0_474

.LBB0_478:
	s_waitcnt vmcnt(15)
	v_lshlrev_b32_e32 v4, 16, v64
	v_and_b32_e32 v5, 0xffff0000, v64
	v_fma_f32 v66, |v4|, s40, 1.0
	v_fma_f32 v67, |v5|, s40, 1.0
	v_mov_b64_e32 v[74:75], s[44:45]
	v_rcp_f32_e32 v66, v66
	v_rcp_f32_e32 v67, v67
	v_cmp_gt_f32_e32 vcc, 0, v4
	v_pk_fma_f32 v[76:77], v[66:67], s[42:43], v[74:75] op_sel_hi:[1,0,0]
	s_nop 0
	v_pk_fma_f32 v[76:77], v[66:67], v[76:77], s[48:49] op_sel_hi:[1,1,0]
	s_nop 0
	v_pk_fma_f32 v[76:77], v[66:67], v[76:77], s[50:51] op_sel_hi:[1,1,0]
	s_nop 0
	v_pk_fma_f32 v[76:77], v[66:67], v[76:77], s[56:57] op_sel_hi:[1,1,0]
	s_nop 0
	v_pk_mul_f32 v[66:67], v[66:67], v[76:77]
	v_pk_mul_f32 v[76:77], v[4:5], v[4:5]
	s_nop 0
	v_pk_mul_f32 v[76:77], v[76:77], s[64:65] op_sel_hi:[1,0]
	s_nop 0
	v_exp_f32_e32 v76, v76
	v_exp_f32_e32 v77, v77
	s_nop 0
	v_pk_mul_f32 v[66:67], v[76:77], v[66:67]
	s_nop 0
	v_pk_mul_f32 v[76:77], v[4:5], v[66:67]
	v_pk_fma_f32 v[66:67], v[4:5], v[66:67], v[4:5] neg_lo:[1,0,0] neg_hi:[1,0,0]
	v_lshlrev_b32_e32 v4, 16, v65
	v_cndmask_b32_e32 v3, v66, v76, vcc
	v_cmp_gt_f32_e32 vcc, 0, v5
	v_and_b32_e32 v5, 0xffff0000, v65
	v_fma_f32 v64, |v4|, s40, 1.0
	v_fma_f32 v65, |v5|, s40, 1.0
	v_cndmask_b32_e32 v73, v67, v77, vcc
	v_rcp_f32_e32 v64, v64
	v_rcp_f32_e32 v65, v65
	v_cmp_gt_f32_e32 vcc, 0, v4
	v_pk_fma_f32 v[66:67], v[64:65], s[42:43], v[74:75] op_sel_hi:[1,0,0]
	s_nop 0
	v_pk_fma_f32 v[66:67], v[64:65], v[66:67], s[48:49] op_sel_hi:[1,1,0]
	s_nop 0
	v_pk_fma_f32 v[66:67], v[64:65], v[66:67], s[50:51] op_sel_hi:[1,1,0]
	s_nop 0
	v_pk_fma_f32 v[66:67], v[64:65], v[66:67], s[56:57] op_sel_hi:[1,1,0]
	s_nop 0
	v_pk_mul_f32 v[64:65], v[64:65], v[66:67]
	v_pk_mul_f32 v[66:67], v[4:5], v[4:5]
	s_nop 0
	v_pk_mul_f32 v[66:67], v[66:67], s[64:65] op_sel_hi:[1,0]
	s_nop 0
	v_exp_f32_e32 v66, v66
	v_exp_f32_e32 v67, v67
	s_nop 0
	v_pk_mul_f32 v[64:65], v[66:67], v[64:65]
	s_nop 0
	v_pk_mul_f32 v[66:67], v[4:5], v[64:65]
	v_pk_fma_f32 v[64:65], v[4:5], v[64:65], v[4:5] neg_lo:[1,0,0] neg_hi:[1,0,0]
	v_add_f32_e32 v4, v72, v22
	v_cndmask_b32_e32 v64, v64, v66, vcc
	v_cmp_gt_f32_e32 vcc, 0, v5
	v_add_f32_e32 v22, v72, v25
	v_mul_f32_e32 v3, v3, v4
	v_cndmask_b32_e32 v5, v65, v67, vcc
	v_add_f32_e32 v4, v72, v23
	v_mul_f32_e32 v5, v5, v22
	v_add_co_u32_e32 v22, vcc, 0x1506e000, v34
	v_mul_f32_e32 v4, v73, v4
	s_nop 0
	v_addc_co_u32_e32 v23, vcc, 0, v35, vcc
	v_cvt_pk_bf16_f32 v4, v3, v4
	v_add_f32_e32 v3, v72, v24
	s_and_b64 vcc, exec, s[4:5]
	v_mul_f32_e32 v3, v64, v3
	v_cvt_pk_bf16_f32 v5, v3, v5
	global_store_dwordx2 v[22:23], v[4:5], off offset:32
	s_cbranch_vccnz .LBB0_480
	ds_read_b128 v[22:25], v71 offset:8704
	s_waitcnt lgkmcnt(0)
	v_mfma_f32_16x16x32_bf16 v[22:25], v[22:25], v[6:9], 0
	s_and_b64 vcc, exec, s[6:7]
	s_cbranch_vccz .LBB0_481
	s_branch .LBB0_482

.LBB0_486:
	s_waitcnt vmcnt(15)
	v_lshlrev_b32_e32 v4, 16, v62
	v_and_b32_e32 v5, 0xffff0000, v62
	v_fma_f32 v64, |v4|, s40, 1.0
	v_fma_f32 v65, |v5|, s40, 1.0
	v_mov_b64_e32 v[66:67], s[44:45]
	v_rcp_f32_e32 v64, v64
	v_rcp_f32_e32 v65, v65
	v_cmp_gt_f32_e32 vcc, 0, v4
	v_pk_fma_f32 v[74:75], v[64:65], s[42:43], v[66:67] op_sel_hi:[1,0,0]
	s_nop 0
	v_pk_fma_f32 v[74:75], v[64:65], v[74:75], s[48:49] op_sel_hi:[1,1,0]
	s_nop 0
	v_pk_fma_f32 v[74:75], v[64:65], v[74:75], s[50:51] op_sel_hi:[1,1,0]
	s_nop 0
	v_pk_fma_f32 v[74:75], v[64:65], v[74:75], s[56:57] op_sel_hi:[1,1,0]
	s_nop 0
	v_pk_mul_f32 v[64:65], v[64:65], v[74:75]
	v_pk_mul_f32 v[74:75], v[4:5], v[4:5]
	s_nop 0
	v_pk_mul_f32 v[74:75], v[74:75], s[64:65] op_sel_hi:[1,0]
	s_nop 0
	v_exp_f32_e32 v74, v74
	v_exp_f32_e32 v75, v75
	s_nop 0
	v_pk_mul_f32 v[64:65], v[74:75], v[64:65]
	s_nop 0
	v_pk_mul_f32 v[74:75], v[4:5], v[64:65]
	v_pk_fma_f32 v[64:65], v[4:5], v[64:65], v[4:5] neg_lo:[1,0,0] neg_hi:[1,0,0]
	v_lshlrev_b32_e32 v4, 16, v63
	v_cndmask_b32_e32 v3, v64, v74, vcc
	v_cmp_gt_f32_e32 vcc, 0, v5
	v_and_b32_e32 v5, 0xffff0000, v63
	v_fma_f32 v62, |v4|, s40, 1.0
	v_fma_f32 v63, |v5|, s40, 1.0
	v_cndmask_b32_e32 v73, v65, v75, vcc
	v_rcp_f32_e32 v62, v62
	v_rcp_f32_e32 v63, v63
	v_cmp_gt_f32_e32 vcc, 0, v4
	v_pk_fma_f32 v[64:65], v[62:63], s[42:43], v[66:67] op_sel_hi:[1,0,0]
	s_nop 0
	v_pk_fma_f32 v[64:65], v[62:63], v[64:65], s[48:49] op_sel_hi:[1,1,0]
	s_nop 0
	v_pk_fma_f32 v[64:65], v[62:63], v[64:65], s[50:51] op_sel_hi:[1,1,0]
	s_nop 0
	v_pk_fma_f32 v[64:65], v[62:63], v[64:65], s[56:57] op_sel_hi:[1,1,0]
	s_nop 0
	v_pk_mul_f32 v[62:63], v[62:63], v[64:65]
	v_pk_mul_f32 v[64:65], v[4:5], v[4:5]
	s_nop 0
	v_pk_mul_f32 v[64:65], v[64:65], s[64:65] op_sel_hi:[1,0]
	s_nop 0
	v_exp_f32_e32 v64, v64
	v_exp_f32_e32 v65, v65
	s_nop 0
	v_pk_mul_f32 v[62:63], v[64:65], v[62:63]
	s_nop 0
	v_pk_mul_f32 v[64:65], v[4:5], v[62:63]
	v_pk_fma_f32 v[62:63], v[4:5], v[62:63], v[4:5] neg_lo:[1,0,0] neg_hi:[1,0,0]
	v_add_f32_e32 v4, v72, v22
	v_cndmask_b32_e32 v62, v62, v64, vcc
	v_cmp_gt_f32_e32 vcc, 0, v5
	v_add_f32_e32 v22, v72, v25
	v_mul_f32_e32 v3, v3, v4
	v_cndmask_b32_e32 v5, v63, v65, vcc
	v_add_f32_e32 v4, v72, v23
	v_mul_f32_e32 v5, v5, v22
	v_add_co_u32_e32 v22, vcc, 0x1506e000, v34
	v_mul_f32_e32 v4, v73, v4
	s_nop 0
	v_addc_co_u32_e32 v23, vcc, 0, v35, vcc
	v_cvt_pk_bf16_f32 v4, v3, v4
	v_add_f32_e32 v3, v72, v24
	s_and_b64 vcc, exec, s[4:5]
	v_mul_f32_e32 v3, v62, v3
	v_cvt_pk_bf16_f32 v5, v3, v5
	global_store_dwordx2 v[22:23], v[4:5], off offset:64
	s_cbranch_vccnz .LBB0_488
	ds_read_b128 v[22:25], v71 offset:13056
	s_waitcnt lgkmcnt(0)
	v_mfma_f32_16x16x32_bf16 v[22:25], v[22:25], v[6:9], 0
	s_and_b64 vcc, exec, s[6:7]
	s_cbranch_vccz .LBB0_489
	s_branch .LBB0_490

.LBB0_494:
	s_waitcnt vmcnt(15)
	v_lshlrev_b32_e32 v4, 16, v60
	v_and_b32_e32 v5, 0xffff0000, v60
	v_fma_f32 v62, |v4|, s40, 1.0
	v_fma_f32 v63, |v5|, s40, 1.0
	v_mov_b64_e32 v[64:65], s[44:45]
	v_rcp_f32_e32 v62, v62
	v_rcp_f32_e32 v63, v63
	v_cmp_gt_f32_e32 vcc, 0, v4
	v_pk_fma_f32 v[66:67], v[62:63], s[42:43], v[64:65] op_sel_hi:[1,0,0]
	s_nop 0
	v_pk_fma_f32 v[66:67], v[62:63], v[66:67], s[48:49] op_sel_hi:[1,1,0]
	s_nop 0
	v_pk_fma_f32 v[66:67], v[62:63], v[66:67], s[50:51] op_sel_hi:[1,1,0]
	s_nop 0
	v_pk_fma_f32 v[66:67], v[62:63], v[66:67], s[56:57] op_sel_hi:[1,1,0]
	s_nop 0
	v_pk_mul_f32 v[62:63], v[62:63], v[66:67]
	v_pk_mul_f32 v[66:67], v[4:5], v[4:5]
	s_nop 0
	v_pk_mul_f32 v[66:67], v[66:67], s[64:65] op_sel_hi:[1,0]
	s_nop 0
	v_exp_f32_e32 v66, v66
	v_exp_f32_e32 v67, v67
	s_nop 0
	v_pk_mul_f32 v[62:63], v[66:67], v[62:63]
	s_nop 0
	v_pk_mul_f32 v[66:67], v[4:5], v[62:63]
	v_pk_fma_f32 v[62:63], v[4:5], v[62:63], v[4:5] neg_lo:[1,0,0] neg_hi:[1,0,0]
	v_lshlrev_b32_e32 v4, 16, v61
	v_cndmask_b32_e32 v3, v62, v66, vcc
	v_cmp_gt_f32_e32 vcc, 0, v5
	v_and_b32_e32 v5, 0xffff0000, v61
	v_fma_f32 v60, |v4|, s40, 1.0
	v_fma_f32 v61, |v5|, s40, 1.0
	v_cndmask_b32_e32 v66, v63, v67, vcc
	v_rcp_f32_e32 v60, v60
	v_rcp_f32_e32 v61, v61
	v_cmp_gt_f32_e32 vcc, 0, v4
	v_pk_fma_f32 v[62:63], v[60:61], s[42:43], v[64:65] op_sel_hi:[1,0,0]
	s_nop 0
	v_pk_fma_f32 v[62:63], v[60:61], v[62:63], s[48:49] op_sel_hi:[1,1,0]
	s_nop 0
	v_pk_fma_f32 v[62:63], v[60:61], v[62:63], s[50:51] op_sel_hi:[1,1,0]
	s_nop 0
	v_pk_fma_f32 v[62:63], v[60:61], v[62:63], s[56:57] op_sel_hi:[1,1,0]
	s_nop 0
	v_pk_mul_f32 v[60:61], v[60:61], v[62:63]
	v_pk_mul_f32 v[62:63], v[4:5], v[4:5]
	s_nop 0
	v_pk_mul_f32 v[62:63], v[62:63], s[64:65] op_sel_hi:[1,0]
	s_nop 0
	v_exp_f32_e32 v62, v62
	v_exp_f32_e32 v63, v63
	s_nop 0
	v_pk_mul_f32 v[60:61], v[62:63], v[60:61]
	s_nop 0
	v_pk_mul_f32 v[62:63], v[4:5], v[60:61]
	v_pk_fma_f32 v[60:61], v[4:5], v[60:61], v[4:5] neg_lo:[1,0,0] neg_hi:[1,0,0]
	v_add_f32_e32 v4, v72, v22
	v_cndmask_b32_e32 v60, v60, v62, vcc
	v_cmp_gt_f32_e32 vcc, 0, v5
	v_add_f32_e32 v22, v72, v25
	v_mul_f32_e32 v3, v3, v4
	v_cndmask_b32_e32 v5, v61, v63, vcc
	v_add_f32_e32 v4, v72, v23
	v_mul_f32_e32 v5, v5, v22
	v_add_co_u32_e32 v22, vcc, 0x1506e000, v34
	v_mul_f32_e32 v4, v66, v4
	s_nop 0
	v_addc_co_u32_e32 v23, vcc, 0, v35, vcc
	v_cvt_pk_bf16_f32 v4, v3, v4
	v_add_f32_e32 v3, v72, v24
	s_and_b64 vcc, exec, s[4:5]
	v_mul_f32_e32 v3, v60, v3
	v_cvt_pk_bf16_f32 v5, v3, v5
	global_store_dwordx2 v[22:23], v[4:5], off offset:96
	s_cbranch_vccnz .LBB0_496
	ds_read_b128 v[22:25], v71 offset:17408
	s_waitcnt lgkmcnt(0)
	v_mfma_f32_16x16x32_bf16 v[22:25], v[22:25], v[6:9], 0
	s_and_b64 vcc, exec, s[6:7]
	s_cbranch_vccz .LBB0_497
	s_branch .LBB0_498

.LBB0_502:
	s_waitcnt vmcnt(15)
	v_lshlrev_b32_e32 v4, 16, v58
	v_and_b32_e32 v5, 0xffff0000, v58
	v_fma_f32 v60, |v4|, s40, 1.0
	v_fma_f32 v61, |v5|, s40, 1.0
	v_mov_b64_e32 v[62:63], s[44:45]
	v_rcp_f32_e32 v60, v60
	v_rcp_f32_e32 v61, v61
	v_cmp_gt_f32_e32 vcc, 0, v4
	v_pk_fma_f32 v[64:65], v[60:61], s[42:43], v[62:63] op_sel_hi:[1,0,0]
	s_nop 0
	v_pk_fma_f32 v[64:65], v[60:61], v[64:65], s[48:49] op_sel_hi:[1,1,0]
	s_nop 0
	v_pk_fma_f32 v[64:65], v[60:61], v[64:65], s[50:51] op_sel_hi:[1,1,0]
	s_nop 0
	v_pk_fma_f32 v[64:65], v[60:61], v[64:65], s[56:57] op_sel_hi:[1,1,0]
	s_nop 0
	v_pk_mul_f32 v[60:61], v[60:61], v[64:65]
	v_pk_mul_f32 v[64:65], v[4:5], v[4:5]
	s_nop 0
	v_pk_mul_f32 v[64:65], v[64:65], s[64:65] op_sel_hi:[1,0]
	s_nop 0
	v_exp_f32_e32 v64, v64
	v_exp_f32_e32 v65, v65
	s_nop 0
	v_pk_mul_f32 v[60:61], v[64:65], v[60:61]
	s_nop 0
	v_pk_mul_f32 v[64:65], v[4:5], v[60:61]
	v_pk_fma_f32 v[60:61], v[4:5], v[60:61], v[4:5] neg_lo:[1,0,0] neg_hi:[1,0,0]
	v_lshlrev_b32_e32 v4, 16, v59
	v_cndmask_b32_e32 v3, v60, v64, vcc
	v_cmp_gt_f32_e32 vcc, 0, v5
	v_and_b32_e32 v5, 0xffff0000, v59
	v_fma_f32 v58, |v4|, s40, 1.0
	v_fma_f32 v59, |v5|, s40, 1.0
	v_cndmask_b32_e32 v64, v61, v65, vcc
	v_rcp_f32_e32 v58, v58
	v_rcp_f32_e32 v59, v59
	v_cmp_gt_f32_e32 vcc, 0, v4
	v_pk_fma_f32 v[60:61], v[58:59], s[42:43], v[62:63] op_sel_hi:[1,0,0]
	s_nop 0
	v_pk_fma_f32 v[60:61], v[58:59], v[60:61], s[48:49] op_sel_hi:[1,1,0]
	s_nop 0
	v_pk_fma_f32 v[60:61], v[58:59], v[60:61], s[50:51] op_sel_hi:[1,1,0]
	s_nop 0
	v_pk_fma_f32 v[60:61], v[58:59], v[60:61], s[56:57] op_sel_hi:[1,1,0]
	s_nop 0
	v_pk_mul_f32 v[58:59], v[58:59], v[60:61]
	v_pk_mul_f32 v[60:61], v[4:5], v[4:5]
	s_nop 0
	v_pk_mul_f32 v[60:61], v[60:61], s[64:65] op_sel_hi:[1,0]
	s_nop 0
	v_exp_f32_e32 v60, v60
	v_exp_f32_e32 v61, v61
	s_nop 0
	v_pk_mul_f32 v[58:59], v[60:61], v[58:59]
	s_nop 0
	v_pk_mul_f32 v[60:61], v[4:5], v[58:59]
	v_pk_fma_f32 v[58:59], v[4:5], v[58:59], v[4:5] neg_lo:[1,0,0] neg_hi:[1,0,0]
	v_add_f32_e32 v4, v72, v22
	v_cndmask_b32_e32 v58, v58, v60, vcc
	v_cmp_gt_f32_e32 vcc, 0, v5
	v_add_f32_e32 v22, v72, v25
	v_mul_f32_e32 v3, v3, v4
	v_cndmask_b32_e32 v5, v59, v61, vcc
	v_add_f32_e32 v4, v72, v23
	v_mul_f32_e32 v5, v5, v22
	v_add_co_u32_e32 v22, vcc, 0x1506e000, v34
	v_mul_f32_e32 v4, v64, v4
	s_nop 0
	v_addc_co_u32_e32 v23, vcc, 0, v35, vcc
	v_cvt_pk_bf16_f32 v4, v3, v4
	v_add_f32_e32 v3, v72, v24
	s_and_b64 vcc, exec, s[4:5]
	v_mul_f32_e32 v3, v58, v3
	v_cvt_pk_bf16_f32 v5, v3, v5
	global_store_dwordx2 v[22:23], v[4:5], off offset:128
	s_cbranch_vccnz .LBB0_504
	ds_read_b128 v[22:25], v71 offset:21760
	s_waitcnt lgkmcnt(0)
	v_mfma_f32_16x16x32_bf16 v[22:25], v[22:25], v[6:9], 0
	s_and_b64 vcc, exec, s[6:7]
	s_cbranch_vccz .LBB0_505
	s_branch .LBB0_506

.LBB0_510:
	s_waitcnt vmcnt(15)
	v_lshlrev_b32_e32 v4, 16, v56
	v_and_b32_e32 v5, 0xffff0000, v56
	v_fma_f32 v58, |v4|, s40, 1.0
	v_fma_f32 v59, |v5|, s40, 1.0
	v_mov_b64_e32 v[60:61], s[44:45]
	v_rcp_f32_e32 v58, v58
	v_rcp_f32_e32 v59, v59
	v_cmp_gt_f32_e32 vcc, 0, v4
	v_pk_fma_f32 v[62:63], v[58:59], s[42:43], v[60:61] op_sel_hi:[1,0,0]
	s_nop 0
	v_pk_fma_f32 v[62:63], v[58:59], v[62:63], s[48:49] op_sel_hi:[1,1,0]
	s_nop 0
	v_pk_fma_f32 v[62:63], v[58:59], v[62:63], s[50:51] op_sel_hi:[1,1,0]
	s_nop 0
	v_pk_fma_f32 v[62:63], v[58:59], v[62:63], s[56:57] op_sel_hi:[1,1,0]
	s_nop 0
	v_pk_mul_f32 v[58:59], v[58:59], v[62:63]
	v_pk_mul_f32 v[62:63], v[4:5], v[4:5]
	s_nop 0
	v_pk_mul_f32 v[62:63], v[62:63], s[64:65] op_sel_hi:[1,0]
	s_nop 0
	v_exp_f32_e32 v62, v62
	v_exp_f32_e32 v63, v63
	s_nop 0
	v_pk_mul_f32 v[58:59], v[62:63], v[58:59]
	s_nop 0
	v_pk_mul_f32 v[62:63], v[4:5], v[58:59]
	v_pk_fma_f32 v[58:59], v[4:5], v[58:59], v[4:5] neg_lo:[1,0,0] neg_hi:[1,0,0]
	v_lshlrev_b32_e32 v4, 16, v57
	v_cndmask_b32_e32 v3, v58, v62, vcc
	v_cmp_gt_f32_e32 vcc, 0, v5
	v_and_b32_e32 v5, 0xffff0000, v57
	v_fma_f32 v56, |v4|, s40, 1.0
	v_fma_f32 v57, |v5|, s40, 1.0
	v_cndmask_b32_e32 v62, v59, v63, vcc
	v_rcp_f32_e32 v56, v56
	v_rcp_f32_e32 v57, v57
	v_cmp_gt_f32_e32 vcc, 0, v4
	v_pk_fma_f32 v[58:59], v[56:57], s[42:43], v[60:61] op_sel_hi:[1,0,0]
	s_nop 0
	v_pk_fma_f32 v[58:59], v[56:57], v[58:59], s[48:49] op_sel_hi:[1,1,0]
	s_nop 0
	v_pk_fma_f32 v[58:59], v[56:57], v[58:59], s[50:51] op_sel_hi:[1,1,0]
	s_nop 0
	v_pk_fma_f32 v[58:59], v[56:57], v[58:59], s[56:57] op_sel_hi:[1,1,0]
	s_nop 0
	v_pk_mul_f32 v[56:57], v[56:57], v[58:59]
	v_pk_mul_f32 v[58:59], v[4:5], v[4:5]
	s_nop 0
	v_pk_mul_f32 v[58:59], v[58:59], s[64:65] op_sel_hi:[1,0]
	s_nop 0
	v_exp_f32_e32 v58, v58
	v_exp_f32_e32 v59, v59
	s_nop 0
	v_pk_mul_f32 v[56:57], v[58:59], v[56:57]
	s_nop 0
	v_pk_mul_f32 v[58:59], v[4:5], v[56:57]
	v_pk_fma_f32 v[56:57], v[4:5], v[56:57], v[4:5] neg_lo:[1,0,0] neg_hi:[1,0,0]
	v_add_f32_e32 v4, v72, v22
	v_cndmask_b32_e32 v56, v56, v58, vcc
	v_cmp_gt_f32_e32 vcc, 0, v5
	v_add_f32_e32 v22, v72, v25
	v_mul_f32_e32 v3, v3, v4
	v_cndmask_b32_e32 v5, v57, v59, vcc
	v_add_f32_e32 v4, v72, v23
	v_mul_f32_e32 v5, v5, v22
	v_add_co_u32_e32 v22, vcc, 0x1506e000, v34
	v_mul_f32_e32 v4, v62, v4
	s_nop 0
	v_addc_co_u32_e32 v23, vcc, 0, v35, vcc
	v_cvt_pk_bf16_f32 v4, v3, v4
	v_add_f32_e32 v3, v72, v24
	s_and_b64 vcc, exec, s[4:5]
	v_mul_f32_e32 v3, v56, v3
	v_cvt_pk_bf16_f32 v5, v3, v5
	global_store_dwordx2 v[22:23], v[4:5], off offset:160
	s_cbranch_vccnz .LBB0_512
	ds_read_b128 v[22:25], v71 offset:26112
	s_waitcnt lgkmcnt(0)
	v_mfma_f32_16x16x32_bf16 v[22:25], v[22:25], v[6:9], 0
	s_and_b64 vcc, exec, s[6:7]
	s_cbranch_vccz .LBB0_513
	s_branch .LBB0_514

.LBB0_518:
	s_waitcnt vmcnt(15)
	v_lshlrev_b32_e32 v4, 16, v54
	v_and_b32_e32 v5, 0xffff0000, v54
	v_fma_f32 v56, |v4|, s40, 1.0
	v_fma_f32 v57, |v5|, s40, 1.0
	v_mov_b64_e32 v[58:59], s[44:45]
	v_rcp_f32_e32 v56, v56
	v_rcp_f32_e32 v57, v57
	v_cmp_gt_f32_e32 vcc, 0, v4
	v_pk_fma_f32 v[60:61], v[56:57], s[42:43], v[58:59] op_sel_hi:[1,0,0]
	s_nop 0
	v_pk_fma_f32 v[60:61], v[56:57], v[60:61], s[48:49] op_sel_hi:[1,1,0]
	s_nop 0
	v_pk_fma_f32 v[60:61], v[56:57], v[60:61], s[50:51] op_sel_hi:[1,1,0]
	s_nop 0
	v_pk_fma_f32 v[60:61], v[56:57], v[60:61], s[56:57] op_sel_hi:[1,1,0]
	s_nop 0
	v_pk_mul_f32 v[56:57], v[56:57], v[60:61]
	v_pk_mul_f32 v[60:61], v[4:5], v[4:5]
	s_nop 0
	v_pk_mul_f32 v[60:61], v[60:61], s[64:65] op_sel_hi:[1,0]
	s_nop 0
	v_exp_f32_e32 v60, v60
	v_exp_f32_e32 v61, v61
	s_nop 0
	v_pk_mul_f32 v[56:57], v[60:61], v[56:57]
	s_nop 0
	v_pk_mul_f32 v[60:61], v[4:5], v[56:57]
	v_pk_fma_f32 v[56:57], v[4:5], v[56:57], v[4:5] neg_lo:[1,0,0] neg_hi:[1,0,0]
	v_lshlrev_b32_e32 v4, 16, v55
	v_cndmask_b32_e32 v3, v56, v60, vcc
	v_cmp_gt_f32_e32 vcc, 0, v5
	v_and_b32_e32 v5, 0xffff0000, v55
	v_fma_f32 v54, |v4|, s40, 1.0
	v_fma_f32 v55, |v5|, s40, 1.0
	v_cndmask_b32_e32 v60, v57, v61, vcc
	v_rcp_f32_e32 v54, v54
	v_rcp_f32_e32 v55, v55
	v_cmp_gt_f32_e32 vcc, 0, v4
	v_pk_fma_f32 v[56:57], v[54:55], s[42:43], v[58:59] op_sel_hi:[1,0,0]
	s_nop 0
	v_pk_fma_f32 v[56:57], v[54:55], v[56:57], s[48:49] op_sel_hi:[1,1,0]
	s_nop 0
	v_pk_fma_f32 v[56:57], v[54:55], v[56:57], s[50:51] op_sel_hi:[1,1,0]
	s_nop 0
	v_pk_fma_f32 v[56:57], v[54:55], v[56:57], s[56:57] op_sel_hi:[1,1,0]
	s_nop 0
	v_pk_mul_f32 v[54:55], v[54:55], v[56:57]
	v_pk_mul_f32 v[56:57], v[4:5], v[4:5]
	s_nop 0
	v_pk_mul_f32 v[56:57], v[56:57], s[64:65] op_sel_hi:[1,0]
	s_nop 0
	v_exp_f32_e32 v56, v56
	v_exp_f32_e32 v57, v57
	s_nop 0
	v_pk_mul_f32 v[54:55], v[56:57], v[54:55]
	s_nop 0
	v_pk_mul_f32 v[56:57], v[4:5], v[54:55]
	v_pk_fma_f32 v[54:55], v[4:5], v[54:55], v[4:5] neg_lo:[1,0,0] neg_hi:[1,0,0]
	v_add_f32_e32 v4, v72, v22
	v_cndmask_b32_e32 v54, v54, v56, vcc
	v_cmp_gt_f32_e32 vcc, 0, v5
	v_add_f32_e32 v22, v72, v25
	v_mul_f32_e32 v3, v3, v4
	v_cndmask_b32_e32 v5, v55, v57, vcc
	v_add_f32_e32 v4, v72, v23
	v_mul_f32_e32 v5, v5, v22
	v_add_co_u32_e32 v22, vcc, 0x1506e000, v34
	v_mul_f32_e32 v4, v60, v4
	s_nop 0
	v_addc_co_u32_e32 v23, vcc, 0, v35, vcc
	v_cvt_pk_bf16_f32 v4, v3, v4
	v_add_f32_e32 v3, v72, v24
	s_and_b64 vcc, exec, s[4:5]
	v_mul_f32_e32 v3, v54, v3
	v_cvt_pk_bf16_f32 v5, v3, v5
	global_store_dwordx2 v[22:23], v[4:5], off offset:192
	s_cbranch_vccnz .LBB0_520
	ds_read_b128 v[22:25], v71 offset:30464
	s_waitcnt lgkmcnt(0)
	v_mfma_f32_16x16x32_bf16 v[22:25], v[22:25], v[6:9], 0
	s_and_b64 vcc, exec, s[6:7]
	s_cbranch_vccz .LBB0_521
	s_branch .LBB0_522

.LBB0_526:
	s_waitcnt vmcnt(15)
	v_lshlrev_b32_e32 v4, 16, v52
	v_and_b32_e32 v5, 0xffff0000, v52
	v_fma_f32 v54, |v4|, s40, 1.0
	v_fma_f32 v55, |v5|, s40, 1.0
	v_mov_b64_e32 v[56:57], s[44:45]
	v_rcp_f32_e32 v54, v54
	v_rcp_f32_e32 v55, v55
	v_cmp_gt_f32_e32 vcc, 0, v4
	v_pk_fma_f32 v[58:59], v[54:55], s[42:43], v[56:57] op_sel_hi:[1,0,0]
	s_nop 0
	v_pk_fma_f32 v[58:59], v[54:55], v[58:59], s[48:49] op_sel_hi:[1,1,0]
	s_nop 0
	v_pk_fma_f32 v[58:59], v[54:55], v[58:59], s[50:51] op_sel_hi:[1,1,0]
	s_nop 0
	v_pk_fma_f32 v[58:59], v[54:55], v[58:59], s[56:57] op_sel_hi:[1,1,0]
	s_nop 0
	v_pk_mul_f32 v[54:55], v[54:55], v[58:59]
	v_pk_mul_f32 v[58:59], v[4:5], v[4:5]
	s_nop 0
	v_pk_mul_f32 v[58:59], v[58:59], s[64:65] op_sel_hi:[1,0]
	s_nop 0
	v_exp_f32_e32 v58, v58
	v_exp_f32_e32 v59, v59
	s_nop 0
	v_pk_mul_f32 v[54:55], v[58:59], v[54:55]
	s_nop 0
	v_pk_mul_f32 v[58:59], v[4:5], v[54:55]
	v_pk_fma_f32 v[54:55], v[4:5], v[54:55], v[4:5] neg_lo:[1,0,0] neg_hi:[1,0,0]
	v_lshlrev_b32_e32 v4, 16, v53
	v_cndmask_b32_e32 v3, v54, v58, vcc
	v_cmp_gt_f32_e32 vcc, 0, v5
	v_and_b32_e32 v5, 0xffff0000, v53
	v_fma_f32 v52, |v4|, s40, 1.0
	v_fma_f32 v53, |v5|, s40, 1.0
	v_cndmask_b32_e32 v58, v55, v59, vcc
	v_rcp_f32_e32 v52, v52
	v_rcp_f32_e32 v53, v53
	v_cmp_gt_f32_e32 vcc, 0, v4
	v_pk_fma_f32 v[54:55], v[52:53], s[42:43], v[56:57] op_sel_hi:[1,0,0]
	s_nop 0
	v_pk_fma_f32 v[54:55], v[52:53], v[54:55], s[48:49] op_sel_hi:[1,1,0]
	s_nop 0
	v_pk_fma_f32 v[54:55], v[52:53], v[54:55], s[50:51] op_sel_hi:[1,1,0]
	s_nop 0
	v_pk_fma_f32 v[54:55], v[52:53], v[54:55], s[56:57] op_sel_hi:[1,1,0]
	s_nop 0
	v_pk_mul_f32 v[52:53], v[52:53], v[54:55]
	v_pk_mul_f32 v[54:55], v[4:5], v[4:5]
	s_nop 0
	v_pk_mul_f32 v[54:55], v[54:55], s[64:65] op_sel_hi:[1,0]
	s_nop 0
	v_exp_f32_e32 v54, v54
	v_exp_f32_e32 v55, v55
	s_nop 0
	v_pk_mul_f32 v[52:53], v[54:55], v[52:53]
	s_nop 0
	v_pk_mul_f32 v[54:55], v[4:5], v[52:53]
	v_pk_fma_f32 v[52:53], v[4:5], v[52:53], v[4:5] neg_lo:[1,0,0] neg_hi:[1,0,0]
	v_add_f32_e32 v4, v72, v22
	v_cndmask_b32_e32 v52, v52, v54, vcc
	v_cmp_gt_f32_e32 vcc, 0, v5
	v_add_f32_e32 v22, v72, v25
	v_mul_f32_e32 v3, v3, v4
	v_cndmask_b32_e32 v5, v53, v55, vcc
	v_add_f32_e32 v4, v72, v23
	v_mul_f32_e32 v5, v5, v22
	v_add_co_u32_e32 v22, vcc, 0x1506e000, v34
	v_mul_f32_e32 v4, v58, v4
	s_nop 0
	v_addc_co_u32_e32 v23, vcc, 0, v35, vcc
	v_cvt_pk_bf16_f32 v4, v3, v4
	v_add_f32_e32 v3, v72, v24
	s_and_b64 vcc, exec, s[4:5]
	v_mul_f32_e32 v3, v52, v3
	v_cvt_pk_bf16_f32 v5, v3, v5
	global_store_dwordx2 v[22:23], v[4:5], off offset:224
	s_cbranch_vccnz .LBB0_528
	ds_read_b128 v[22:25], v71 offset:34816
	s_waitcnt lgkmcnt(0)
	v_mfma_f32_16x16x32_bf16 v[22:25], v[22:25], v[6:9], 0
	s_and_b64 vcc, exec, s[6:7]
	s_cbranch_vccz .LBB0_529
	s_branch .LBB0_530

.LBB0_534:
	s_waitcnt vmcnt(15)
	v_lshlrev_b32_e32 v4, 16, v50
	v_and_b32_e32 v5, 0xffff0000, v50
	v_fma_f32 v52, |v4|, s40, 1.0
	v_fma_f32 v53, |v5|, s40, 1.0
	v_mov_b64_e32 v[54:55], s[44:45]
	v_rcp_f32_e32 v52, v52
	v_rcp_f32_e32 v53, v53
	v_cmp_gt_f32_e32 vcc, 0, v4
	v_pk_fma_f32 v[56:57], v[52:53], s[42:43], v[54:55] op_sel_hi:[1,0,0]
	s_nop 0
	v_pk_fma_f32 v[56:57], v[52:53], v[56:57], s[48:49] op_sel_hi:[1,1,0]
	s_nop 0
	v_pk_fma_f32 v[56:57], v[52:53], v[56:57], s[50:51] op_sel_hi:[1,1,0]
	s_nop 0
	v_pk_fma_f32 v[56:57], v[52:53], v[56:57], s[56:57] op_sel_hi:[1,1,0]
	s_nop 0
	v_pk_mul_f32 v[52:53], v[52:53], v[56:57]
	v_pk_mul_f32 v[56:57], v[4:5], v[4:5]
	s_nop 0
	v_pk_mul_f32 v[56:57], v[56:57], s[64:65] op_sel_hi:[1,0]
	s_nop 0
	v_exp_f32_e32 v56, v56
	v_exp_f32_e32 v57, v57
	s_nop 0
	v_pk_mul_f32 v[52:53], v[56:57], v[52:53]
	s_nop 0
	v_pk_mul_f32 v[56:57], v[4:5], v[52:53]
	v_pk_fma_f32 v[52:53], v[4:5], v[52:53], v[4:5] neg_lo:[1,0,0] neg_hi:[1,0,0]
	v_lshlrev_b32_e32 v4, 16, v51
	v_cndmask_b32_e32 v3, v52, v56, vcc
	v_cmp_gt_f32_e32 vcc, 0, v5
	v_and_b32_e32 v5, 0xffff0000, v51
	v_fma_f32 v50, |v4|, s40, 1.0
	v_fma_f32 v51, |v5|, s40, 1.0
	v_cndmask_b32_e32 v56, v53, v57, vcc
	v_rcp_f32_e32 v50, v50
	v_rcp_f32_e32 v51, v51
	v_cmp_gt_f32_e32 vcc, 0, v4
	v_pk_fma_f32 v[52:53], v[50:51], s[42:43], v[54:55] op_sel_hi:[1,0,0]
	s_nop 0
	v_pk_fma_f32 v[52:53], v[50:51], v[52:53], s[48:49] op_sel_hi:[1,1,0]
	s_nop 0
	v_pk_fma_f32 v[52:53], v[50:51], v[52:53], s[50:51] op_sel_hi:[1,1,0]
	s_nop 0
	v_pk_fma_f32 v[52:53], v[50:51], v[52:53], s[56:57] op_sel_hi:[1,1,0]
	s_nop 0
	v_pk_mul_f32 v[50:51], v[50:51], v[52:53]
	v_pk_mul_f32 v[52:53], v[4:5], v[4:5]
	s_nop 0
	v_pk_mul_f32 v[52:53], v[52:53], s[64:65] op_sel_hi:[1,0]
	s_nop 0
	v_exp_f32_e32 v52, v52
	v_exp_f32_e32 v53, v53
	s_nop 0
	v_pk_mul_f32 v[50:51], v[52:53], v[50:51]
	s_nop 0
	v_pk_mul_f32 v[52:53], v[4:5], v[50:51]
	v_pk_fma_f32 v[50:51], v[4:5], v[50:51], v[4:5] neg_lo:[1,0,0] neg_hi:[1,0,0]
	v_add_f32_e32 v4, v72, v22
	v_cndmask_b32_e32 v50, v50, v52, vcc
	v_cmp_gt_f32_e32 vcc, 0, v5
	v_add_f32_e32 v22, v72, v25
	v_mul_f32_e32 v3, v3, v4
	v_cndmask_b32_e32 v5, v51, v53, vcc
	v_add_f32_e32 v4, v72, v23
	v_mul_f32_e32 v5, v5, v22
	v_add_co_u32_e32 v22, vcc, 0x1506e000, v34
	v_mul_f32_e32 v4, v56, v4
	s_nop 0
	v_addc_co_u32_e32 v23, vcc, 0, v35, vcc
	v_cvt_pk_bf16_f32 v4, v3, v4
	v_add_f32_e32 v3, v72, v24
	s_and_b64 vcc, exec, s[4:5]
	v_mul_f32_e32 v3, v50, v3
	v_cvt_pk_bf16_f32 v5, v3, v5
	global_store_dwordx2 v[22:23], v[4:5], off offset:256
	s_cbranch_vccnz .LBB0_536
	ds_read_b128 v[22:25], v71 offset:39168
	s_waitcnt lgkmcnt(0)
	v_mfma_f32_16x16x32_bf16 v[22:25], v[22:25], v[6:9], 0
	s_and_b64 vcc, exec, s[6:7]
	s_cbranch_vccz .LBB0_537
	s_branch .LBB0_538

.LBB0_542:
	s_waitcnt vmcnt(15)
	v_lshlrev_b32_e32 v4, 16, v48
	v_and_b32_e32 v5, 0xffff0000, v48
	v_fma_f32 v50, |v4|, s40, 1.0
	v_fma_f32 v51, |v5|, s40, 1.0
	v_mov_b64_e32 v[52:53], s[44:45]
	v_rcp_f32_e32 v50, v50
	v_rcp_f32_e32 v51, v51
	v_cmp_gt_f32_e32 vcc, 0, v4
	v_pk_fma_f32 v[54:55], v[50:51], s[42:43], v[52:53] op_sel_hi:[1,0,0]
	s_nop 0
	v_pk_fma_f32 v[54:55], v[50:51], v[54:55], s[48:49] op_sel_hi:[1,1,0]
	s_nop 0
	v_pk_fma_f32 v[54:55], v[50:51], v[54:55], s[50:51] op_sel_hi:[1,1,0]
	s_nop 0
	v_pk_fma_f32 v[54:55], v[50:51], v[54:55], s[56:57] op_sel_hi:[1,1,0]
	s_nop 0
	v_pk_mul_f32 v[50:51], v[50:51], v[54:55]
	v_pk_mul_f32 v[54:55], v[4:5], v[4:5]
	s_nop 0
	v_pk_mul_f32 v[54:55], v[54:55], s[64:65] op_sel_hi:[1,0]
	s_nop 0
	v_exp_f32_e32 v54, v54
	v_exp_f32_e32 v55, v55
	s_nop 0
	v_pk_mul_f32 v[50:51], v[54:55], v[50:51]
	s_nop 0
	v_pk_mul_f32 v[54:55], v[4:5], v[50:51]
	v_pk_fma_f32 v[50:51], v[4:5], v[50:51], v[4:5] neg_lo:[1,0,0] neg_hi:[1,0,0]
	v_lshlrev_b32_e32 v4, 16, v49
	v_cndmask_b32_e32 v3, v50, v54, vcc
	v_cmp_gt_f32_e32 vcc, 0, v5
	v_and_b32_e32 v5, 0xffff0000, v49
	v_fma_f32 v48, |v4|, s40, 1.0
	v_fma_f32 v49, |v5|, s40, 1.0
	v_cndmask_b32_e32 v54, v51, v55, vcc
	v_rcp_f32_e32 v48, v48
	v_rcp_f32_e32 v49, v49
	v_cmp_gt_f32_e32 vcc, 0, v4
	v_pk_fma_f32 v[50:51], v[48:49], s[42:43], v[52:53] op_sel_hi:[1,0,0]
	s_nop 0
	v_pk_fma_f32 v[50:51], v[48:49], v[50:51], s[48:49] op_sel_hi:[1,1,0]
	s_nop 0
	v_pk_fma_f32 v[50:51], v[48:49], v[50:51], s[50:51] op_sel_hi:[1,1,0]
	s_nop 0
	v_pk_fma_f32 v[50:51], v[48:49], v[50:51], s[56:57] op_sel_hi:[1,1,0]
	s_nop 0
	v_pk_mul_f32 v[48:49], v[48:49], v[50:51]
	v_pk_mul_f32 v[50:51], v[4:5], v[4:5]
	s_nop 0
	v_pk_mul_f32 v[50:51], v[50:51], s[64:65] op_sel_hi:[1,0]
	s_nop 0
	v_exp_f32_e32 v50, v50
	v_exp_f32_e32 v51, v51
	s_nop 0
	v_pk_mul_f32 v[48:49], v[50:51], v[48:49]
	s_nop 0
	v_pk_mul_f32 v[50:51], v[4:5], v[48:49]
	v_pk_fma_f32 v[48:49], v[4:5], v[48:49], v[4:5] neg_lo:[1,0,0] neg_hi:[1,0,0]
	v_add_f32_e32 v4, v72, v22
	v_cndmask_b32_e32 v48, v48, v50, vcc
	v_cmp_gt_f32_e32 vcc, 0, v5
	v_add_f32_e32 v22, v72, v25
	v_mul_f32_e32 v3, v3, v4
	v_cndmask_b32_e32 v5, v49, v51, vcc
	v_add_f32_e32 v4, v72, v23
	v_mul_f32_e32 v5, v5, v22
	v_add_co_u32_e32 v22, vcc, 0x1506e000, v34
	v_mul_f32_e32 v4, v54, v4
	s_nop 0
	v_addc_co_u32_e32 v23, vcc, 0, v35, vcc
	v_cvt_pk_bf16_f32 v4, v3, v4
	v_add_f32_e32 v3, v72, v24
	s_and_b64 vcc, exec, s[4:5]
	v_mul_f32_e32 v3, v48, v3
	v_cvt_pk_bf16_f32 v5, v3, v5
	global_store_dwordx2 v[22:23], v[4:5], off offset:288
	s_cbranch_vccnz .LBB0_544
	ds_read_b128 v[22:25], v71 offset:43520
	s_waitcnt lgkmcnt(0)
	v_mfma_f32_16x16x32_bf16 v[22:25], v[22:25], v[6:9], 0
	s_and_b64 vcc, exec, s[6:7]
	s_cbranch_vccz .LBB0_545
	s_branch .LBB0_546

.LBB0_550:
	s_waitcnt vmcnt(15)
	v_lshlrev_b32_e32 v4, 16, v46
	v_and_b32_e32 v5, 0xffff0000, v46
	v_fma_f32 v48, |v4|, s40, 1.0
	v_fma_f32 v49, |v5|, s40, 1.0
	v_mov_b64_e32 v[50:51], s[44:45]
	v_rcp_f32_e32 v48, v48
	v_rcp_f32_e32 v49, v49
	v_cmp_gt_f32_e32 vcc, 0, v4
	v_pk_fma_f32 v[52:53], v[48:49], s[42:43], v[50:51] op_sel_hi:[1,0,0]
	s_nop 0
	v_pk_fma_f32 v[52:53], v[48:49], v[52:53], s[48:49] op_sel_hi:[1,1,0]
	s_nop 0
	v_pk_fma_f32 v[52:53], v[48:49], v[52:53], s[50:51] op_sel_hi:[1,1,0]
	s_nop 0
	v_pk_fma_f32 v[52:53], v[48:49], v[52:53], s[56:57] op_sel_hi:[1,1,0]
	s_nop 0
	v_pk_mul_f32 v[48:49], v[48:49], v[52:53]
	v_pk_mul_f32 v[52:53], v[4:5], v[4:5]
	s_nop 0
	v_pk_mul_f32 v[52:53], v[52:53], s[64:65] op_sel_hi:[1,0]
	s_nop 0
	v_exp_f32_e32 v52, v52
	v_exp_f32_e32 v53, v53
	s_nop 0
	v_pk_mul_f32 v[48:49], v[52:53], v[48:49]
	s_nop 0
	v_pk_mul_f32 v[52:53], v[4:5], v[48:49]
	v_pk_fma_f32 v[48:49], v[4:5], v[48:49], v[4:5] neg_lo:[1,0,0] neg_hi:[1,0,0]
	v_lshlrev_b32_e32 v4, 16, v47
	v_cndmask_b32_e32 v3, v48, v52, vcc
	v_cmp_gt_f32_e32 vcc, 0, v5
	v_and_b32_e32 v5, 0xffff0000, v47
	v_fma_f32 v46, |v4|, s40, 1.0
	v_fma_f32 v47, |v5|, s40, 1.0
	v_cndmask_b32_e32 v52, v49, v53, vcc
	v_rcp_f32_e32 v46, v46
	v_rcp_f32_e32 v47, v47
	v_cmp_gt_f32_e32 vcc, 0, v4
	v_pk_fma_f32 v[48:49], v[46:47], s[42:43], v[50:51] op_sel_hi:[1,0,0]
	s_nop 0
	v_pk_fma_f32 v[48:49], v[46:47], v[48:49], s[48:49] op_sel_hi:[1,1,0]
	s_nop 0
	v_pk_fma_f32 v[48:49], v[46:47], v[48:49], s[50:51] op_sel_hi:[1,1,0]
	s_nop 0
	v_pk_fma_f32 v[48:49], v[46:47], v[48:49], s[56:57] op_sel_hi:[1,1,0]
	s_nop 0
	v_pk_mul_f32 v[46:47], v[46:47], v[48:49]
	v_pk_mul_f32 v[48:49], v[4:5], v[4:5]
	s_nop 0
	v_pk_mul_f32 v[48:49], v[48:49], s[64:65] op_sel_hi:[1,0]
	s_nop 0
	v_exp_f32_e32 v48, v48
	v_exp_f32_e32 v49, v49
	s_nop 0
	v_pk_mul_f32 v[46:47], v[48:49], v[46:47]
	s_nop 0
	v_pk_mul_f32 v[48:49], v[4:5], v[46:47]
	v_pk_fma_f32 v[46:47], v[4:5], v[46:47], v[4:5] neg_lo:[1,0,0] neg_hi:[1,0,0]
	v_add_f32_e32 v4, v72, v22
	v_cndmask_b32_e32 v46, v46, v48, vcc
	v_cmp_gt_f32_e32 vcc, 0, v5
	v_add_f32_e32 v22, v72, v25
	v_mul_f32_e32 v3, v3, v4
	v_cndmask_b32_e32 v5, v47, v49, vcc
	v_add_f32_e32 v4, v72, v23
	v_mul_f32_e32 v5, v5, v22
	v_add_co_u32_e32 v22, vcc, 0x1506e000, v34
	v_mul_f32_e32 v4, v52, v4
	s_nop 0
	v_addc_co_u32_e32 v23, vcc, 0, v35, vcc
	v_cvt_pk_bf16_f32 v4, v3, v4
	v_add_f32_e32 v3, v72, v24
	s_and_b64 vcc, exec, s[4:5]
	v_mul_f32_e32 v3, v46, v3
	v_cvt_pk_bf16_f32 v5, v3, v5
	global_store_dwordx2 v[22:23], v[4:5], off offset:320
	s_cbranch_vccnz .LBB0_552
	ds_read_b128 v[22:25], v71 offset:47872
	s_waitcnt lgkmcnt(0)
	v_mfma_f32_16x16x32_bf16 v[22:25], v[22:25], v[6:9], 0
	s_and_b64 vcc, exec, s[6:7]
	s_cbranch_vccz .LBB0_553
	s_branch .LBB0_554

.LBB0_558:
	s_waitcnt vmcnt(15)
	v_lshlrev_b32_e32 v4, 16, v44
	v_and_b32_e32 v5, 0xffff0000, v44
	v_fma_f32 v46, |v4|, s40, 1.0
	v_fma_f32 v47, |v5|, s40, 1.0
	v_mov_b64_e32 v[48:49], s[44:45]
	v_rcp_f32_e32 v46, v46
	v_rcp_f32_e32 v47, v47
	v_cmp_gt_f32_e32 vcc, 0, v4
	v_pk_fma_f32 v[50:51], v[46:47], s[42:43], v[48:49] op_sel_hi:[1,0,0]
	s_nop 0
	v_pk_fma_f32 v[50:51], v[46:47], v[50:51], s[48:49] op_sel_hi:[1,1,0]
	s_nop 0
	v_pk_fma_f32 v[50:51], v[46:47], v[50:51], s[50:51] op_sel_hi:[1,1,0]
	s_nop 0
	v_pk_fma_f32 v[50:51], v[46:47], v[50:51], s[56:57] op_sel_hi:[1,1,0]
	s_nop 0
	v_pk_mul_f32 v[46:47], v[46:47], v[50:51]
	v_pk_mul_f32 v[50:51], v[4:5], v[4:5]
	s_nop 0
	v_pk_mul_f32 v[50:51], v[50:51], s[64:65] op_sel_hi:[1,0]
	s_nop 0
	v_exp_f32_e32 v50, v50
	v_exp_f32_e32 v51, v51
	s_nop 0
	v_pk_mul_f32 v[46:47], v[50:51], v[46:47]
	s_nop 0
	v_pk_mul_f32 v[50:51], v[4:5], v[46:47]
	v_pk_fma_f32 v[46:47], v[4:5], v[46:47], v[4:5] neg_lo:[1,0,0] neg_hi:[1,0,0]
	v_lshlrev_b32_e32 v4, 16, v45
	v_cndmask_b32_e32 v3, v46, v50, vcc
	v_cmp_gt_f32_e32 vcc, 0, v5
	v_and_b32_e32 v5, 0xffff0000, v45
	v_fma_f32 v44, |v4|, s40, 1.0
	v_fma_f32 v45, |v5|, s40, 1.0
	v_cndmask_b32_e32 v50, v47, v51, vcc
	v_rcp_f32_e32 v44, v44
	v_rcp_f32_e32 v45, v45
	v_cmp_gt_f32_e32 vcc, 0, v4
	v_pk_fma_f32 v[46:47], v[44:45], s[42:43], v[48:49] op_sel_hi:[1,0,0]
	s_nop 0
	v_pk_fma_f32 v[46:47], v[44:45], v[46:47], s[48:49] op_sel_hi:[1,1,0]
	s_nop 0
	v_pk_fma_f32 v[46:47], v[44:45], v[46:47], s[50:51] op_sel_hi:[1,1,0]
	s_nop 0
	v_pk_fma_f32 v[46:47], v[44:45], v[46:47], s[56:57] op_sel_hi:[1,1,0]
	s_nop 0
	v_pk_mul_f32 v[44:45], v[44:45], v[46:47]
	v_pk_mul_f32 v[46:47], v[4:5], v[4:5]
	s_nop 0
	v_pk_mul_f32 v[46:47], v[46:47], s[64:65] op_sel_hi:[1,0]
	s_nop 0
	v_exp_f32_e32 v46, v46
	v_exp_f32_e32 v47, v47
	s_nop 0
	v_pk_mul_f32 v[44:45], v[46:47], v[44:45]
	s_nop 0
	v_pk_mul_f32 v[46:47], v[4:5], v[44:45]
	v_pk_fma_f32 v[44:45], v[4:5], v[44:45], v[4:5] neg_lo:[1,0,0] neg_hi:[1,0,0]
	v_add_f32_e32 v4, v72, v22
	v_cndmask_b32_e32 v44, v44, v46, vcc
	v_cmp_gt_f32_e32 vcc, 0, v5
	v_add_f32_e32 v22, v72, v25
	v_mul_f32_e32 v3, v3, v4
	v_cndmask_b32_e32 v5, v45, v47, vcc
	v_add_f32_e32 v4, v72, v23
	v_mul_f32_e32 v5, v5, v22
	v_add_co_u32_e32 v22, vcc, 0x1506e000, v34
	v_mul_f32_e32 v4, v50, v4
	s_nop 0
	v_addc_co_u32_e32 v23, vcc, 0, v35, vcc
	v_cvt_pk_bf16_f32 v4, v3, v4
	v_add_f32_e32 v3, v72, v24
	s_and_b64 vcc, exec, s[4:5]
	v_mul_f32_e32 v3, v44, v3
	v_cvt_pk_bf16_f32 v5, v3, v5
	global_store_dwordx2 v[22:23], v[4:5], off offset:352
	s_cbranch_vccnz .LBB0_560
	ds_read_b128 v[22:25], v71 offset:52224
	s_waitcnt lgkmcnt(0)
	v_mfma_f32_16x16x32_bf16 v[22:25], v[22:25], v[6:9], 0
	s_and_b64 vcc, exec, s[6:7]
	s_cbranch_vccz .LBB0_561
	s_branch .LBB0_562

.LBB0_566:
	s_waitcnt vmcnt(15)
	v_lshlrev_b32_e32 v4, 16, v42
	v_and_b32_e32 v5, 0xffff0000, v42
	v_fma_f32 v44, |v4|, s40, 1.0
	v_fma_f32 v45, |v5|, s40, 1.0
	v_mov_b64_e32 v[46:47], s[44:45]
	v_rcp_f32_e32 v44, v44
	v_rcp_f32_e32 v45, v45
	v_cmp_gt_f32_e32 vcc, 0, v4
	v_pk_fma_f32 v[48:49], v[44:45], s[42:43], v[46:47] op_sel_hi:[1,0,0]
	s_nop 0
	v_pk_fma_f32 v[48:49], v[44:45], v[48:49], s[48:49] op_sel_hi:[1,1,0]
	s_nop 0
	v_pk_fma_f32 v[48:49], v[44:45], v[48:49], s[50:51] op_sel_hi:[1,1,0]
	s_nop 0
	v_pk_fma_f32 v[48:49], v[44:45], v[48:49], s[56:57] op_sel_hi:[1,1,0]
	s_nop 0
	v_pk_mul_f32 v[44:45], v[44:45], v[48:49]
	v_pk_mul_f32 v[48:49], v[4:5], v[4:5]
	s_nop 0
	v_pk_mul_f32 v[48:49], v[48:49], s[64:65] op_sel_hi:[1,0]
	s_nop 0
	v_exp_f32_e32 v48, v48
	v_exp_f32_e32 v49, v49
	s_nop 0
	v_pk_mul_f32 v[44:45], v[48:49], v[44:45]
	s_nop 0
	v_pk_mul_f32 v[48:49], v[4:5], v[44:45]
	v_pk_fma_f32 v[44:45], v[4:5], v[44:45], v[4:5] neg_lo:[1,0,0] neg_hi:[1,0,0]
	v_lshlrev_b32_e32 v4, 16, v43
	v_cndmask_b32_e32 v3, v44, v48, vcc
	v_cmp_gt_f32_e32 vcc, 0, v5
	v_and_b32_e32 v5, 0xffff0000, v43
	v_fma_f32 v42, |v4|, s40, 1.0
	v_fma_f32 v43, |v5|, s40, 1.0
	v_cndmask_b32_e32 v48, v45, v49, vcc
	v_rcp_f32_e32 v42, v42
	v_rcp_f32_e32 v43, v43
	v_cmp_gt_f32_e32 vcc, 0, v4
	v_pk_fma_f32 v[44:45], v[42:43], s[42:43], v[46:47] op_sel_hi:[1,0,0]
	s_nop 0
	v_pk_fma_f32 v[44:45], v[42:43], v[44:45], s[48:49] op_sel_hi:[1,1,0]
	s_nop 0
	v_pk_fma_f32 v[44:45], v[42:43], v[44:45], s[50:51] op_sel_hi:[1,1,0]
	s_nop 0
	v_pk_fma_f32 v[44:45], v[42:43], v[44:45], s[56:57] op_sel_hi:[1,1,0]
	s_nop 0
	v_pk_mul_f32 v[42:43], v[42:43], v[44:45]
	v_pk_mul_f32 v[44:45], v[4:5], v[4:5]
	s_nop 0
	v_pk_mul_f32 v[44:45], v[44:45], s[64:65] op_sel_hi:[1,0]
	s_nop 0
	v_exp_f32_e32 v44, v44
	v_exp_f32_e32 v45, v45
	s_nop 0
	v_pk_mul_f32 v[42:43], v[44:45], v[42:43]
	s_nop 0
	v_pk_mul_f32 v[44:45], v[4:5], v[42:43]
	v_pk_fma_f32 v[42:43], v[4:5], v[42:43], v[4:5] neg_lo:[1,0,0] neg_hi:[1,0,0]
	v_add_f32_e32 v4, v72, v22
	v_cndmask_b32_e32 v42, v42, v44, vcc
	v_cmp_gt_f32_e32 vcc, 0, v5
	v_add_f32_e32 v22, v72, v25
	v_mul_f32_e32 v3, v3, v4
	v_cndmask_b32_e32 v5, v43, v45, vcc
	v_add_f32_e32 v4, v72, v23
	v_mul_f32_e32 v5, v5, v22
	v_add_co_u32_e32 v22, vcc, 0x1506e000, v34
	v_mul_f32_e32 v4, v48, v4
	s_nop 0
	v_addc_co_u32_e32 v23, vcc, 0, v35, vcc
	v_cvt_pk_bf16_f32 v4, v3, v4
	v_add_f32_e32 v3, v72, v24
	s_and_b64 vcc, exec, s[4:5]
	v_mul_f32_e32 v3, v42, v3
	v_cvt_pk_bf16_f32 v5, v3, v5
	global_store_dwordx2 v[22:23], v[4:5], off offset:384
	s_cbranch_vccnz .LBB0_568
	ds_read_b128 v[22:25], v71 offset:56576
	s_waitcnt lgkmcnt(0)
	v_mfma_f32_16x16x32_bf16 v[22:25], v[22:25], v[6:9], 0
	s_and_b64 vcc, exec, s[6:7]
	s_cbranch_vccz .LBB0_569
	s_branch .LBB0_570

.LBB0_574:
	s_waitcnt vmcnt(15)
	v_lshlrev_b32_e32 v4, 16, v40
	v_and_b32_e32 v5, 0xffff0000, v40
	v_fma_f32 v42, |v4|, s40, 1.0
	v_fma_f32 v43, |v5|, s40, 1.0
	v_mov_b64_e32 v[44:45], s[44:45]
	v_rcp_f32_e32 v42, v42
	v_rcp_f32_e32 v43, v43
	v_cmp_gt_f32_e32 vcc, 0, v4
	v_pk_fma_f32 v[46:47], v[42:43], s[42:43], v[44:45] op_sel_hi:[1,0,0]
	s_nop 0
	v_pk_fma_f32 v[46:47], v[42:43], v[46:47], s[48:49] op_sel_hi:[1,1,0]
	s_nop 0
	v_pk_fma_f32 v[46:47], v[42:43], v[46:47], s[50:51] op_sel_hi:[1,1,0]
	s_nop 0
	v_pk_fma_f32 v[46:47], v[42:43], v[46:47], s[56:57] op_sel_hi:[1,1,0]
	s_nop 0
	v_pk_mul_f32 v[42:43], v[42:43], v[46:47]
	v_pk_mul_f32 v[46:47], v[4:5], v[4:5]
	s_nop 0
	v_pk_mul_f32 v[46:47], v[46:47], s[64:65] op_sel_hi:[1,0]
	s_nop 0
	v_exp_f32_e32 v46, v46
	v_exp_f32_e32 v47, v47
	s_nop 0
	v_pk_mul_f32 v[42:43], v[46:47], v[42:43]
	s_nop 0
	v_pk_mul_f32 v[46:47], v[4:5], v[42:43]
	v_pk_fma_f32 v[42:43], v[4:5], v[42:43], v[4:5] neg_lo:[1,0,0] neg_hi:[1,0,0]
	v_lshlrev_b32_e32 v4, 16, v41
	v_cndmask_b32_e32 v3, v42, v46, vcc
	v_cmp_gt_f32_e32 vcc, 0, v5
	v_and_b32_e32 v5, 0xffff0000, v41
	v_fma_f32 v40, |v4|, s40, 1.0
	v_fma_f32 v41, |v5|, s40, 1.0
	v_cndmask_b32_e32 v46, v43, v47, vcc
	v_rcp_f32_e32 v40, v40
	v_rcp_f32_e32 v41, v41
	v_cmp_gt_f32_e32 vcc, 0, v4
	v_pk_fma_f32 v[42:43], v[40:41], s[42:43], v[44:45] op_sel_hi:[1,0,0]
	s_nop 0
	v_pk_fma_f32 v[42:43], v[40:41], v[42:43], s[48:49] op_sel_hi:[1,1,0]
	s_nop 0
	v_pk_fma_f32 v[42:43], v[40:41], v[42:43], s[50:51] op_sel_hi:[1,1,0]
	s_nop 0
	v_pk_fma_f32 v[42:43], v[40:41], v[42:43], s[56:57] op_sel_hi:[1,1,0]
	s_nop 0
	v_pk_mul_f32 v[40:41], v[40:41], v[42:43]
	v_pk_mul_f32 v[42:43], v[4:5], v[4:5]
	s_nop 0
	v_pk_mul_f32 v[42:43], v[42:43], s[64:65] op_sel_hi:[1,0]
	s_nop 0
	v_exp_f32_e32 v42, v42
	v_exp_f32_e32 v43, v43
	s_nop 0
	v_pk_mul_f32 v[40:41], v[42:43], v[40:41]
	s_nop 0
	v_pk_mul_f32 v[42:43], v[4:5], v[40:41]
	v_pk_fma_f32 v[40:41], v[4:5], v[40:41], v[4:5] neg_lo:[1,0,0] neg_hi:[1,0,0]
	v_add_f32_e32 v4, v72, v22
	v_cndmask_b32_e32 v40, v40, v42, vcc
	v_cmp_gt_f32_e32 vcc, 0, v5
	v_add_f32_e32 v22, v72, v25
	v_mul_f32_e32 v3, v3, v4
	v_cndmask_b32_e32 v5, v41, v43, vcc
	v_add_f32_e32 v4, v72, v23
	v_mul_f32_e32 v5, v5, v22
	v_add_co_u32_e32 v22, vcc, 0x1506e000, v34
	v_mul_f32_e32 v4, v46, v4
	s_nop 0
	v_addc_co_u32_e32 v23, vcc, 0, v35, vcc
	v_cvt_pk_bf16_f32 v4, v3, v4
	v_add_f32_e32 v3, v72, v24
	s_and_b64 vcc, exec, s[4:5]
	v_mul_f32_e32 v3, v40, v3
	v_cvt_pk_bf16_f32 v5, v3, v5
	global_store_dwordx2 v[22:23], v[4:5], off offset:416
	s_cbranch_vccnz .LBB0_576
	ds_read_b128 v[22:25], v71 offset:60928
	s_waitcnt lgkmcnt(0)
	v_mfma_f32_16x16x32_bf16 v[22:25], v[22:25], v[6:9], 0
	s_and_b64 vcc, exec, s[6:7]
	s_cbranch_vccz .LBB0_577
	s_branch .LBB0_578

.LBB0_582:
	s_waitcnt vmcnt(15)
	v_lshlrev_b32_e32 v4, 16, v38
	v_and_b32_e32 v5, 0xffff0000, v38
	v_fma_f32 v40, |v4|, s40, 1.0
	v_fma_f32 v41, |v5|, s40, 1.0
	v_mov_b64_e32 v[42:43], s[44:45]
	v_rcp_f32_e32 v40, v40
	v_rcp_f32_e32 v41, v41
	v_cmp_gt_f32_e32 vcc, 0, v4
	v_pk_fma_f32 v[44:45], v[40:41], s[42:43], v[42:43] op_sel_hi:[1,0,0]
	s_nop 0
	v_pk_fma_f32 v[44:45], v[40:41], v[44:45], s[48:49] op_sel_hi:[1,1,0]
	s_nop 0
	v_pk_fma_f32 v[44:45], v[40:41], v[44:45], s[50:51] op_sel_hi:[1,1,0]
	s_nop 0
	v_pk_fma_f32 v[44:45], v[40:41], v[44:45], s[56:57] op_sel_hi:[1,1,0]
	s_nop 0
	v_pk_mul_f32 v[40:41], v[40:41], v[44:45]
	v_pk_mul_f32 v[44:45], v[4:5], v[4:5]
	s_nop 0
	v_pk_mul_f32 v[44:45], v[44:45], s[64:65] op_sel_hi:[1,0]
	s_nop 0
	v_exp_f32_e32 v44, v44
	v_exp_f32_e32 v45, v45
	s_nop 0
	v_pk_mul_f32 v[40:41], v[44:45], v[40:41]
	s_nop 0
	v_pk_mul_f32 v[44:45], v[4:5], v[40:41]
	v_pk_fma_f32 v[40:41], v[4:5], v[40:41], v[4:5] neg_lo:[1,0,0] neg_hi:[1,0,0]
	v_lshlrev_b32_e32 v4, 16, v39
	v_cndmask_b32_e32 v3, v40, v44, vcc
	v_cmp_gt_f32_e32 vcc, 0, v5
	v_and_b32_e32 v5, 0xffff0000, v39
	v_fma_f32 v38, |v4|, s40, 1.0
	v_fma_f32 v39, |v5|, s40, 1.0
	v_cndmask_b32_e32 v44, v41, v45, vcc
	v_rcp_f32_e32 v38, v38
	v_rcp_f32_e32 v39, v39
	v_cmp_gt_f32_e32 vcc, 0, v4
	v_pk_fma_f32 v[40:41], v[38:39], s[42:43], v[42:43] op_sel_hi:[1,0,0]
	s_nop 0
	v_pk_fma_f32 v[40:41], v[38:39], v[40:41], s[48:49] op_sel_hi:[1,1,0]
	s_nop 0
	v_pk_fma_f32 v[40:41], v[38:39], v[40:41], s[50:51] op_sel_hi:[1,1,0]
	s_nop 0
	v_pk_fma_f32 v[40:41], v[38:39], v[40:41], s[56:57] op_sel_hi:[1,1,0]
	s_nop 0
	v_pk_mul_f32 v[38:39], v[38:39], v[40:41]
	v_pk_mul_f32 v[40:41], v[4:5], v[4:5]
	s_nop 0
	v_pk_mul_f32 v[40:41], v[40:41], s[64:65] op_sel_hi:[1,0]
	s_nop 0
	v_exp_f32_e32 v40, v40
	v_exp_f32_e32 v41, v41
	s_nop 0
	v_pk_mul_f32 v[38:39], v[40:41], v[38:39]
	s_nop 0
	v_pk_mul_f32 v[40:41], v[4:5], v[38:39]
	v_pk_fma_f32 v[38:39], v[4:5], v[38:39], v[4:5] neg_lo:[1,0,0] neg_hi:[1,0,0]
	v_add_f32_e32 v4, v72, v22
	v_cndmask_b32_e32 v38, v38, v40, vcc
	v_cmp_gt_f32_e32 vcc, 0, v5
	v_add_f32_e32 v22, v72, v25
	v_mul_f32_e32 v3, v3, v4
	v_cndmask_b32_e32 v5, v39, v41, vcc
	v_add_f32_e32 v4, v72, v23
	v_mul_f32_e32 v5, v5, v22
	v_add_co_u32_e32 v22, vcc, 0x1506e000, v34
	v_mul_f32_e32 v4, v44, v4
	s_nop 0
	v_addc_co_u32_e32 v23, vcc, 0, v35, vcc
	v_cvt_pk_bf16_f32 v4, v3, v4
	v_add_f32_e32 v3, v72, v24
	s_and_b64 vcc, exec, s[4:5]
	v_mul_f32_e32 v3, v38, v3
	v_cvt_pk_bf16_f32 v5, v3, v5
	global_store_dwordx2 v[22:23], v[4:5], off offset:448
	s_cbranch_vccnz .LBB0_584
	ds_read_b128 v[22:25], v71 offset:65280
	s_waitcnt lgkmcnt(0)
	v_mfma_f32_16x16x32_bf16 v[4:7], v[22:25], v[6:9], 0
	s_and_b64 vcc, exec, s[6:7]
	s_cbranch_vccz .LBB0_585
	s_branch .LBB0_586
